# GEMM K-loops: per-phase s_setprio flips removed, one static priority raise for waves 4-7 at kernel entry
# speedup vs baseline: 1.0200x; 1.0131x over previous
_Z11mega_kernel6Params:
	v_readfirstlane_b32 s94, v0
	s_nop 3
	s_and_b32 s94, s94, 0x3ff
	s_lshr_b32 s94, s94, 6
	s_cmp_ge_u32 s94, 4
	s_cbranch_scc0 .Lprio_done
	s_setprio 1
.Lprio_done:
	s_load_dwordx16 s[36:51], s[0:1], 0x100
	s_load_dwordx2 s[24:25], s[0:1], 0x140
	v_and_b32_e32 v129, 0x3ff, v0
	v_cmp_gt_u32_e32 vcc, 4, v129
	s_and_saveexec_b64 s[4:5], vcc
	v_lshl_add_u32 v1, v129, 2, 0
	v_add_u32_e32 v1, 0x20000, v1
	v_mov_b32_e32 v2, 0
	ds_write_b32 v1, v2
	s_or_b64 exec, exec, s[4:5]
	s_waitcnt lgkmcnt(0)
	s_barrier
	s_getreg_b32 s3, hwreg(HW_REG_XCC_ID, 0, 4)
	s_and_b32 s33, s3, 15
	v_cmp_eq_u32_e64 s[92:93], 0, v129
	s_and_saveexec_b64 s[4:5], s[92:93]
	s_cbranch_execz .LBB0_5
	s_mov_b64 s[6:7], exec
	v_mbcnt_lo_u32_b32 v1, s6, 0
	v_mbcnt_hi_u32_b32 v1, s7, v1
	v_cmp_eq_u32_e32 vcc, 0, v1
	s_and_b64 s[8:9], exec, vcc
	s_mov_b64 exec, s[8:9]
	s_cbranch_execz .LBB0_5
	s_lshl_b32 s3, s33, 8
	s_bcnt1_i32_b64 s6, s[6:7]
	v_mov_b32_e32 v1, s3
	v_mov_b32_e32 v2, s6
	global_atomic_add v1, v2, s[48:49] offset:1024

.LBB0_155:
	ds_read_b128 v[154:157], v150
	ds_read_b128 v[158:161], v150 offset:1024
	ds_read_b128 v[162:165], v150 offset:2048
	ds_read_b128 v[166:169], v150 offset:3072
	s_add_u32 s26, s20, 0xfffc0080
	s_addc_u32 s27, s21, -1
	s_cmp_eq_u32 s86, 12
	s_cselect_b32 s29, s15, s27
	s_cselect_b32 s28, s82, s26
	s_cselect_b32 s27, s13, s85
	s_cselect_b32 s26, s83, s84
	v_lshl_add_u64 v[202:203], s[20:21], 0, v[138:139]
	s_add_i32 m0, s11, 0xc000
	ds_read_b128 v[170:173], v151
	ds_read_b128 v[174:177], v151 offset:1024
	ds_read_b128 v[178:181], v151 offset:2048
	ds_read_b128 v[182:185], v151 offset:3072
	ds_read_b128 v[186:189], v151 offset:4096
	ds_read_b128 v[190:193], v151 offset:5120
	ds_read_b128 v[194:197], v151 offset:6144
	ds_read_b128 v[198:201], v151 offset:7168
	global_load_lds_dwordx4 v[202:203], off
	v_lshl_add_u64 v[202:203], s[20:21], 0, v[140:141]
	s_add_i32 m0, s11, 0xe000
	s_nop 0
	global_load_lds_dwordx4 v[202:203], off
	s_waitcnt lgkmcnt(8)
	s_barrier
	s_waitcnt lgkmcnt(0)
	s_waitcnt lgkmcnt(0)
	v_mfma_f32_16x16x32_bf16 v[124:127], v[154:157], v[170:173], v[124:127]
	v_mfma_f32_16x16x32_bf16 v[120:123], v[162:165], v[170:173], v[120:123]
	v_mfma_f32_16x16x32_bf16 v[116:119], v[154:157], v[178:181], v[116:119]
	v_mfma_f32_16x16x32_bf16 v[112:115], v[162:165], v[178:181], v[112:115]
	v_mfma_f32_16x16x32_bf16 v[100:103], v[154:157], v[186:189], v[100:103]
	v_mfma_f32_16x16x32_bf16 v[96:99], v[162:165], v[186:189], v[96:99]
	v_mfma_f32_16x16x32_bf16 v[84:87], v[154:157], v[194:197], v[84:87]
	v_mfma_f32_16x16x32_bf16 v[80:83], v[162:165], v[194:197], v[80:83]
	v_mfma_f32_16x16x32_bf16 v[124:127], v[158:161], v[174:177], v[124:127]
	v_mfma_f32_16x16x32_bf16 v[120:123], v[166:169], v[174:177], v[120:123]
	v_mfma_f32_16x16x32_bf16 v[116:119], v[158:161], v[182:185], v[116:119]
	v_mfma_f32_16x16x32_bf16 v[112:115], v[166:169], v[182:185], v[112:115]
	v_mfma_f32_16x16x32_bf16 v[100:103], v[158:161], v[190:193], v[100:103]
	v_mfma_f32_16x16x32_bf16 v[96:99], v[166:169], v[190:193], v[96:99]
	v_mfma_f32_16x16x32_bf16 v[84:87], v[158:161], v[198:201], v[84:87]
	v_mfma_f32_16x16x32_bf16 v[80:83], v[166:169], v[198:201], v[80:83]
	s_barrier
	s_add_i32 s87, s72, s34
	v_lshl_add_u64 v[218:219], s[26:27], 0, v[134:135]
	s_mov_b32 m0, s87
	ds_read_b128 v[202:205], v152
	ds_read_b128 v[206:209], v152 offset:1024
	ds_read_b128 v[210:213], v152 offset:2048
	ds_read_b128 v[214:217], v152 offset:3072
	global_load_lds_dwordx4 v[218:219], off
	v_lshl_add_u64 v[220:221], s[26:27], 0, v[130:131]
	s_add_i32 m0, s87, 0x2000
	s_nop 0
	global_load_lds_dwordx4 v[220:221], off
	s_barrier
	s_waitcnt lgkmcnt(0)
	s_waitcnt lgkmcnt(0)
	v_mfma_f32_16x16x32_bf16 v[108:111], v[202:205], v[170:173], v[108:111]
	v_mfma_f32_16x16x32_bf16 v[104:107], v[210:213], v[170:173], v[104:107]
	v_mfma_f32_16x16x32_bf16 v[92:95], v[202:205], v[178:181], v[92:95]
	v_mfma_f32_16x16x32_bf16 v[88:91], v[210:213], v[178:181], v[88:91]
	v_mfma_f32_16x16x32_bf16 v[76:79], v[202:205], v[186:189], v[76:79]
	v_mfma_f32_16x16x32_bf16 v[72:75], v[210:213], v[186:189], v[72:75]
	v_mfma_f32_16x16x32_bf16 v[68:71], v[202:205], v[194:197], v[68:71]
	v_mfma_f32_16x16x32_bf16 v[64:67], v[210:213], v[194:197], v[64:67]
	v_mfma_f32_16x16x32_bf16 v[108:111], v[206:209], v[174:177], v[108:111]
	v_mfma_f32_16x16x32_bf16 v[104:107], v[214:217], v[174:177], v[104:107]
	v_mfma_f32_16x16x32_bf16 v[92:95], v[206:209], v[182:185], v[92:95]
	v_mfma_f32_16x16x32_bf16 v[88:91], v[214:217], v[182:185], v[88:91]
	v_mfma_f32_16x16x32_bf16 v[76:79], v[206:209], v[190:193], v[76:79]
	v_mfma_f32_16x16x32_bf16 v[72:75], v[214:217], v[190:193], v[72:75]
	v_mfma_f32_16x16x32_bf16 v[68:71], v[206:209], v[198:201], v[68:71]
	v_mfma_f32_16x16x32_bf16 v[64:67], v[214:217], v[198:201], v[64:67]
	s_mov_b32 m0, s11
	v_lshl_add_u64 v[222:223], s[28:29], 0, v[136:137]
	s_barrier
	ds_read_b128 v[170:173], v151 offset:16384
	ds_read_b128 v[174:177], v151 offset:17408
	ds_read_b128 v[178:181], v151 offset:18432
	ds_read_b128 v[182:185], v151 offset:19456
	ds_read_b128 v[186:189], v151 offset:20480
	ds_read_b128 v[190:193], v151 offset:21504
	ds_read_b128 v[194:197], v151 offset:22528
	ds_read_b128 v[198:201], v151 offset:23552
	global_load_lds_dwordx4 v[222:223], off
	v_lshl_add_u64 v[224:225], s[28:29], 0, v[132:133]
	s_mov_b32 m0, s35
	s_nop 0
	global_load_lds_dwordx4 v[224:225], off
	s_barrier
	s_waitcnt lgkmcnt(0)
	s_waitcnt lgkmcnt(0)
	v_mfma_f32_16x16x32_bf16 v[60:63], v[154:157], v[170:173], v[60:63]
	v_mfma_f32_16x16x32_bf16 v[56:59], v[162:165], v[170:173], v[56:59]
	v_mfma_f32_16x16x32_bf16 v[52:55], v[154:157], v[178:181], v[52:55]
	v_mfma_f32_16x16x32_bf16 v[48:51], v[162:165], v[178:181], v[48:51]
	v_mfma_f32_16x16x32_bf16 v[36:39], v[154:157], v[186:189], v[36:39]
	v_mfma_f32_16x16x32_bf16 v[32:35], v[162:165], v[186:189], v[32:35]
	v_mfma_f32_16x16x32_bf16 v[20:23], v[154:157], v[194:197], v[20:23]
	v_mfma_f32_16x16x32_bf16 v[16:19], v[162:165], v[194:197], v[16:19]
	v_mfma_f32_16x16x32_bf16 v[60:63], v[158:161], v[174:177], v[60:63]
	v_mfma_f32_16x16x32_bf16 v[56:59], v[166:169], v[174:177], v[56:59]
	v_mfma_f32_16x16x32_bf16 v[52:55], v[158:161], v[182:185], v[52:55]
	v_mfma_f32_16x16x32_bf16 v[48:51], v[166:169], v[182:185], v[48:51]
	v_mfma_f32_16x16x32_bf16 v[36:39], v[158:161], v[190:193], v[36:39]
	v_mfma_f32_16x16x32_bf16 v[32:35], v[166:169], v[190:193], v[32:35]
	v_mfma_f32_16x16x32_bf16 v[20:23], v[158:161], v[198:201], v[20:23]
	v_mfma_f32_16x16x32_bf16 v[16:19], v[166:169], v[198:201], v[16:19]
	s_barrier
	s_add_u32 s88, s26, 0x40000
	s_addc_u32 s89, s27, 0
	s_add_i32 s87, s73, s34
	v_lshl_add_u64 v[154:155], s[88:89], 0, v[134:135]
	s_mov_b32 m0, s87
	s_nop 0
	global_load_lds_dwordx4 v[154:155], off
	v_lshl_add_u64 v[154:155], s[88:89], 0, v[130:131]
	s_add_i32 m0, s87, 0x2000
	s_nop 0
	global_load_lds_dwordx4 v[154:155], off
	s_waitcnt vmcnt(6)
	s_barrier
	v_mfma_f32_16x16x32_bf16 v[44:47], v[202:205], v[170:173], v[44:47]
	v_mfma_f32_16x16x32_bf16 v[40:43], v[210:213], v[170:173], v[40:43]
	v_mfma_f32_16x16x32_bf16 v[28:31], v[202:205], v[178:181], v[28:31]
	v_mfma_f32_16x16x32_bf16 v[24:27], v[210:213], v[178:181], v[24:27]
	v_mfma_f32_16x16x32_bf16 v[12:15], v[202:205], v[186:189], v[12:15]
	v_mfma_f32_16x16x32_bf16 v[8:11], v[210:213], v[186:189], v[8:11]
	v_mfma_f32_16x16x32_bf16 v[4:7], v[202:205], v[194:197], v[4:7]
	v_mfma_f32_16x16x32_bf16 v[0:3], v[210:213], v[194:197], v[0:3]
	v_mfma_f32_16x16x32_bf16 v[44:47], v[206:209], v[174:177], v[44:47]
	v_mfma_f32_16x16x32_bf16 v[40:43], v[214:217], v[174:177], v[40:43]
	v_mfma_f32_16x16x32_bf16 v[28:31], v[206:209], v[182:185], v[28:31]
	v_mfma_f32_16x16x32_bf16 v[24:27], v[214:217], v[182:185], v[24:27]
	v_mfma_f32_16x16x32_bf16 v[12:15], v[206:209], v[190:193], v[12:15]
	v_mfma_f32_16x16x32_bf16 v[8:11], v[214:217], v[190:193], v[8:11]
	v_mfma_f32_16x16x32_bf16 v[4:7], v[206:209], v[198:201], v[4:7]
	v_mfma_f32_16x16x32_bf16 v[0:3], v[214:217], v[198:201], v[0:3]
	s_add_i32 s87, 0, 0x18000
	v_add_u32_e32 v153, s87, v148
	s_barrier
	ds_read_b128 v[154:157], v153
	ds_read_b128 v[158:161], v153 offset:1024
	ds_read_b128 v[162:165], v153 offset:2048
	ds_read_b128 v[166:169], v153 offset:3072
	s_add_u32 s28, s28, 0x40000
	s_addc_u32 s29, s29, 0
	s_mov_b32 m0, s54
	v_lshl_add_u64 v[202:203], s[28:29], 0, v[136:137]
	ds_read_b128 v[170:173], v151 offset:32768
	ds_read_b128 v[174:177], v151 offset:33792
	ds_read_b128 v[178:181], v151 offset:34816
	ds_read_b128 v[182:185], v151 offset:35840
	ds_read_b128 v[186:189], v151 offset:36864
	ds_read_b128 v[190:193], v151 offset:37888
	ds_read_b128 v[194:197], v151 offset:38912
	ds_read_b128 v[198:201], v151 offset:39936
	global_load_lds_dwordx4 v[202:203], off
	v_lshl_add_u64 v[202:203], s[28:29], 0, v[132:133]
	s_mov_b32 m0, s55
	s_nop 0
	global_load_lds_dwordx4 v[202:203], off
	s_waitcnt lgkmcnt(8)
	s_barrier
	s_waitcnt lgkmcnt(0)
	s_waitcnt lgkmcnt(0)
	v_mfma_f32_16x16x32_bf16 v[124:127], v[154:157], v[170:173], v[124:127]
	v_mfma_f32_16x16x32_bf16 v[120:123], v[162:165], v[170:173], v[120:123]
	v_mfma_f32_16x16x32_bf16 v[116:119], v[154:157], v[178:181], v[116:119]
	v_mfma_f32_16x16x32_bf16 v[112:115], v[162:165], v[178:181], v[112:115]
	v_mfma_f32_16x16x32_bf16 v[100:103], v[154:157], v[186:189], v[100:103]
	v_mfma_f32_16x16x32_bf16 v[96:99], v[162:165], v[186:189], v[96:99]
	v_mfma_f32_16x16x32_bf16 v[84:87], v[154:157], v[194:197], v[84:87]
	v_mfma_f32_16x16x32_bf16 v[80:83], v[162:165], v[194:197], v[80:83]
	v_mfma_f32_16x16x32_bf16 v[124:127], v[158:161], v[174:177], v[124:127]
	v_mfma_f32_16x16x32_bf16 v[120:123], v[166:169], v[174:177], v[120:123]
	v_mfma_f32_16x16x32_bf16 v[116:119], v[158:161], v[182:185], v[116:119]
	v_mfma_f32_16x16x32_bf16 v[112:115], v[166:169], v[182:185], v[112:115]
	v_mfma_f32_16x16x32_bf16 v[100:103], v[158:161], v[190:193], v[100:103]
	v_mfma_f32_16x16x32_bf16 v[96:99], v[166:169], v[190:193], v[96:99]
	v_mfma_f32_16x16x32_bf16 v[84:87], v[158:161], v[198:201], v[84:87]
	v_mfma_f32_16x16x32_bf16 v[80:83], v[166:169], v[198:201], v[80:83]
	s_barrier
	s_add_i32 s28, 0, 0x1c000
	s_add_i32 s29, s87, s34
	v_add_u32_e32 v153, s28, v148
	v_lshl_add_u64 v[218:219], v[218:219], 0, s[8:9]
	s_mov_b32 m0, s29
	ds_read_b128 v[202:205], v153
	ds_read_b128 v[206:209], v153 offset:1024
	ds_read_b128 v[210:213], v153 offset:2048
	ds_read_b128 v[214:217], v153 offset:3072
	global_load_lds_dwordx4 v[218:219], off
	v_lshl_add_u64 v[218:219], v[220:221], 0, s[8:9]
	s_add_i32 m0, s29, 0x2000
	s_nop 0
	global_load_lds_dwordx4 v[218:219], off
	s_barrier
	s_waitcnt lgkmcnt(0)
	s_waitcnt lgkmcnt(0)
	v_mfma_f32_16x16x32_bf16 v[108:111], v[202:205], v[170:173], v[108:111]
	v_mfma_f32_16x16x32_bf16 v[104:107], v[210:213], v[170:173], v[104:107]
	v_mfma_f32_16x16x32_bf16 v[92:95], v[202:205], v[178:181], v[92:95]
	v_mfma_f32_16x16x32_bf16 v[88:91], v[210:213], v[178:181], v[88:91]
	v_mfma_f32_16x16x32_bf16 v[76:79], v[202:205], v[186:189], v[76:79]
	v_mfma_f32_16x16x32_bf16 v[72:75], v[210:213], v[186:189], v[72:75]
	v_mfma_f32_16x16x32_bf16 v[68:71], v[202:205], v[194:197], v[68:71]
	v_mfma_f32_16x16x32_bf16 v[64:67], v[210:213], v[194:197], v[64:67]
	v_mfma_f32_16x16x32_bf16 v[108:111], v[206:209], v[174:177], v[108:111]
	v_mfma_f32_16x16x32_bf16 v[104:107], v[214:217], v[174:177], v[104:107]
	v_mfma_f32_16x16x32_bf16 v[92:95], v[206:209], v[182:185], v[92:95]
	v_mfma_f32_16x16x32_bf16 v[88:91], v[214:217], v[182:185], v[88:91]
	v_mfma_f32_16x16x32_bf16 v[76:79], v[206:209], v[190:193], v[76:79]
	v_mfma_f32_16x16x32_bf16 v[72:75], v[214:217], v[190:193], v[72:75]
	v_mfma_f32_16x16x32_bf16 v[68:71], v[206:209], v[198:201], v[68:71]
	v_mfma_f32_16x16x32_bf16 v[64:67], v[214:217], v[198:201], v[64:67]
	s_mov_b32 m0, s57
	v_lshl_add_u64 v[218:219], v[222:223], 0, s[8:9]
	s_barrier
	ds_read_b128 v[170:173], v151 offset:49152
	ds_read_b128 v[174:177], v151 offset:50176
	ds_read_b128 v[178:181], v151 offset:51200
	ds_read_b128 v[182:185], v151 offset:52224
	ds_read_b128 v[186:189], v151 offset:53248
	ds_read_b128 v[190:193], v151 offset:54272
	ds_read_b128 v[194:197], v151 offset:55296
	ds_read_b128 v[198:201], v151 offset:56320
	global_load_lds_dwordx4 v[218:219], off
	v_lshl_add_u64 v[218:219], v[224:225], 0, s[8:9]
	s_mov_b32 m0, s70
	s_nop 0
	global_load_lds_dwordx4 v[218:219], off
	s_barrier
	s_waitcnt lgkmcnt(0)
	s_waitcnt lgkmcnt(0)
	v_mfma_f32_16x16x32_bf16 v[60:63], v[154:157], v[170:173], v[60:63]
	v_mfma_f32_16x16x32_bf16 v[56:59], v[162:165], v[170:173], v[56:59]
	v_mfma_f32_16x16x32_bf16 v[52:55], v[154:157], v[178:181], v[52:55]
	v_mfma_f32_16x16x32_bf16 v[48:51], v[162:165], v[178:181], v[48:51]
	v_mfma_f32_16x16x32_bf16 v[36:39], v[154:157], v[186:189], v[36:39]
	v_mfma_f32_16x16x32_bf16 v[32:35], v[162:165], v[186:189], v[32:35]
	v_mfma_f32_16x16x32_bf16 v[20:23], v[154:157], v[194:197], v[20:23]
	v_mfma_f32_16x16x32_bf16 v[16:19], v[162:165], v[194:197], v[16:19]
	v_mfma_f32_16x16x32_bf16 v[60:63], v[158:161], v[174:177], v[60:63]
	v_mfma_f32_16x16x32_bf16 v[56:59], v[166:169], v[174:177], v[56:59]
	v_mfma_f32_16x16x32_bf16 v[52:55], v[158:161], v[182:185], v[52:55]
	v_mfma_f32_16x16x32_bf16 v[48:51], v[166:169], v[182:185], v[48:51]
	v_mfma_f32_16x16x32_bf16 v[36:39], v[158:161], v[190:193], v[36:39]
	v_mfma_f32_16x16x32_bf16 v[32:35], v[166:169], v[190:193], v[32:35]
	v_mfma_f32_16x16x32_bf16 v[20:23], v[158:161], v[198:201], v[20:23]
	v_mfma_f32_16x16x32_bf16 v[16:19], v[166:169], v[198:201], v[16:19]
	s_barrier
	s_add_u32 s26, s26, 0x40080
	s_addc_u32 s27, s27, 0
	s_add_i32 s28, s28, s34
	v_lshl_add_u64 v[154:155], s[26:27], 0, v[134:135]
	s_mov_b32 m0, s28
	s_nop 0
	global_load_lds_dwordx4 v[154:155], off
	v_lshl_add_u64 v[154:155], s[26:27], 0, v[130:131]
	s_add_i32 m0, s28, 0x2000
	s_nop 0
	global_load_lds_dwordx4 v[154:155], off
	s_waitcnt vmcnt(6)
	s_barrier
	v_mfma_f32_16x16x32_bf16 v[44:47], v[202:205], v[170:173], v[44:47]
	v_mfma_f32_16x16x32_bf16 v[40:43], v[210:213], v[170:173], v[40:43]
	v_mfma_f32_16x16x32_bf16 v[28:31], v[202:205], v[178:181], v[28:31]
	v_mfma_f32_16x16x32_bf16 v[24:27], v[210:213], v[178:181], v[24:27]
	v_mfma_f32_16x16x32_bf16 v[12:15], v[202:205], v[186:189], v[12:15]
	v_mfma_f32_16x16x32_bf16 v[8:11], v[210:213], v[186:189], v[8:11]
	v_mfma_f32_16x16x32_bf16 v[4:7], v[202:205], v[194:197], v[4:7]
	v_mfma_f32_16x16x32_bf16 v[0:3], v[210:213], v[194:197], v[0:3]
	v_mfma_f32_16x16x32_bf16 v[44:47], v[206:209], v[174:177], v[44:47]
	v_mfma_f32_16x16x32_bf16 v[40:43], v[214:217], v[174:177], v[40:43]
	v_mfma_f32_16x16x32_bf16 v[28:31], v[206:209], v[182:185], v[28:31]
	v_mfma_f32_16x16x32_bf16 v[24:27], v[214:217], v[182:185], v[24:27]
	v_mfma_f32_16x16x32_bf16 v[12:15], v[206:209], v[190:193], v[12:15]
	v_mfma_f32_16x16x32_bf16 v[8:11], v[214:217], v[190:193], v[8:11]
	v_mfma_f32_16x16x32_bf16 v[4:7], v[206:209], v[198:201], v[4:7]
	v_mfma_f32_16x16x32_bf16 v[0:3], v[214:217], v[198:201], v[0:3]
	s_add_i32 s86, s86, 2
	s_add_u32 s20, s20, 0x100
	s_addc_u32 s21, s21, 0
	s_add_u32 s84, s84, 0x100
	s_addc_u32 s85, s85, 0
	s_cmp_gt_u32 s86, 13
	s_barrier
	s_cbranch_scc0 .LBB0_155
	v_lshl_add_u32 v153, s10, 8, v147
	v_lshl_or_b32 v154, s75, 8, v149
	v_mov_b64_e32 v[156:157], s[46:47]
	v_ashrrev_i32_e32 v155, 31, v154
	v_cvt_pk_bf16_f32 v68, v68, v69
	v_cvt_pk_bf16_f32 v69, v70, v71
	v_cvt_pk_bf16_f32 v70, v64, v65
	v_add_u32_e32 v64, 0x80, v153
	v_mad_i64_i32 v[158:159], s[20:21], v153, s74, v[156:157]
	v_cvt_pk_bf16_f32 v124, v124, v125
	v_cvt_pk_bf16_f32 v125, v126, v127
	v_cvt_pk_bf16_f32 v126, v120, v121
	v_lshlrev_b64 v[120:121], 1, v[154:155]
	v_mad_i64_i32 v[64:65], s[20:21], v64, s74, v[156:157]
	v_cvt_pk_bf16_f32 v127, v122, v123
	v_lshl_add_u64 v[122:123], v[158:159], 0, v[120:121]
	v_cvt_pk_bf16_f32 v108, v108, v109
	v_cvt_pk_bf16_f32 v109, v110, v111
	v_cvt_pk_bf16_f32 v110, v104, v105
	v_cvt_pk_bf16_f32 v111, v106, v107
	v_or_b32_e32 v104, 16, v153
	v_cvt_pk_bf16_f32 v60, v60, v61
	v_cvt_pk_bf16_f32 v61, v62, v63
	v_cvt_pk_bf16_f32 v62, v56, v57
	v_lshl_add_u64 v[56:57], v[64:65], 0, v[120:121]
	v_cvt_pk_bf16_f32 v44, v44, v45
	v_cvt_pk_bf16_f32 v45, v46, v47
	v_cvt_pk_bf16_f32 v46, v40, v41
	v_cvt_pk_bf16_f32 v47, v42, v43
	v_add_u32_e32 v40, 0x90, v153
	global_store_dwordx4 v[122:123], v[108:111], off offset:256
	global_store_dwordx4 v[56:57], v[44:47], off offset:256
	v_cvt_pk_bf16_f32 v92, v92, v93
	v_mad_i64_i32 v[108:109], s[20:21], v104, s74, v[156:157]
	v_mad_i64_i32 v[44:45], s[20:21], v40, s74, v[156:157]
	v_lshl_add_u64 v[108:109], v[108:109], 0, v[120:121]
	v_cvt_pk_bf16_f32 v93, v94, v95
	v_cvt_pk_bf16_f32 v94, v88, v89
	v_cvt_pk_bf16_f32 v95, v90, v91
	v_or_b32_e32 v88, 32, v153
	v_lshl_add_u64 v[44:45], v[44:45], 0, v[120:121]
	v_cvt_pk_bf16_f32 v28, v28, v29
	v_cvt_pk_bf16_f32 v29, v30, v31
	v_cvt_pk_bf16_f32 v30, v24, v25
	v_cvt_pk_bf16_f32 v31, v26, v27
	v_add_u32_e32 v24, 0xa0, v153
	global_store_dwordx4 v[108:109], v[92:95], off offset:256
	global_store_dwordx4 v[44:45], v[28:31], off offset:256
	v_cvt_pk_bf16_f32 v76, v76, v77
	v_mad_i64_i32 v[92:93], s[20:21], v88, s74, v[156:157]
	v_mad_i64_i32 v[28:29], s[20:21], v24, s74, v[156:157]
	v_lshl_add_u64 v[92:93], v[92:93], 0, v[120:121]
	v_cvt_pk_bf16_f32 v77, v78, v79
	v_cvt_pk_bf16_f32 v78, v72, v73
	v_cvt_pk_bf16_f32 v79, v74, v75
	v_or_b32_e32 v72, 48, v153
	v_lshl_add_u64 v[28:29], v[28:29], 0, v[120:121]
	v_cvt_pk_bf16_f32 v12, v12, v13
	v_cvt_pk_bf16_f32 v13, v14, v15
	v_cvt_pk_bf16_f32 v14, v8, v9
	v_cvt_pk_bf16_f32 v15, v10, v11
	v_add_u32_e32 v8, 0xb0, v153
	global_store_dwordx4 v[92:93], v[76:79], off offset:256
	global_store_dwordx4 v[28:29], v[12:15], off offset:256
	v_cvt_pk_bf16_f32 v104, v116, v117
	v_mad_i64_i32 v[76:77], s[20:21], v72, s74, v[156:157]
	v_mad_i64_i32 v[12:13], s[20:21], v8, s74, v[156:157]
	v_cvt_pk_bf16_f32 v105, v118, v119
	v_cvt_pk_bf16_f32 v106, v112, v113
	v_cvt_pk_bf16_f32 v107, v114, v115
	v_cvt_pk_bf16_f32 v88, v100, v101
	v_cvt_pk_bf16_f32 v89, v102, v103
	v_cvt_pk_bf16_f32 v90, v96, v97
	v_cvt_pk_bf16_f32 v91, v98, v99
	v_cvt_pk_bf16_f32 v72, v84, v85
	v_cvt_pk_bf16_f32 v73, v86, v87
	v_cvt_pk_bf16_f32 v74, v80, v81
	v_cvt_pk_bf16_f32 v75, v82, v83
	v_lshl_add_u64 v[76:77], v[76:77], 0, v[120:121]
	v_cvt_pk_bf16_f32 v71, v66, v67
	v_cvt_pk_bf16_f32 v63, v58, v59
	v_cvt_pk_bf16_f32 v40, v52, v53
	v_cvt_pk_bf16_f32 v41, v54, v55
	v_cvt_pk_bf16_f32 v42, v48, v49
	v_cvt_pk_bf16_f32 v43, v50, v51
	v_cvt_pk_bf16_f32 v24, v36, v37
	v_cvt_pk_bf16_f32 v25, v38, v39
	v_cvt_pk_bf16_f32 v26, v32, v33
	v_cvt_pk_bf16_f32 v27, v34, v35
	v_cvt_pk_bf16_f32 v8, v20, v21
	v_cvt_pk_bf16_f32 v9, v22, v23
	v_cvt_pk_bf16_f32 v10, v16, v17
	v_cvt_pk_bf16_f32 v11, v18, v19
	v_lshl_add_u64 v[12:13], v[12:13], 0, v[120:121]
	v_cvt_pk_bf16_f32 v4, v4, v5
	v_cvt_pk_bf16_f32 v5, v6, v7
	v_cvt_pk_bf16_f32 v6, v0, v1
	v_cvt_pk_bf16_f32 v7, v2, v3
	s_and_b64 vcc, exec, s[4:5]
	s_mov_b32 s75, s12
	s_mov_b32 s10, s14
	s_mov_b64 s[26:27], s[18:19]
	s_mov_b64 s[20:21], s[16:17]
	global_store_dwordx4 v[122:123], v[124:127], off
	global_store_dwordx4 v[108:109], v[104:107], off
	global_store_dwordx4 v[92:93], v[88:91], off
	global_store_dwordx4 v[76:77], v[72:75], off
	global_store_dwordx4 v[76:77], v[68:71], off offset:256
	global_store_dwordx4 v[56:57], v[60:63], off
	global_store_dwordx4 v[44:45], v[40:43], off
	global_store_dwordx4 v[28:29], v[24:27], off
	global_store_dwordx4 v[12:13], v[8:11], off
	global_store_dwordx4 v[12:13], v[4:7], off offset:256
	s_cbranch_vccz .LBB0_152
	s_waitcnt vmcnt(0)
	s_cmpk_gt_u32 s30, 0xff
	s_cbranch_scc1 .LBB0_159
	s_barrier

.LBB0_486:
	ds_read_b128 v[154:157], v151
	ds_read_b128 v[158:161], v151 offset:1024
	ds_read_b128 v[162:165], v151 offset:2048
	ds_read_b128 v[166:169], v151 offset:3072
	s_add_u32 s30, s28, 0xfffc0080
	s_addc_u32 s31, s29, -1
	s_cmp_eq_u32 s84, 12
	s_cselect_b32 s35, s19, s31
	s_cselect_b32 s34, s80, s30
	s_cselect_b32 s31, s17, s83
	s_cselect_b32 s30, s81, s82
	v_lshl_add_u64 v[202:203], s[28:29], 0, v[138:139]
	s_add_i32 m0, s15, 0xc000
	ds_read_b128 v[170:173], v152
	ds_read_b128 v[174:177], v152 offset:1024
	ds_read_b128 v[178:181], v152 offset:2048
	ds_read_b128 v[182:185], v152 offset:3072
	ds_read_b128 v[186:189], v152 offset:4096
	ds_read_b128 v[190:193], v152 offset:5120
	ds_read_b128 v[194:197], v152 offset:6144
	ds_read_b128 v[198:201], v152 offset:7168
	global_load_lds_dwordx4 v[202:203], off
	v_lshl_add_u64 v[202:203], s[28:29], 0, v[140:141]
	s_add_i32 m0, s15, 0xe000
	s_nop 0
	global_load_lds_dwordx4 v[202:203], off
	s_waitcnt lgkmcnt(8)
	s_barrier
	s_waitcnt lgkmcnt(0)
	s_waitcnt lgkmcnt(0)
	v_mfma_f32_16x16x32_bf16 v[124:127], v[154:157], v[170:173], v[124:127]
	v_mfma_f32_16x16x32_bf16 v[120:123], v[162:165], v[170:173], v[120:123]
	v_mfma_f32_16x16x32_bf16 v[116:119], v[154:157], v[178:181], v[116:119]
	v_mfma_f32_16x16x32_bf16 v[112:115], v[162:165], v[178:181], v[112:115]
	v_mfma_f32_16x16x32_bf16 v[100:103], v[154:157], v[186:189], v[100:103]
	v_mfma_f32_16x16x32_bf16 v[96:99], v[162:165], v[186:189], v[96:99]
	v_mfma_f32_16x16x32_bf16 v[84:87], v[154:157], v[194:197], v[84:87]
	v_mfma_f32_16x16x32_bf16 v[80:83], v[162:165], v[194:197], v[80:83]
	v_mfma_f32_16x16x32_bf16 v[124:127], v[158:161], v[174:177], v[124:127]
	v_mfma_f32_16x16x32_bf16 v[120:123], v[166:169], v[174:177], v[120:123]
	v_mfma_f32_16x16x32_bf16 v[116:119], v[158:161], v[182:185], v[116:119]
	v_mfma_f32_16x16x32_bf16 v[112:115], v[166:169], v[182:185], v[112:115]
	v_mfma_f32_16x16x32_bf16 v[100:103], v[158:161], v[190:193], v[100:103]
	v_mfma_f32_16x16x32_bf16 v[96:99], v[166:169], v[190:193], v[96:99]
	v_mfma_f32_16x16x32_bf16 v[84:87], v[158:161], v[198:201], v[84:87]
	v_mfma_f32_16x16x32_bf16 v[80:83], v[166:169], v[198:201], v[80:83]
	s_barrier
	s_add_i32 s85, s74, s55
	v_lshl_add_u64 v[218:219], s[30:31], 0, v[134:135]
	s_mov_b32 m0, s85
	ds_read_b128 v[202:205], v153
	ds_read_b128 v[206:209], v153 offset:1024
	ds_read_b128 v[210:213], v153 offset:2048
	ds_read_b128 v[214:217], v153 offset:3072
	global_load_lds_dwordx4 v[218:219], off
	v_lshl_add_u64 v[220:221], s[30:31], 0, v[130:131]
	s_add_i32 m0, s85, 0x2000
	s_nop 0
	global_load_lds_dwordx4 v[220:221], off
	s_barrier
	s_waitcnt lgkmcnt(0)
	s_waitcnt lgkmcnt(0)
	v_mfma_f32_16x16x32_bf16 v[108:111], v[202:205], v[170:173], v[108:111]
	v_mfma_f32_16x16x32_bf16 v[104:107], v[210:213], v[170:173], v[104:107]
	v_mfma_f32_16x16x32_bf16 v[92:95], v[202:205], v[178:181], v[92:95]
	v_mfma_f32_16x16x32_bf16 v[88:91], v[210:213], v[178:181], v[88:91]
	v_mfma_f32_16x16x32_bf16 v[76:79], v[202:205], v[186:189], v[76:79]
	v_mfma_f32_16x16x32_bf16 v[72:75], v[210:213], v[186:189], v[72:75]
	v_mfma_f32_16x16x32_bf16 v[68:71], v[202:205], v[194:197], v[68:71]
	v_mfma_f32_16x16x32_bf16 v[64:67], v[210:213], v[194:197], v[64:67]
	v_mfma_f32_16x16x32_bf16 v[108:111], v[206:209], v[174:177], v[108:111]
	v_mfma_f32_16x16x32_bf16 v[104:107], v[214:217], v[174:177], v[104:107]
	v_mfma_f32_16x16x32_bf16 v[92:95], v[206:209], v[182:185], v[92:95]
	v_mfma_f32_16x16x32_bf16 v[88:91], v[214:217], v[182:185], v[88:91]
	v_mfma_f32_16x16x32_bf16 v[76:79], v[206:209], v[190:193], v[76:79]
	v_mfma_f32_16x16x32_bf16 v[72:75], v[214:217], v[190:193], v[72:75]
	v_mfma_f32_16x16x32_bf16 v[68:71], v[206:209], v[198:201], v[68:71]
	v_mfma_f32_16x16x32_bf16 v[64:67], v[214:217], v[198:201], v[64:67]
	s_mov_b32 m0, s15
	v_lshl_add_u64 v[222:223], s[34:35], 0, v[136:137]
	s_barrier
	ds_read_b128 v[170:173], v152 offset:16384
	ds_read_b128 v[174:177], v152 offset:17408
	ds_read_b128 v[178:181], v152 offset:18432
	ds_read_b128 v[182:185], v152 offset:19456
	ds_read_b128 v[186:189], v152 offset:20480
	ds_read_b128 v[190:193], v152 offset:21504
	ds_read_b128 v[194:197], v152 offset:22528
	ds_read_b128 v[198:201], v152 offset:23552
	global_load_lds_dwordx4 v[222:223], off
	v_lshl_add_u64 v[224:225], s[34:35], 0, v[132:133]
	s_mov_b32 m0, s57
	s_nop 0
	global_load_lds_dwordx4 v[224:225], off
	s_barrier
	s_waitcnt lgkmcnt(0)
	s_waitcnt lgkmcnt(0)
	v_mfma_f32_16x16x32_bf16 v[60:63], v[154:157], v[170:173], v[60:63]
	v_mfma_f32_16x16x32_bf16 v[56:59], v[162:165], v[170:173], v[56:59]
	v_mfma_f32_16x16x32_bf16 v[52:55], v[154:157], v[178:181], v[52:55]
	v_mfma_f32_16x16x32_bf16 v[48:51], v[162:165], v[178:181], v[48:51]
	v_mfma_f32_16x16x32_bf16 v[36:39], v[154:157], v[186:189], v[36:39]
	v_mfma_f32_16x16x32_bf16 v[32:35], v[162:165], v[186:189], v[32:35]
	v_mfma_f32_16x16x32_bf16 v[20:23], v[154:157], v[194:197], v[20:23]
	v_mfma_f32_16x16x32_bf16 v[16:19], v[162:165], v[194:197], v[16:19]
	v_mfma_f32_16x16x32_bf16 v[60:63], v[158:161], v[174:177], v[60:63]
	v_mfma_f32_16x16x32_bf16 v[56:59], v[166:169], v[174:177], v[56:59]
	v_mfma_f32_16x16x32_bf16 v[52:55], v[158:161], v[182:185], v[52:55]
	v_mfma_f32_16x16x32_bf16 v[48:51], v[166:169], v[182:185], v[48:51]
	v_mfma_f32_16x16x32_bf16 v[36:39], v[158:161], v[190:193], v[36:39]
	v_mfma_f32_16x16x32_bf16 v[32:35], v[166:169], v[190:193], v[32:35]
	v_mfma_f32_16x16x32_bf16 v[20:23], v[158:161], v[198:201], v[20:23]
	v_mfma_f32_16x16x32_bf16 v[16:19], v[166:169], v[198:201], v[16:19]
	s_barrier
	s_add_u32 s86, s30, 0x40000
	s_addc_u32 s87, s31, 0
	s_add_i32 s85, s75, s55
	v_lshl_add_u64 v[154:155], s[86:87], 0, v[134:135]
	s_mov_b32 m0, s85
	s_nop 0
	global_load_lds_dwordx4 v[154:155], off
	v_lshl_add_u64 v[154:155], s[86:87], 0, v[130:131]
	s_add_i32 m0, s85, 0x2000
	s_nop 0
	global_load_lds_dwordx4 v[154:155], off
	s_waitcnt vmcnt(6)
	s_barrier
	v_mfma_f32_16x16x32_bf16 v[44:47], v[202:205], v[170:173], v[44:47]
	v_mfma_f32_16x16x32_bf16 v[40:43], v[210:213], v[170:173], v[40:43]
	v_mfma_f32_16x16x32_bf16 v[28:31], v[202:205], v[178:181], v[28:31]
	v_mfma_f32_16x16x32_bf16 v[24:27], v[210:213], v[178:181], v[24:27]
	v_mfma_f32_16x16x32_bf16 v[12:15], v[202:205], v[186:189], v[12:15]
	v_mfma_f32_16x16x32_bf16 v[8:11], v[210:213], v[186:189], v[8:11]
	v_mfma_f32_16x16x32_bf16 v[4:7], v[202:205], v[194:197], v[4:7]
	v_mfma_f32_16x16x32_bf16 v[0:3], v[210:213], v[194:197], v[0:3]
	v_mfma_f32_16x16x32_bf16 v[44:47], v[206:209], v[174:177], v[44:47]
	v_mfma_f32_16x16x32_bf16 v[40:43], v[214:217], v[174:177], v[40:43]
	v_mfma_f32_16x16x32_bf16 v[28:31], v[206:209], v[182:185], v[28:31]
	v_mfma_f32_16x16x32_bf16 v[24:27], v[214:217], v[182:185], v[24:27]
	v_mfma_f32_16x16x32_bf16 v[12:15], v[206:209], v[190:193], v[12:15]
	v_mfma_f32_16x16x32_bf16 v[8:11], v[214:217], v[190:193], v[8:11]
	v_mfma_f32_16x16x32_bf16 v[4:7], v[206:209], v[198:201], v[4:7]
	v_mfma_f32_16x16x32_bf16 v[0:3], v[214:217], v[198:201], v[0:3]
	s_add_i32 s85, 0, 0x18000
	v_add_u32_e32 v166, s85, v149
	s_barrier
	ds_read_b128 v[154:157], v166
	ds_read_b128 v[158:161], v166 offset:1024
	ds_read_b128 v[162:165], v166 offset:2048
	ds_read_b128 v[166:169], v166 offset:3072
	s_add_u32 s34, s34, 0x40000
	s_addc_u32 s35, s35, 0
	s_mov_b32 m0, s60
	v_lshl_add_u64 v[202:203], s[34:35], 0, v[136:137]
	ds_read_b128 v[170:173], v152 offset:32768
	ds_read_b128 v[174:177], v152 offset:33792
	ds_read_b128 v[178:181], v152 offset:34816
	ds_read_b128 v[182:185], v152 offset:35840
	ds_read_b128 v[186:189], v152 offset:36864
	ds_read_b128 v[190:193], v152 offset:37888
	ds_read_b128 v[194:197], v152 offset:38912
	ds_read_b128 v[198:201], v152 offset:39936
	global_load_lds_dwordx4 v[202:203], off
	v_lshl_add_u64 v[202:203], s[34:35], 0, v[132:133]
	s_mov_b32 m0, s61
	s_nop 0
	global_load_lds_dwordx4 v[202:203], off
	s_waitcnt lgkmcnt(8)
	s_barrier
	s_waitcnt lgkmcnt(0)
	s_waitcnt lgkmcnt(0)
	v_mfma_f32_16x16x32_bf16 v[124:127], v[154:157], v[170:173], v[124:127]
	v_mfma_f32_16x16x32_bf16 v[120:123], v[162:165], v[170:173], v[120:123]
	v_mfma_f32_16x16x32_bf16 v[116:119], v[154:157], v[178:181], v[116:119]
	v_mfma_f32_16x16x32_bf16 v[112:115], v[162:165], v[178:181], v[112:115]
	v_mfma_f32_16x16x32_bf16 v[100:103], v[154:157], v[186:189], v[100:103]
	v_mfma_f32_16x16x32_bf16 v[96:99], v[162:165], v[186:189], v[96:99]
	v_mfma_f32_16x16x32_bf16 v[84:87], v[154:157], v[194:197], v[84:87]
	v_mfma_f32_16x16x32_bf16 v[80:83], v[162:165], v[194:197], v[80:83]
	v_mfma_f32_16x16x32_bf16 v[124:127], v[158:161], v[174:177], v[124:127]
	v_mfma_f32_16x16x32_bf16 v[120:123], v[166:169], v[174:177], v[120:123]
	v_mfma_f32_16x16x32_bf16 v[116:119], v[158:161], v[182:185], v[116:119]
	v_mfma_f32_16x16x32_bf16 v[112:115], v[166:169], v[182:185], v[112:115]
	v_mfma_f32_16x16x32_bf16 v[100:103], v[158:161], v[190:193], v[100:103]
	v_mfma_f32_16x16x32_bf16 v[96:99], v[166:169], v[190:193], v[96:99]
	v_mfma_f32_16x16x32_bf16 v[84:87], v[158:161], v[198:201], v[84:87]
	v_mfma_f32_16x16x32_bf16 v[80:83], v[166:169], v[198:201], v[80:83]
	s_barrier
	s_add_i32 s34, 0, 0x1c000
	s_add_i32 s35, s85, s55
	v_add_u32_e32 v214, s34, v149
	v_lshl_add_u64 v[218:219], v[218:219], 0, s[8:9]
	s_mov_b32 m0, s35
	ds_read_b128 v[202:205], v214
	ds_read_b128 v[206:209], v214 offset:1024
	ds_read_b128 v[210:213], v214 offset:2048
	ds_read_b128 v[214:217], v214 offset:3072
	global_load_lds_dwordx4 v[218:219], off
	v_lshl_add_u64 v[218:219], v[220:221], 0, s[8:9]
	s_add_i32 m0, s35, 0x2000
	s_nop 0
	global_load_lds_dwordx4 v[218:219], off
	s_barrier
	s_waitcnt lgkmcnt(0)
	s_waitcnt lgkmcnt(0)
	v_mfma_f32_16x16x32_bf16 v[108:111], v[202:205], v[170:173], v[108:111]
	v_mfma_f32_16x16x32_bf16 v[104:107], v[210:213], v[170:173], v[104:107]
	v_mfma_f32_16x16x32_bf16 v[92:95], v[202:205], v[178:181], v[92:95]
	v_mfma_f32_16x16x32_bf16 v[88:91], v[210:213], v[178:181], v[88:91]
	v_mfma_f32_16x16x32_bf16 v[76:79], v[202:205], v[186:189], v[76:79]
	v_mfma_f32_16x16x32_bf16 v[72:75], v[210:213], v[186:189], v[72:75]
	v_mfma_f32_16x16x32_bf16 v[68:71], v[202:205], v[194:197], v[68:71]
	v_mfma_f32_16x16x32_bf16 v[64:67], v[210:213], v[194:197], v[64:67]
	v_mfma_f32_16x16x32_bf16 v[108:111], v[206:209], v[174:177], v[108:111]
	v_mfma_f32_16x16x32_bf16 v[104:107], v[214:217], v[174:177], v[104:107]
	v_mfma_f32_16x16x32_bf16 v[92:95], v[206:209], v[182:185], v[92:95]
	v_mfma_f32_16x16x32_bf16 v[88:91], v[214:217], v[182:185], v[88:91]
	v_mfma_f32_16x16x32_bf16 v[76:79], v[206:209], v[190:193], v[76:79]
	v_mfma_f32_16x16x32_bf16 v[72:75], v[214:217], v[190:193], v[72:75]
	v_mfma_f32_16x16x32_bf16 v[68:71], v[206:209], v[198:201], v[68:71]
	v_mfma_f32_16x16x32_bf16 v[64:67], v[214:217], v[198:201], v[64:67]
	s_mov_b32 m0, s71
	v_lshl_add_u64 v[218:219], v[222:223], 0, s[8:9]
	s_barrier
	ds_read_b128 v[170:173], v152 offset:49152
	ds_read_b128 v[174:177], v152 offset:50176
	ds_read_b128 v[178:181], v152 offset:51200
	ds_read_b128 v[182:185], v152 offset:52224
	ds_read_b128 v[186:189], v152 offset:53248
	ds_read_b128 v[190:193], v152 offset:54272
	ds_read_b128 v[194:197], v152 offset:55296
	ds_read_b128 v[198:201], v152 offset:56320
	global_load_lds_dwordx4 v[218:219], off
	v_lshl_add_u64 v[218:219], v[224:225], 0, s[8:9]
	s_mov_b32 m0, s72
	s_nop 0
	global_load_lds_dwordx4 v[218:219], off
	s_barrier
	s_waitcnt lgkmcnt(0)
	s_waitcnt lgkmcnt(0)
	v_mfma_f32_16x16x32_bf16 v[60:63], v[154:157], v[170:173], v[60:63]
	v_mfma_f32_16x16x32_bf16 v[56:59], v[162:165], v[170:173], v[56:59]
	v_mfma_f32_16x16x32_bf16 v[52:55], v[154:157], v[178:181], v[52:55]
	v_mfma_f32_16x16x32_bf16 v[48:51], v[162:165], v[178:181], v[48:51]
	v_mfma_f32_16x16x32_bf16 v[36:39], v[154:157], v[186:189], v[36:39]
	v_mfma_f32_16x16x32_bf16 v[32:35], v[162:165], v[186:189], v[32:35]
	v_mfma_f32_16x16x32_bf16 v[20:23], v[154:157], v[194:197], v[20:23]
	v_mfma_f32_16x16x32_bf16 v[16:19], v[162:165], v[194:197], v[16:19]
	v_mfma_f32_16x16x32_bf16 v[60:63], v[158:161], v[174:177], v[60:63]
	v_mfma_f32_16x16x32_bf16 v[56:59], v[166:169], v[174:177], v[56:59]
	v_mfma_f32_16x16x32_bf16 v[52:55], v[158:161], v[182:185], v[52:55]
	v_mfma_f32_16x16x32_bf16 v[48:51], v[166:169], v[182:185], v[48:51]
	v_mfma_f32_16x16x32_bf16 v[36:39], v[158:161], v[190:193], v[36:39]
	v_mfma_f32_16x16x32_bf16 v[32:35], v[166:169], v[190:193], v[32:35]
	v_mfma_f32_16x16x32_bf16 v[20:23], v[158:161], v[198:201], v[20:23]
	v_mfma_f32_16x16x32_bf16 v[16:19], v[166:169], v[198:201], v[16:19]
	s_barrier
	s_add_u32 s30, s30, 0x40080
	s_addc_u32 s31, s31, 0
	s_add_i32 s34, s34, s55
	v_lshl_add_u64 v[154:155], s[30:31], 0, v[134:135]
	s_mov_b32 m0, s34
	s_nop 0
	global_load_lds_dwordx4 v[154:155], off
	v_lshl_add_u64 v[154:155], s[30:31], 0, v[130:131]
	s_add_i32 m0, s34, 0x2000
	s_nop 0
	global_load_lds_dwordx4 v[154:155], off
	s_waitcnt vmcnt(6)
	s_barrier
	v_mfma_f32_16x16x32_bf16 v[44:47], v[202:205], v[170:173], v[44:47]
	v_mfma_f32_16x16x32_bf16 v[40:43], v[210:213], v[170:173], v[40:43]
	v_mfma_f32_16x16x32_bf16 v[28:31], v[202:205], v[178:181], v[28:31]
	v_mfma_f32_16x16x32_bf16 v[24:27], v[210:213], v[178:181], v[24:27]
	v_mfma_f32_16x16x32_bf16 v[12:15], v[202:205], v[186:189], v[12:15]
	v_mfma_f32_16x16x32_bf16 v[8:11], v[210:213], v[186:189], v[8:11]
	v_mfma_f32_16x16x32_bf16 v[4:7], v[202:205], v[194:197], v[4:7]
	v_mfma_f32_16x16x32_bf16 v[0:3], v[210:213], v[194:197], v[0:3]
	v_mfma_f32_16x16x32_bf16 v[44:47], v[206:209], v[174:177], v[44:47]
	v_mfma_f32_16x16x32_bf16 v[40:43], v[214:217], v[174:177], v[40:43]
	v_mfma_f32_16x16x32_bf16 v[28:31], v[206:209], v[182:185], v[28:31]
	v_mfma_f32_16x16x32_bf16 v[24:27], v[214:217], v[182:185], v[24:27]
	v_mfma_f32_16x16x32_bf16 v[12:15], v[206:209], v[190:193], v[12:15]
	v_mfma_f32_16x16x32_bf16 v[8:11], v[214:217], v[190:193], v[8:11]
	v_mfma_f32_16x16x32_bf16 v[4:7], v[206:209], v[198:201], v[4:7]
	v_mfma_f32_16x16x32_bf16 v[0:3], v[214:217], v[198:201], v[0:3]
	s_add_i32 s84, s84, 2
	s_add_u32 s28, s28, 0x100
	s_addc_u32 s29, s29, 0
	s_add_u32 s82, s82, 0x100
	s_addc_u32 s83, s83, 0
	s_cmp_gt_u32 s84, 13
	s_barrier
	s_cbranch_scc0 .LBB0_486
	v_lshl_add_u32 v154, s14, 8, v148
	v_lshl_or_b32 v156, s79, 8, v150
	v_ashrrev_i32_e32 v155, 31, v154
	v_lshlrev_b64 v[158:159], 11, v[154:155]
	v_ashrrev_i32_e32 v157, 31, v156
	v_lshl_add_u64 v[158:159], s[46:47], 0, v[158:159]
	v_cvt_pk_bf16_f32 v124, v124, v125
	v_cvt_pk_bf16_f32 v125, v126, v127
	v_cvt_pk_bf16_f32 v126, v120, v121
	v_lshlrev_b64 v[120:121], 1, v[156:157]
	v_cvt_pk_bf16_f32 v127, v122, v123
	v_lshl_add_u64 v[122:123], v[158:159], 0, v[120:121]
	s_mov_b32 s14, 0x40000
	v_cvt_pk_bf16_f32 v108, v108, v109
	v_cvt_pk_bf16_f32 v109, v110, v111
	v_cvt_pk_bf16_f32 v110, v104, v105
	v_or_b32_e32 v104, 16, v154
	v_cvt_pk_bf16_f32 v60, v60, v61
	v_cvt_pk_bf16_f32 v61, v62, v63
	v_cvt_pk_bf16_f32 v63, v58, v59
	s_mov_b64 s[28:29], 0x40000
	v_add_co_u32_e32 v58, vcc, s14, v122
	v_ashrrev_i32_e32 v105, 31, v104
	v_cvt_pk_bf16_f32 v62, v56, v57
	v_lshl_add_u64 v[56:57], v[122:123], 0, s[28:29]
	v_addc_co_u32_e32 v59, vcc, 0, v123, vcc
	v_cvt_pk_bf16_f32 v44, v44, v45
	v_cvt_pk_bf16_f32 v45, v46, v47
	v_cvt_pk_bf16_f32 v46, v40, v41
	v_cvt_pk_bf16_f32 v47, v42, v43
	v_cvt_pk_bf16_f32 v111, v106, v107
	v_lshlrev_b64 v[104:105], 11, v[104:105]
	v_cvt_pk_bf16_f32 v92, v92, v93
	v_cvt_pk_bf16_f32 v93, v94, v95
	v_cvt_pk_bf16_f32 v94, v88, v89
	v_or_b32_e32 v88, 32, v154
	global_store_dwordx4 v[56:57], v[44:47], off offset:256
	s_mov_b64 s[28:29], 0x48000
	global_store_dwordx4 v[122:123], v[108:111], off offset:256
	v_add_co_u32_e32 v46, vcc, s76, v122
	s_nop 0
	v_lshl_add_u64 v[108:109], s[46:47], 0, v[104:105]
	v_ashrrev_i32_e32 v89, 31, v88
	v_lshl_add_u64 v[44:45], v[122:123], 0, s[28:29]
	v_addc_co_u32_e32 v47, vcc, 0, v123, vcc
	v_cvt_pk_bf16_f32 v28, v28, v29
	v_cvt_pk_bf16_f32 v29, v30, v31
	v_cvt_pk_bf16_f32 v30, v24, v25
	v_cvt_pk_bf16_f32 v31, v26, v27
	v_lshl_add_u64 v[108:109], v[108:109], 0, v[120:121]
	v_cvt_pk_bf16_f32 v95, v90, v91
	v_lshlrev_b64 v[88:89], 11, v[88:89]
	v_cvt_pk_bf16_f32 v76, v76, v77
	v_cvt_pk_bf16_f32 v77, v78, v79
	v_cvt_pk_bf16_f32 v78, v72, v73
	v_or_b32_e32 v72, 48, v154
	global_store_dwordx4 v[44:45], v[28:31], off offset:256
	global_store_dwordx4 v[108:109], v[92:95], off offset:256
	v_ashrrev_i32_e32 v73, 31, v72
	v_add_co_u32_e32 v30, vcc, s77, v122
	v_lshl_add_u64 v[92:93], s[46:47], 0, v[88:89]
	v_lshl_add_u64 v[28:29], v[122:123], 0, s[10:11]
	v_addc_co_u32_e32 v31, vcc, 0, v123, vcc
	v_cvt_pk_bf16_f32 v12, v12, v13
	v_cvt_pk_bf16_f32 v13, v14, v15
	v_cvt_pk_bf16_f32 v14, v8, v9
	v_cvt_pk_bf16_f32 v15, v10, v11
	v_lshl_add_u64 v[92:93], v[92:93], 0, v[120:121]
	v_cvt_pk_bf16_f32 v79, v74, v75
	v_lshlrev_b64 v[72:73], 11, v[72:73]
	global_store_dwordx4 v[28:29], v[12:15], off offset:256
	global_store_dwordx4 v[92:93], v[76:79], off offset:256
	v_cvt_pk_bf16_f32 v104, v116, v117
	v_add_co_u32_e32 v14, vcc, s78, v122
	v_lshl_add_u64 v[76:77], s[46:47], 0, v[72:73]
	s_nop 0
	v_addc_co_u32_e32 v15, vcc, 0, v123, vcc
	v_cvt_pk_bf16_f32 v105, v118, v119
	v_cvt_pk_bf16_f32 v106, v112, v113
	v_cvt_pk_bf16_f32 v107, v114, v115
	v_cvt_pk_bf16_f32 v88, v100, v101
	v_cvt_pk_bf16_f32 v89, v102, v103
	v_cvt_pk_bf16_f32 v90, v96, v97
	v_cvt_pk_bf16_f32 v91, v98, v99
	v_cvt_pk_bf16_f32 v72, v84, v85
	v_cvt_pk_bf16_f32 v73, v86, v87
	v_cvt_pk_bf16_f32 v74, v80, v81
	v_cvt_pk_bf16_f32 v75, v82, v83
	v_lshl_add_u64 v[76:77], v[76:77], 0, v[120:121]
	v_cvt_pk_bf16_f32 v68, v68, v69
	v_cvt_pk_bf16_f32 v69, v70, v71
	v_cvt_pk_bf16_f32 v70, v64, v65
	v_cvt_pk_bf16_f32 v71, v66, v67
	v_cvt_pk_bf16_f32 v40, v52, v53
	v_cvt_pk_bf16_f32 v41, v54, v55
	v_cvt_pk_bf16_f32 v42, v48, v49
	v_cvt_pk_bf16_f32 v43, v50, v51
	v_cvt_pk_bf16_f32 v24, v36, v37
	v_cvt_pk_bf16_f32 v25, v38, v39
	v_cvt_pk_bf16_f32 v26, v32, v33
	v_cvt_pk_bf16_f32 v27, v34, v35
	v_cvt_pk_bf16_f32 v8, v20, v21
	v_cvt_pk_bf16_f32 v9, v22, v23
	v_cvt_pk_bf16_f32 v10, v16, v17
	v_cvt_pk_bf16_f32 v11, v18, v19
	v_lshl_add_u64 v[12:13], v[122:123], 0, s[12:13]
	v_cvt_pk_bf16_f32 v4, v4, v5
	v_cvt_pk_bf16_f32 v5, v6, v7
	v_cvt_pk_bf16_f32 v6, v0, v1
	v_cvt_pk_bf16_f32 v7, v2, v3
	s_and_b64 vcc, exec, s[4:5]
	s_mov_b32 s79, s16
	s_mov_b32 s14, s18
	s_mov_b64 s[30:31], s[26:27]
	s_mov_b64 s[28:29], s[20:21]
	global_store_dwordx4 v[122:123], v[124:127], off
	global_store_dwordx4 v[108:109], v[104:107], off
	global_store_dwordx4 v[92:93], v[88:91], off
	global_store_dwordx4 v[76:77], v[72:75], off
	global_store_dwordx4 v[76:77], v[68:71], off offset:256
	global_store_dwordx4 v[58:59], v[60:63], off
	global_store_dwordx4 v[46:47], v[40:43], off
	global_store_dwordx4 v[30:31], v[24:27], off
	global_store_dwordx4 v[14:15], v[8:11], off
	global_store_dwordx4 v[12:13], v[4:7], off offset:256
	s_cbranch_vccz .LBB0_483
	s_waitcnt vmcnt(0)
	s_cmpk_gt_u32 s54, 0xff
	s_cbranch_scc1 .LBB0_490
	s_barrier

.LBB0_683:
	ds_read_b128 v[154:157], v151
	ds_read_b128 v[158:161], v151 offset:1024
	ds_read_b128 v[162:165], v151 offset:2048
	ds_read_b128 v[166:169], v151 offset:3072
	s_add_u32 s34, s30, 0xfffc0080
	s_addc_u32 s35, s31, -1
	s_cmp_eq_u32 s85, 12
	s_cselect_b32 s55, s19, s35
	s_cselect_b32 s54, s81, s34
	s_cselect_b32 s35, s17, s84
	s_cselect_b32 s34, s82, s83
	v_lshl_add_u64 v[202:203], s[30:31], 0, v[138:139]
	s_add_i32 m0, s29, 0xc000
	ds_read_b128 v[170:173], v152
	ds_read_b128 v[174:177], v152 offset:1024
	ds_read_b128 v[178:181], v152 offset:2048
	ds_read_b128 v[182:185], v152 offset:3072
	ds_read_b128 v[186:189], v152 offset:4096
	ds_read_b128 v[190:193], v152 offset:5120
	ds_read_b128 v[194:197], v152 offset:6144
	ds_read_b128 v[198:201], v152 offset:7168
	global_load_lds_dwordx4 v[202:203], off
	v_lshl_add_u64 v[202:203], s[30:31], 0, v[140:141]
	s_add_i32 m0, s29, 0xe000
	s_nop 0
	global_load_lds_dwordx4 v[202:203], off
	s_waitcnt lgkmcnt(8)
	s_barrier
	s_waitcnt lgkmcnt(0)
	s_waitcnt lgkmcnt(0)
	v_mfma_f32_16x16x32_bf16 v[124:127], v[154:157], v[170:173], v[124:127]
	v_mfma_f32_16x16x32_bf16 v[120:123], v[162:165], v[170:173], v[120:123]
	v_mfma_f32_16x16x32_bf16 v[108:111], v[154:157], v[178:181], v[108:111]
	v_mfma_f32_16x16x32_bf16 v[104:107], v[162:165], v[178:181], v[104:107]
	v_mfma_f32_16x16x32_bf16 v[92:95], v[154:157], v[186:189], v[92:95]
	v_mfma_f32_16x16x32_bf16 v[88:91], v[162:165], v[186:189], v[88:91]
	v_mfma_f32_16x16x32_bf16 v[76:79], v[154:157], v[194:197], v[76:79]
	v_mfma_f32_16x16x32_bf16 v[72:75], v[162:165], v[194:197], v[72:75]
	v_mfma_f32_16x16x32_bf16 v[124:127], v[158:161], v[174:177], v[124:127]
	v_mfma_f32_16x16x32_bf16 v[120:123], v[166:169], v[174:177], v[120:123]
	v_mfma_f32_16x16x32_bf16 v[108:111], v[158:161], v[182:185], v[108:111]
	v_mfma_f32_16x16x32_bf16 v[104:107], v[166:169], v[182:185], v[104:107]
	v_mfma_f32_16x16x32_bf16 v[92:95], v[158:161], v[190:193], v[92:95]
	v_mfma_f32_16x16x32_bf16 v[88:91], v[166:169], v[190:193], v[88:91]
	v_mfma_f32_16x16x32_bf16 v[76:79], v[158:161], v[198:201], v[76:79]
	v_mfma_f32_16x16x32_bf16 v[72:75], v[166:169], v[198:201], v[72:75]
	s_barrier
	s_add_i32 s86, s74, s60
	v_lshl_add_u64 v[218:219], s[34:35], 0, v[132:133]
	s_mov_b32 m0, s86
	ds_read_b128 v[202:205], v153
	ds_read_b128 v[206:209], v153 offset:1024
	ds_read_b128 v[210:213], v153 offset:2048
	ds_read_b128 v[214:217], v153 offset:3072
	global_load_lds_dwordx4 v[218:219], off
	v_lshl_add_u64 v[220:221], s[34:35], 0, v[136:137]
	s_add_i32 m0, s86, 0x2000
	s_nop 0
	global_load_lds_dwordx4 v[220:221], off
	s_barrier
	s_waitcnt lgkmcnt(0)
	s_waitcnt lgkmcnt(0)
	v_mfma_f32_16x16x32_bf16 v[116:119], v[202:205], v[170:173], v[116:119]
	v_mfma_f32_16x16x32_bf16 v[112:115], v[210:213], v[170:173], v[112:115]
	v_mfma_f32_16x16x32_bf16 v[100:103], v[202:205], v[178:181], v[100:103]
	v_mfma_f32_16x16x32_bf16 v[96:99], v[210:213], v[178:181], v[96:99]
	v_mfma_f32_16x16x32_bf16 v[84:87], v[202:205], v[186:189], v[84:87]
	v_mfma_f32_16x16x32_bf16 v[80:83], v[210:213], v[186:189], v[80:83]
	v_mfma_f32_16x16x32_bf16 v[68:71], v[202:205], v[194:197], v[68:71]
	v_mfma_f32_16x16x32_bf16 v[64:67], v[210:213], v[194:197], v[64:67]
	v_mfma_f32_16x16x32_bf16 v[116:119], v[206:209], v[174:177], v[116:119]
	v_mfma_f32_16x16x32_bf16 v[112:115], v[214:217], v[174:177], v[112:115]
	v_mfma_f32_16x16x32_bf16 v[100:103], v[206:209], v[182:185], v[100:103]
	v_mfma_f32_16x16x32_bf16 v[96:99], v[214:217], v[182:185], v[96:99]
	v_mfma_f32_16x16x32_bf16 v[84:87], v[206:209], v[190:193], v[84:87]
	v_mfma_f32_16x16x32_bf16 v[80:83], v[214:217], v[190:193], v[80:83]
	v_mfma_f32_16x16x32_bf16 v[68:71], v[206:209], v[198:201], v[68:71]
	v_mfma_f32_16x16x32_bf16 v[64:67], v[214:217], v[198:201], v[64:67]
	s_mov_b32 m0, s29
	v_lshl_add_u64 v[222:223], s[54:55], 0, v[130:131]
	s_barrier
	ds_read_b128 v[170:173], v152 offset:16384
	ds_read_b128 v[174:177], v152 offset:17408
	ds_read_b128 v[178:181], v152 offset:18432
	ds_read_b128 v[182:185], v152 offset:19456
	ds_read_b128 v[186:189], v152 offset:20480
	ds_read_b128 v[190:193], v152 offset:21504
	ds_read_b128 v[194:197], v152 offset:22528
	ds_read_b128 v[198:201], v152 offset:23552
	global_load_lds_dwordx4 v[222:223], off
	v_lshl_add_u64 v[224:225], s[54:55], 0, v[134:135]
	s_mov_b32 m0, s61
	s_nop 0
	global_load_lds_dwordx4 v[224:225], off
	s_barrier
	s_waitcnt lgkmcnt(0)
	s_waitcnt lgkmcnt(0)
	v_mfma_f32_16x16x32_bf16 v[60:63], v[154:157], v[170:173], v[60:63]
	v_mfma_f32_16x16x32_bf16 v[56:59], v[162:165], v[170:173], v[56:59]
	v_mfma_f32_16x16x32_bf16 v[44:47], v[154:157], v[178:181], v[44:47]
	v_mfma_f32_16x16x32_bf16 v[40:43], v[162:165], v[178:181], v[40:43]
	v_mfma_f32_16x16x32_bf16 v[28:31], v[154:157], v[186:189], v[28:31]
	v_mfma_f32_16x16x32_bf16 v[24:27], v[162:165], v[186:189], v[24:27]
	v_mfma_f32_16x16x32_bf16 v[12:15], v[154:157], v[194:197], v[12:15]
	v_mfma_f32_16x16x32_bf16 v[8:11], v[162:165], v[194:197], v[8:11]
	v_mfma_f32_16x16x32_bf16 v[60:63], v[158:161], v[174:177], v[60:63]
	v_mfma_f32_16x16x32_bf16 v[56:59], v[166:169], v[174:177], v[56:59]
	v_mfma_f32_16x16x32_bf16 v[44:47], v[158:161], v[182:185], v[44:47]
	v_mfma_f32_16x16x32_bf16 v[40:43], v[166:169], v[182:185], v[40:43]
	v_mfma_f32_16x16x32_bf16 v[28:31], v[158:161], v[190:193], v[28:31]
	v_mfma_f32_16x16x32_bf16 v[24:27], v[166:169], v[190:193], v[24:27]
	v_mfma_f32_16x16x32_bf16 v[12:15], v[158:161], v[198:201], v[12:15]
	v_mfma_f32_16x16x32_bf16 v[8:11], v[166:169], v[198:201], v[8:11]
	s_barrier
	s_add_u32 s86, s34, 0x40000
	s_addc_u32 s87, s35, 0
	s_add_i32 s88, s75, s60
	v_lshl_add_u64 v[154:155], s[86:87], 0, v[132:133]
	s_mov_b32 m0, s88
	s_nop 0
	global_load_lds_dwordx4 v[154:155], off
	v_lshl_add_u64 v[154:155], s[86:87], 0, v[136:137]
	s_add_i32 m0, s88, 0x2000
	s_nop 0
	global_load_lds_dwordx4 v[154:155], off
	s_waitcnt vmcnt(6)
	s_barrier
	v_mfma_f32_16x16x32_bf16 v[52:55], v[202:205], v[170:173], v[52:55]
	v_mfma_f32_16x16x32_bf16 v[48:51], v[210:213], v[170:173], v[48:51]
	v_mfma_f32_16x16x32_bf16 v[36:39], v[202:205], v[178:181], v[36:39]
	v_mfma_f32_16x16x32_bf16 v[32:35], v[210:213], v[178:181], v[32:35]
	v_mfma_f32_16x16x32_bf16 v[20:23], v[202:205], v[186:189], v[20:23]
	v_mfma_f32_16x16x32_bf16 v[16:19], v[210:213], v[186:189], v[16:19]
	v_mfma_f32_16x16x32_bf16 v[4:7], v[202:205], v[194:197], v[4:7]
	v_mfma_f32_16x16x32_bf16 v[0:3], v[210:213], v[194:197], v[0:3]
	v_mfma_f32_16x16x32_bf16 v[52:55], v[206:209], v[174:177], v[52:55]
	v_mfma_f32_16x16x32_bf16 v[48:51], v[214:217], v[174:177], v[48:51]
	v_mfma_f32_16x16x32_bf16 v[36:39], v[206:209], v[182:185], v[36:39]
	v_mfma_f32_16x16x32_bf16 v[32:35], v[214:217], v[182:185], v[32:35]
	v_mfma_f32_16x16x32_bf16 v[20:23], v[206:209], v[190:193], v[20:23]
	v_mfma_f32_16x16x32_bf16 v[16:19], v[214:217], v[190:193], v[16:19]
	v_mfma_f32_16x16x32_bf16 v[4:7], v[206:209], v[198:201], v[4:7]
	v_mfma_f32_16x16x32_bf16 v[0:3], v[214:217], v[198:201], v[0:3]
	s_add_i32 s86, 0, 0x18000
	v_add_u32_e32 v166, s86, v149
	s_barrier
	ds_read_b128 v[154:157], v166
	ds_read_b128 v[158:161], v166 offset:1024
	ds_read_b128 v[162:165], v166 offset:2048
	ds_read_b128 v[166:169], v166 offset:3072
	s_add_u32 s54, s54, 0x40000
	s_addc_u32 s55, s55, 0
	s_mov_b32 m0, s62
	v_lshl_add_u64 v[202:203], s[54:55], 0, v[130:131]
	ds_read_b128 v[170:173], v152 offset:32768
	ds_read_b128 v[174:177], v152 offset:33792
	ds_read_b128 v[178:181], v152 offset:34816
	ds_read_b128 v[182:185], v152 offset:35840
	ds_read_b128 v[186:189], v152 offset:36864
	ds_read_b128 v[190:193], v152 offset:37888
	ds_read_b128 v[194:197], v152 offset:38912
	ds_read_b128 v[198:201], v152 offset:39936
	global_load_lds_dwordx4 v[202:203], off
	v_lshl_add_u64 v[202:203], s[54:55], 0, v[134:135]
	s_mov_b32 m0, s63
	s_nop 0
	global_load_lds_dwordx4 v[202:203], off
	s_waitcnt lgkmcnt(8)
	s_barrier
	s_waitcnt lgkmcnt(0)
	s_waitcnt lgkmcnt(0)
	v_mfma_f32_16x16x32_bf16 v[124:127], v[154:157], v[170:173], v[124:127]
	v_mfma_f32_16x16x32_bf16 v[120:123], v[162:165], v[170:173], v[120:123]
	v_mfma_f32_16x16x32_bf16 v[108:111], v[154:157], v[178:181], v[108:111]
	v_mfma_f32_16x16x32_bf16 v[104:107], v[162:165], v[178:181], v[104:107]
	v_mfma_f32_16x16x32_bf16 v[92:95], v[154:157], v[186:189], v[92:95]
	v_mfma_f32_16x16x32_bf16 v[88:91], v[162:165], v[186:189], v[88:91]
	v_mfma_f32_16x16x32_bf16 v[76:79], v[154:157], v[194:197], v[76:79]
	v_mfma_f32_16x16x32_bf16 v[72:75], v[162:165], v[194:197], v[72:75]
	v_mfma_f32_16x16x32_bf16 v[124:127], v[158:161], v[174:177], v[124:127]
	v_mfma_f32_16x16x32_bf16 v[120:123], v[166:169], v[174:177], v[120:123]
	v_mfma_f32_16x16x32_bf16 v[108:111], v[158:161], v[182:185], v[108:111]
	v_mfma_f32_16x16x32_bf16 v[104:107], v[166:169], v[182:185], v[104:107]
	v_mfma_f32_16x16x32_bf16 v[92:95], v[158:161], v[190:193], v[92:95]
	v_mfma_f32_16x16x32_bf16 v[88:91], v[166:169], v[190:193], v[88:91]
	v_mfma_f32_16x16x32_bf16 v[76:79], v[158:161], v[198:201], v[76:79]
	v_mfma_f32_16x16x32_bf16 v[72:75], v[166:169], v[198:201], v[72:75]
	s_barrier
	s_add_i32 s54, 0, 0x1c000
	s_add_i32 s55, s86, s60
	v_add_u32_e32 v214, s54, v149
	v_lshl_add_u64 v[218:219], v[218:219], 0, s[8:9]
	s_mov_b32 m0, s55
	ds_read_b128 v[202:205], v214
	ds_read_b128 v[206:209], v214 offset:1024
	ds_read_b128 v[210:213], v214 offset:2048
	ds_read_b128 v[214:217], v214 offset:3072
	global_load_lds_dwordx4 v[218:219], off
	v_lshl_add_u64 v[218:219], v[220:221], 0, s[8:9]
	s_add_i32 m0, s55, 0x2000
	s_nop 0
	global_load_lds_dwordx4 v[218:219], off
	s_barrier
	s_waitcnt lgkmcnt(0)
	s_waitcnt lgkmcnt(0)
	v_mfma_f32_16x16x32_bf16 v[116:119], v[202:205], v[170:173], v[116:119]
	v_mfma_f32_16x16x32_bf16 v[112:115], v[210:213], v[170:173], v[112:115]
	v_mfma_f32_16x16x32_bf16 v[100:103], v[202:205], v[178:181], v[100:103]
	v_mfma_f32_16x16x32_bf16 v[96:99], v[210:213], v[178:181], v[96:99]
	v_mfma_f32_16x16x32_bf16 v[84:87], v[202:205], v[186:189], v[84:87]
	v_mfma_f32_16x16x32_bf16 v[80:83], v[210:213], v[186:189], v[80:83]
	v_mfma_f32_16x16x32_bf16 v[68:71], v[202:205], v[194:197], v[68:71]
	v_mfma_f32_16x16x32_bf16 v[64:67], v[210:213], v[194:197], v[64:67]
	v_mfma_f32_16x16x32_bf16 v[116:119], v[206:209], v[174:177], v[116:119]
	v_mfma_f32_16x16x32_bf16 v[112:115], v[214:217], v[174:177], v[112:115]
	v_mfma_f32_16x16x32_bf16 v[100:103], v[206:209], v[182:185], v[100:103]
	v_mfma_f32_16x16x32_bf16 v[96:99], v[214:217], v[182:185], v[96:99]
	v_mfma_f32_16x16x32_bf16 v[84:87], v[206:209], v[190:193], v[84:87]
	v_mfma_f32_16x16x32_bf16 v[80:83], v[214:217], v[190:193], v[80:83]
	v_mfma_f32_16x16x32_bf16 v[68:71], v[206:209], v[198:201], v[68:71]
	v_mfma_f32_16x16x32_bf16 v[64:67], v[214:217], v[198:201], v[64:67]
	s_mov_b32 m0, s71
	v_lshl_add_u64 v[218:219], v[222:223], 0, s[8:9]
	s_barrier
	ds_read_b128 v[170:173], v152 offset:49152
	ds_read_b128 v[174:177], v152 offset:50176
	ds_read_b128 v[178:181], v152 offset:51200
	ds_read_b128 v[182:185], v152 offset:52224
	ds_read_b128 v[186:189], v152 offset:53248
	ds_read_b128 v[190:193], v152 offset:54272
	ds_read_b128 v[194:197], v152 offset:55296
	ds_read_b128 v[198:201], v152 offset:56320
	global_load_lds_dwordx4 v[218:219], off
	v_lshl_add_u64 v[218:219], v[224:225], 0, s[8:9]
	s_mov_b32 m0, s72
	s_nop 0
	global_load_lds_dwordx4 v[218:219], off
	s_barrier
	s_waitcnt lgkmcnt(0)
	s_waitcnt lgkmcnt(0)
	v_mfma_f32_16x16x32_bf16 v[60:63], v[154:157], v[170:173], v[60:63]
	v_mfma_f32_16x16x32_bf16 v[56:59], v[162:165], v[170:173], v[56:59]
	v_mfma_f32_16x16x32_bf16 v[44:47], v[154:157], v[178:181], v[44:47]
	v_mfma_f32_16x16x32_bf16 v[40:43], v[162:165], v[178:181], v[40:43]
	v_mfma_f32_16x16x32_bf16 v[28:31], v[154:157], v[186:189], v[28:31]
	v_mfma_f32_16x16x32_bf16 v[24:27], v[162:165], v[186:189], v[24:27]
	v_mfma_f32_16x16x32_bf16 v[12:15], v[154:157], v[194:197], v[12:15]
	v_mfma_f32_16x16x32_bf16 v[8:11], v[162:165], v[194:197], v[8:11]
	v_mfma_f32_16x16x32_bf16 v[60:63], v[158:161], v[174:177], v[60:63]
	v_mfma_f32_16x16x32_bf16 v[56:59], v[166:169], v[174:177], v[56:59]
	v_mfma_f32_16x16x32_bf16 v[44:47], v[158:161], v[182:185], v[44:47]
	v_mfma_f32_16x16x32_bf16 v[40:43], v[166:169], v[182:185], v[40:43]
	v_mfma_f32_16x16x32_bf16 v[28:31], v[158:161], v[190:193], v[28:31]
	v_mfma_f32_16x16x32_bf16 v[24:27], v[166:169], v[190:193], v[24:27]
	v_mfma_f32_16x16x32_bf16 v[12:15], v[158:161], v[198:201], v[12:15]
	v_mfma_f32_16x16x32_bf16 v[8:11], v[166:169], v[198:201], v[8:11]
	s_barrier
	s_add_u32 s34, s34, 0x40080
	s_addc_u32 s35, s35, 0
	s_add_i32 s54, s54, s60
	v_lshl_add_u64 v[154:155], s[34:35], 0, v[132:133]
	s_mov_b32 m0, s54
	s_nop 0
	global_load_lds_dwordx4 v[154:155], off
	v_lshl_add_u64 v[154:155], s[34:35], 0, v[136:137]
	s_add_i32 m0, s54, 0x2000
	s_nop 0
	global_load_lds_dwordx4 v[154:155], off
	s_waitcnt vmcnt(6)
	s_barrier
	v_mfma_f32_16x16x32_bf16 v[52:55], v[202:205], v[170:173], v[52:55]
	v_mfma_f32_16x16x32_bf16 v[48:51], v[210:213], v[170:173], v[48:51]
	v_mfma_f32_16x16x32_bf16 v[36:39], v[202:205], v[178:181], v[36:39]
	v_mfma_f32_16x16x32_bf16 v[32:35], v[210:213], v[178:181], v[32:35]
	v_mfma_f32_16x16x32_bf16 v[20:23], v[202:205], v[186:189], v[20:23]
	v_mfma_f32_16x16x32_bf16 v[16:19], v[210:213], v[186:189], v[16:19]
	v_mfma_f32_16x16x32_bf16 v[4:7], v[202:205], v[194:197], v[4:7]
	v_mfma_f32_16x16x32_bf16 v[0:3], v[210:213], v[194:197], v[0:3]
	v_mfma_f32_16x16x32_bf16 v[52:55], v[206:209], v[174:177], v[52:55]
	v_mfma_f32_16x16x32_bf16 v[48:51], v[214:217], v[174:177], v[48:51]
	v_mfma_f32_16x16x32_bf16 v[36:39], v[206:209], v[182:185], v[36:39]
	v_mfma_f32_16x16x32_bf16 v[32:35], v[214:217], v[182:185], v[32:35]
	v_mfma_f32_16x16x32_bf16 v[20:23], v[206:209], v[190:193], v[20:23]
	v_mfma_f32_16x16x32_bf16 v[16:19], v[214:217], v[190:193], v[16:19]
	v_mfma_f32_16x16x32_bf16 v[4:7], v[206:209], v[198:201], v[4:7]
	v_mfma_f32_16x16x32_bf16 v[0:3], v[214:217], v[198:201], v[0:3]
	s_add_i32 s85, s85, 2
	s_add_u32 s30, s30, 0x100
	s_addc_u32 s31, s31, 0
	s_add_u32 s83, s83, 0x100
	s_addc_u32 s84, s84, 0
	s_cmp_gt_u32 s85, 13
	s_barrier
	s_cbranch_scc0 .LBB0_683
	v_lshl_add_u32 v154, s28, 8, v148
	v_max_f32_e32 v126, v126, v126
	v_max_f32_e32 v127, v127, v127
	v_lshl_or_b32 v156, s80, 8, v150
	v_ashrrev_i32_e32 v155, 31, v154
	v_max_f32_e32 v124, v124, v124
	v_max_f32_e32 v120, v120, v120
	v_max_f32_e32 v125, v125, v125
	v_max_f32_e32 v121, v121, v121
	v_max_f32_e32 v126, 0, v126
	v_max_f32_e32 v122, v122, v122
	v_max_f32_e32 v127, 0, v127
	v_max_f32_e32 v123, v123, v123
	v_lshlrev_b64 v[158:159], 13, v[154:155]
	v_max_f32_e32 v124, 0, v124
	v_max_f32_e32 v120, 0, v120
	v_max_f32_e32 v125, 0, v125
	v_max_f32_e32 v121, 0, v121
	v_max_f32_e32 v122, 0, v122
	v_max_f32_e32 v123, 0, v123
	v_pk_mul_f32 v[126:127], v[126:127], v[126:127]
	v_ashrrev_i32_e32 v157, 31, v156
	v_lshl_add_u64 v[158:159], s[46:47], 0, v[158:159]
	v_pk_mul_f32 v[124:125], v[124:125], v[124:125]
	v_pk_mul_f32 v[120:121], v[120:121], v[120:121]
	v_pk_mul_f32 v[160:161], v[122:123], v[122:123]
	v_cvt_pk_bf16_f32 v123, v126, v127
	v_lshlrev_b64 v[126:127], 1, v[156:157]
	v_max_f32_e32 v112, v112, v112
	v_max_f32_e32 v113, v113, v113
	v_cvt_pk_bf16_f32 v122, v124, v125
	v_cvt_pk_bf16_f32 v124, v120, v121
	v_cvt_pk_bf16_f32 v125, v160, v161
	v_lshl_add_u64 v[120:121], v[158:159], 0, v[126:127]
	v_max_f32_e32 v112, 0, v112
	v_max_f32_e32 v113, 0, v113
	global_store_dwordx4 v[120:121], v[122:125], off
	v_max_f32_e32 v116, v116, v116
	v_max_f32_e32 v117, v117, v117
	v_pk_mul_f32 v[122:123], v[112:113], v[112:113]
	v_max_f32_e32 v113, v114, v114
	v_max_f32_e32 v112, v118, v118
	v_max_f32_e32 v114, 0, v113
	v_max_f32_e32 v113, v119, v119
	v_max_f32_e32 v115, v115, v115
	v_max_f32_e32 v116, 0, v116
	v_max_f32_e32 v117, 0, v117
	v_max_f32_e32 v112, 0, v112
	v_max_f32_e32 v113, 0, v113
	v_max_f32_e32 v115, 0, v115
	v_pk_mul_f32 v[116:117], v[116:117], v[116:117]
	v_pk_mul_f32 v[118:119], v[112:113], v[112:113]
	v_pk_mul_f32 v[124:125], v[114:115], v[114:115]
	v_max_f32_e32 v104, v104, v104
	v_max_f32_e32 v105, v105, v105
	v_cvt_pk_bf16_f32 v112, v116, v117
	v_cvt_pk_bf16_f32 v113, v118, v119
	v_cvt_pk_bf16_f32 v114, v122, v123
	v_cvt_pk_bf16_f32 v115, v124, v125
	v_max_f32_e32 v104, 0, v104
	v_max_f32_e32 v105, 0, v105
	global_store_dwordx4 v[120:121], v[112:115], off offset:256
	v_max_f32_e32 v108, v108, v108
	v_max_f32_e32 v109, v109, v109
	v_or_b32_e32 v112, 16, v154
	v_pk_mul_f32 v[114:115], v[104:105], v[104:105]
	v_max_f32_e32 v105, v106, v106
	v_ashrrev_i32_e32 v113, 31, v112
	v_max_f32_e32 v104, v110, v110
	v_max_f32_e32 v106, 0, v105
	v_max_f32_e32 v105, v111, v111
	v_max_f32_e32 v107, v107, v107
	v_lshlrev_b64 v[112:113], 13, v[112:113]
	v_max_f32_e32 v108, 0, v108
	v_max_f32_e32 v109, 0, v109
	v_max_f32_e32 v104, 0, v104
	v_max_f32_e32 v105, 0, v105
	v_max_f32_e32 v107, 0, v107
	v_lshl_add_u64 v[112:113], s[46:47], 0, v[112:113]
	v_pk_mul_f32 v[108:109], v[108:109], v[108:109]
	v_pk_mul_f32 v[110:111], v[104:105], v[104:105]
	v_pk_mul_f32 v[116:117], v[106:107], v[106:107]
	v_max_f32_e32 v96, v96, v96
	v_max_f32_e32 v97, v97, v97
	v_cvt_pk_bf16_f32 v104, v108, v109
	v_cvt_pk_bf16_f32 v105, v110, v111
	v_cvt_pk_bf16_f32 v106, v114, v115
	v_cvt_pk_bf16_f32 v107, v116, v117
	v_lshl_add_u64 v[108:109], v[112:113], 0, v[126:127]
	v_max_f32_e32 v96, 0, v96
	v_max_f32_e32 v97, 0, v97
	global_store_dwordx4 v[108:109], v[104:107], off
	v_max_f32_e32 v100, v100, v100
	v_max_f32_e32 v101, v101, v101
	v_pk_mul_f32 v[104:105], v[96:97], v[96:97]
	v_max_f32_e32 v97, v98, v98
	v_max_f32_e32 v96, v102, v102
	v_max_f32_e32 v98, 0, v97
	v_max_f32_e32 v97, v103, v103
	v_max_f32_e32 v99, v99, v99
	v_max_f32_e32 v100, 0, v100
	v_max_f32_e32 v101, 0, v101
	v_max_f32_e32 v96, 0, v96
	v_max_f32_e32 v97, 0, v97
	v_max_f32_e32 v99, 0, v99
	v_pk_mul_f32 v[100:101], v[100:101], v[100:101]
	v_pk_mul_f32 v[102:103], v[96:97], v[96:97]
	v_pk_mul_f32 v[106:107], v[98:99], v[98:99]
	v_max_f32_e32 v88, v88, v88
	v_max_f32_e32 v89, v89, v89
	v_cvt_pk_bf16_f32 v96, v100, v101
	v_cvt_pk_bf16_f32 v97, v102, v103
	v_cvt_pk_bf16_f32 v98, v104, v105
	v_cvt_pk_bf16_f32 v99, v106, v107
	v_max_f32_e32 v88, 0, v88
	v_max_f32_e32 v89, 0, v89
	global_store_dwordx4 v[108:109], v[96:99], off offset:256
	v_max_f32_e32 v92, v92, v92
	v_max_f32_e32 v93, v93, v93
	v_or_b32_e32 v96, 32, v154
	v_pk_mul_f32 v[98:99], v[88:89], v[88:89]
	v_max_f32_e32 v89, v90, v90
	v_ashrrev_i32_e32 v97, 31, v96
	v_max_f32_e32 v88, v94, v94
	v_max_f32_e32 v90, 0, v89
	v_max_f32_e32 v89, v95, v95
	v_max_f32_e32 v91, v91, v91
	v_lshlrev_b64 v[96:97], 13, v[96:97]
	v_max_f32_e32 v92, 0, v92
	v_max_f32_e32 v93, 0, v93
	v_max_f32_e32 v88, 0, v88
	v_max_f32_e32 v89, 0, v89
	v_max_f32_e32 v91, 0, v91
	v_lshl_add_u64 v[96:97], s[46:47], 0, v[96:97]
	v_pk_mul_f32 v[92:93], v[92:93], v[92:93]
	v_pk_mul_f32 v[94:95], v[88:89], v[88:89]
	v_pk_mul_f32 v[100:101], v[90:91], v[90:91]
	v_max_f32_e32 v80, v80, v80
	v_max_f32_e32 v81, v81, v81
	v_cvt_pk_bf16_f32 v88, v92, v93
	v_cvt_pk_bf16_f32 v89, v94, v95
	v_cvt_pk_bf16_f32 v90, v98, v99
	v_cvt_pk_bf16_f32 v91, v100, v101
	v_lshl_add_u64 v[92:93], v[96:97], 0, v[126:127]
	v_max_f32_e32 v80, 0, v80
	v_max_f32_e32 v81, 0, v81
	global_store_dwordx4 v[92:93], v[88:91], off
	v_max_f32_e32 v84, v84, v84
	v_max_f32_e32 v85, v85, v85
	v_pk_mul_f32 v[88:89], v[80:81], v[80:81]
	v_max_f32_e32 v81, v82, v82
	v_max_f32_e32 v80, v86, v86
	v_max_f32_e32 v82, 0, v81
	v_max_f32_e32 v81, v87, v87
	v_max_f32_e32 v83, v83, v83
	v_max_f32_e32 v84, 0, v84
	v_max_f32_e32 v85, 0, v85
	v_max_f32_e32 v80, 0, v80
	v_max_f32_e32 v81, 0, v81
	v_max_f32_e32 v83, 0, v83
	v_pk_mul_f32 v[84:85], v[84:85], v[84:85]
	v_pk_mul_f32 v[86:87], v[80:81], v[80:81]
	v_pk_mul_f32 v[90:91], v[82:83], v[82:83]
	v_max_f32_e32 v72, v72, v72
	v_max_f32_e32 v73, v73, v73
	v_cvt_pk_bf16_f32 v80, v84, v85
	v_cvt_pk_bf16_f32 v81, v86, v87
	v_cvt_pk_bf16_f32 v82, v88, v89
	v_cvt_pk_bf16_f32 v83, v90, v91
	v_max_f32_e32 v72, 0, v72
	v_max_f32_e32 v73, 0, v73
	global_store_dwordx4 v[92:93], v[80:83], off offset:256
	v_max_f32_e32 v76, v76, v76
	v_max_f32_e32 v77, v77, v77
	v_or_b32_e32 v80, 48, v154
	v_pk_mul_f32 v[82:83], v[72:73], v[72:73]
	v_max_f32_e32 v73, v74, v74
	v_ashrrev_i32_e32 v81, 31, v80
	v_max_f32_e32 v72, v78, v78
	v_max_f32_e32 v74, 0, v73
	v_max_f32_e32 v73, v79, v79
	v_max_f32_e32 v75, v75, v75
	v_lshlrev_b64 v[80:81], 13, v[80:81]
	v_max_f32_e32 v76, 0, v76
	v_max_f32_e32 v77, 0, v77
	v_max_f32_e32 v72, 0, v72
	v_max_f32_e32 v73, 0, v73
	v_max_f32_e32 v75, 0, v75
	v_lshl_add_u64 v[80:81], s[46:47], 0, v[80:81]
	v_pk_mul_f32 v[76:77], v[76:77], v[76:77]
	v_pk_mul_f32 v[78:79], v[72:73], v[72:73]
	v_pk_mul_f32 v[84:85], v[74:75], v[74:75]
	v_max_f32_e32 v64, v64, v64
	v_max_f32_e32 v65, v65, v65
	v_cvt_pk_bf16_f32 v72, v76, v77
	v_cvt_pk_bf16_f32 v73, v78, v79
	v_cvt_pk_bf16_f32 v74, v82, v83
	v_cvt_pk_bf16_f32 v75, v84, v85
	v_lshl_add_u64 v[76:77], v[80:81], 0, v[126:127]
	v_max_f32_e32 v64, 0, v64
	v_max_f32_e32 v65, 0, v65
	global_store_dwordx4 v[76:77], v[72:75], off
	v_max_f32_e32 v68, v68, v68
	v_max_f32_e32 v69, v69, v69
	v_pk_mul_f32 v[72:73], v[64:65], v[64:65]
	v_max_f32_e32 v65, v66, v66
	v_max_f32_e32 v64, v70, v70
	v_max_f32_e32 v66, 0, v65
	v_max_f32_e32 v65, v71, v71
	v_max_f32_e32 v67, v67, v67
	v_max_f32_e32 v68, 0, v68
	v_max_f32_e32 v69, 0, v69
	v_max_f32_e32 v64, 0, v64
	v_max_f32_e32 v65, 0, v65
	v_max_f32_e32 v67, 0, v67
	v_pk_mul_f32 v[68:69], v[68:69], v[68:69]
	v_pk_mul_f32 v[70:71], v[64:65], v[64:65]
	v_pk_mul_f32 v[74:75], v[66:67], v[66:67]
	v_max_f32_e32 v56, v56, v56
	v_max_f32_e32 v57, v57, v57
	v_cvt_pk_bf16_f32 v64, v68, v69
	v_cvt_pk_bf16_f32 v65, v70, v71
	v_cvt_pk_bf16_f32 v66, v72, v73
	v_cvt_pk_bf16_f32 v67, v74, v75
	v_max_f32_e32 v56, 0, v56
	v_max_f32_e32 v57, 0, v57
	global_store_dwordx4 v[76:77], v[64:67], off offset:256
	v_max_f32_e32 v60, v60, v60
	v_max_f32_e32 v61, v61, v61
	v_pk_mul_f32 v[64:65], v[56:57], v[56:57]
	v_max_f32_e32 v57, v58, v58
	v_max_f32_e32 v56, v62, v62
	v_max_f32_e32 v58, 0, v57
	v_max_f32_e32 v57, v63, v63
	v_max_f32_e32 v56, 0, v56
	v_max_f32_e32 v57, 0, v57
	v_max_f32_e32 v59, v59, v59
	v_max_f32_e32 v60, 0, v60
	v_max_f32_e32 v61, 0, v61
	v_max_f32_e32 v59, 0, v59
	v_pk_mul_f32 v[62:63], v[56:57], v[56:57]
	v_pk_mul_f32 v[60:61], v[60:61], v[60:61]
	v_pk_mul_f32 v[66:67], v[58:59], v[58:59]
	v_cvt_pk_bf16_f32 v57, v62, v63
	v_add_co_u32_e32 v62, vcc, s76, v120
	v_max_f32_e32 v48, v48, v48
	v_max_f32_e32 v49, v49, v49
	v_cvt_pk_bf16_f32 v56, v60, v61
	v_cvt_pk_bf16_f32 v58, v64, v65
	v_cvt_pk_bf16_f32 v59, v66, v67
	v_addc_co_u32_e32 v63, vcc, 0, v121, vcc
	v_max_f32_e32 v48, 0, v48
	v_max_f32_e32 v49, 0, v49
	global_store_dwordx4 v[62:63], v[56:59], off
	v_max_f32_e32 v52, v52, v52
	v_max_f32_e32 v53, v53, v53
	v_pk_mul_f32 v[56:57], v[48:49], v[48:49]
	v_max_f32_e32 v49, v50, v50
	v_max_f32_e32 v48, v54, v54
	v_max_f32_e32 v50, 0, v49
	v_max_f32_e32 v49, v55, v55
	v_max_f32_e32 v51, v51, v51
	v_max_f32_e32 v52, 0, v52
	v_max_f32_e32 v53, 0, v53
	v_max_f32_e32 v48, 0, v48
	v_max_f32_e32 v49, 0, v49
	v_max_f32_e32 v51, 0, v51
	s_mov_b64 s[30:31], 0x100000
	v_pk_mul_f32 v[52:53], v[52:53], v[52:53]
	v_pk_mul_f32 v[54:55], v[48:49], v[48:49]
	v_pk_mul_f32 v[58:59], v[50:51], v[50:51]
	v_max_f32_e32 v40, v40, v40
	v_max_f32_e32 v41, v41, v41
	v_lshl_add_u64 v[60:61], v[120:121], 0, s[30:31]
	v_cvt_pk_bf16_f32 v48, v52, v53
	v_cvt_pk_bf16_f32 v49, v54, v55
	v_cvt_pk_bf16_f32 v50, v56, v57
	v_cvt_pk_bf16_f32 v51, v58, v59
	v_max_f32_e32 v40, 0, v40
	v_max_f32_e32 v41, 0, v41
	global_store_dwordx4 v[60:61], v[48:51], off offset:256
	v_max_f32_e32 v44, v44, v44
	v_max_f32_e32 v45, v45, v45
	v_pk_mul_f32 v[48:49], v[40:41], v[40:41]
	v_max_f32_e32 v41, v42, v42
	v_max_f32_e32 v40, v46, v46
	v_max_f32_e32 v42, 0, v41
	v_max_f32_e32 v41, v47, v47
	v_max_f32_e32 v40, 0, v40
	v_max_f32_e32 v41, 0, v41
	v_max_f32_e32 v43, v43, v43
	v_max_f32_e32 v44, 0, v44
	v_max_f32_e32 v45, 0, v45
	v_max_f32_e32 v43, 0, v43
	v_pk_mul_f32 v[46:47], v[40:41], v[40:41]
	v_pk_mul_f32 v[44:45], v[44:45], v[44:45]
	v_pk_mul_f32 v[50:51], v[42:43], v[42:43]
	v_cvt_pk_bf16_f32 v41, v46, v47
	v_add_co_u32_e32 v46, vcc, s77, v120
	v_max_f32_e32 v32, v32, v32
	v_max_f32_e32 v33, v33, v33
	v_cvt_pk_bf16_f32 v40, v44, v45
	v_cvt_pk_bf16_f32 v42, v48, v49
	v_cvt_pk_bf16_f32 v43, v50, v51
	v_addc_co_u32_e32 v47, vcc, 0, v121, vcc
	v_max_f32_e32 v32, 0, v32
	v_max_f32_e32 v33, 0, v33
	global_store_dwordx4 v[46:47], v[40:43], off
	v_max_f32_e32 v36, v36, v36
	v_max_f32_e32 v37, v37, v37
	v_pk_mul_f32 v[40:41], v[32:33], v[32:33]
	v_max_f32_e32 v33, v34, v34
	v_max_f32_e32 v32, v38, v38
	v_max_f32_e32 v34, 0, v33
	v_max_f32_e32 v33, v39, v39
	v_max_f32_e32 v35, v35, v35
	v_max_f32_e32 v36, 0, v36
	v_max_f32_e32 v37, 0, v37
	v_max_f32_e32 v32, 0, v32
	v_max_f32_e32 v33, 0, v33
	v_max_f32_e32 v35, 0, v35
	v_pk_mul_f32 v[36:37], v[36:37], v[36:37]
	v_pk_mul_f32 v[38:39], v[32:33], v[32:33]
	v_pk_mul_f32 v[42:43], v[34:35], v[34:35]
	v_max_f32_e32 v24, v24, v24
	v_max_f32_e32 v25, v25, v25
	v_lshl_add_u64 v[44:45], v[120:121], 0, s[10:11]
	v_cvt_pk_bf16_f32 v32, v36, v37
	v_cvt_pk_bf16_f32 v33, v38, v39
	v_cvt_pk_bf16_f32 v34, v40, v41
	v_cvt_pk_bf16_f32 v35, v42, v43
	v_max_f32_e32 v24, 0, v24
	v_max_f32_e32 v25, 0, v25
	global_store_dwordx4 v[44:45], v[32:35], off offset:256
	v_max_f32_e32 v28, v28, v28
	v_max_f32_e32 v29, v29, v29
	v_pk_mul_f32 v[32:33], v[24:25], v[24:25]
	v_max_f32_e32 v25, v26, v26
	v_max_f32_e32 v24, v30, v30
	v_max_f32_e32 v26, 0, v25
	v_max_f32_e32 v25, v31, v31
	v_max_f32_e32 v24, 0, v24
	v_max_f32_e32 v25, 0, v25
	v_max_f32_e32 v27, v27, v27
	v_max_f32_e32 v28, 0, v28
	v_max_f32_e32 v29, 0, v29
	v_max_f32_e32 v27, 0, v27
	v_pk_mul_f32 v[30:31], v[24:25], v[24:25]
	v_pk_mul_f32 v[28:29], v[28:29], v[28:29]
	v_pk_mul_f32 v[34:35], v[26:27], v[26:27]
	v_cvt_pk_bf16_f32 v25, v30, v31
	v_add_co_u32_e32 v30, vcc, s78, v120
	v_max_f32_e32 v16, v16, v16
	v_max_f32_e32 v17, v17, v17
	v_cvt_pk_bf16_f32 v24, v28, v29
	v_cvt_pk_bf16_f32 v26, v32, v33
	v_cvt_pk_bf16_f32 v27, v34, v35
	v_addc_co_u32_e32 v31, vcc, 0, v121, vcc
	v_max_f32_e32 v16, 0, v16
	v_max_f32_e32 v17, 0, v17
	global_store_dwordx4 v[30:31], v[24:27], off
	v_max_f32_e32 v20, v20, v20
	v_max_f32_e32 v21, v21, v21
	v_pk_mul_f32 v[24:25], v[16:17], v[16:17]
	v_max_f32_e32 v17, v18, v18
	v_max_f32_e32 v16, v22, v22
	v_max_f32_e32 v18, 0, v17
	v_max_f32_e32 v17, v23, v23
	v_max_f32_e32 v19, v19, v19
	v_max_f32_e32 v20, 0, v20
	v_max_f32_e32 v21, 0, v21
	v_max_f32_e32 v16, 0, v16
	v_max_f32_e32 v17, 0, v17
	v_max_f32_e32 v19, 0, v19
	v_pk_mul_f32 v[20:21], v[20:21], v[20:21]
	v_pk_mul_f32 v[22:23], v[16:17], v[16:17]
	v_pk_mul_f32 v[26:27], v[18:19], v[18:19]
	v_max_f32_e32 v8, v8, v8
	v_max_f32_e32 v9, v9, v9
	v_lshl_add_u64 v[28:29], v[120:121], 0, s[12:13]
	v_cvt_pk_bf16_f32 v16, v20, v21
	v_cvt_pk_bf16_f32 v17, v22, v23
	v_cvt_pk_bf16_f32 v18, v24, v25
	v_cvt_pk_bf16_f32 v19, v26, v27
	v_max_f32_e32 v8, 0, v8
	v_max_f32_e32 v9, 0, v9
	global_store_dwordx4 v[28:29], v[16:19], off offset:256
	v_max_f32_e32 v12, v12, v12
	v_max_f32_e32 v13, v13, v13
	v_pk_mul_f32 v[16:17], v[8:9], v[8:9]
	v_max_f32_e32 v9, v10, v10
	v_max_f32_e32 v8, v14, v14
	v_max_f32_e32 v10, 0, v9
	v_max_f32_e32 v9, v15, v15
	v_max_f32_e32 v8, 0, v8
	v_max_f32_e32 v9, 0, v9
	v_max_f32_e32 v11, v11, v11
	v_max_f32_e32 v12, 0, v12
	v_max_f32_e32 v13, 0, v13
	v_max_f32_e32 v11, 0, v11
	v_pk_mul_f32 v[14:15], v[8:9], v[8:9]
	v_pk_mul_f32 v[12:13], v[12:13], v[12:13]
	v_pk_mul_f32 v[18:19], v[10:11], v[10:11]
	v_cvt_pk_bf16_f32 v9, v14, v15
	v_add_co_u32_e32 v14, vcc, s79, v120
	v_max_f32_e32 v0, v0, v0
	v_max_f32_e32 v1, v1, v1
	v_cvt_pk_bf16_f32 v8, v12, v13
	v_cvt_pk_bf16_f32 v10, v16, v17
	v_cvt_pk_bf16_f32 v11, v18, v19
	v_addc_co_u32_e32 v15, vcc, 0, v121, vcc
	v_max_f32_e32 v0, 0, v0
	v_max_f32_e32 v1, 0, v1
	global_store_dwordx4 v[14:15], v[8:11], off
	v_max_f32_e32 v4, v4, v4
	v_max_f32_e32 v5, v5, v5
	v_pk_mul_f32 v[8:9], v[0:1], v[0:1]
	v_max_f32_e32 v1, v2, v2
	v_max_f32_e32 v0, v6, v6
	v_max_f32_e32 v2, 0, v1
	v_max_f32_e32 v1, v7, v7
	v_max_f32_e32 v3, v3, v3
	v_max_f32_e32 v4, 0, v4
	v_max_f32_e32 v5, 0, v5
	v_max_f32_e32 v0, 0, v0
	v_max_f32_e32 v1, 0, v1
	v_max_f32_e32 v3, 0, v3
	v_pk_mul_f32 v[4:5], v[4:5], v[4:5]
	v_pk_mul_f32 v[6:7], v[0:1], v[0:1]
	v_pk_mul_f32 v[10:11], v[2:3], v[2:3]
	v_lshl_add_u64 v[12:13], v[120:121], 0, s[14:15]
	v_cvt_pk_bf16_f32 v0, v4, v5
	v_cvt_pk_bf16_f32 v1, v6, v7
	v_cvt_pk_bf16_f32 v2, v8, v9
	v_cvt_pk_bf16_f32 v3, v10, v11
	s_and_b64 vcc, exec, s[4:5]
	s_mov_b32 s80, s16
	s_mov_b32 s28, s18
	s_mov_b64 s[34:35], s[26:27]
	s_mov_b64 s[30:31], s[20:21]
	global_store_dwordx4 v[12:13], v[0:3], off offset:256
	s_cbranch_vccz .LBB0_676
	s_waitcnt vmcnt(0)
	s_cmpk_gt_u32 s56, 0xff
	s_cbranch_scc1 .LBB0_687
	s_barrier

.LBB0_776:
	ds_read_b128 v[156:159], v152
	ds_read_b128 v[160:163], v152 offset:1024
	ds_read_b128 v[164:167], v152 offset:2048
	ds_read_b128 v[168:171], v152 offset:3072
	s_add_u32 s34, s30, 0xfff00080
	s_addc_u32 s35, s31, -1
	s_cmp_eq_u32 s85, 60
	s_cselect_b32 s55, s21, s35
	s_cselect_b32 s54, s81, s34
	s_cselect_b32 s35, s19, s84
	s_cselect_b32 s34, s82, s83
	v_lshl_add_u64 v[204:205], s[30:31], 0, v[138:139]
	s_add_i32 m0, s17, 0xc000
	ds_read_b128 v[172:175], v153
	ds_read_b128 v[176:179], v153 offset:1024
	ds_read_b128 v[180:183], v153 offset:2048
	ds_read_b128 v[184:187], v153 offset:3072
	ds_read_b128 v[188:191], v153 offset:4096
	ds_read_b128 v[192:195], v153 offset:5120
	ds_read_b128 v[196:199], v153 offset:6144
	ds_read_b128 v[200:203], v153 offset:7168
	global_load_lds_dwordx4 v[204:205], off
	v_lshl_add_u64 v[204:205], s[30:31], 0, v[140:141]
	s_add_i32 m0, s17, 0xe000
	s_nop 0
	global_load_lds_dwordx4 v[204:205], off
	s_waitcnt lgkmcnt(8)
	s_barrier
	s_waitcnt lgkmcnt(0)
	s_waitcnt lgkmcnt(0)
	v_mfma_f32_16x16x32_bf16 v[124:127], v[156:159], v[172:175], v[124:127]
	v_mfma_f32_16x16x32_bf16 v[120:123], v[164:167], v[172:175], v[120:123]
	v_mfma_f32_16x16x32_bf16 v[116:119], v[156:159], v[180:183], v[116:119]
	v_mfma_f32_16x16x32_bf16 v[112:115], v[164:167], v[180:183], v[112:115]
	v_mfma_f32_16x16x32_bf16 v[100:103], v[156:159], v[188:191], v[100:103]
	v_mfma_f32_16x16x32_bf16 v[96:99], v[164:167], v[188:191], v[96:99]
	v_mfma_f32_16x16x32_bf16 v[84:87], v[156:159], v[196:199], v[84:87]
	v_mfma_f32_16x16x32_bf16 v[80:83], v[164:167], v[196:199], v[80:83]
	v_mfma_f32_16x16x32_bf16 v[124:127], v[160:163], v[176:179], v[124:127]
	v_mfma_f32_16x16x32_bf16 v[120:123], v[168:171], v[176:179], v[120:123]
	v_mfma_f32_16x16x32_bf16 v[116:119], v[160:163], v[184:187], v[116:119]
	v_mfma_f32_16x16x32_bf16 v[112:115], v[168:171], v[184:187], v[112:115]
	v_mfma_f32_16x16x32_bf16 v[100:103], v[160:163], v[192:195], v[100:103]
	v_mfma_f32_16x16x32_bf16 v[96:99], v[168:171], v[192:195], v[96:99]
	v_mfma_f32_16x16x32_bf16 v[84:87], v[160:163], v[200:203], v[84:87]
	v_mfma_f32_16x16x32_bf16 v[80:83], v[168:171], v[200:203], v[80:83]
	s_barrier
	s_add_i32 s86, s74, s57
	v_lshl_add_u64 v[220:221], s[34:35], 0, v[134:135]
	s_mov_b32 m0, s86
	ds_read_b128 v[204:207], v154
	ds_read_b128 v[208:211], v154 offset:1024
	ds_read_b128 v[212:215], v154 offset:2048
	ds_read_b128 v[216:219], v154 offset:3072
	global_load_lds_dwordx4 v[220:221], off
	v_lshl_add_u64 v[222:223], s[34:35], 0, v[130:131]
	s_add_i32 m0, s86, 0x2000
	s_nop 0
	global_load_lds_dwordx4 v[222:223], off
	s_barrier
	s_waitcnt lgkmcnt(0)
	s_waitcnt lgkmcnt(0)
	v_mfma_f32_16x16x32_bf16 v[108:111], v[204:207], v[172:175], v[108:111]
	v_mfma_f32_16x16x32_bf16 v[104:107], v[212:215], v[172:175], v[104:107]
	v_mfma_f32_16x16x32_bf16 v[92:95], v[204:207], v[180:183], v[92:95]
	v_mfma_f32_16x16x32_bf16 v[88:91], v[212:215], v[180:183], v[88:91]
	v_mfma_f32_16x16x32_bf16 v[76:79], v[204:207], v[188:191], v[76:79]
	v_mfma_f32_16x16x32_bf16 v[72:75], v[212:215], v[188:191], v[72:75]
	v_mfma_f32_16x16x32_bf16 v[68:71], v[204:207], v[196:199], v[68:71]
	v_mfma_f32_16x16x32_bf16 v[64:67], v[212:215], v[196:199], v[64:67]
	v_mfma_f32_16x16x32_bf16 v[108:111], v[208:211], v[176:179], v[108:111]
	v_mfma_f32_16x16x32_bf16 v[104:107], v[216:219], v[176:179], v[104:107]
	v_mfma_f32_16x16x32_bf16 v[92:95], v[208:211], v[184:187], v[92:95]
	v_mfma_f32_16x16x32_bf16 v[88:91], v[216:219], v[184:187], v[88:91]
	v_mfma_f32_16x16x32_bf16 v[76:79], v[208:211], v[192:195], v[76:79]
	v_mfma_f32_16x16x32_bf16 v[72:75], v[216:219], v[192:195], v[72:75]
	v_mfma_f32_16x16x32_bf16 v[68:71], v[208:211], v[200:203], v[68:71]
	v_mfma_f32_16x16x32_bf16 v[64:67], v[216:219], v[200:203], v[64:67]
	s_mov_b32 m0, s17
	v_lshl_add_u64 v[224:225], s[54:55], 0, v[136:137]
	s_barrier
	ds_read_b128 v[172:175], v153 offset:16384
	ds_read_b128 v[176:179], v153 offset:17408
	ds_read_b128 v[180:183], v153 offset:18432
	ds_read_b128 v[184:187], v153 offset:19456
	ds_read_b128 v[188:191], v153 offset:20480
	ds_read_b128 v[192:195], v153 offset:21504
	ds_read_b128 v[196:199], v153 offset:22528
	ds_read_b128 v[200:203], v153 offset:23552
	global_load_lds_dwordx4 v[224:225], off
	v_lshl_add_u64 v[226:227], s[54:55], 0, v[132:133]
	s_mov_b32 m0, s61
	s_nop 0
	global_load_lds_dwordx4 v[226:227], off
	s_barrier
	s_waitcnt lgkmcnt(0)
	s_waitcnt lgkmcnt(0)
	v_mfma_f32_16x16x32_bf16 v[60:63], v[156:159], v[172:175], v[60:63]
	v_mfma_f32_16x16x32_bf16 v[56:59], v[164:167], v[172:175], v[56:59]
	v_mfma_f32_16x16x32_bf16 v[52:55], v[156:159], v[180:183], v[52:55]
	v_mfma_f32_16x16x32_bf16 v[48:51], v[164:167], v[180:183], v[48:51]
	v_mfma_f32_16x16x32_bf16 v[36:39], v[156:159], v[188:191], v[36:39]
	v_mfma_f32_16x16x32_bf16 v[32:35], v[164:167], v[188:191], v[32:35]
	v_mfma_f32_16x16x32_bf16 v[20:23], v[156:159], v[196:199], v[20:23]
	v_mfma_f32_16x16x32_bf16 v[16:19], v[164:167], v[196:199], v[16:19]
	v_mfma_f32_16x16x32_bf16 v[60:63], v[160:163], v[176:179], v[60:63]
	v_mfma_f32_16x16x32_bf16 v[56:59], v[168:171], v[176:179], v[56:59]
	v_mfma_f32_16x16x32_bf16 v[52:55], v[160:163], v[184:187], v[52:55]
	v_mfma_f32_16x16x32_bf16 v[48:51], v[168:171], v[184:187], v[48:51]
	v_mfma_f32_16x16x32_bf16 v[36:39], v[160:163], v[192:195], v[36:39]
	v_mfma_f32_16x16x32_bf16 v[32:35], v[168:171], v[192:195], v[32:35]
	v_mfma_f32_16x16x32_bf16 v[20:23], v[160:163], v[200:203], v[20:23]
	v_mfma_f32_16x16x32_bf16 v[16:19], v[168:171], v[200:203], v[16:19]
	s_barrier
	s_add_u32 s86, s34, 0x100000
	s_addc_u32 s87, s35, 0
	s_add_i32 s88, s75, s57
	v_lshl_add_u64 v[156:157], s[86:87], 0, v[134:135]
	s_mov_b32 m0, s88
	s_nop 0
	global_load_lds_dwordx4 v[156:157], off
	v_lshl_add_u64 v[156:157], s[86:87], 0, v[130:131]
	s_add_i32 m0, s88, 0x2000
	s_nop 0
	global_load_lds_dwordx4 v[156:157], off
	s_waitcnt vmcnt(6)
	s_barrier
	v_mfma_f32_16x16x32_bf16 v[44:47], v[204:207], v[172:175], v[44:47]
	v_mfma_f32_16x16x32_bf16 v[40:43], v[212:215], v[172:175], v[40:43]
	v_mfma_f32_16x16x32_bf16 v[28:31], v[204:207], v[180:183], v[28:31]
	v_mfma_f32_16x16x32_bf16 v[24:27], v[212:215], v[180:183], v[24:27]
	v_mfma_f32_16x16x32_bf16 v[12:15], v[204:207], v[188:191], v[12:15]
	v_mfma_f32_16x16x32_bf16 v[8:11], v[212:215], v[188:191], v[8:11]
	v_mfma_f32_16x16x32_bf16 v[4:7], v[204:207], v[196:199], v[4:7]
	v_mfma_f32_16x16x32_bf16 v[0:3], v[212:215], v[196:199], v[0:3]
	v_mfma_f32_16x16x32_bf16 v[44:47], v[208:211], v[176:179], v[44:47]
	v_mfma_f32_16x16x32_bf16 v[40:43], v[216:219], v[176:179], v[40:43]
	v_mfma_f32_16x16x32_bf16 v[28:31], v[208:211], v[184:187], v[28:31]
	v_mfma_f32_16x16x32_bf16 v[24:27], v[216:219], v[184:187], v[24:27]
	v_mfma_f32_16x16x32_bf16 v[12:15], v[208:211], v[192:195], v[12:15]
	v_mfma_f32_16x16x32_bf16 v[8:11], v[216:219], v[192:195], v[8:11]
	v_mfma_f32_16x16x32_bf16 v[4:7], v[208:211], v[200:203], v[4:7]
	v_mfma_f32_16x16x32_bf16 v[0:3], v[216:219], v[200:203], v[0:3]
	s_add_i32 s86, 0, 0x18000
	v_add_u32_e32 v155, s86, v150
	s_barrier
	ds_read_b128 v[156:159], v155
	ds_read_b128 v[160:163], v155 offset:1024
	ds_read_b128 v[164:167], v155 offset:2048
	ds_read_b128 v[168:171], v155 offset:3072
	s_add_u32 s54, s54, 0x100000
	s_addc_u32 s55, s55, 0
	s_mov_b32 m0, s62
	v_lshl_add_u64 v[204:205], s[54:55], 0, v[136:137]
	ds_read_b128 v[172:175], v153 offset:32768
	ds_read_b128 v[176:179], v153 offset:33792
	ds_read_b128 v[180:183], v153 offset:34816
	ds_read_b128 v[184:187], v153 offset:35840
	ds_read_b128 v[188:191], v153 offset:36864
	ds_read_b128 v[192:195], v153 offset:37888
	ds_read_b128 v[196:199], v153 offset:38912
	ds_read_b128 v[200:203], v153 offset:39936
	global_load_lds_dwordx4 v[204:205], off
	v_lshl_add_u64 v[204:205], s[54:55], 0, v[132:133]
	s_mov_b32 m0, s63
	s_nop 0
	global_load_lds_dwordx4 v[204:205], off
	s_waitcnt lgkmcnt(8)
	s_barrier
	s_waitcnt lgkmcnt(0)
	s_waitcnt lgkmcnt(0)
	v_mfma_f32_16x16x32_bf16 v[124:127], v[156:159], v[172:175], v[124:127]
	v_mfma_f32_16x16x32_bf16 v[120:123], v[164:167], v[172:175], v[120:123]
	v_mfma_f32_16x16x32_bf16 v[116:119], v[156:159], v[180:183], v[116:119]
	v_mfma_f32_16x16x32_bf16 v[112:115], v[164:167], v[180:183], v[112:115]
	v_mfma_f32_16x16x32_bf16 v[100:103], v[156:159], v[188:191], v[100:103]
	v_mfma_f32_16x16x32_bf16 v[96:99], v[164:167], v[188:191], v[96:99]
	v_mfma_f32_16x16x32_bf16 v[84:87], v[156:159], v[196:199], v[84:87]
	v_mfma_f32_16x16x32_bf16 v[80:83], v[164:167], v[196:199], v[80:83]
	v_mfma_f32_16x16x32_bf16 v[124:127], v[160:163], v[176:179], v[124:127]
	v_mfma_f32_16x16x32_bf16 v[120:123], v[168:171], v[176:179], v[120:123]
	v_mfma_f32_16x16x32_bf16 v[116:119], v[160:163], v[184:187], v[116:119]
	v_mfma_f32_16x16x32_bf16 v[112:115], v[168:171], v[184:187], v[112:115]
	v_mfma_f32_16x16x32_bf16 v[100:103], v[160:163], v[192:195], v[100:103]
	v_mfma_f32_16x16x32_bf16 v[96:99], v[168:171], v[192:195], v[96:99]
	v_mfma_f32_16x16x32_bf16 v[84:87], v[160:163], v[200:203], v[84:87]
	v_mfma_f32_16x16x32_bf16 v[80:83], v[168:171], v[200:203], v[80:83]
	s_barrier
	s_add_i32 s54, 0, 0x1c000
	s_add_i32 s55, s86, s57
	v_add_u32_e32 v155, s54, v150
	v_lshl_add_u64 v[220:221], v[220:221], 0, s[8:9]
	s_mov_b32 m0, s55
	ds_read_b128 v[204:207], v155
	ds_read_b128 v[208:211], v155 offset:1024
	ds_read_b128 v[212:215], v155 offset:2048
	ds_read_b128 v[216:219], v155 offset:3072
	global_load_lds_dwordx4 v[220:221], off
	v_lshl_add_u64 v[220:221], v[222:223], 0, s[8:9]
	s_add_i32 m0, s55, 0x2000
	s_nop 0
	global_load_lds_dwordx4 v[220:221], off
	s_barrier
	s_waitcnt lgkmcnt(0)
	s_waitcnt lgkmcnt(0)
	v_mfma_f32_16x16x32_bf16 v[108:111], v[204:207], v[172:175], v[108:111]
	v_mfma_f32_16x16x32_bf16 v[104:107], v[212:215], v[172:175], v[104:107]
	v_mfma_f32_16x16x32_bf16 v[92:95], v[204:207], v[180:183], v[92:95]
	v_mfma_f32_16x16x32_bf16 v[88:91], v[212:215], v[180:183], v[88:91]
	v_mfma_f32_16x16x32_bf16 v[76:79], v[204:207], v[188:191], v[76:79]
	v_mfma_f32_16x16x32_bf16 v[72:75], v[212:215], v[188:191], v[72:75]
	v_mfma_f32_16x16x32_bf16 v[68:71], v[204:207], v[196:199], v[68:71]
	v_mfma_f32_16x16x32_bf16 v[64:67], v[212:215], v[196:199], v[64:67]
	v_mfma_f32_16x16x32_bf16 v[108:111], v[208:211], v[176:179], v[108:111]
	v_mfma_f32_16x16x32_bf16 v[104:107], v[216:219], v[176:179], v[104:107]
	v_mfma_f32_16x16x32_bf16 v[92:95], v[208:211], v[184:187], v[92:95]
	v_mfma_f32_16x16x32_bf16 v[88:91], v[216:219], v[184:187], v[88:91]
	v_mfma_f32_16x16x32_bf16 v[76:79], v[208:211], v[192:195], v[76:79]
	v_mfma_f32_16x16x32_bf16 v[72:75], v[216:219], v[192:195], v[72:75]
	v_mfma_f32_16x16x32_bf16 v[68:71], v[208:211], v[200:203], v[68:71]
	v_mfma_f32_16x16x32_bf16 v[64:67], v[216:219], v[200:203], v[64:67]
	s_mov_b32 m0, s71
	v_lshl_add_u64 v[220:221], v[224:225], 0, s[8:9]
	s_barrier
	ds_read_b128 v[172:175], v153 offset:49152
	ds_read_b128 v[176:179], v153 offset:50176
	ds_read_b128 v[180:183], v153 offset:51200
	ds_read_b128 v[184:187], v153 offset:52224
	ds_read_b128 v[188:191], v153 offset:53248
	ds_read_b128 v[192:195], v153 offset:54272
	ds_read_b128 v[196:199], v153 offset:55296
	ds_read_b128 v[200:203], v153 offset:56320
	global_load_lds_dwordx4 v[220:221], off
	v_lshl_add_u64 v[220:221], v[226:227], 0, s[8:9]
	s_mov_b32 m0, s72
	s_nop 0
	global_load_lds_dwordx4 v[220:221], off
	s_barrier
	s_waitcnt lgkmcnt(0)
	s_waitcnt lgkmcnt(0)
	v_mfma_f32_16x16x32_bf16 v[60:63], v[156:159], v[172:175], v[60:63]
	v_mfma_f32_16x16x32_bf16 v[56:59], v[164:167], v[172:175], v[56:59]
	v_mfma_f32_16x16x32_bf16 v[52:55], v[156:159], v[180:183], v[52:55]
	v_mfma_f32_16x16x32_bf16 v[48:51], v[164:167], v[180:183], v[48:51]
	v_mfma_f32_16x16x32_bf16 v[36:39], v[156:159], v[188:191], v[36:39]
	v_mfma_f32_16x16x32_bf16 v[32:35], v[164:167], v[188:191], v[32:35]
	v_mfma_f32_16x16x32_bf16 v[20:23], v[156:159], v[196:199], v[20:23]
	v_mfma_f32_16x16x32_bf16 v[16:19], v[164:167], v[196:199], v[16:19]
	v_mfma_f32_16x16x32_bf16 v[60:63], v[160:163], v[176:179], v[60:63]
	v_mfma_f32_16x16x32_bf16 v[56:59], v[168:171], v[176:179], v[56:59]
	v_mfma_f32_16x16x32_bf16 v[52:55], v[160:163], v[184:187], v[52:55]
	v_mfma_f32_16x16x32_bf16 v[48:51], v[168:171], v[184:187], v[48:51]
	v_mfma_f32_16x16x32_bf16 v[36:39], v[160:163], v[192:195], v[36:39]
	v_mfma_f32_16x16x32_bf16 v[32:35], v[168:171], v[192:195], v[32:35]
	v_mfma_f32_16x16x32_bf16 v[20:23], v[160:163], v[200:203], v[20:23]
	v_mfma_f32_16x16x32_bf16 v[16:19], v[168:171], v[200:203], v[16:19]
	s_barrier
	s_add_u32 s34, s34, 0x100080
	s_addc_u32 s35, s35, 0
	s_add_i32 s54, s54, s57
	v_lshl_add_u64 v[156:157], s[34:35], 0, v[134:135]
	s_mov_b32 m0, s54
	s_nop 0
	global_load_lds_dwordx4 v[156:157], off
	v_lshl_add_u64 v[156:157], s[34:35], 0, v[130:131]
	s_add_i32 m0, s54, 0x2000
	s_nop 0
	global_load_lds_dwordx4 v[156:157], off
	s_waitcnt vmcnt(6)
	s_barrier
	v_mfma_f32_16x16x32_bf16 v[44:47], v[204:207], v[172:175], v[44:47]
	v_mfma_f32_16x16x32_bf16 v[40:43], v[212:215], v[172:175], v[40:43]
	v_mfma_f32_16x16x32_bf16 v[28:31], v[204:207], v[180:183], v[28:31]
	v_mfma_f32_16x16x32_bf16 v[24:27], v[212:215], v[180:183], v[24:27]
	v_mfma_f32_16x16x32_bf16 v[12:15], v[204:207], v[188:191], v[12:15]
	v_mfma_f32_16x16x32_bf16 v[8:11], v[212:215], v[188:191], v[8:11]
	v_mfma_f32_16x16x32_bf16 v[4:7], v[204:207], v[196:199], v[4:7]
	v_mfma_f32_16x16x32_bf16 v[0:3], v[212:215], v[196:199], v[0:3]
	v_mfma_f32_16x16x32_bf16 v[44:47], v[208:211], v[176:179], v[44:47]
	v_mfma_f32_16x16x32_bf16 v[40:43], v[216:219], v[176:179], v[40:43]
	v_mfma_f32_16x16x32_bf16 v[28:31], v[208:211], v[184:187], v[28:31]
	v_mfma_f32_16x16x32_bf16 v[24:27], v[216:219], v[184:187], v[24:27]
	v_mfma_f32_16x16x32_bf16 v[12:15], v[208:211], v[192:195], v[12:15]
	v_mfma_f32_16x16x32_bf16 v[8:11], v[216:219], v[192:195], v[8:11]
	v_mfma_f32_16x16x32_bf16 v[4:7], v[208:211], v[200:203], v[4:7]
	v_mfma_f32_16x16x32_bf16 v[0:3], v[216:219], v[200:203], v[0:3]
	s_add_i32 s85, s85, 2
	s_add_u32 s30, s30, 0x100
	s_addc_u32 s31, s31, 0
	s_add_u32 s83, s83, 0x100
	s_addc_u32 s84, s84, 0
	s_cmp_gt_u32 s85, 61
	s_barrier
	s_cbranch_scc0 .LBB0_776
	v_lshl_add_u32 v156, s16, 8, v149
	v_lshl_or_b32 v158, s80, 8, v151
	v_ashrrev_i32_e32 v157, 31, v156
	v_lshlrev_b64 v[160:161], 11, v[156:157]
	v_ashrrev_i32_e32 v159, 31, v158
	v_lshl_add_u64 v[160:161], s[44:45], 0, v[160:161]
	v_cvt_pk_bf16_f32 v124, v124, v125
	v_cvt_pk_bf16_f32 v125, v126, v127
	v_cvt_pk_bf16_f32 v126, v120, v121
	v_lshlrev_b64 v[120:121], 1, v[158:159]
	v_cvt_pk_bf16_f32 v127, v122, v123
	v_lshl_add_u64 v[122:123], v[160:161], 0, v[120:121]
	v_cvt_pk_bf16_f32 v108, v108, v109
	v_cvt_pk_bf16_f32 v109, v110, v111
	v_cvt_pk_bf16_f32 v110, v104, v105
	v_or_b32_e32 v104, 16, v156
	v_cvt_pk_bf16_f32 v60, v60, v61
	v_cvt_pk_bf16_f32 v61, v62, v63
	v_cvt_pk_bf16_f32 v63, v58, v59
	s_mov_b64 s[30:31], 0x40000
	v_add_co_u32_e32 v58, vcc, s76, v122
	v_ashrrev_i32_e32 v105, 31, v104
	v_cvt_pk_bf16_f32 v62, v56, v57
	v_lshl_add_u64 v[56:57], v[122:123], 0, s[30:31]
	v_addc_co_u32_e32 v59, vcc, 0, v123, vcc
	v_cvt_pk_bf16_f32 v44, v44, v45
	v_cvt_pk_bf16_f32 v45, v46, v47
	v_cvt_pk_bf16_f32 v46, v40, v41
	v_cvt_pk_bf16_f32 v47, v42, v43
	v_cvt_pk_bf16_f32 v111, v106, v107
	v_lshlrev_b64 v[104:105], 11, v[104:105]
	v_cvt_pk_bf16_f32 v92, v92, v93
	v_cvt_pk_bf16_f32 v93, v94, v95
	v_cvt_pk_bf16_f32 v94, v88, v89
	v_or_b32_e32 v88, 32, v156
	global_store_dwordx4 v[56:57], v[44:47], off offset:256
	global_store_dwordx4 v[122:123], v[108:111], off offset:256
	v_ashrrev_i32_e32 v89, 31, v88
	v_add_co_u32_e32 v46, vcc, s77, v122
	v_lshl_add_u64 v[108:109], s[44:45], 0, v[104:105]
	v_lshl_add_u64 v[44:45], v[122:123], 0, s[10:11]
	v_addc_co_u32_e32 v47, vcc, 0, v123, vcc
	v_cvt_pk_bf16_f32 v28, v28, v29
	v_cvt_pk_bf16_f32 v29, v30, v31
	v_cvt_pk_bf16_f32 v30, v24, v25
	v_cvt_pk_bf16_f32 v31, v26, v27
	v_lshl_add_u64 v[108:109], v[108:109], 0, v[120:121]
	v_cvt_pk_bf16_f32 v95, v90, v91
	v_lshlrev_b64 v[88:89], 11, v[88:89]
	v_cvt_pk_bf16_f32 v76, v76, v77
	v_cvt_pk_bf16_f32 v77, v78, v79
	v_cvt_pk_bf16_f32 v78, v72, v73
	v_or_b32_e32 v72, 48, v156
	global_store_dwordx4 v[44:45], v[28:31], off offset:256
	global_store_dwordx4 v[108:109], v[92:95], off offset:256
	v_ashrrev_i32_e32 v73, 31, v72
	v_add_co_u32_e32 v30, vcc, s78, v122
	v_lshl_add_u64 v[92:93], s[44:45], 0, v[88:89]
	v_lshl_add_u64 v[28:29], v[122:123], 0, s[12:13]
	v_addc_co_u32_e32 v31, vcc, 0, v123, vcc
	v_cvt_pk_bf16_f32 v12, v12, v13
	v_cvt_pk_bf16_f32 v13, v14, v15
	v_cvt_pk_bf16_f32 v14, v8, v9
	v_cvt_pk_bf16_f32 v15, v10, v11
	v_lshl_add_u64 v[92:93], v[92:93], 0, v[120:121]
	v_cvt_pk_bf16_f32 v79, v74, v75
	v_lshlrev_b64 v[72:73], 11, v[72:73]
	global_store_dwordx4 v[28:29], v[12:15], off offset:256
	global_store_dwordx4 v[92:93], v[76:79], off offset:256
	v_cvt_pk_bf16_f32 v104, v116, v117
	v_add_co_u32_e32 v14, vcc, s79, v122
	v_lshl_add_u64 v[76:77], s[44:45], 0, v[72:73]
	s_nop 0
	v_addc_co_u32_e32 v15, vcc, 0, v123, vcc
	v_cvt_pk_bf16_f32 v105, v118, v119
	v_cvt_pk_bf16_f32 v106, v112, v113
	v_cvt_pk_bf16_f32 v107, v114, v115
	v_cvt_pk_bf16_f32 v88, v100, v101
	v_cvt_pk_bf16_f32 v89, v102, v103
	v_cvt_pk_bf16_f32 v90, v96, v97
	v_cvt_pk_bf16_f32 v91, v98, v99
	v_cvt_pk_bf16_f32 v72, v84, v85
	v_cvt_pk_bf16_f32 v73, v86, v87
	v_cvt_pk_bf16_f32 v74, v80, v81
	v_cvt_pk_bf16_f32 v75, v82, v83
	v_lshl_add_u64 v[76:77], v[76:77], 0, v[120:121]
	v_cvt_pk_bf16_f32 v68, v68, v69
	v_cvt_pk_bf16_f32 v69, v70, v71
	v_cvt_pk_bf16_f32 v70, v64, v65
	v_cvt_pk_bf16_f32 v71, v66, v67
	v_cvt_pk_bf16_f32 v40, v52, v53
	v_cvt_pk_bf16_f32 v41, v54, v55
	v_cvt_pk_bf16_f32 v42, v48, v49
	v_cvt_pk_bf16_f32 v43, v50, v51
	v_cvt_pk_bf16_f32 v24, v36, v37
	v_cvt_pk_bf16_f32 v25, v38, v39
	v_cvt_pk_bf16_f32 v26, v32, v33
	v_cvt_pk_bf16_f32 v27, v34, v35
	v_cvt_pk_bf16_f32 v8, v20, v21
	v_cvt_pk_bf16_f32 v9, v22, v23
	v_cvt_pk_bf16_f32 v10, v16, v17
	v_cvt_pk_bf16_f32 v11, v18, v19
	v_lshl_add_u64 v[12:13], v[122:123], 0, s[14:15]
	v_cvt_pk_bf16_f32 v4, v4, v5
	v_cvt_pk_bf16_f32 v5, v6, v7
	v_cvt_pk_bf16_f32 v6, v0, v1
	v_cvt_pk_bf16_f32 v7, v2, v3
	s_and_b64 vcc, exec, s[4:5]
	s_mov_b32 s80, s18
	s_mov_b32 s16, s20
	s_mov_b64 s[34:35], s[28:29]
	s_mov_b64 s[30:31], s[26:27]
	global_store_dwordx4 v[122:123], v[124:127], off
	global_store_dwordx4 v[108:109], v[104:107], off
	global_store_dwordx4 v[92:93], v[88:91], off
	global_store_dwordx4 v[76:77], v[72:75], off
	global_store_dwordx4 v[76:77], v[68:71], off offset:256
	global_store_dwordx4 v[58:59], v[60:63], off
	global_store_dwordx4 v[46:47], v[40:43], off
	global_store_dwordx4 v[30:31], v[24:27], off
	global_store_dwordx4 v[14:15], v[8:11], off
	global_store_dwordx4 v[12:13], v[4:7], off offset:256
	s_cbranch_vccz .LBB0_773
	s_waitcnt vmcnt(0)
	s_cmpk_gt_u32 s56, 0xff
	s_cbranch_scc1 .LBB0_780
	s_barrier

.LBB0_912:
	ds_read_b128 v[156:159], v152
	ds_read_b128 v[160:163], v152 offset:1024
	ds_read_b128 v[164:167], v152 offset:2048
	ds_read_b128 v[168:171], v152 offset:3072
	s_add_u32 s54, s34, 0xfffc0080
	s_addc_u32 s55, s35, -1
	s_cmp_eq_u32 s87, 12
	s_cselect_b32 s57, s27, s55
	s_cselect_b32 s56, s83, s54
	s_cselect_b32 s55, s21, s86
	s_cselect_b32 s54, s84, s85
	v_lshl_add_u64 v[204:205], s[34:35], 0, v[138:139]
	s_add_i32 m0, s19, 0xc000
	ds_read_b128 v[172:175], v153
	ds_read_b128 v[176:179], v153 offset:1024
	ds_read_b128 v[180:183], v153 offset:2048
	ds_read_b128 v[184:187], v153 offset:3072
	ds_read_b128 v[188:191], v153 offset:4096
	ds_read_b128 v[192:195], v153 offset:5120
	ds_read_b128 v[196:199], v153 offset:6144
	ds_read_b128 v[200:203], v153 offset:7168
	global_load_lds_dwordx4 v[204:205], off
	v_lshl_add_u64 v[204:205], s[34:35], 0, v[140:141]
	s_add_i32 m0, s19, 0xe000
	s_nop 0
	global_load_lds_dwordx4 v[204:205], off
	s_waitcnt lgkmcnt(8)
	s_barrier
	s_waitcnt lgkmcnt(0)
	s_waitcnt lgkmcnt(0)
	v_mfma_f32_16x16x32_bf16 v[124:127], v[156:159], v[172:175], v[124:127]
	v_mfma_f32_16x16x32_bf16 v[120:123], v[164:167], v[172:175], v[120:123]
	v_mfma_f32_16x16x32_bf16 v[116:119], v[156:159], v[180:183], v[116:119]
	v_mfma_f32_16x16x32_bf16 v[112:115], v[164:167], v[180:183], v[112:115]
	v_mfma_f32_16x16x32_bf16 v[100:103], v[156:159], v[188:191], v[100:103]
	v_mfma_f32_16x16x32_bf16 v[96:99], v[164:167], v[188:191], v[96:99]
	v_mfma_f32_16x16x32_bf16 v[84:87], v[156:159], v[196:199], v[84:87]
	v_mfma_f32_16x16x32_bf16 v[80:83], v[164:167], v[196:199], v[80:83]
	v_mfma_f32_16x16x32_bf16 v[124:127], v[160:163], v[176:179], v[124:127]
	v_mfma_f32_16x16x32_bf16 v[120:123], v[168:171], v[176:179], v[120:123]
	v_mfma_f32_16x16x32_bf16 v[116:119], v[160:163], v[184:187], v[116:119]
	v_mfma_f32_16x16x32_bf16 v[112:115], v[168:171], v[184:187], v[112:115]
	v_mfma_f32_16x16x32_bf16 v[100:103], v[160:163], v[192:195], v[100:103]
	v_mfma_f32_16x16x32_bf16 v[96:99], v[168:171], v[192:195], v[96:99]
	v_mfma_f32_16x16x32_bf16 v[84:87], v[160:163], v[200:203], v[84:87]
	v_mfma_f32_16x16x32_bf16 v[80:83], v[168:171], v[200:203], v[80:83]
	s_barrier
	s_add_i32 s88, s76, s61
	v_lshl_add_u64 v[220:221], s[54:55], 0, v[134:135]
	s_mov_b32 m0, s88
	ds_read_b128 v[204:207], v154
	ds_read_b128 v[208:211], v154 offset:1024
	ds_read_b128 v[212:215], v154 offset:2048
	ds_read_b128 v[216:219], v154 offset:3072
	global_load_lds_dwordx4 v[220:221], off
	v_lshl_add_u64 v[222:223], s[54:55], 0, v[130:131]
	s_add_i32 m0, s88, 0x2000
	s_nop 0
	global_load_lds_dwordx4 v[222:223], off
	s_barrier
	s_waitcnt lgkmcnt(0)
	s_waitcnt lgkmcnt(0)
	v_mfma_f32_16x16x32_bf16 v[108:111], v[204:207], v[172:175], v[108:111]
	v_mfma_f32_16x16x32_bf16 v[104:107], v[212:215], v[172:175], v[104:107]
	v_mfma_f32_16x16x32_bf16 v[92:95], v[204:207], v[180:183], v[92:95]
	v_mfma_f32_16x16x32_bf16 v[88:91], v[212:215], v[180:183], v[88:91]
	v_mfma_f32_16x16x32_bf16 v[76:79], v[204:207], v[188:191], v[76:79]
	v_mfma_f32_16x16x32_bf16 v[72:75], v[212:215], v[188:191], v[72:75]
	v_mfma_f32_16x16x32_bf16 v[68:71], v[204:207], v[196:199], v[68:71]
	v_mfma_f32_16x16x32_bf16 v[64:67], v[212:215], v[196:199], v[64:67]
	v_mfma_f32_16x16x32_bf16 v[108:111], v[208:211], v[176:179], v[108:111]
	v_mfma_f32_16x16x32_bf16 v[104:107], v[216:219], v[176:179], v[104:107]
	v_mfma_f32_16x16x32_bf16 v[92:95], v[208:211], v[184:187], v[92:95]
	v_mfma_f32_16x16x32_bf16 v[88:91], v[216:219], v[184:187], v[88:91]
	v_mfma_f32_16x16x32_bf16 v[76:79], v[208:211], v[192:195], v[76:79]
	v_mfma_f32_16x16x32_bf16 v[72:75], v[216:219], v[192:195], v[72:75]
	v_mfma_f32_16x16x32_bf16 v[68:71], v[208:211], v[200:203], v[68:71]
	v_mfma_f32_16x16x32_bf16 v[64:67], v[216:219], v[200:203], v[64:67]
	s_mov_b32 m0, s19
	v_lshl_add_u64 v[224:225], s[56:57], 0, v[136:137]
	s_barrier
	ds_read_b128 v[172:175], v153 offset:16384
	ds_read_b128 v[176:179], v153 offset:17408
	ds_read_b128 v[180:183], v153 offset:18432
	ds_read_b128 v[184:187], v153 offset:19456
	ds_read_b128 v[188:191], v153 offset:20480
	ds_read_b128 v[192:195], v153 offset:21504
	ds_read_b128 v[196:199], v153 offset:22528
	ds_read_b128 v[200:203], v153 offset:23552
	global_load_lds_dwordx4 v[224:225], off
	v_lshl_add_u64 v[226:227], s[56:57], 0, v[132:133]
	s_mov_b32 m0, s63
	s_nop 0
	global_load_lds_dwordx4 v[226:227], off
	s_barrier
	s_waitcnt lgkmcnt(0)
	s_waitcnt lgkmcnt(0)
	v_mfma_f32_16x16x32_bf16 v[60:63], v[156:159], v[172:175], v[60:63]
	v_mfma_f32_16x16x32_bf16 v[56:59], v[164:167], v[172:175], v[56:59]
	v_mfma_f32_16x16x32_bf16 v[52:55], v[156:159], v[180:183], v[52:55]
	v_mfma_f32_16x16x32_bf16 v[48:51], v[164:167], v[180:183], v[48:51]
	v_mfma_f32_16x16x32_bf16 v[36:39], v[156:159], v[188:191], v[36:39]
	v_mfma_f32_16x16x32_bf16 v[32:35], v[164:167], v[188:191], v[32:35]
	v_mfma_f32_16x16x32_bf16 v[20:23], v[156:159], v[196:199], v[20:23]
	v_mfma_f32_16x16x32_bf16 v[16:19], v[164:167], v[196:199], v[16:19]
	v_mfma_f32_16x16x32_bf16 v[60:63], v[160:163], v[176:179], v[60:63]
	v_mfma_f32_16x16x32_bf16 v[56:59], v[168:171], v[176:179], v[56:59]
	v_mfma_f32_16x16x32_bf16 v[52:55], v[160:163], v[184:187], v[52:55]
	v_mfma_f32_16x16x32_bf16 v[48:51], v[168:171], v[184:187], v[48:51]
	v_mfma_f32_16x16x32_bf16 v[36:39], v[160:163], v[192:195], v[36:39]
	v_mfma_f32_16x16x32_bf16 v[32:35], v[168:171], v[192:195], v[32:35]
	v_mfma_f32_16x16x32_bf16 v[20:23], v[160:163], v[200:203], v[20:23]
	v_mfma_f32_16x16x32_bf16 v[16:19], v[168:171], v[200:203], v[16:19]
	s_barrier
	s_add_u32 s88, s54, 0x40000
	s_addc_u32 s89, s55, 0
	s_add_i32 s90, s77, s61
	v_lshl_add_u64 v[156:157], s[88:89], 0, v[134:135]
	s_mov_b32 m0, s90
	s_nop 0
	global_load_lds_dwordx4 v[156:157], off
	v_lshl_add_u64 v[156:157], s[88:89], 0, v[130:131]
	s_add_i32 m0, s90, 0x2000
	s_nop 0
	global_load_lds_dwordx4 v[156:157], off
	s_waitcnt vmcnt(6)
	s_barrier
	v_mfma_f32_16x16x32_bf16 v[44:47], v[204:207], v[172:175], v[44:47]
	v_mfma_f32_16x16x32_bf16 v[40:43], v[212:215], v[172:175], v[40:43]
	v_mfma_f32_16x16x32_bf16 v[28:31], v[204:207], v[180:183], v[28:31]
	v_mfma_f32_16x16x32_bf16 v[24:27], v[212:215], v[180:183], v[24:27]
	v_mfma_f32_16x16x32_bf16 v[12:15], v[204:207], v[188:191], v[12:15]
	v_mfma_f32_16x16x32_bf16 v[8:11], v[212:215], v[188:191], v[8:11]
	v_mfma_f32_16x16x32_bf16 v[4:7], v[204:207], v[196:199], v[4:7]
	v_mfma_f32_16x16x32_bf16 v[0:3], v[212:215], v[196:199], v[0:3]
	v_mfma_f32_16x16x32_bf16 v[44:47], v[208:211], v[176:179], v[44:47]
	v_mfma_f32_16x16x32_bf16 v[40:43], v[216:219], v[176:179], v[40:43]
	v_mfma_f32_16x16x32_bf16 v[28:31], v[208:211], v[184:187], v[28:31]
	v_mfma_f32_16x16x32_bf16 v[24:27], v[216:219], v[184:187], v[24:27]
	v_mfma_f32_16x16x32_bf16 v[12:15], v[208:211], v[192:195], v[12:15]
	v_mfma_f32_16x16x32_bf16 v[8:11], v[216:219], v[192:195], v[8:11]
	v_mfma_f32_16x16x32_bf16 v[4:7], v[208:211], v[200:203], v[4:7]
	v_mfma_f32_16x16x32_bf16 v[0:3], v[216:219], v[200:203], v[0:3]
	s_add_i32 s88, 0, 0x18000
	v_add_u32_e32 v155, s88, v150
	s_barrier
	ds_read_b128 v[156:159], v155
	ds_read_b128 v[160:163], v155 offset:1024
	ds_read_b128 v[164:167], v155 offset:2048
	ds_read_b128 v[168:171], v155 offset:3072
	s_add_u32 s56, s56, 0x40000
	s_addc_u32 s57, s57, 0
	s_mov_b32 m0, s70
	v_lshl_add_u64 v[204:205], s[56:57], 0, v[136:137]
	ds_read_b128 v[172:175], v153 offset:32768
	ds_read_b128 v[176:179], v153 offset:33792
	ds_read_b128 v[180:183], v153 offset:34816
	ds_read_b128 v[184:187], v153 offset:35840
	ds_read_b128 v[188:191], v153 offset:36864
	ds_read_b128 v[192:195], v153 offset:37888
	ds_read_b128 v[196:199], v153 offset:38912
	ds_read_b128 v[200:203], v153 offset:39936
	global_load_lds_dwordx4 v[204:205], off
	v_lshl_add_u64 v[204:205], s[56:57], 0, v[132:133]
	s_mov_b32 m0, s71
	s_nop 0
	global_load_lds_dwordx4 v[204:205], off
	s_waitcnt lgkmcnt(8)
	s_barrier
	s_waitcnt lgkmcnt(0)
	s_waitcnt lgkmcnt(0)
	v_mfma_f32_16x16x32_bf16 v[124:127], v[156:159], v[172:175], v[124:127]
	v_mfma_f32_16x16x32_bf16 v[120:123], v[164:167], v[172:175], v[120:123]
	v_mfma_f32_16x16x32_bf16 v[116:119], v[156:159], v[180:183], v[116:119]
	v_mfma_f32_16x16x32_bf16 v[112:115], v[164:167], v[180:183], v[112:115]
	v_mfma_f32_16x16x32_bf16 v[100:103], v[156:159], v[188:191], v[100:103]
	v_mfma_f32_16x16x32_bf16 v[96:99], v[164:167], v[188:191], v[96:99]
	v_mfma_f32_16x16x32_bf16 v[84:87], v[156:159], v[196:199], v[84:87]
	v_mfma_f32_16x16x32_bf16 v[80:83], v[164:167], v[196:199], v[80:83]
	v_mfma_f32_16x16x32_bf16 v[124:127], v[160:163], v[176:179], v[124:127]
	v_mfma_f32_16x16x32_bf16 v[120:123], v[168:171], v[176:179], v[120:123]
	v_mfma_f32_16x16x32_bf16 v[116:119], v[160:163], v[184:187], v[116:119]
	v_mfma_f32_16x16x32_bf16 v[112:115], v[168:171], v[184:187], v[112:115]
	v_mfma_f32_16x16x32_bf16 v[100:103], v[160:163], v[192:195], v[100:103]
	v_mfma_f32_16x16x32_bf16 v[96:99], v[168:171], v[192:195], v[96:99]
	v_mfma_f32_16x16x32_bf16 v[84:87], v[160:163], v[200:203], v[84:87]
	v_mfma_f32_16x16x32_bf16 v[80:83], v[168:171], v[200:203], v[80:83]
	s_barrier
	s_add_i32 s56, 0, 0x1c000
	s_add_i32 s57, s88, s61
	v_add_u32_e32 v155, s56, v150
	v_lshl_add_u64 v[220:221], v[220:221], 0, s[10:11]
	s_mov_b32 m0, s57
	ds_read_b128 v[204:207], v155
	ds_read_b128 v[208:211], v155 offset:1024
	ds_read_b128 v[212:215], v155 offset:2048
	ds_read_b128 v[216:219], v155 offset:3072
	global_load_lds_dwordx4 v[220:221], off
	v_lshl_add_u64 v[220:221], v[222:223], 0, s[10:11]
	s_add_i32 m0, s57, 0x2000
	s_nop 0
	global_load_lds_dwordx4 v[220:221], off
	s_barrier
	s_waitcnt lgkmcnt(0)
	s_waitcnt lgkmcnt(0)
	v_mfma_f32_16x16x32_bf16 v[108:111], v[204:207], v[172:175], v[108:111]
	v_mfma_f32_16x16x32_bf16 v[104:107], v[212:215], v[172:175], v[104:107]
	v_mfma_f32_16x16x32_bf16 v[92:95], v[204:207], v[180:183], v[92:95]
	v_mfma_f32_16x16x32_bf16 v[88:91], v[212:215], v[180:183], v[88:91]
	v_mfma_f32_16x16x32_bf16 v[76:79], v[204:207], v[188:191], v[76:79]
	v_mfma_f32_16x16x32_bf16 v[72:75], v[212:215], v[188:191], v[72:75]
	v_mfma_f32_16x16x32_bf16 v[68:71], v[204:207], v[196:199], v[68:71]
	v_mfma_f32_16x16x32_bf16 v[64:67], v[212:215], v[196:199], v[64:67]
	v_mfma_f32_16x16x32_bf16 v[108:111], v[208:211], v[176:179], v[108:111]
	v_mfma_f32_16x16x32_bf16 v[104:107], v[216:219], v[176:179], v[104:107]
	v_mfma_f32_16x16x32_bf16 v[92:95], v[208:211], v[184:187], v[92:95]
	v_mfma_f32_16x16x32_bf16 v[88:91], v[216:219], v[184:187], v[88:91]
	v_mfma_f32_16x16x32_bf16 v[76:79], v[208:211], v[192:195], v[76:79]
	v_mfma_f32_16x16x32_bf16 v[72:75], v[216:219], v[192:195], v[72:75]
	v_mfma_f32_16x16x32_bf16 v[68:71], v[208:211], v[200:203], v[68:71]
	v_mfma_f32_16x16x32_bf16 v[64:67], v[216:219], v[200:203], v[64:67]
	s_mov_b32 m0, s73
	v_lshl_add_u64 v[220:221], v[224:225], 0, s[10:11]
	s_barrier
	ds_read_b128 v[172:175], v153 offset:49152
	ds_read_b128 v[176:179], v153 offset:50176
	ds_read_b128 v[180:183], v153 offset:51200
	ds_read_b128 v[184:187], v153 offset:52224
	ds_read_b128 v[188:191], v153 offset:53248
	ds_read_b128 v[192:195], v153 offset:54272
	ds_read_b128 v[196:199], v153 offset:55296
	ds_read_b128 v[200:203], v153 offset:56320
	global_load_lds_dwordx4 v[220:221], off
	v_lshl_add_u64 v[220:221], v[226:227], 0, s[10:11]
	s_mov_b32 m0, s74
	s_nop 0
	global_load_lds_dwordx4 v[220:221], off
	s_barrier
	s_waitcnt lgkmcnt(0)
	s_waitcnt lgkmcnt(0)
	v_mfma_f32_16x16x32_bf16 v[60:63], v[156:159], v[172:175], v[60:63]
	v_mfma_f32_16x16x32_bf16 v[56:59], v[164:167], v[172:175], v[56:59]
	v_mfma_f32_16x16x32_bf16 v[52:55], v[156:159], v[180:183], v[52:55]
	v_mfma_f32_16x16x32_bf16 v[48:51], v[164:167], v[180:183], v[48:51]
	v_mfma_f32_16x16x32_bf16 v[36:39], v[156:159], v[188:191], v[36:39]
	v_mfma_f32_16x16x32_bf16 v[32:35], v[164:167], v[188:191], v[32:35]
	v_mfma_f32_16x16x32_bf16 v[20:23], v[156:159], v[196:199], v[20:23]
	v_mfma_f32_16x16x32_bf16 v[16:19], v[164:167], v[196:199], v[16:19]
	v_mfma_f32_16x16x32_bf16 v[60:63], v[160:163], v[176:179], v[60:63]
	v_mfma_f32_16x16x32_bf16 v[56:59], v[168:171], v[176:179], v[56:59]
	v_mfma_f32_16x16x32_bf16 v[52:55], v[160:163], v[184:187], v[52:55]
	v_mfma_f32_16x16x32_bf16 v[48:51], v[168:171], v[184:187], v[48:51]
	v_mfma_f32_16x16x32_bf16 v[36:39], v[160:163], v[192:195], v[36:39]
	v_mfma_f32_16x16x32_bf16 v[32:35], v[168:171], v[192:195], v[32:35]
	v_mfma_f32_16x16x32_bf16 v[20:23], v[160:163], v[200:203], v[20:23]
	v_mfma_f32_16x16x32_bf16 v[16:19], v[168:171], v[200:203], v[16:19]
	s_barrier
	s_add_u32 s54, s54, 0x40080
	s_addc_u32 s55, s55, 0
	s_add_i32 s56, s56, s61
	v_lshl_add_u64 v[156:157], s[54:55], 0, v[134:135]
	s_mov_b32 m0, s56
	s_nop 0
	global_load_lds_dwordx4 v[156:157], off
	v_lshl_add_u64 v[156:157], s[54:55], 0, v[130:131]
	s_add_i32 m0, s56, 0x2000
	s_nop 0
	global_load_lds_dwordx4 v[156:157], off
	s_waitcnt vmcnt(6)
	s_barrier
	v_mfma_f32_16x16x32_bf16 v[44:47], v[204:207], v[172:175], v[44:47]
	v_mfma_f32_16x16x32_bf16 v[40:43], v[212:215], v[172:175], v[40:43]
	v_mfma_f32_16x16x32_bf16 v[28:31], v[204:207], v[180:183], v[28:31]
	v_mfma_f32_16x16x32_bf16 v[24:27], v[212:215], v[180:183], v[24:27]
	v_mfma_f32_16x16x32_bf16 v[12:15], v[204:207], v[188:191], v[12:15]
	v_mfma_f32_16x16x32_bf16 v[8:11], v[212:215], v[188:191], v[8:11]
	v_mfma_f32_16x16x32_bf16 v[4:7], v[204:207], v[196:199], v[4:7]
	v_mfma_f32_16x16x32_bf16 v[0:3], v[212:215], v[196:199], v[0:3]
	v_mfma_f32_16x16x32_bf16 v[44:47], v[208:211], v[176:179], v[44:47]
	v_mfma_f32_16x16x32_bf16 v[40:43], v[216:219], v[176:179], v[40:43]
	v_mfma_f32_16x16x32_bf16 v[28:31], v[208:211], v[184:187], v[28:31]
	v_mfma_f32_16x16x32_bf16 v[24:27], v[216:219], v[184:187], v[24:27]
	v_mfma_f32_16x16x32_bf16 v[12:15], v[208:211], v[192:195], v[12:15]
	v_mfma_f32_16x16x32_bf16 v[8:11], v[216:219], v[192:195], v[8:11]
	v_mfma_f32_16x16x32_bf16 v[4:7], v[208:211], v[200:203], v[4:7]
	v_mfma_f32_16x16x32_bf16 v[0:3], v[216:219], v[200:203], v[0:3]
	s_add_i32 s87, s87, 2
	s_add_u32 s34, s34, 0x100
	s_addc_u32 s35, s35, 0
	s_add_u32 s85, s85, 0x100
	s_addc_u32 s86, s86, 0
	s_cmp_gt_u32 s87, 13
	s_barrier
	s_cbranch_scc0 .LBB0_912
	v_lshl_add_u32 v156, s18, 8, v149
	v_lshl_or_b32 v158, s82, 8, v151
	v_ashrrev_i32_e32 v157, 31, v156
	v_lshlrev_b64 v[160:161], 11, v[156:157]
	v_ashrrev_i32_e32 v159, 31, v158
	v_lshl_add_u64 v[160:161], s[46:47], 0, v[160:161]
	v_cvt_pk_bf16_f32 v124, v124, v125
	v_cvt_pk_bf16_f32 v125, v126, v127
	v_cvt_pk_bf16_f32 v126, v120, v121
	v_lshlrev_b64 v[120:121], 1, v[158:159]
	v_cvt_pk_bf16_f32 v127, v122, v123
	v_lshl_add_u64 v[122:123], v[160:161], 0, v[120:121]
	v_cvt_pk_bf16_f32 v108, v108, v109
	v_cvt_pk_bf16_f32 v109, v110, v111
	v_cvt_pk_bf16_f32 v110, v104, v105
	v_or_b32_e32 v104, 16, v156
	v_cvt_pk_bf16_f32 v60, v60, v61
	v_cvt_pk_bf16_f32 v61, v62, v63
	v_cvt_pk_bf16_f32 v63, v58, v59
	v_add_co_u32_e32 v58, vcc, s78, v122
	v_ashrrev_i32_e32 v105, 31, v104
	v_cvt_pk_bf16_f32 v62, v56, v57
	v_lshl_add_u64 v[56:57], v[122:123], 0, s[8:9]
	v_addc_co_u32_e32 v59, vcc, 0, v123, vcc
	v_cvt_pk_bf16_f32 v44, v44, v45
	v_cvt_pk_bf16_f32 v45, v46, v47
	v_cvt_pk_bf16_f32 v46, v40, v41
	v_cvt_pk_bf16_f32 v47, v42, v43
	v_cvt_pk_bf16_f32 v111, v106, v107
	v_lshlrev_b64 v[104:105], 11, v[104:105]
	v_cvt_pk_bf16_f32 v92, v92, v93
	v_cvt_pk_bf16_f32 v93, v94, v95
	v_cvt_pk_bf16_f32 v94, v88, v89
	v_or_b32_e32 v88, 32, v156
	global_store_dwordx4 v[56:57], v[44:47], off offset:256
	global_store_dwordx4 v[122:123], v[108:111], off offset:256
	v_ashrrev_i32_e32 v89, 31, v88
	v_add_co_u32_e32 v46, vcc, s79, v122
	v_lshl_add_u64 v[108:109], s[46:47], 0, v[104:105]
	v_lshl_add_u64 v[44:45], v[122:123], 0, s[12:13]
	v_addc_co_u32_e32 v47, vcc, 0, v123, vcc
	v_cvt_pk_bf16_f32 v28, v28, v29
	v_cvt_pk_bf16_f32 v29, v30, v31
	v_cvt_pk_bf16_f32 v30, v24, v25
	v_cvt_pk_bf16_f32 v31, v26, v27
	v_lshl_add_u64 v[108:109], v[108:109], 0, v[120:121]
	v_cvt_pk_bf16_f32 v95, v90, v91
	v_lshlrev_b64 v[88:89], 11, v[88:89]
	v_cvt_pk_bf16_f32 v76, v76, v77
	v_cvt_pk_bf16_f32 v77, v78, v79
	v_cvt_pk_bf16_f32 v78, v72, v73
	v_or_b32_e32 v72, 48, v156
	global_store_dwordx4 v[44:45], v[28:31], off offset:256
	global_store_dwordx4 v[108:109], v[92:95], off offset:256
	v_ashrrev_i32_e32 v73, 31, v72
	v_add_co_u32_e32 v30, vcc, s80, v122
	v_lshl_add_u64 v[92:93], s[46:47], 0, v[88:89]
	v_lshl_add_u64 v[28:29], v[122:123], 0, s[14:15]
	v_addc_co_u32_e32 v31, vcc, 0, v123, vcc
	v_cvt_pk_bf16_f32 v12, v12, v13
	v_cvt_pk_bf16_f32 v13, v14, v15
	v_cvt_pk_bf16_f32 v14, v8, v9
	v_cvt_pk_bf16_f32 v15, v10, v11
	v_lshl_add_u64 v[92:93], v[92:93], 0, v[120:121]
	v_cvt_pk_bf16_f32 v79, v74, v75
	v_lshlrev_b64 v[72:73], 11, v[72:73]
	global_store_dwordx4 v[28:29], v[12:15], off offset:256
	global_store_dwordx4 v[92:93], v[76:79], off offset:256
	v_cvt_pk_bf16_f32 v104, v116, v117
	v_add_co_u32_e32 v14, vcc, s81, v122
	v_lshl_add_u64 v[76:77], s[46:47], 0, v[72:73]
	s_nop 0
	v_addc_co_u32_e32 v15, vcc, 0, v123, vcc
	v_cvt_pk_bf16_f32 v105, v118, v119
	v_cvt_pk_bf16_f32 v106, v112, v113
	v_cvt_pk_bf16_f32 v107, v114, v115
	v_cvt_pk_bf16_f32 v88, v100, v101
	v_cvt_pk_bf16_f32 v89, v102, v103
	v_cvt_pk_bf16_f32 v90, v96, v97
	v_cvt_pk_bf16_f32 v91, v98, v99
	v_cvt_pk_bf16_f32 v72, v84, v85
	v_cvt_pk_bf16_f32 v73, v86, v87
	v_cvt_pk_bf16_f32 v74, v80, v81
	v_cvt_pk_bf16_f32 v75, v82, v83
	v_lshl_add_u64 v[76:77], v[76:77], 0, v[120:121]
	v_cvt_pk_bf16_f32 v68, v68, v69
	v_cvt_pk_bf16_f32 v69, v70, v71
	v_cvt_pk_bf16_f32 v70, v64, v65
	v_cvt_pk_bf16_f32 v71, v66, v67
	v_cvt_pk_bf16_f32 v40, v52, v53
	v_cvt_pk_bf16_f32 v41, v54, v55
	v_cvt_pk_bf16_f32 v42, v48, v49
	v_cvt_pk_bf16_f32 v43, v50, v51
	v_cvt_pk_bf16_f32 v24, v36, v37
	v_cvt_pk_bf16_f32 v25, v38, v39
	v_cvt_pk_bf16_f32 v26, v32, v33
	v_cvt_pk_bf16_f32 v27, v34, v35
	v_cvt_pk_bf16_f32 v8, v20, v21
	v_cvt_pk_bf16_f32 v9, v22, v23
	v_cvt_pk_bf16_f32 v10, v16, v17
	v_cvt_pk_bf16_f32 v11, v18, v19
	v_lshl_add_u64 v[12:13], v[122:123], 0, s[16:17]
	v_cvt_pk_bf16_f32 v4, v4, v5
	v_cvt_pk_bf16_f32 v5, v6, v7
	v_cvt_pk_bf16_f32 v6, v0, v1
	v_cvt_pk_bf16_f32 v7, v2, v3
	s_and_b64 vcc, exec, s[4:5]
	s_mov_b32 s82, s20
	s_mov_b32 s18, s26
	s_mov_b64 s[54:55], s[30:31]
	s_mov_b64 s[34:35], s[28:29]
	global_store_dwordx4 v[122:123], v[124:127], off
	global_store_dwordx4 v[108:109], v[104:107], off
	global_store_dwordx4 v[92:93], v[88:91], off
	global_store_dwordx4 v[76:77], v[72:75], off
	global_store_dwordx4 v[76:77], v[68:71], off offset:256
	global_store_dwordx4 v[58:59], v[60:63], off
	global_store_dwordx4 v[46:47], v[40:43], off
	global_store_dwordx4 v[30:31], v[24:27], off
	global_store_dwordx4 v[14:15], v[8:11], off
	global_store_dwordx4 v[12:13], v[4:7], off offset:256
	s_cbranch_vccz .LBB0_909
	s_waitcnt vmcnt(0)
	s_cmpk_gt_u32 s60, 0xff
	s_cbranch_scc1 .LBB0_916
	s_barrier

.LBB0_1116:
	ds_read_b128 v[154:157], v150
	ds_read_b128 v[158:161], v150 offset:1024
	ds_read_b128 v[162:165], v150 offset:2048
	ds_read_b128 v[166:169], v150 offset:3072
	s_add_u32 s34, s30, 0xfffc0080
	s_addc_u32 s35, s31, -1
	s_cmp_eq_u32 s77, 12
	s_cselect_b32 s37, s19, s35
	s_cselect_b32 s36, s73, s34
	s_cselect_b32 s35, s17, s76
	s_cselect_b32 s34, s74, s75
	v_lshl_add_u64 v[202:203], s[30:31], 0, v[134:135]
	s_add_i32 m0, s29, 0xc000
	ds_read_b128 v[170:173], v151
	ds_read_b128 v[174:177], v151 offset:1024
	ds_read_b128 v[178:181], v151 offset:2048
	ds_read_b128 v[182:185], v151 offset:3072
	ds_read_b128 v[186:189], v151 offset:4096
	ds_read_b128 v[190:193], v151 offset:5120
	ds_read_b128 v[194:197], v151 offset:6144
	ds_read_b128 v[198:201], v151 offset:7168
	global_load_lds_dwordx4 v[202:203], off
	v_lshl_add_u64 v[202:203], s[30:31], 0, v[136:137]
	s_add_i32 m0, s29, 0xe000
	s_nop 0
	global_load_lds_dwordx4 v[202:203], off
	s_waitcnt lgkmcnt(8)
	s_barrier
	s_waitcnt lgkmcnt(0)
	s_waitcnt lgkmcnt(0)
	v_mfma_f32_16x16x32_bf16 v[120:123], v[154:157], v[170:173], v[120:123]
	v_mfma_f32_16x16x32_bf16 v[124:127], v[162:165], v[170:173], v[124:127]
	v_mfma_f32_16x16x32_bf16 v[104:107], v[154:157], v[178:181], v[104:107]
	v_mfma_f32_16x16x32_bf16 v[108:111], v[162:165], v[178:181], v[108:111]
	v_mfma_f32_16x16x32_bf16 v[88:91], v[154:157], v[186:189], v[88:91]
	v_mfma_f32_16x16x32_bf16 v[92:95], v[162:165], v[186:189], v[92:95]
	v_mfma_f32_16x16x32_bf16 v[72:75], v[154:157], v[194:197], v[72:75]
	v_mfma_f32_16x16x32_bf16 v[76:79], v[162:165], v[194:197], v[76:79]
	v_mfma_f32_16x16x32_bf16 v[120:123], v[158:161], v[174:177], v[120:123]
	v_mfma_f32_16x16x32_bf16 v[124:127], v[166:169], v[174:177], v[124:127]
	v_mfma_f32_16x16x32_bf16 v[104:107], v[158:161], v[182:185], v[104:107]
	v_mfma_f32_16x16x32_bf16 v[108:111], v[166:169], v[182:185], v[108:111]
	v_mfma_f32_16x16x32_bf16 v[88:91], v[158:161], v[190:193], v[88:91]
	v_mfma_f32_16x16x32_bf16 v[92:95], v[166:169], v[190:193], v[92:95]
	v_mfma_f32_16x16x32_bf16 v[72:75], v[158:161], v[198:201], v[72:75]
	v_mfma_f32_16x16x32_bf16 v[76:79], v[166:169], v[198:201], v[76:79]
	s_barrier
	s_add_i32 s78, s60, s42
	v_lshl_add_u64 v[218:219], s[34:35], 0, v[130:131]
	s_mov_b32 m0, s78
	ds_read_b128 v[202:205], v152
	ds_read_b128 v[206:209], v152 offset:1024
	ds_read_b128 v[210:213], v152 offset:2048
	ds_read_b128 v[214:217], v152 offset:3072
	global_load_lds_dwordx4 v[218:219], off
	v_lshl_add_u64 v[220:221], s[34:35], 0, v[132:133]
	s_add_i32 m0, s78, 0x2000
	s_nop 0
	global_load_lds_dwordx4 v[220:221], off
	s_barrier
	s_waitcnt lgkmcnt(0)
	s_waitcnt lgkmcnt(0)
	v_mfma_f32_16x16x32_bf16 v[112:115], v[202:205], v[170:173], v[112:115]
	v_mfma_f32_16x16x32_bf16 v[116:119], v[210:213], v[170:173], v[116:119]
	v_mfma_f32_16x16x32_bf16 v[96:99], v[202:205], v[178:181], v[96:99]
	v_mfma_f32_16x16x32_bf16 v[100:103], v[210:213], v[178:181], v[100:103]
	v_mfma_f32_16x16x32_bf16 v[80:83], v[202:205], v[186:189], v[80:83]
	v_mfma_f32_16x16x32_bf16 v[84:87], v[210:213], v[186:189], v[84:87]
	v_mfma_f32_16x16x32_bf16 v[64:67], v[202:205], v[194:197], v[64:67]
	v_mfma_f32_16x16x32_bf16 v[68:71], v[210:213], v[194:197], v[68:71]
	v_mfma_f32_16x16x32_bf16 v[112:115], v[206:209], v[174:177], v[112:115]
	v_mfma_f32_16x16x32_bf16 v[116:119], v[214:217], v[174:177], v[116:119]
	v_mfma_f32_16x16x32_bf16 v[96:99], v[206:209], v[182:185], v[96:99]
	v_mfma_f32_16x16x32_bf16 v[100:103], v[214:217], v[182:185], v[100:103]
	v_mfma_f32_16x16x32_bf16 v[80:83], v[206:209], v[190:193], v[80:83]
	v_mfma_f32_16x16x32_bf16 v[84:87], v[214:217], v[190:193], v[84:87]
	v_mfma_f32_16x16x32_bf16 v[64:67], v[206:209], v[198:201], v[64:67]
	v_mfma_f32_16x16x32_bf16 v[68:71], v[214:217], v[198:201], v[68:71]
	s_mov_b32 m0, s29
	v_lshl_add_u64 v[222:223], s[36:37], 0, v[130:131]
	s_barrier
	ds_read_b128 v[170:173], v151 offset:16384
	ds_read_b128 v[174:177], v151 offset:17408
	ds_read_b128 v[178:181], v151 offset:18432
	ds_read_b128 v[182:185], v151 offset:19456
	ds_read_b128 v[186:189], v151 offset:20480
	ds_read_b128 v[190:193], v151 offset:21504
	ds_read_b128 v[194:197], v151 offset:22528
	ds_read_b128 v[198:201], v151 offset:23552
	global_load_lds_dwordx4 v[222:223], off
	v_lshl_add_u64 v[224:225], s[36:37], 0, v[132:133]
	s_mov_b32 m0, s43
	s_nop 0
	global_load_lds_dwordx4 v[224:225], off
	s_barrier
	s_waitcnt lgkmcnt(0)
	s_waitcnt lgkmcnt(0)
	v_mfma_f32_16x16x32_bf16 v[56:59], v[154:157], v[170:173], v[56:59]
	v_mfma_f32_16x16x32_bf16 v[60:63], v[162:165], v[170:173], v[60:63]
	v_mfma_f32_16x16x32_bf16 v[40:43], v[154:157], v[178:181], v[40:43]
	v_mfma_f32_16x16x32_bf16 v[44:47], v[162:165], v[178:181], v[44:47]
	v_mfma_f32_16x16x32_bf16 v[24:27], v[154:157], v[186:189], v[24:27]
	v_mfma_f32_16x16x32_bf16 v[28:31], v[162:165], v[186:189], v[28:31]
	v_mfma_f32_16x16x32_bf16 v[8:11], v[154:157], v[194:197], v[8:11]
	v_mfma_f32_16x16x32_bf16 v[12:15], v[162:165], v[194:197], v[12:15]
	v_mfma_f32_16x16x32_bf16 v[56:59], v[158:161], v[174:177], v[56:59]
	v_mfma_f32_16x16x32_bf16 v[60:63], v[166:169], v[174:177], v[60:63]
	v_mfma_f32_16x16x32_bf16 v[40:43], v[158:161], v[182:185], v[40:43]
	v_mfma_f32_16x16x32_bf16 v[44:47], v[166:169], v[182:185], v[44:47]
	v_mfma_f32_16x16x32_bf16 v[24:27], v[158:161], v[190:193], v[24:27]
	v_mfma_f32_16x16x32_bf16 v[28:31], v[166:169], v[190:193], v[28:31]
	v_mfma_f32_16x16x32_bf16 v[8:11], v[158:161], v[198:201], v[8:11]
	v_mfma_f32_16x16x32_bf16 v[12:15], v[166:169], v[198:201], v[12:15]
	s_barrier
	s_add_u32 s78, s34, 0x40000
	s_addc_u32 s79, s35, 0
	s_add_i32 s80, s61, s42
	v_lshl_add_u64 v[154:155], s[78:79], 0, v[130:131]
	s_mov_b32 m0, s80
	s_nop 0
	global_load_lds_dwordx4 v[154:155], off
	v_lshl_add_u64 v[154:155], s[78:79], 0, v[132:133]
	s_add_i32 m0, s80, 0x2000
	s_nop 0
	global_load_lds_dwordx4 v[154:155], off
	s_waitcnt vmcnt(6)
	s_barrier
	v_mfma_f32_16x16x32_bf16 v[48:51], v[202:205], v[170:173], v[48:51]
	v_mfma_f32_16x16x32_bf16 v[52:55], v[210:213], v[170:173], v[52:55]
	v_mfma_f32_16x16x32_bf16 v[32:35], v[202:205], v[178:181], v[32:35]
	v_mfma_f32_16x16x32_bf16 v[36:39], v[210:213], v[178:181], v[36:39]
	v_mfma_f32_16x16x32_bf16 v[16:19], v[202:205], v[186:189], v[16:19]
	v_mfma_f32_16x16x32_bf16 v[20:23], v[210:213], v[186:189], v[20:23]
	v_mfma_f32_16x16x32_bf16 v[0:3], v[202:205], v[194:197], v[0:3]
	v_mfma_f32_16x16x32_bf16 v[4:7], v[210:213], v[194:197], v[4:7]
	v_mfma_f32_16x16x32_bf16 v[48:51], v[206:209], v[174:177], v[48:51]
	v_mfma_f32_16x16x32_bf16 v[52:55], v[214:217], v[174:177], v[52:55]
	v_mfma_f32_16x16x32_bf16 v[32:35], v[206:209], v[182:185], v[32:35]
	v_mfma_f32_16x16x32_bf16 v[36:39], v[214:217], v[182:185], v[36:39]
	v_mfma_f32_16x16x32_bf16 v[16:19], v[206:209], v[190:193], v[16:19]
	v_mfma_f32_16x16x32_bf16 v[20:23], v[214:217], v[190:193], v[20:23]
	v_mfma_f32_16x16x32_bf16 v[0:3], v[206:209], v[198:201], v[0:3]
	v_mfma_f32_16x16x32_bf16 v[4:7], v[214:217], v[198:201], v[4:7]
	s_add_i32 s78, 0, 0x18000
	v_add_u32_e32 v153, s78, v148
	s_barrier
	ds_read_b128 v[154:157], v153
	ds_read_b128 v[158:161], v153 offset:1024
	ds_read_b128 v[162:165], v153 offset:2048
	ds_read_b128 v[166:169], v153 offset:3072
	s_add_u32 s36, s36, 0x40000
	s_addc_u32 s37, s37, 0
	s_mov_b32 m0, s52
	v_lshl_add_u64 v[202:203], s[36:37], 0, v[130:131]
	ds_read_b128 v[170:173], v151 offset:32768
	ds_read_b128 v[174:177], v151 offset:33792
	ds_read_b128 v[178:181], v151 offset:34816
	ds_read_b128 v[182:185], v151 offset:35840
	ds_read_b128 v[186:189], v151 offset:36864
	ds_read_b128 v[190:193], v151 offset:37888
	ds_read_b128 v[194:197], v151 offset:38912
	ds_read_b128 v[198:201], v151 offset:39936
	global_load_lds_dwordx4 v[202:203], off
	v_lshl_add_u64 v[202:203], s[36:37], 0, v[132:133]
	s_mov_b32 m0, s53
	s_nop 0
	global_load_lds_dwordx4 v[202:203], off
	s_waitcnt lgkmcnt(8)
	s_barrier
	s_waitcnt lgkmcnt(0)
	s_waitcnt lgkmcnt(0)
	v_mfma_f32_16x16x32_bf16 v[120:123], v[154:157], v[170:173], v[120:123]
	v_mfma_f32_16x16x32_bf16 v[124:127], v[162:165], v[170:173], v[124:127]
	v_mfma_f32_16x16x32_bf16 v[104:107], v[154:157], v[178:181], v[104:107]
	v_mfma_f32_16x16x32_bf16 v[108:111], v[162:165], v[178:181], v[108:111]
	v_mfma_f32_16x16x32_bf16 v[88:91], v[154:157], v[186:189], v[88:91]
	v_mfma_f32_16x16x32_bf16 v[92:95], v[162:165], v[186:189], v[92:95]
	v_mfma_f32_16x16x32_bf16 v[72:75], v[154:157], v[194:197], v[72:75]
	v_mfma_f32_16x16x32_bf16 v[76:79], v[162:165], v[194:197], v[76:79]
	v_mfma_f32_16x16x32_bf16 v[120:123], v[158:161], v[174:177], v[120:123]
	v_mfma_f32_16x16x32_bf16 v[124:127], v[166:169], v[174:177], v[124:127]
	v_mfma_f32_16x16x32_bf16 v[104:107], v[158:161], v[182:185], v[104:107]
	v_mfma_f32_16x16x32_bf16 v[108:111], v[166:169], v[182:185], v[108:111]
	v_mfma_f32_16x16x32_bf16 v[88:91], v[158:161], v[190:193], v[88:91]
	v_mfma_f32_16x16x32_bf16 v[92:95], v[166:169], v[190:193], v[92:95]
	v_mfma_f32_16x16x32_bf16 v[72:75], v[158:161], v[198:201], v[72:75]
	v_mfma_f32_16x16x32_bf16 v[76:79], v[166:169], v[198:201], v[76:79]
	s_barrier
	s_add_i32 s36, 0, 0x1c000
	s_add_i32 s37, s78, s42
	v_add_u32_e32 v153, s36, v148
	v_lshl_add_u64 v[218:219], v[218:219], 0, s[8:9]
	s_mov_b32 m0, s37
	ds_read_b128 v[202:205], v153
	ds_read_b128 v[206:209], v153 offset:1024
	ds_read_b128 v[210:213], v153 offset:2048
	ds_read_b128 v[214:217], v153 offset:3072
	global_load_lds_dwordx4 v[218:219], off
	v_lshl_add_u64 v[218:219], v[220:221], 0, s[8:9]
	s_add_i32 m0, s37, 0x2000
	s_nop 0
	global_load_lds_dwordx4 v[218:219], off
	s_barrier
	s_waitcnt lgkmcnt(0)
	s_waitcnt lgkmcnt(0)
	v_mfma_f32_16x16x32_bf16 v[112:115], v[202:205], v[170:173], v[112:115]
	v_mfma_f32_16x16x32_bf16 v[116:119], v[210:213], v[170:173], v[116:119]
	v_mfma_f32_16x16x32_bf16 v[96:99], v[202:205], v[178:181], v[96:99]
	v_mfma_f32_16x16x32_bf16 v[100:103], v[210:213], v[178:181], v[100:103]
	v_mfma_f32_16x16x32_bf16 v[80:83], v[202:205], v[186:189], v[80:83]
	v_mfma_f32_16x16x32_bf16 v[84:87], v[210:213], v[186:189], v[84:87]
	v_mfma_f32_16x16x32_bf16 v[64:67], v[202:205], v[194:197], v[64:67]
	v_mfma_f32_16x16x32_bf16 v[68:71], v[210:213], v[194:197], v[68:71]
	v_mfma_f32_16x16x32_bf16 v[112:115], v[206:209], v[174:177], v[112:115]
	v_mfma_f32_16x16x32_bf16 v[116:119], v[214:217], v[174:177], v[116:119]
	v_mfma_f32_16x16x32_bf16 v[96:99], v[206:209], v[182:185], v[96:99]
	v_mfma_f32_16x16x32_bf16 v[100:103], v[214:217], v[182:185], v[100:103]
	v_mfma_f32_16x16x32_bf16 v[80:83], v[206:209], v[190:193], v[80:83]
	v_mfma_f32_16x16x32_bf16 v[84:87], v[214:217], v[190:193], v[84:87]
	v_mfma_f32_16x16x32_bf16 v[64:67], v[206:209], v[198:201], v[64:67]
	v_mfma_f32_16x16x32_bf16 v[68:71], v[214:217], v[198:201], v[68:71]
	s_mov_b32 m0, s55
	v_lshl_add_u64 v[218:219], v[222:223], 0, s[8:9]
	s_barrier
	ds_read_b128 v[170:173], v151 offset:49152
	ds_read_b128 v[174:177], v151 offset:50176
	ds_read_b128 v[178:181], v151 offset:51200
	ds_read_b128 v[182:185], v151 offset:52224
	ds_read_b128 v[186:189], v151 offset:53248
	ds_read_b128 v[190:193], v151 offset:54272
	ds_read_b128 v[194:197], v151 offset:55296
	ds_read_b128 v[198:201], v151 offset:56320
	global_load_lds_dwordx4 v[218:219], off
	v_lshl_add_u64 v[218:219], v[224:225], 0, s[8:9]
	s_mov_b32 m0, s56
	s_nop 0
	global_load_lds_dwordx4 v[218:219], off
	s_barrier
	s_waitcnt lgkmcnt(0)
	s_waitcnt lgkmcnt(0)
	v_mfma_f32_16x16x32_bf16 v[56:59], v[154:157], v[170:173], v[56:59]
	v_mfma_f32_16x16x32_bf16 v[60:63], v[162:165], v[170:173], v[60:63]
	v_mfma_f32_16x16x32_bf16 v[40:43], v[154:157], v[178:181], v[40:43]
	v_mfma_f32_16x16x32_bf16 v[44:47], v[162:165], v[178:181], v[44:47]
	v_mfma_f32_16x16x32_bf16 v[24:27], v[154:157], v[186:189], v[24:27]
	v_mfma_f32_16x16x32_bf16 v[28:31], v[162:165], v[186:189], v[28:31]
	v_mfma_f32_16x16x32_bf16 v[8:11], v[154:157], v[194:197], v[8:11]
	v_mfma_f32_16x16x32_bf16 v[12:15], v[162:165], v[194:197], v[12:15]
	v_mfma_f32_16x16x32_bf16 v[56:59], v[158:161], v[174:177], v[56:59]
	v_mfma_f32_16x16x32_bf16 v[60:63], v[166:169], v[174:177], v[60:63]
	v_mfma_f32_16x16x32_bf16 v[40:43], v[158:161], v[182:185], v[40:43]
	v_mfma_f32_16x16x32_bf16 v[44:47], v[166:169], v[182:185], v[44:47]
	v_mfma_f32_16x16x32_bf16 v[24:27], v[158:161], v[190:193], v[24:27]
	v_mfma_f32_16x16x32_bf16 v[28:31], v[166:169], v[190:193], v[28:31]
	v_mfma_f32_16x16x32_bf16 v[8:11], v[158:161], v[198:201], v[8:11]
	v_mfma_f32_16x16x32_bf16 v[12:15], v[166:169], v[198:201], v[12:15]
	s_barrier
	s_add_u32 s34, s34, 0x40080
	s_addc_u32 s35, s35, 0
	s_add_i32 s36, s36, s42
	v_lshl_add_u64 v[154:155], s[34:35], 0, v[130:131]
	s_mov_b32 m0, s36
	s_nop 0
	global_load_lds_dwordx4 v[154:155], off
	v_lshl_add_u64 v[154:155], s[34:35], 0, v[132:133]
	s_add_i32 m0, s36, 0x2000
	s_nop 0
	global_load_lds_dwordx4 v[154:155], off
	s_waitcnt vmcnt(6)
	s_barrier
	v_mfma_f32_16x16x32_bf16 v[48:51], v[202:205], v[170:173], v[48:51]
	v_mfma_f32_16x16x32_bf16 v[52:55], v[210:213], v[170:173], v[52:55]
	v_mfma_f32_16x16x32_bf16 v[32:35], v[202:205], v[178:181], v[32:35]
	v_mfma_f32_16x16x32_bf16 v[36:39], v[210:213], v[178:181], v[36:39]
	v_mfma_f32_16x16x32_bf16 v[16:19], v[202:205], v[186:189], v[16:19]
	v_mfma_f32_16x16x32_bf16 v[20:23], v[210:213], v[186:189], v[20:23]
	v_mfma_f32_16x16x32_bf16 v[0:3], v[202:205], v[194:197], v[0:3]
	v_mfma_f32_16x16x32_bf16 v[4:7], v[210:213], v[194:197], v[4:7]
	v_mfma_f32_16x16x32_bf16 v[48:51], v[206:209], v[174:177], v[48:51]
	v_mfma_f32_16x16x32_bf16 v[52:55], v[214:217], v[174:177], v[52:55]
	v_mfma_f32_16x16x32_bf16 v[32:35], v[206:209], v[182:185], v[32:35]
	v_mfma_f32_16x16x32_bf16 v[36:39], v[214:217], v[182:185], v[36:39]
	v_mfma_f32_16x16x32_bf16 v[16:19], v[206:209], v[190:193], v[16:19]
	v_mfma_f32_16x16x32_bf16 v[20:23], v[214:217], v[190:193], v[20:23]
	v_mfma_f32_16x16x32_bf16 v[0:3], v[206:209], v[198:201], v[0:3]
	v_mfma_f32_16x16x32_bf16 v[4:7], v[214:217], v[198:201], v[4:7]
	s_add_i32 s77, s77, 2
	s_add_u32 s30, s30, 0x100
	s_addc_u32 s31, s31, 0
	s_add_u32 s75, s75, 0x100
	s_addc_u32 s76, s76, 0
	s_cmp_gt_u32 s77, 13
	s_barrier
	s_cbranch_scc0 .LBB0_1116
	v_mul_f32_e32 v124, 0xbfb8aa3b, v124
	v_exp_f32_e32 v154, v124
	v_mul_f32_e32 v124, 0xbfb8aa3b, v125
	v_exp_f32_e32 v155, v124
	v_lshl_add_u32 v124, s28, 8, v145
	v_ashrrev_i32_e32 v125, 31, v124
	v_lshlrev_b64 v[158:159], 11, v[124:125]
	v_pk_add_f32 v[154:155], v[154:155], 1.0 op_sel_hi:[1,0]
	v_mul_f32_e32 v126, 0xbfb8aa3b, v126
	v_div_scale_f32 v153, s[30:31], v155, v155, v121
	v_rcp_f32_e32 v157, v153
	v_mul_f32_e32 v127, 0xbfb8aa3b, v127
	v_exp_f32_e32 v126, v126
	v_exp_f32_e32 v127, v127
	v_fma_f32 v125, -v153, v157, 1.0
	v_fmac_f32_e32 v157, v125, v157
	v_div_scale_f32 v125, vcc, v121, v155, v121
	v_mul_f32_e32 v160, v125, v157
	v_fma_f32 v161, -v153, v160, v125
	v_fmac_f32_e32 v160, v161, v157
	v_fma_f32 v125, -v153, v160, v125
	v_div_scale_f32 v153, s[30:31], v154, v154, v120
	v_rcp_f32_e32 v161, v153
	v_div_fmas_f32 v125, v125, v157, v160
	v_div_fixup_f32 v121, v125, v155, v121
	v_pk_add_f32 v[126:127], v[126:127], 1.0 op_sel_hi:[1,0]
	v_fma_f32 v125, -v153, v161, 1.0
	v_fmac_f32_e32 v161, v125, v161
	v_div_scale_f32 v125, vcc, v120, v154, v120
	v_mul_f32_e32 v155, v125, v161
	v_fma_f32 v157, -v153, v155, v125
	v_fmac_f32_e32 v155, v157, v161
	v_fma_f32 v125, -v153, v155, v125
	v_div_scale_f32 v153, s[30:31], v127, v127, v123
	v_rcp_f32_e32 v157, v153
	v_div_fmas_f32 v125, v125, v161, v155
	v_div_fixup_f32 v120, v125, v154, v120
	v_mul_f32_e32 v116, 0xbfb8aa3b, v116
	v_fma_f32 v125, -v153, v157, 1.0
	v_fmac_f32_e32 v157, v125, v157
	v_div_scale_f32 v125, vcc, v123, v127, v123
	v_mul_f32_e32 v154, v125, v157
	v_fma_f32 v155, -v153, v154, v125
	v_fmac_f32_e32 v154, v155, v157
	v_fma_f32 v125, -v153, v154, v125
	v_div_scale_f32 v153, s[30:31], v126, v126, v122
	v_rcp_f32_e32 v155, v153
	v_div_fmas_f32 v125, v125, v157, v154
	v_div_fixup_f32 v123, v125, v127, v123
	v_mul_f32_e32 v117, 0xbfb8aa3b, v117
	v_fma_f32 v125, -v153, v155, 1.0
	v_fmac_f32_e32 v155, v125, v155
	v_div_scale_f32 v125, vcc, v122, v126, v122
	v_mul_f32_e32 v127, v125, v155
	v_fma_f32 v154, -v153, v127, v125
	v_exp_f32_e32 v116, v116
	v_exp_f32_e32 v117, v117
	v_fmac_f32_e32 v127, v154, v155
	v_fma_f32 v125, -v153, v127, v125
	v_div_fmas_f32 v125, v125, v155, v127
	v_div_fixup_f32 v125, v125, v126, v122
	v_pk_add_f32 v[126:127], v[116:117], 1.0 op_sel_hi:[1,0]
	v_cvt_pk_bf16_f32 v123, v125, v123
	v_div_scale_f32 v125, s[30:31], v127, v127, v113
	v_lshl_or_b32 v156, s72, 7, v149
	v_rcp_f32_e32 v153, v125
	v_ashrrev_i32_e32 v157, 31, v156
	v_lshl_add_u64 v[158:159], s[46:47], 0, v[158:159]
	v_cvt_pk_bf16_f32 v122, v120, v121
	v_lshlrev_b64 v[120:121], 1, v[156:157]
	v_lshl_add_u64 v[116:117], v[158:159], 0, v[120:121]
	global_store_dwordx2 v[116:117], v[122:123], off
	v_fma_f32 v122, -v125, v153, 1.0
	v_fmac_f32_e32 v153, v122, v153
	v_div_scale_f32 v122, vcc, v113, v127, v113
	v_mul_f32_e32 v123, v122, v153
	v_fma_f32 v154, -v125, v123, v122
	v_fmac_f32_e32 v123, v154, v153
	v_fma_f32 v122, -v125, v123, v122
	v_div_scale_f32 v125, s[30:31], v126, v126, v112
	v_rcp_f32_e32 v154, v125
	v_div_fmas_f32 v122, v122, v153, v123
	v_mul_f32_e32 v118, 0xbfb8aa3b, v118
	v_mul_f32_e32 v119, 0xbfb8aa3b, v119
	v_div_fixup_f32 v113, v122, v127, v113
	v_fma_f32 v122, -v125, v154, 1.0
	v_exp_f32_e32 v118, v118
	v_exp_f32_e32 v119, v119
	v_fmac_f32_e32 v154, v122, v154
	v_div_scale_f32 v122, vcc, v112, v126, v112
	v_mul_f32_e32 v123, v122, v154
	v_fma_f32 v127, -v125, v123, v122
	v_fmac_f32_e32 v123, v127, v154
	v_pk_add_f32 v[118:119], v[118:119], 1.0 op_sel_hi:[1,0]
	v_fma_f32 v122, -v125, v123, v122
	v_div_scale_f32 v125, s[30:31], v119, v119, v115
	v_rcp_f32_e32 v127, v125
	v_div_fmas_f32 v122, v122, v154, v123
	v_div_fixup_f32 v112, v122, v126, v112
	v_mul_f32_e32 v108, 0xbfb8aa3b, v108
	v_fma_f32 v122, -v125, v127, 1.0
	v_fmac_f32_e32 v127, v122, v127
	v_div_scale_f32 v122, vcc, v115, v119, v115
	v_mul_f32_e32 v123, v122, v127
	v_fma_f32 v126, -v125, v123, v122
	v_fmac_f32_e32 v123, v126, v127
	v_fma_f32 v122, -v125, v123, v122
	v_div_scale_f32 v125, s[30:31], v118, v118, v114
	v_rcp_f32_e32 v126, v125
	v_div_fmas_f32 v122, v122, v127, v123
	v_div_fixup_f32 v115, v122, v119, v115
	v_mul_f32_e32 v109, 0xbfb8aa3b, v109
	v_fma_f32 v119, -v125, v126, 1.0
	v_fmac_f32_e32 v126, v119, v126
	v_div_scale_f32 v119, vcc, v114, v118, v114
	v_mul_f32_e32 v122, v119, v126
	v_fma_f32 v123, -v125, v122, v119
	v_exp_f32_e32 v108, v108
	v_exp_f32_e32 v109, v109
	v_fmac_f32_e32 v122, v123, v126
	v_fma_f32 v119, -v125, v122, v119
	v_div_fmas_f32 v119, v119, v126, v122
	v_div_fixup_f32 v114, v119, v118, v114
	v_pk_add_f32 v[108:109], v[108:109], 1.0 op_sel_hi:[1,0]
	v_cvt_pk_bf16_f32 v112, v112, v113
	v_cvt_pk_bf16_f32 v113, v114, v115
	v_div_scale_f32 v114, s[30:31], v109, v109, v105
	v_rcp_f32_e32 v115, v114
	v_mul_f32_e32 v110, 0xbfb8aa3b, v110
	v_mul_f32_e32 v111, 0xbfb8aa3b, v111
	v_exp_f32_e32 v110, v110
	v_fma_f32 v118, -v114, v115, 1.0
	v_fmac_f32_e32 v115, v118, v115
	v_div_scale_f32 v118, vcc, v105, v109, v105
	v_mul_f32_e32 v119, v118, v115
	v_fma_f32 v122, -v114, v119, v118
	v_fmac_f32_e32 v119, v122, v115
	v_fma_f32 v114, -v114, v119, v118
	v_div_scale_f32 v118, s[30:31], v108, v108, v104
	v_rcp_f32_e32 v122, v118
	v_div_fmas_f32 v114, v114, v115, v119
	v_exp_f32_e32 v111, v111
	v_div_fixup_f32 v105, v114, v109, v105
	v_fma_f32 v109, -v118, v122, 1.0
	v_fmac_f32_e32 v122, v109, v122
	v_div_scale_f32 v109, vcc, v104, v108, v104
	v_mul_f32_e32 v114, v109, v122
	v_fma_f32 v115, -v118, v114, v109
	v_pk_add_f32 v[110:111], v[110:111], 1.0 op_sel_hi:[1,0]
	v_fmac_f32_e32 v114, v115, v122
	v_div_scale_f32 v115, s[30:31], v111, v111, v107
	v_fma_f32 v109, -v118, v114, v109
	v_rcp_f32_e32 v118, v115
	v_div_fmas_f32 v109, v109, v122, v114
	v_div_fixup_f32 v104, v109, v108, v104
	v_mul_f32_e32 v100, 0xbfb8aa3b, v100
	v_fma_f32 v108, -v115, v118, 1.0
	v_fmac_f32_e32 v118, v108, v118
	v_div_scale_f32 v108, vcc, v107, v111, v107
	v_mul_f32_e32 v109, v108, v118
	v_fma_f32 v114, -v115, v109, v108
	v_fmac_f32_e32 v109, v114, v118
	v_div_scale_f32 v114, s[30:31], v110, v110, v106
	v_fma_f32 v108, -v115, v109, v108
	v_rcp_f32_e32 v115, v114
	v_div_fmas_f32 v108, v108, v118, v109
	v_div_fixup_f32 v107, v108, v111, v107
	v_mul_f32_e32 v101, 0xbfb8aa3b, v101
	v_fma_f32 v108, -v114, v115, 1.0
	v_fmac_f32_e32 v115, v108, v115
	v_div_scale_f32 v108, vcc, v106, v110, v106
	v_mul_f32_e32 v109, v108, v115
	v_exp_f32_e32 v100, v100
	v_exp_f32_e32 v101, v101
	v_fma_f32 v111, -v114, v109, v108
	v_fmac_f32_e32 v109, v111, v115
	v_fma_f32 v108, -v114, v109, v108
	v_div_fmas_f32 v108, v108, v115, v109
	v_pk_add_f32 v[100:101], v[100:101], 1.0 op_sel_hi:[1,0]
	global_store_dwordx2 v[116:117], v[112:113], off offset:128
	v_or_b32_e32 v112, 16, v124
	v_div_fixup_f32 v106, v108, v110, v106
	v_div_scale_f32 v108, s[30:31], v101, v101, v97
	v_ashrrev_i32_e32 v113, 31, v112
	v_rcp_f32_e32 v109, v108
	v_lshlrev_b64 v[112:113], 11, v[112:113]
	v_lshl_add_u64 v[112:113], s[46:47], 0, v[112:113]
	v_cvt_pk_bf16_f32 v104, v104, v105
	v_cvt_pk_bf16_f32 v105, v106, v107
	v_lshl_add_u64 v[106:107], v[112:113], 0, v[120:121]
	global_store_dwordx2 v[106:107], v[104:105], off
	v_fma_f32 v104, -v108, v109, 1.0
	v_fmac_f32_e32 v109, v104, v109
	v_div_scale_f32 v104, vcc, v97, v101, v97
	v_mul_f32_e32 v105, v104, v109
	v_fma_f32 v110, -v108, v105, v104
	v_fmac_f32_e32 v105, v110, v109
	v_fma_f32 v104, -v108, v105, v104
	v_div_scale_f32 v108, s[30:31], v100, v100, v96
	v_rcp_f32_e32 v110, v108
	v_mul_f32_e32 v102, 0xbfb8aa3b, v102
	v_mul_f32_e32 v103, 0xbfb8aa3b, v103
	v_div_fmas_f32 v104, v104, v109, v105
	v_exp_f32_e32 v102, v102
	v_exp_f32_e32 v103, v103
	v_div_fixup_f32 v97, v104, v101, v97
	v_fma_f32 v101, -v108, v110, 1.0
	v_fmac_f32_e32 v110, v101, v110
	v_div_scale_f32 v101, vcc, v96, v100, v96
	v_mul_f32_e32 v104, v101, v110
	v_fma_f32 v105, -v108, v104, v101
	v_pk_add_f32 v[102:103], v[102:103], 1.0 op_sel_hi:[1,0]
	v_fmac_f32_e32 v104, v105, v110
	v_div_scale_f32 v105, s[30:31], v103, v103, v99
	v_fma_f32 v101, -v108, v104, v101
	v_rcp_f32_e32 v108, v105
	v_div_fmas_f32 v101, v101, v110, v104
	v_div_fixup_f32 v96, v101, v100, v96
	v_mul_f32_e32 v92, 0xbfb8aa3b, v92
	v_fma_f32 v100, -v105, v108, 1.0
	v_fmac_f32_e32 v108, v100, v108
	v_div_scale_f32 v100, vcc, v99, v103, v99
	v_mul_f32_e32 v101, v100, v108
	v_fma_f32 v104, -v105, v101, v100
	v_fmac_f32_e32 v101, v104, v108
	v_div_scale_f32 v104, s[30:31], v102, v102, v98
	v_fma_f32 v100, -v105, v101, v100
	v_rcp_f32_e32 v105, v104
	v_div_fmas_f32 v100, v100, v108, v101
	v_div_fixup_f32 v99, v100, v103, v99
	v_mul_f32_e32 v93, 0xbfb8aa3b, v93
	v_fma_f32 v100, -v104, v105, 1.0
	v_fmac_f32_e32 v105, v100, v105
	v_div_scale_f32 v100, vcc, v98, v102, v98
	v_mul_f32_e32 v101, v100, v105
	v_fma_f32 v103, -v104, v101, v100
	v_exp_f32_e32 v92, v92
	v_exp_f32_e32 v93, v93
	v_fmac_f32_e32 v101, v103, v105
	v_fma_f32 v100, -v104, v101, v100
	v_div_fmas_f32 v100, v100, v105, v101
	v_div_fixup_f32 v98, v100, v102, v98
	v_pk_add_f32 v[92:93], v[92:93], 1.0 op_sel_hi:[1,0]
	v_cvt_pk_bf16_f32 v96, v96, v97
	v_cvt_pk_bf16_f32 v97, v98, v99
	v_div_scale_f32 v98, s[30:31], v93, v93, v89
	v_rcp_f32_e32 v99, v98
	v_mul_f32_e32 v94, 0xbfb8aa3b, v94
	v_mul_f32_e32 v95, 0xbfb8aa3b, v95
	v_exp_f32_e32 v94, v94
	v_fma_f32 v100, -v98, v99, 1.0
	v_fmac_f32_e32 v99, v100, v99
	v_div_scale_f32 v100, vcc, v89, v93, v89
	v_mul_f32_e32 v101, v100, v99
	v_fma_f32 v102, -v98, v101, v100
	v_fmac_f32_e32 v101, v102, v99
	v_fma_f32 v98, -v98, v101, v100
	v_div_scale_f32 v100, s[30:31], v92, v92, v88
	v_rcp_f32_e32 v102, v100
	v_div_fmas_f32 v98, v98, v99, v101
	v_exp_f32_e32 v95, v95
	v_div_fixup_f32 v89, v98, v93, v89
	v_fma_f32 v93, -v100, v102, 1.0
	v_fmac_f32_e32 v102, v93, v102
	v_div_scale_f32 v93, vcc, v88, v92, v88
	v_mul_f32_e32 v98, v93, v102
	v_fma_f32 v99, -v100, v98, v93
	v_pk_add_f32 v[94:95], v[94:95], 1.0 op_sel_hi:[1,0]
	v_fmac_f32_e32 v98, v99, v102
	v_div_scale_f32 v99, s[30:31], v95, v95, v91
	v_fma_f32 v93, -v100, v98, v93
	v_rcp_f32_e32 v100, v99
	v_div_fmas_f32 v93, v93, v102, v98
	v_div_fixup_f32 v88, v93, v92, v88
	v_mul_f32_e32 v84, 0xbfb8aa3b, v84
	v_fma_f32 v92, -v99, v100, 1.0
	v_fmac_f32_e32 v100, v92, v100
	v_div_scale_f32 v92, vcc, v91, v95, v91
	v_mul_f32_e32 v93, v92, v100
	v_fma_f32 v98, -v99, v93, v92
	v_fmac_f32_e32 v93, v98, v100
	v_div_scale_f32 v98, s[30:31], v94, v94, v90
	v_fma_f32 v92, -v99, v93, v92
	v_rcp_f32_e32 v99, v98
	v_div_fmas_f32 v92, v92, v100, v93
	v_div_fixup_f32 v91, v92, v95, v91
	v_mul_f32_e32 v85, 0xbfb8aa3b, v85
	v_fma_f32 v92, -v98, v99, 1.0
	v_fmac_f32_e32 v99, v92, v99
	v_div_scale_f32 v92, vcc, v90, v94, v90
	v_mul_f32_e32 v93, v92, v99
	v_exp_f32_e32 v84, v84
	v_exp_f32_e32 v85, v85
	v_fma_f32 v95, -v98, v93, v92
	v_fmac_f32_e32 v93, v95, v99
	v_fma_f32 v92, -v98, v93, v92
	v_div_fmas_f32 v92, v92, v99, v93
	v_pk_add_f32 v[84:85], v[84:85], 1.0 op_sel_hi:[1,0]
	global_store_dwordx2 v[106:107], v[96:97], off offset:128
	v_or_b32_e32 v96, 32, v124
	v_div_fixup_f32 v90, v92, v94, v90
	v_div_scale_f32 v92, s[30:31], v85, v85, v81
	v_ashrrev_i32_e32 v97, 31, v96
	v_rcp_f32_e32 v93, v92
	v_lshlrev_b64 v[96:97], 11, v[96:97]
	v_lshl_add_u64 v[96:97], s[46:47], 0, v[96:97]
	v_cvt_pk_bf16_f32 v88, v88, v89
	v_cvt_pk_bf16_f32 v89, v90, v91
	v_lshl_add_u64 v[90:91], v[96:97], 0, v[120:121]
	global_store_dwordx2 v[90:91], v[88:89], off
	v_fma_f32 v88, -v92, v93, 1.0
	v_fmac_f32_e32 v93, v88, v93
	v_div_scale_f32 v88, vcc, v81, v85, v81
	v_mul_f32_e32 v89, v88, v93
	v_fma_f32 v94, -v92, v89, v88
	v_fmac_f32_e32 v89, v94, v93
	v_fma_f32 v88, -v92, v89, v88
	v_div_scale_f32 v92, s[30:31], v84, v84, v80
	v_rcp_f32_e32 v94, v92
	v_mul_f32_e32 v86, 0xbfb8aa3b, v86
	v_mul_f32_e32 v87, 0xbfb8aa3b, v87
	v_div_fmas_f32 v88, v88, v93, v89
	v_exp_f32_e32 v86, v86
	v_exp_f32_e32 v87, v87
	v_div_fixup_f32 v81, v88, v85, v81
	v_fma_f32 v85, -v92, v94, 1.0
	v_fmac_f32_e32 v94, v85, v94
	v_div_scale_f32 v85, vcc, v80, v84, v80
	v_mul_f32_e32 v88, v85, v94
	v_fma_f32 v89, -v92, v88, v85
	v_pk_add_f32 v[86:87], v[86:87], 1.0 op_sel_hi:[1,0]
	v_fmac_f32_e32 v88, v89, v94
	v_div_scale_f32 v89, s[30:31], v87, v87, v83
	v_fma_f32 v85, -v92, v88, v85
	v_rcp_f32_e32 v92, v89
	v_div_fmas_f32 v85, v85, v94, v88
	v_div_fixup_f32 v80, v85, v84, v80
	v_mul_f32_e32 v76, 0xbfb8aa3b, v76
	v_fma_f32 v84, -v89, v92, 1.0
	v_fmac_f32_e32 v92, v84, v92
	v_div_scale_f32 v84, vcc, v83, v87, v83
	v_mul_f32_e32 v85, v84, v92
	v_fma_f32 v88, -v89, v85, v84
	v_fmac_f32_e32 v85, v88, v92
	v_div_scale_f32 v88, s[30:31], v86, v86, v82
	v_fma_f32 v84, -v89, v85, v84
	v_rcp_f32_e32 v89, v88
	v_div_fmas_f32 v84, v84, v92, v85
	v_div_fixup_f32 v83, v84, v87, v83
	v_mul_f32_e32 v77, 0xbfb8aa3b, v77
	v_fma_f32 v84, -v88, v89, 1.0
	v_fmac_f32_e32 v89, v84, v89
	v_div_scale_f32 v84, vcc, v82, v86, v82
	v_mul_f32_e32 v85, v84, v89
	v_fma_f32 v87, -v88, v85, v84
	v_exp_f32_e32 v76, v76
	v_exp_f32_e32 v77, v77
	v_fmac_f32_e32 v85, v87, v89
	v_fma_f32 v84, -v88, v85, v84
	v_div_fmas_f32 v84, v84, v89, v85
	v_div_fixup_f32 v82, v84, v86, v82
	v_pk_add_f32 v[76:77], v[76:77], 1.0 op_sel_hi:[1,0]
	v_cvt_pk_bf16_f32 v80, v80, v81
	v_cvt_pk_bf16_f32 v81, v82, v83
	v_div_scale_f32 v82, s[30:31], v77, v77, v73
	v_rcp_f32_e32 v83, v82
	v_mul_f32_e32 v78, 0xbfb8aa3b, v78
	v_mul_f32_e32 v79, 0xbfb8aa3b, v79
	v_exp_f32_e32 v78, v78
	v_fma_f32 v84, -v82, v83, 1.0
	v_fmac_f32_e32 v83, v84, v83
	v_div_scale_f32 v84, vcc, v73, v77, v73
	v_mul_f32_e32 v85, v84, v83
	v_fma_f32 v86, -v82, v85, v84
	v_fmac_f32_e32 v85, v86, v83
	v_fma_f32 v82, -v82, v85, v84
	v_div_scale_f32 v84, s[30:31], v76, v76, v72
	v_rcp_f32_e32 v86, v84
	v_div_fmas_f32 v82, v82, v83, v85
	v_exp_f32_e32 v79, v79
	v_div_fixup_f32 v73, v82, v77, v73
	v_fma_f32 v77, -v84, v86, 1.0
	v_fmac_f32_e32 v86, v77, v86
	v_div_scale_f32 v77, vcc, v72, v76, v72
	v_mul_f32_e32 v82, v77, v86
	v_fma_f32 v83, -v84, v82, v77
	v_pk_add_f32 v[78:79], v[78:79], 1.0 op_sel_hi:[1,0]
	v_fmac_f32_e32 v82, v83, v86
	v_div_scale_f32 v83, s[30:31], v79, v79, v75
	v_fma_f32 v77, -v84, v82, v77
	v_rcp_f32_e32 v84, v83
	v_div_fmas_f32 v77, v77, v86, v82
	v_div_fixup_f32 v72, v77, v76, v72
	v_mul_f32_e32 v68, 0xbfb8aa3b, v68
	v_fma_f32 v76, -v83, v84, 1.0
	v_fmac_f32_e32 v84, v76, v84
	v_div_scale_f32 v76, vcc, v75, v79, v75
	v_mul_f32_e32 v77, v76, v84
	v_fma_f32 v82, -v83, v77, v76
	v_fmac_f32_e32 v77, v82, v84
	v_div_scale_f32 v82, s[30:31], v78, v78, v74
	v_fma_f32 v76, -v83, v77, v76
	v_rcp_f32_e32 v83, v82
	v_div_fmas_f32 v76, v76, v84, v77
	v_div_fixup_f32 v75, v76, v79, v75
	v_mul_f32_e32 v69, 0xbfb8aa3b, v69
	v_fma_f32 v76, -v82, v83, 1.0
	v_fmac_f32_e32 v83, v76, v83
	v_div_scale_f32 v76, vcc, v74, v78, v74
	v_mul_f32_e32 v77, v76, v83
	v_exp_f32_e32 v68, v68
	v_exp_f32_e32 v69, v69
	v_fma_f32 v79, -v82, v77, v76
	v_fmac_f32_e32 v77, v79, v83
	v_fma_f32 v76, -v82, v77, v76
	v_div_fmas_f32 v76, v76, v83, v77
	v_pk_add_f32 v[68:69], v[68:69], 1.0 op_sel_hi:[1,0]
	global_store_dwordx2 v[90:91], v[80:81], off offset:128
	v_or_b32_e32 v80, 48, v124
	v_div_fixup_f32 v74, v76, v78, v74
	v_div_scale_f32 v76, s[30:31], v69, v69, v65
	v_ashrrev_i32_e32 v81, 31, v80
	v_rcp_f32_e32 v77, v76
	v_lshlrev_b64 v[80:81], 11, v[80:81]
	v_lshl_add_u64 v[80:81], s[46:47], 0, v[80:81]
	v_cvt_pk_bf16_f32 v72, v72, v73
	v_cvt_pk_bf16_f32 v73, v74, v75
	v_lshl_add_u64 v[74:75], v[80:81], 0, v[120:121]
	global_store_dwordx2 v[74:75], v[72:73], off
	v_fma_f32 v72, -v76, v77, 1.0
	v_fmac_f32_e32 v77, v72, v77
	v_div_scale_f32 v72, vcc, v65, v69, v65
	v_mul_f32_e32 v73, v72, v77
	v_fma_f32 v78, -v76, v73, v72
	v_fmac_f32_e32 v73, v78, v77
	v_fma_f32 v72, -v76, v73, v72
	v_div_scale_f32 v76, s[30:31], v68, v68, v64
	v_rcp_f32_e32 v78, v76
	v_mul_f32_e32 v70, 0xbfb8aa3b, v70
	v_mul_f32_e32 v71, 0xbfb8aa3b, v71
	v_div_fmas_f32 v72, v72, v77, v73
	v_exp_f32_e32 v70, v70
	v_exp_f32_e32 v71, v71
	v_div_fixup_f32 v65, v72, v69, v65
	v_fma_f32 v69, -v76, v78, 1.0
	v_fmac_f32_e32 v78, v69, v78
	v_div_scale_f32 v69, vcc, v64, v68, v64
	v_mul_f32_e32 v72, v69, v78
	v_fma_f32 v73, -v76, v72, v69
	v_pk_add_f32 v[70:71], v[70:71], 1.0 op_sel_hi:[1,0]
	v_fmac_f32_e32 v72, v73, v78
	v_div_scale_f32 v73, s[30:31], v71, v71, v67
	v_fma_f32 v69, -v76, v72, v69
	v_rcp_f32_e32 v76, v73
	v_div_fmas_f32 v69, v69, v78, v72
	v_div_fixup_f32 v64, v69, v68, v64
	v_mul_f32_e32 v60, 0xbfb8aa3b, v60
	v_fma_f32 v68, -v73, v76, 1.0
	v_fmac_f32_e32 v76, v68, v76
	v_div_scale_f32 v68, vcc, v67, v71, v67
	v_mul_f32_e32 v69, v68, v76
	v_fma_f32 v72, -v73, v69, v68
	v_fmac_f32_e32 v69, v72, v76
	v_div_scale_f32 v72, s[30:31], v70, v70, v66
	v_fma_f32 v68, -v73, v69, v68
	v_rcp_f32_e32 v73, v72
	v_div_fmas_f32 v68, v68, v76, v69
	v_div_fixup_f32 v67, v68, v71, v67
	v_mul_f32_e32 v61, 0xbfb8aa3b, v61
	v_fma_f32 v68, -v72, v73, 1.0
	v_fmac_f32_e32 v73, v68, v73
	v_div_scale_f32 v68, vcc, v66, v70, v66
	v_mul_f32_e32 v69, v68, v73
	v_exp_f32_e32 v60, v60
	v_exp_f32_e32 v61, v61
	v_fma_f32 v71, -v72, v69, v68
	v_fmac_f32_e32 v69, v71, v73
	v_fma_f32 v68, -v72, v69, v68
	v_div_fmas_f32 v68, v68, v73, v69
	v_pk_add_f32 v[60:61], v[60:61], 1.0 op_sel_hi:[1,0]
	v_div_fixup_f32 v66, v68, v70, v66
	v_div_scale_f32 v68, s[30:31], v61, v61, v57
	v_rcp_f32_e32 v69, v68
	v_cvt_pk_bf16_f32 v64, v64, v65
	v_cvt_pk_bf16_f32 v65, v66, v67
	global_store_dwordx2 v[74:75], v[64:65], off offset:128
	v_fma_f32 v64, -v68, v69, 1.0
	v_fmac_f32_e32 v69, v64, v69
	v_div_scale_f32 v64, vcc, v57, v61, v57
	v_mul_f32_e32 v65, v64, v69
	v_fma_f32 v66, -v68, v65, v64
	v_fmac_f32_e32 v65, v66, v69
	v_div_scale_f32 v66, s[30:31], v60, v60, v56
	v_rcp_f32_e32 v67, v66
	v_fma_f32 v64, -v68, v65, v64
	v_mul_f32_e32 v62, 0xbfb8aa3b, v62
	v_mul_f32_e32 v63, 0xbfb8aa3b, v63
	v_div_fmas_f32 v64, v64, v69, v65
	v_exp_f32_e32 v62, v62
	v_exp_f32_e32 v63, v63
	v_div_fixup_f32 v57, v64, v61, v57
	v_fma_f32 v61, -v66, v67, 1.0
	v_fmac_f32_e32 v67, v61, v67
	v_div_scale_f32 v61, vcc, v56, v60, v56
	v_mul_f32_e32 v64, v61, v67
	v_fma_f32 v65, -v66, v64, v61
	v_pk_add_f32 v[62:63], v[62:63], 1.0 op_sel_hi:[1,0]
	v_fmac_f32_e32 v64, v65, v67
	v_div_scale_f32 v65, s[30:31], v63, v63, v59
	v_fma_f32 v61, -v66, v64, v61
	v_rcp_f32_e32 v66, v65
	v_div_fmas_f32 v61, v61, v67, v64
	v_div_fixup_f32 v56, v61, v60, v56
	v_mul_f32_e32 v52, 0xbfb8aa3b, v52
	v_fma_f32 v60, -v65, v66, 1.0
	v_fmac_f32_e32 v66, v60, v66
	v_div_scale_f32 v60, vcc, v59, v63, v59
	v_mul_f32_e32 v61, v60, v66
	v_fma_f32 v64, -v65, v61, v60
	v_fmac_f32_e32 v61, v64, v66
	v_div_scale_f32 v64, s[30:31], v62, v62, v58
	v_fma_f32 v60, -v65, v61, v60
	v_rcp_f32_e32 v65, v64
	v_div_fmas_f32 v60, v60, v66, v61
	v_div_fixup_f32 v59, v60, v63, v59
	v_mul_f32_e32 v53, 0xbfb8aa3b, v53
	v_fma_f32 v60, -v64, v65, 1.0
	v_fmac_f32_e32 v65, v60, v65
	v_div_scale_f32 v60, vcc, v58, v62, v58
	v_mul_f32_e32 v61, v60, v65
	v_exp_f32_e32 v52, v52
	v_exp_f32_e32 v53, v53
	v_fma_f32 v63, -v64, v61, v60
	v_fmac_f32_e32 v61, v63, v65
	v_fma_f32 v60, -v64, v61, v60
	v_div_fmas_f32 v60, v60, v65, v61
	v_pk_add_f32 v[52:53], v[52:53], 1.0 op_sel_hi:[1,0]
	v_div_fixup_f32 v58, v60, v62, v58
	v_div_scale_f32 v62, s[30:31], v53, v53, v49
	v_rcp_f32_e32 v63, v62
	v_add_co_u32_e32 v60, vcc, s62, v116
	v_cvt_pk_bf16_f32 v56, v56, v57
	v_cvt_pk_bf16_f32 v57, v58, v59
	v_addc_co_u32_e32 v61, vcc, 0, v117, vcc
	global_store_dwordx2 v[60:61], v[56:57], off
	v_fma_f32 v56, -v62, v63, 1.0
	v_fmac_f32_e32 v63, v56, v63
	v_div_scale_f32 v56, vcc, v49, v53, v49
	v_mul_f32_e32 v57, v56, v63
	v_fma_f32 v60, -v62, v57, v56
	v_fmac_f32_e32 v57, v60, v63
	v_div_scale_f32 v60, s[30:31], v52, v52, v48
	v_rcp_f32_e32 v61, v60
	v_fma_f32 v56, -v62, v57, v56
	v_mul_f32_e32 v54, 0xbfb8aa3b, v54
	v_mul_f32_e32 v55, 0xbfb8aa3b, v55
	v_div_fmas_f32 v56, v56, v63, v57
	v_exp_f32_e32 v54, v54
	v_exp_f32_e32 v55, v55
	v_div_fixup_f32 v49, v56, v53, v49
	v_fma_f32 v53, -v60, v61, 1.0
	v_fmac_f32_e32 v61, v53, v61
	v_div_scale_f32 v53, vcc, v48, v52, v48
	v_mul_f32_e32 v56, v53, v61
	v_fma_f32 v57, -v60, v56, v53
	v_pk_add_f32 v[54:55], v[54:55], 1.0 op_sel_hi:[1,0]
	v_fmac_f32_e32 v56, v57, v61
	v_div_scale_f32 v57, s[30:31], v55, v55, v51
	v_fma_f32 v53, -v60, v56, v53
	v_rcp_f32_e32 v60, v57
	v_div_fmas_f32 v53, v53, v61, v56
	v_div_fixup_f32 v48, v53, v52, v48
	v_mul_f32_e32 v44, 0xbfb8aa3b, v44
	v_fma_f32 v52, -v57, v60, 1.0
	v_fmac_f32_e32 v60, v52, v60
	v_div_scale_f32 v52, vcc, v51, v55, v51
	v_mul_f32_e32 v53, v52, v60
	v_fma_f32 v56, -v57, v53, v52
	v_fmac_f32_e32 v53, v56, v60
	v_div_scale_f32 v56, s[30:31], v54, v54, v50
	v_fma_f32 v52, -v57, v53, v52
	v_rcp_f32_e32 v57, v56
	v_div_fmas_f32 v52, v52, v60, v53
	v_div_fixup_f32 v51, v52, v55, v51
	v_mul_f32_e32 v45, 0xbfb8aa3b, v45
	v_fma_f32 v52, -v56, v57, 1.0
	v_fmac_f32_e32 v57, v52, v57
	v_div_scale_f32 v52, vcc, v50, v54, v50
	v_mul_f32_e32 v53, v52, v57
	v_exp_f32_e32 v44, v44
	v_exp_f32_e32 v45, v45
	v_fma_f32 v55, -v56, v53, v52
	v_fmac_f32_e32 v53, v55, v57
	v_fma_f32 v52, -v56, v53, v52
	v_div_fmas_f32 v52, v52, v57, v53
	v_pk_add_f32 v[44:45], v[44:45], 1.0 op_sel_hi:[1,0]
	v_div_fixup_f32 v50, v52, v54, v50
	v_div_scale_f32 v52, s[30:31], v45, v45, v41
	v_rcp_f32_e32 v53, v52
	v_lshl_add_u64 v[58:59], v[116:117], 0, s[6:7]
	v_cvt_pk_bf16_f32 v48, v48, v49
	v_cvt_pk_bf16_f32 v49, v50, v51
	global_store_dwordx2 v[58:59], v[48:49], off offset:128
	v_fma_f32 v48, -v52, v53, 1.0
	v_fmac_f32_e32 v53, v48, v53
	v_div_scale_f32 v48, vcc, v41, v45, v41
	v_mul_f32_e32 v49, v48, v53
	v_fma_f32 v50, -v52, v49, v48
	v_fmac_f32_e32 v49, v50, v53
	v_div_scale_f32 v50, s[30:31], v44, v44, v40
	v_rcp_f32_e32 v51, v50
	v_fma_f32 v48, -v52, v49, v48
	v_mul_f32_e32 v46, 0xbfb8aa3b, v46
	v_mul_f32_e32 v47, 0xbfb8aa3b, v47
	v_div_fmas_f32 v48, v48, v53, v49
	v_exp_f32_e32 v46, v46
	v_exp_f32_e32 v47, v47
	v_div_fixup_f32 v41, v48, v45, v41
	v_fma_f32 v45, -v50, v51, 1.0
	v_fmac_f32_e32 v51, v45, v51
	v_div_scale_f32 v45, vcc, v40, v44, v40
	v_mul_f32_e32 v48, v45, v51
	v_fma_f32 v49, -v50, v48, v45
	v_pk_add_f32 v[46:47], v[46:47], 1.0 op_sel_hi:[1,0]
	v_fmac_f32_e32 v48, v49, v51
	v_div_scale_f32 v49, s[30:31], v47, v47, v43
	v_fma_f32 v45, -v50, v48, v45
	v_rcp_f32_e32 v50, v49
	v_div_fmas_f32 v45, v45, v51, v48
	v_div_fixup_f32 v40, v45, v44, v40
	v_mul_f32_e32 v36, 0xbfb8aa3b, v36
	v_fma_f32 v44, -v49, v50, 1.0
	v_fmac_f32_e32 v50, v44, v50
	v_div_scale_f32 v44, vcc, v43, v47, v43
	v_mul_f32_e32 v45, v44, v50
	v_fma_f32 v48, -v49, v45, v44
	v_fmac_f32_e32 v45, v48, v50
	v_div_scale_f32 v48, s[30:31], v46, v46, v42
	v_fma_f32 v44, -v49, v45, v44
	v_rcp_f32_e32 v49, v48
	v_div_fmas_f32 v44, v44, v50, v45
	v_div_fixup_f32 v43, v44, v47, v43
	v_mul_f32_e32 v37, 0xbfb8aa3b, v37
	v_fma_f32 v44, -v48, v49, 1.0
	v_fmac_f32_e32 v49, v44, v49
	v_div_scale_f32 v44, vcc, v42, v46, v42
	v_mul_f32_e32 v45, v44, v49
	v_exp_f32_e32 v36, v36
	v_exp_f32_e32 v37, v37
	v_fma_f32 v47, -v48, v45, v44
	v_fmac_f32_e32 v45, v47, v49
	v_fma_f32 v44, -v48, v45, v44
	v_div_fmas_f32 v44, v44, v49, v45
	v_pk_add_f32 v[36:37], v[36:37], 1.0 op_sel_hi:[1,0]
	v_div_fixup_f32 v42, v44, v46, v42
	v_div_scale_f32 v46, s[30:31], v37, v37, v33
	v_rcp_f32_e32 v47, v46
	v_add_co_u32_e32 v44, vcc, s63, v116
	v_cvt_pk_bf16_f32 v40, v40, v41
	v_cvt_pk_bf16_f32 v41, v42, v43
	v_addc_co_u32_e32 v45, vcc, 0, v117, vcc
	global_store_dwordx2 v[44:45], v[40:41], off
	v_fma_f32 v40, -v46, v47, 1.0
	v_fmac_f32_e32 v47, v40, v47
	v_div_scale_f32 v40, vcc, v33, v37, v33
	v_mul_f32_e32 v41, v40, v47
	v_fma_f32 v44, -v46, v41, v40
	v_fmac_f32_e32 v41, v44, v47
	v_div_scale_f32 v44, s[30:31], v36, v36, v32
	v_rcp_f32_e32 v45, v44
	v_fma_f32 v40, -v46, v41, v40
	v_mul_f32_e32 v38, 0xbfb8aa3b, v38
	v_mul_f32_e32 v39, 0xbfb8aa3b, v39
	v_div_fmas_f32 v40, v40, v47, v41
	v_exp_f32_e32 v38, v38
	v_exp_f32_e32 v39, v39
	v_div_fixup_f32 v33, v40, v37, v33
	v_fma_f32 v37, -v44, v45, 1.0
	v_fmac_f32_e32 v45, v37, v45
	v_div_scale_f32 v37, vcc, v32, v36, v32
	v_mul_f32_e32 v40, v37, v45
	v_fma_f32 v41, -v44, v40, v37
	v_pk_add_f32 v[38:39], v[38:39], 1.0 op_sel_hi:[1,0]
	v_fmac_f32_e32 v40, v41, v45
	v_div_scale_f32 v41, s[30:31], v39, v39, v35
	v_fma_f32 v37, -v44, v40, v37
	v_rcp_f32_e32 v44, v41
	v_div_fmas_f32 v37, v37, v45, v40
	v_div_fixup_f32 v32, v37, v36, v32
	v_mul_f32_e32 v28, 0xbfb8aa3b, v28
	v_fma_f32 v36, -v41, v44, 1.0
	v_fmac_f32_e32 v44, v36, v44
	v_div_scale_f32 v36, vcc, v35, v39, v35
	v_mul_f32_e32 v37, v36, v44
	v_fma_f32 v40, -v41, v37, v36
	v_fmac_f32_e32 v37, v40, v44
	v_div_scale_f32 v40, s[30:31], v38, v38, v34
	v_fma_f32 v36, -v41, v37, v36
	v_rcp_f32_e32 v41, v40
	v_div_fmas_f32 v36, v36, v44, v37
	v_div_fixup_f32 v35, v36, v39, v35
	v_mul_f32_e32 v29, 0xbfb8aa3b, v29
	v_fma_f32 v36, -v40, v41, 1.0
	v_fmac_f32_e32 v41, v36, v41
	v_div_scale_f32 v36, vcc, v34, v38, v34
	v_mul_f32_e32 v37, v36, v41
	v_exp_f32_e32 v28, v28
	v_exp_f32_e32 v29, v29
	v_fma_f32 v39, -v40, v37, v36
	v_fmac_f32_e32 v37, v39, v41
	v_fma_f32 v36, -v40, v37, v36
	v_div_fmas_f32 v36, v36, v41, v37
	v_pk_add_f32 v[28:29], v[28:29], 1.0 op_sel_hi:[1,0]
	v_div_fixup_f32 v34, v36, v38, v34
	v_div_scale_f32 v36, s[30:31], v29, v29, v25
	v_rcp_f32_e32 v37, v36
	v_lshl_add_u64 v[42:43], v[116:117], 0, s[10:11]
	v_cvt_pk_bf16_f32 v32, v32, v33
	v_cvt_pk_bf16_f32 v33, v34, v35
	global_store_dwordx2 v[42:43], v[32:33], off offset:128
	v_fma_f32 v32, -v36, v37, 1.0
	v_fmac_f32_e32 v37, v32, v37
	v_div_scale_f32 v32, vcc, v25, v29, v25
	v_mul_f32_e32 v33, v32, v37
	v_fma_f32 v34, -v36, v33, v32
	v_fmac_f32_e32 v33, v34, v37
	v_div_scale_f32 v34, s[30:31], v28, v28, v24
	v_rcp_f32_e32 v35, v34
	v_fma_f32 v32, -v36, v33, v32
	v_mul_f32_e32 v30, 0xbfb8aa3b, v30
	v_mul_f32_e32 v31, 0xbfb8aa3b, v31
	v_div_fmas_f32 v32, v32, v37, v33
	v_exp_f32_e32 v30, v30
	v_exp_f32_e32 v31, v31
	v_div_fixup_f32 v25, v32, v29, v25
	v_fma_f32 v29, -v34, v35, 1.0
	v_fmac_f32_e32 v35, v29, v35
	v_div_scale_f32 v29, vcc, v24, v28, v24
	v_mul_f32_e32 v32, v29, v35
	v_fma_f32 v33, -v34, v32, v29
	v_pk_add_f32 v[30:31], v[30:31], 1.0 op_sel_hi:[1,0]
	v_fmac_f32_e32 v32, v33, v35
	v_div_scale_f32 v33, s[30:31], v31, v31, v27
	v_fma_f32 v29, -v34, v32, v29
	v_rcp_f32_e32 v34, v33
	v_div_fmas_f32 v29, v29, v35, v32
	v_div_fixup_f32 v24, v29, v28, v24
	v_mul_f32_e32 v20, 0xbfb8aa3b, v20
	v_fma_f32 v28, -v33, v34, 1.0
	v_fmac_f32_e32 v34, v28, v34
	v_div_scale_f32 v28, vcc, v27, v31, v27
	v_mul_f32_e32 v29, v28, v34
	v_fma_f32 v32, -v33, v29, v28
	v_fmac_f32_e32 v29, v32, v34
	v_div_scale_f32 v32, s[30:31], v30, v30, v26
	v_fma_f32 v28, -v33, v29, v28
	v_rcp_f32_e32 v33, v32
	v_div_fmas_f32 v28, v28, v34, v29
	v_div_fixup_f32 v27, v28, v31, v27
	v_mul_f32_e32 v21, 0xbfb8aa3b, v21
	v_fma_f32 v28, -v32, v33, 1.0
	v_fmac_f32_e32 v33, v28, v33
	v_div_scale_f32 v28, vcc, v26, v30, v26
	v_mul_f32_e32 v29, v28, v33
	v_exp_f32_e32 v20, v20
	v_exp_f32_e32 v21, v21
	v_fma_f32 v31, -v32, v29, v28
	v_fmac_f32_e32 v29, v31, v33
	v_fma_f32 v28, -v32, v29, v28
	v_div_fmas_f32 v28, v28, v33, v29
	v_pk_add_f32 v[20:21], v[20:21], 1.0 op_sel_hi:[1,0]
	v_div_fixup_f32 v26, v28, v30, v26
	v_div_scale_f32 v30, s[30:31], v21, v21, v17
	v_rcp_f32_e32 v31, v30
	v_add_co_u32_e32 v28, vcc, s70, v116
	v_cvt_pk_bf16_f32 v24, v24, v25
	v_cvt_pk_bf16_f32 v25, v26, v27
	v_addc_co_u32_e32 v29, vcc, 0, v117, vcc
	global_store_dwordx2 v[28:29], v[24:25], off
	v_fma_f32 v24, -v30, v31, 1.0
	v_fmac_f32_e32 v31, v24, v31
	v_div_scale_f32 v24, vcc, v17, v21, v17
	v_mul_f32_e32 v25, v24, v31
	v_fma_f32 v28, -v30, v25, v24
	v_fmac_f32_e32 v25, v28, v31
	v_div_scale_f32 v28, s[30:31], v20, v20, v16
	v_rcp_f32_e32 v29, v28
	v_fma_f32 v24, -v30, v25, v24
	v_mul_f32_e32 v22, 0xbfb8aa3b, v22
	v_mul_f32_e32 v23, 0xbfb8aa3b, v23
	v_div_fmas_f32 v24, v24, v31, v25
	v_exp_f32_e32 v22, v22
	v_exp_f32_e32 v23, v23
	v_div_fixup_f32 v17, v24, v21, v17
	v_fma_f32 v21, -v28, v29, 1.0
	v_fmac_f32_e32 v29, v21, v29
	v_div_scale_f32 v21, vcc, v16, v20, v16
	v_mul_f32_e32 v24, v21, v29
	v_fma_f32 v25, -v28, v24, v21
	v_pk_add_f32 v[22:23], v[22:23], 1.0 op_sel_hi:[1,0]
	v_fmac_f32_e32 v24, v25, v29
	v_div_scale_f32 v25, s[30:31], v23, v23, v19
	v_fma_f32 v21, -v28, v24, v21
	v_rcp_f32_e32 v28, v25
	v_div_fmas_f32 v21, v21, v29, v24
	v_div_fixup_f32 v16, v21, v20, v16
	v_mul_f32_e32 v12, 0xbfb8aa3b, v12
	v_fma_f32 v20, -v25, v28, 1.0
	v_fmac_f32_e32 v28, v20, v28
	v_div_scale_f32 v20, vcc, v19, v23, v19
	v_mul_f32_e32 v21, v20, v28
	v_fma_f32 v24, -v25, v21, v20
	v_fmac_f32_e32 v21, v24, v28
	v_div_scale_f32 v24, s[30:31], v22, v22, v18
	v_fma_f32 v20, -v25, v21, v20
	v_rcp_f32_e32 v25, v24
	v_div_fmas_f32 v20, v20, v28, v21
	v_div_fixup_f32 v19, v20, v23, v19
	v_mul_f32_e32 v13, 0xbfb8aa3b, v13
	v_fma_f32 v20, -v24, v25, 1.0
	v_fmac_f32_e32 v25, v20, v25
	v_div_scale_f32 v20, vcc, v18, v22, v18
	v_mul_f32_e32 v21, v20, v25
	v_exp_f32_e32 v12, v12
	v_exp_f32_e32 v13, v13
	v_fma_f32 v23, -v24, v21, v20
	v_fmac_f32_e32 v21, v23, v25
	v_fma_f32 v20, -v24, v21, v20
	v_div_fmas_f32 v20, v20, v25, v21
	v_pk_add_f32 v[12:13], v[12:13], 1.0 op_sel_hi:[1,0]
	v_div_fixup_f32 v18, v20, v22, v18
	v_div_scale_f32 v20, s[30:31], v13, v13, v9
	v_rcp_f32_e32 v21, v20
	v_lshl_add_u64 v[26:27], v[116:117], 0, s[12:13]
	v_cvt_pk_bf16_f32 v16, v16, v17
	v_cvt_pk_bf16_f32 v17, v18, v19
	global_store_dwordx2 v[26:27], v[16:17], off offset:128
	v_fma_f32 v16, -v20, v21, 1.0
	v_fmac_f32_e32 v21, v16, v21
	v_div_scale_f32 v16, vcc, v9, v13, v9
	v_mul_f32_e32 v17, v16, v21
	v_fma_f32 v18, -v20, v17, v16
	v_fmac_f32_e32 v17, v18, v21
	v_div_scale_f32 v18, s[30:31], v12, v12, v8
	v_rcp_f32_e32 v19, v18
	v_fma_f32 v16, -v20, v17, v16
	v_mul_f32_e32 v14, 0xbfb8aa3b, v14
	v_mul_f32_e32 v15, 0xbfb8aa3b, v15
	v_div_fmas_f32 v16, v16, v21, v17
	v_exp_f32_e32 v14, v14
	v_exp_f32_e32 v15, v15
	v_div_fixup_f32 v9, v16, v13, v9
	v_fma_f32 v13, -v18, v19, 1.0
	v_fmac_f32_e32 v19, v13, v19
	v_div_scale_f32 v13, vcc, v8, v12, v8
	v_mul_f32_e32 v16, v13, v19
	v_fma_f32 v17, -v18, v16, v13
	v_pk_add_f32 v[14:15], v[14:15], 1.0 op_sel_hi:[1,0]
	v_fmac_f32_e32 v16, v17, v19
	v_div_scale_f32 v17, s[30:31], v15, v15, v11
	v_fma_f32 v13, -v18, v16, v13
	v_rcp_f32_e32 v18, v17
	v_div_fmas_f32 v13, v13, v19, v16
	v_div_fixup_f32 v8, v13, v12, v8
	v_mul_f32_e32 v4, 0xbfb8aa3b, v4
	v_fma_f32 v12, -v17, v18, 1.0
	v_fmac_f32_e32 v18, v12, v18
	v_div_scale_f32 v12, vcc, v11, v15, v11
	v_mul_f32_e32 v13, v12, v18
	v_fma_f32 v16, -v17, v13, v12
	v_fmac_f32_e32 v13, v16, v18
	v_div_scale_f32 v16, s[30:31], v14, v14, v10
	v_fma_f32 v12, -v17, v13, v12
	v_rcp_f32_e32 v17, v16
	v_div_fmas_f32 v12, v12, v18, v13
	v_div_fixup_f32 v11, v12, v15, v11
	v_mul_f32_e32 v5, 0xbfb8aa3b, v5
	v_fma_f32 v12, -v16, v17, 1.0
	v_fmac_f32_e32 v17, v12, v17
	v_div_scale_f32 v12, vcc, v10, v14, v10
	v_mul_f32_e32 v13, v12, v17
	v_exp_f32_e32 v4, v4
	v_exp_f32_e32 v5, v5
	v_fma_f32 v15, -v16, v13, v12
	v_fmac_f32_e32 v13, v15, v17
	v_fma_f32 v12, -v16, v13, v12
	v_div_fmas_f32 v12, v12, v17, v13
	v_pk_add_f32 v[4:5], v[4:5], 1.0 op_sel_hi:[1,0]
	v_div_fixup_f32 v10, v12, v14, v10
	v_div_scale_f32 v14, s[30:31], v5, v5, v1
	v_rcp_f32_e32 v15, v14
	v_add_co_u32_e32 v12, vcc, s71, v116
	v_cvt_pk_bf16_f32 v8, v8, v9
	v_cvt_pk_bf16_f32 v9, v10, v11
	v_addc_co_u32_e32 v13, vcc, 0, v117, vcc
	global_store_dwordx2 v[12:13], v[8:9], off
	v_fma_f32 v8, -v14, v15, 1.0
	v_fmac_f32_e32 v15, v8, v15
	v_div_scale_f32 v8, vcc, v1, v5, v1
	v_mul_f32_e32 v9, v8, v15
	v_fma_f32 v12, -v14, v9, v8
	v_fmac_f32_e32 v9, v12, v15
	v_div_scale_f32 v12, s[30:31], v4, v4, v0
	v_rcp_f32_e32 v13, v12
	v_fma_f32 v8, -v14, v9, v8
	v_mul_f32_e32 v6, 0xbfb8aa3b, v6
	v_mul_f32_e32 v7, 0xbfb8aa3b, v7
	v_div_fmas_f32 v8, v8, v15, v9
	v_exp_f32_e32 v6, v6
	v_exp_f32_e32 v7, v7
	v_div_fixup_f32 v1, v8, v5, v1
	v_fma_f32 v5, -v12, v13, 1.0
	v_fmac_f32_e32 v13, v5, v13
	v_div_scale_f32 v5, vcc, v0, v4, v0
	v_mul_f32_e32 v8, v5, v13
	v_fma_f32 v9, -v12, v8, v5
	v_pk_add_f32 v[6:7], v[6:7], 1.0 op_sel_hi:[1,0]
	v_fmac_f32_e32 v8, v9, v13
	v_div_scale_f32 v9, s[30:31], v7, v7, v3
	v_fma_f32 v5, -v12, v8, v5
	v_rcp_f32_e32 v12, v9
	v_div_fmas_f32 v5, v5, v13, v8
	v_div_fixup_f32 v0, v5, v4, v0
	v_lshl_add_u64 v[10:11], v[116:117], 0, s[14:15]
	v_fma_f32 v4, -v9, v12, 1.0
	v_fmac_f32_e32 v12, v4, v12
	v_div_scale_f32 v4, vcc, v3, v7, v3
	v_mul_f32_e32 v5, v4, v12
	v_fma_f32 v8, -v9, v5, v4
	v_fmac_f32_e32 v5, v8, v12
	v_div_scale_f32 v8, s[30:31], v6, v6, v2
	v_fma_f32 v4, -v9, v5, v4
	v_rcp_f32_e32 v9, v8
	v_div_fmas_f32 v4, v4, v12, v5
	v_div_fixup_f32 v3, v4, v7, v3
	v_cvt_pk_bf16_f32 v0, v0, v1
	v_fma_f32 v4, -v8, v9, 1.0
	v_fmac_f32_e32 v9, v4, v9
	v_div_scale_f32 v4, vcc, v2, v6, v2
	v_mul_f32_e32 v5, v4, v9
	v_fma_f32 v7, -v8, v5, v4
	v_fmac_f32_e32 v5, v7, v9
	v_fma_f32 v4, -v8, v5, v4
	v_div_fmas_f32 v4, v4, v9, v5
	v_div_fixup_f32 v2, v4, v6, v2
	v_cvt_pk_bf16_f32 v1, v2, v3
	s_and_b64 vcc, exec, s[4:5]
	s_mov_b32 s72, s16
	s_mov_b32 s28, s18
	s_mov_b64 s[34:35], s[26:27]
	s_mov_b64 s[30:31], s[20:21]
	global_store_dwordx2 v[10:11], v[0:1], off offset:128
	s_cbranch_vccz .LBB0_1109
	s_waitcnt vmcnt(0)
	s_cmpk_gt_u32 s40, 0xff
	s_cbranch_scc1 .LBB0_1120
	s_barrier

.LBB0_1141:
	ds_read_b128 v[150:153], v145
	ds_read_b128 v[154:157], v145 offset:1024
	ds_read_b128 v[158:161], v145 offset:2048
	ds_read_b128 v[162:165], v145 offset:3072
	s_add_u32 s34, s30, 0xfffc0080
	s_addc_u32 s35, s31, -1
	s_cmp_eq_u32 s77, 12
	s_cselect_b32 s37, s19, s35
	s_cselect_b32 s36, s73, s34
	s_cselect_b32 s35, s17, s76
	s_cselect_b32 s34, s74, s75
	v_lshl_add_u64 v[198:199], s[30:31], 0, v[134:135]
	s_add_i32 m0, s29, 0xc000
	ds_read_b128 v[166:169], v148
	ds_read_b128 v[170:173], v148 offset:1024
	ds_read_b128 v[174:177], v148 offset:2048
	ds_read_b128 v[178:181], v148 offset:3072
	ds_read_b128 v[182:185], v148 offset:4096
	ds_read_b128 v[186:189], v148 offset:5120
	ds_read_b128 v[190:193], v148 offset:6144
	ds_read_b128 v[194:197], v148 offset:7168
	global_load_lds_dwordx4 v[198:199], off
	v_lshl_add_u64 v[198:199], s[30:31], 0, v[136:137]
	s_add_i32 m0, s29, 0xe000
	s_nop 0
	global_load_lds_dwordx4 v[198:199], off
	s_waitcnt lgkmcnt(8)
	s_barrier
	s_waitcnt lgkmcnt(0)
	s_waitcnt lgkmcnt(0)
	v_mfma_f32_16x16x32_bf16 v[120:123], v[150:153], v[166:169], v[120:123]
	v_mfma_f32_16x16x32_bf16 v[124:127], v[158:161], v[166:169], v[124:127]
	v_mfma_f32_16x16x32_bf16 v[104:107], v[150:153], v[174:177], v[104:107]
	v_mfma_f32_16x16x32_bf16 v[108:111], v[158:161], v[174:177], v[108:111]
	v_mfma_f32_16x16x32_bf16 v[88:91], v[150:153], v[182:185], v[88:91]
	v_mfma_f32_16x16x32_bf16 v[92:95], v[158:161], v[182:185], v[92:95]
	v_mfma_f32_16x16x32_bf16 v[72:75], v[150:153], v[190:193], v[72:75]
	v_mfma_f32_16x16x32_bf16 v[76:79], v[158:161], v[190:193], v[76:79]
	v_mfma_f32_16x16x32_bf16 v[120:123], v[154:157], v[170:173], v[120:123]
	v_mfma_f32_16x16x32_bf16 v[124:127], v[162:165], v[170:173], v[124:127]
	v_mfma_f32_16x16x32_bf16 v[104:107], v[154:157], v[178:181], v[104:107]
	v_mfma_f32_16x16x32_bf16 v[108:111], v[162:165], v[178:181], v[108:111]
	v_mfma_f32_16x16x32_bf16 v[88:91], v[154:157], v[186:189], v[88:91]
	v_mfma_f32_16x16x32_bf16 v[92:95], v[162:165], v[186:189], v[92:95]
	v_mfma_f32_16x16x32_bf16 v[72:75], v[154:157], v[194:197], v[72:75]
	v_mfma_f32_16x16x32_bf16 v[76:79], v[162:165], v[194:197], v[76:79]
	s_barrier
	s_add_i32 s78, s60, s42
	v_lshl_add_u64 v[214:215], s[34:35], 0, v[130:131]
	s_mov_b32 m0, s78
	ds_read_b128 v[198:201], v149
	ds_read_b128 v[202:205], v149 offset:1024
	ds_read_b128 v[206:209], v149 offset:2048
	ds_read_b128 v[210:213], v149 offset:3072
	global_load_lds_dwordx4 v[214:215], off
	v_lshl_add_u64 v[216:217], s[34:35], 0, v[132:133]
	s_add_i32 m0, s78, 0x2000
	s_nop 0
	global_load_lds_dwordx4 v[216:217], off
	s_barrier
	s_waitcnt lgkmcnt(0)
	s_waitcnt lgkmcnt(0)
	v_mfma_f32_16x16x32_bf16 v[112:115], v[198:201], v[166:169], v[112:115]
	v_mfma_f32_16x16x32_bf16 v[116:119], v[206:209], v[166:169], v[116:119]
	v_mfma_f32_16x16x32_bf16 v[96:99], v[198:201], v[174:177], v[96:99]
	v_mfma_f32_16x16x32_bf16 v[100:103], v[206:209], v[174:177], v[100:103]
	v_mfma_f32_16x16x32_bf16 v[80:83], v[198:201], v[182:185], v[80:83]
	v_mfma_f32_16x16x32_bf16 v[84:87], v[206:209], v[182:185], v[84:87]
	v_mfma_f32_16x16x32_bf16 v[64:67], v[198:201], v[190:193], v[64:67]
	v_mfma_f32_16x16x32_bf16 v[68:71], v[206:209], v[190:193], v[68:71]
	v_mfma_f32_16x16x32_bf16 v[112:115], v[202:205], v[170:173], v[112:115]
	v_mfma_f32_16x16x32_bf16 v[116:119], v[210:213], v[170:173], v[116:119]
	v_mfma_f32_16x16x32_bf16 v[96:99], v[202:205], v[178:181], v[96:99]
	v_mfma_f32_16x16x32_bf16 v[100:103], v[210:213], v[178:181], v[100:103]
	v_mfma_f32_16x16x32_bf16 v[80:83], v[202:205], v[186:189], v[80:83]
	v_mfma_f32_16x16x32_bf16 v[84:87], v[210:213], v[186:189], v[84:87]
	v_mfma_f32_16x16x32_bf16 v[64:67], v[202:205], v[194:197], v[64:67]
	v_mfma_f32_16x16x32_bf16 v[68:71], v[210:213], v[194:197], v[68:71]
	s_mov_b32 m0, s29
	v_lshl_add_u64 v[218:219], s[36:37], 0, v[130:131]
	s_barrier
	ds_read_b128 v[166:169], v148 offset:16384
	ds_read_b128 v[170:173], v148 offset:17408
	ds_read_b128 v[174:177], v148 offset:18432
	ds_read_b128 v[178:181], v148 offset:19456
	ds_read_b128 v[182:185], v148 offset:20480
	ds_read_b128 v[186:189], v148 offset:21504
	ds_read_b128 v[190:193], v148 offset:22528
	ds_read_b128 v[194:197], v148 offset:23552
	global_load_lds_dwordx4 v[218:219], off
	v_lshl_add_u64 v[220:221], s[36:37], 0, v[132:133]
	s_mov_b32 m0, s43
	s_nop 0
	global_load_lds_dwordx4 v[220:221], off
	s_barrier
	s_waitcnt lgkmcnt(0)
	s_waitcnt lgkmcnt(0)
	v_mfma_f32_16x16x32_bf16 v[56:59], v[150:153], v[166:169], v[56:59]
	v_mfma_f32_16x16x32_bf16 v[60:63], v[158:161], v[166:169], v[60:63]
	v_mfma_f32_16x16x32_bf16 v[40:43], v[150:153], v[174:177], v[40:43]
	v_mfma_f32_16x16x32_bf16 v[44:47], v[158:161], v[174:177], v[44:47]
	v_mfma_f32_16x16x32_bf16 v[24:27], v[150:153], v[182:185], v[24:27]
	v_mfma_f32_16x16x32_bf16 v[28:31], v[158:161], v[182:185], v[28:31]
	v_mfma_f32_16x16x32_bf16 v[8:11], v[150:153], v[190:193], v[8:11]
	v_mfma_f32_16x16x32_bf16 v[12:15], v[158:161], v[190:193], v[12:15]
	v_mfma_f32_16x16x32_bf16 v[56:59], v[154:157], v[170:173], v[56:59]
	v_mfma_f32_16x16x32_bf16 v[60:63], v[162:165], v[170:173], v[60:63]
	v_mfma_f32_16x16x32_bf16 v[40:43], v[154:157], v[178:181], v[40:43]
	v_mfma_f32_16x16x32_bf16 v[44:47], v[162:165], v[178:181], v[44:47]
	v_mfma_f32_16x16x32_bf16 v[24:27], v[154:157], v[186:189], v[24:27]
	v_mfma_f32_16x16x32_bf16 v[28:31], v[162:165], v[186:189], v[28:31]
	v_mfma_f32_16x16x32_bf16 v[8:11], v[154:157], v[194:197], v[8:11]
	v_mfma_f32_16x16x32_bf16 v[12:15], v[162:165], v[194:197], v[12:15]
	s_barrier
	s_add_u32 s78, s34, 0x40000
	s_addc_u32 s79, s35, 0
	s_add_i32 s80, s61, s42
	v_lshl_add_u64 v[150:151], s[78:79], 0, v[130:131]
	s_mov_b32 m0, s80
	s_nop 0
	global_load_lds_dwordx4 v[150:151], off
	v_lshl_add_u64 v[150:151], s[78:79], 0, v[132:133]
	s_add_i32 m0, s80, 0x2000
	s_nop 0
	global_load_lds_dwordx4 v[150:151], off
	s_waitcnt vmcnt(6)
	s_barrier
	v_mfma_f32_16x16x32_bf16 v[48:51], v[198:201], v[166:169], v[48:51]
	v_mfma_f32_16x16x32_bf16 v[52:55], v[206:209], v[166:169], v[52:55]
	v_mfma_f32_16x16x32_bf16 v[32:35], v[198:201], v[174:177], v[32:35]
	v_mfma_f32_16x16x32_bf16 v[36:39], v[206:209], v[174:177], v[36:39]
	v_mfma_f32_16x16x32_bf16 v[16:19], v[198:201], v[182:185], v[16:19]
	v_mfma_f32_16x16x32_bf16 v[20:23], v[206:209], v[182:185], v[20:23]
	v_mfma_f32_16x16x32_bf16 v[0:3], v[198:201], v[190:193], v[0:3]
	v_mfma_f32_16x16x32_bf16 v[4:7], v[206:209], v[190:193], v[4:7]
	v_mfma_f32_16x16x32_bf16 v[48:51], v[202:205], v[170:173], v[48:51]
	v_mfma_f32_16x16x32_bf16 v[52:55], v[210:213], v[170:173], v[52:55]
	v_mfma_f32_16x16x32_bf16 v[32:35], v[202:205], v[178:181], v[32:35]
	v_mfma_f32_16x16x32_bf16 v[36:39], v[210:213], v[178:181], v[36:39]
	v_mfma_f32_16x16x32_bf16 v[16:19], v[202:205], v[186:189], v[16:19]
	v_mfma_f32_16x16x32_bf16 v[20:23], v[210:213], v[186:189], v[20:23]
	v_mfma_f32_16x16x32_bf16 v[0:3], v[202:205], v[194:197], v[0:3]
	v_mfma_f32_16x16x32_bf16 v[4:7], v[210:213], v[194:197], v[4:7]
	s_add_i32 s78, 0, 0x18000
	v_add_u32_e32 v162, s78, v143
	s_barrier
	ds_read_b128 v[150:153], v162
	ds_read_b128 v[154:157], v162 offset:1024
	ds_read_b128 v[158:161], v162 offset:2048
	ds_read_b128 v[162:165], v162 offset:3072
	s_add_u32 s36, s36, 0x40000
	s_addc_u32 s37, s37, 0
	s_mov_b32 m0, s52
	v_lshl_add_u64 v[198:199], s[36:37], 0, v[130:131]
	ds_read_b128 v[166:169], v148 offset:32768
	ds_read_b128 v[170:173], v148 offset:33792
	ds_read_b128 v[174:177], v148 offset:34816
	ds_read_b128 v[178:181], v148 offset:35840
	ds_read_b128 v[182:185], v148 offset:36864
	ds_read_b128 v[186:189], v148 offset:37888
	ds_read_b128 v[190:193], v148 offset:38912
	ds_read_b128 v[194:197], v148 offset:39936
	global_load_lds_dwordx4 v[198:199], off
	v_lshl_add_u64 v[198:199], s[36:37], 0, v[132:133]
	s_mov_b32 m0, s53
	s_nop 0
	global_load_lds_dwordx4 v[198:199], off
	s_waitcnt lgkmcnt(8)
	s_barrier
	s_waitcnt lgkmcnt(0)
	s_waitcnt lgkmcnt(0)
	v_mfma_f32_16x16x32_bf16 v[120:123], v[150:153], v[166:169], v[120:123]
	v_mfma_f32_16x16x32_bf16 v[124:127], v[158:161], v[166:169], v[124:127]
	v_mfma_f32_16x16x32_bf16 v[104:107], v[150:153], v[174:177], v[104:107]
	v_mfma_f32_16x16x32_bf16 v[108:111], v[158:161], v[174:177], v[108:111]
	v_mfma_f32_16x16x32_bf16 v[88:91], v[150:153], v[182:185], v[88:91]
	v_mfma_f32_16x16x32_bf16 v[92:95], v[158:161], v[182:185], v[92:95]
	v_mfma_f32_16x16x32_bf16 v[72:75], v[150:153], v[190:193], v[72:75]
	v_mfma_f32_16x16x32_bf16 v[76:79], v[158:161], v[190:193], v[76:79]
	v_mfma_f32_16x16x32_bf16 v[120:123], v[154:157], v[170:173], v[120:123]
	v_mfma_f32_16x16x32_bf16 v[124:127], v[162:165], v[170:173], v[124:127]
	v_mfma_f32_16x16x32_bf16 v[104:107], v[154:157], v[178:181], v[104:107]
	v_mfma_f32_16x16x32_bf16 v[108:111], v[162:165], v[178:181], v[108:111]
	v_mfma_f32_16x16x32_bf16 v[88:91], v[154:157], v[186:189], v[88:91]
	v_mfma_f32_16x16x32_bf16 v[92:95], v[162:165], v[186:189], v[92:95]
	v_mfma_f32_16x16x32_bf16 v[72:75], v[154:157], v[194:197], v[72:75]
	v_mfma_f32_16x16x32_bf16 v[76:79], v[162:165], v[194:197], v[76:79]
	s_barrier
	s_add_i32 s36, 0, 0x1c000
	s_add_i32 s37, s78, s42
	v_add_u32_e32 v210, s36, v143
	v_lshl_add_u64 v[214:215], v[214:215], 0, s[8:9]
	s_mov_b32 m0, s37
	ds_read_b128 v[198:201], v210
	ds_read_b128 v[202:205], v210 offset:1024
	ds_read_b128 v[206:209], v210 offset:2048
	ds_read_b128 v[210:213], v210 offset:3072
	global_load_lds_dwordx4 v[214:215], off
	v_lshl_add_u64 v[214:215], v[216:217], 0, s[8:9]
	s_add_i32 m0, s37, 0x2000
	s_nop 0
	global_load_lds_dwordx4 v[214:215], off
	s_barrier
	s_waitcnt lgkmcnt(0)
	s_waitcnt lgkmcnt(0)
	v_mfma_f32_16x16x32_bf16 v[112:115], v[198:201], v[166:169], v[112:115]
	v_mfma_f32_16x16x32_bf16 v[116:119], v[206:209], v[166:169], v[116:119]
	v_mfma_f32_16x16x32_bf16 v[96:99], v[198:201], v[174:177], v[96:99]
	v_mfma_f32_16x16x32_bf16 v[100:103], v[206:209], v[174:177], v[100:103]
	v_mfma_f32_16x16x32_bf16 v[80:83], v[198:201], v[182:185], v[80:83]
	v_mfma_f32_16x16x32_bf16 v[84:87], v[206:209], v[182:185], v[84:87]
	v_mfma_f32_16x16x32_bf16 v[64:67], v[198:201], v[190:193], v[64:67]
	v_mfma_f32_16x16x32_bf16 v[68:71], v[206:209], v[190:193], v[68:71]
	v_mfma_f32_16x16x32_bf16 v[112:115], v[202:205], v[170:173], v[112:115]
	v_mfma_f32_16x16x32_bf16 v[116:119], v[210:213], v[170:173], v[116:119]
	v_mfma_f32_16x16x32_bf16 v[96:99], v[202:205], v[178:181], v[96:99]
	v_mfma_f32_16x16x32_bf16 v[100:103], v[210:213], v[178:181], v[100:103]
	v_mfma_f32_16x16x32_bf16 v[80:83], v[202:205], v[186:189], v[80:83]
	v_mfma_f32_16x16x32_bf16 v[84:87], v[210:213], v[186:189], v[84:87]
	v_mfma_f32_16x16x32_bf16 v[64:67], v[202:205], v[194:197], v[64:67]
	v_mfma_f32_16x16x32_bf16 v[68:71], v[210:213], v[194:197], v[68:71]
	s_mov_b32 m0, s55
	v_lshl_add_u64 v[214:215], v[218:219], 0, s[8:9]
	s_barrier
	ds_read_b128 v[166:169], v148 offset:49152
	ds_read_b128 v[170:173], v148 offset:50176
	ds_read_b128 v[174:177], v148 offset:51200
	ds_read_b128 v[178:181], v148 offset:52224
	ds_read_b128 v[182:185], v148 offset:53248
	ds_read_b128 v[186:189], v148 offset:54272
	ds_read_b128 v[190:193], v148 offset:55296
	ds_read_b128 v[194:197], v148 offset:56320
	global_load_lds_dwordx4 v[214:215], off
	v_lshl_add_u64 v[214:215], v[220:221], 0, s[8:9]
	s_mov_b32 m0, s56
	s_nop 0
	global_load_lds_dwordx4 v[214:215], off
	s_barrier
	s_waitcnt lgkmcnt(0)
	s_waitcnt lgkmcnt(0)
	v_mfma_f32_16x16x32_bf16 v[56:59], v[150:153], v[166:169], v[56:59]
	v_mfma_f32_16x16x32_bf16 v[60:63], v[158:161], v[166:169], v[60:63]
	v_mfma_f32_16x16x32_bf16 v[40:43], v[150:153], v[174:177], v[40:43]
	v_mfma_f32_16x16x32_bf16 v[44:47], v[158:161], v[174:177], v[44:47]
	v_mfma_f32_16x16x32_bf16 v[24:27], v[150:153], v[182:185], v[24:27]
	v_mfma_f32_16x16x32_bf16 v[28:31], v[158:161], v[182:185], v[28:31]
	v_mfma_f32_16x16x32_bf16 v[8:11], v[150:153], v[190:193], v[8:11]
	v_mfma_f32_16x16x32_bf16 v[12:15], v[158:161], v[190:193], v[12:15]
	v_mfma_f32_16x16x32_bf16 v[56:59], v[154:157], v[170:173], v[56:59]
	v_mfma_f32_16x16x32_bf16 v[60:63], v[162:165], v[170:173], v[60:63]
	v_mfma_f32_16x16x32_bf16 v[40:43], v[154:157], v[178:181], v[40:43]
	v_mfma_f32_16x16x32_bf16 v[44:47], v[162:165], v[178:181], v[44:47]
	v_mfma_f32_16x16x32_bf16 v[24:27], v[154:157], v[186:189], v[24:27]
	v_mfma_f32_16x16x32_bf16 v[28:31], v[162:165], v[186:189], v[28:31]
	v_mfma_f32_16x16x32_bf16 v[8:11], v[154:157], v[194:197], v[8:11]
	v_mfma_f32_16x16x32_bf16 v[12:15], v[162:165], v[194:197], v[12:15]
	s_barrier
	s_add_u32 s34, s34, 0x40080
	s_addc_u32 s35, s35, 0
	s_add_i32 s36, s36, s42
	v_lshl_add_u64 v[150:151], s[34:35], 0, v[130:131]
	s_mov_b32 m0, s36
	s_nop 0
	global_load_lds_dwordx4 v[150:151], off
	v_lshl_add_u64 v[150:151], s[34:35], 0, v[132:133]
	s_add_i32 m0, s36, 0x2000
	s_nop 0
	global_load_lds_dwordx4 v[150:151], off
	s_waitcnt vmcnt(6)
	s_barrier
	v_mfma_f32_16x16x32_bf16 v[48:51], v[198:201], v[166:169], v[48:51]
	v_mfma_f32_16x16x32_bf16 v[52:55], v[206:209], v[166:169], v[52:55]
	v_mfma_f32_16x16x32_bf16 v[32:35], v[198:201], v[174:177], v[32:35]
	v_mfma_f32_16x16x32_bf16 v[36:39], v[206:209], v[174:177], v[36:39]
	v_mfma_f32_16x16x32_bf16 v[16:19], v[198:201], v[182:185], v[16:19]
	v_mfma_f32_16x16x32_bf16 v[20:23], v[206:209], v[182:185], v[20:23]
	v_mfma_f32_16x16x32_bf16 v[0:3], v[198:201], v[190:193], v[0:3]
	v_mfma_f32_16x16x32_bf16 v[4:7], v[206:209], v[190:193], v[4:7]
	v_mfma_f32_16x16x32_bf16 v[48:51], v[202:205], v[170:173], v[48:51]
	v_mfma_f32_16x16x32_bf16 v[52:55], v[210:213], v[170:173], v[52:55]
	v_mfma_f32_16x16x32_bf16 v[32:35], v[202:205], v[178:181], v[32:35]
	v_mfma_f32_16x16x32_bf16 v[36:39], v[210:213], v[178:181], v[36:39]
	v_mfma_f32_16x16x32_bf16 v[16:19], v[202:205], v[186:189], v[16:19]
	v_mfma_f32_16x16x32_bf16 v[20:23], v[210:213], v[186:189], v[20:23]
	v_mfma_f32_16x16x32_bf16 v[0:3], v[202:205], v[194:197], v[0:3]
	v_mfma_f32_16x16x32_bf16 v[4:7], v[210:213], v[194:197], v[4:7]
	s_add_i32 s77, s77, 2
	s_add_u32 s30, s30, 0x100
	s_addc_u32 s31, s31, 0
	s_add_u32 s75, s75, 0x100
	s_addc_u32 s76, s76, 0
	s_cmp_gt_u32 s77, 13
	s_barrier
	s_cbranch_scc0 .LBB0_1141
	v_mul_f32_e32 v124, 0xbfb8aa3b, v124
	v_exp_f32_e32 v150, v124
	v_mul_f32_e32 v124, 0xbfb8aa3b, v125
	v_exp_f32_e32 v151, v124
	v_lshl_add_u32 v124, s28, 8, v142
	v_ashrrev_i32_e32 v125, 31, v124
	v_lshlrev_b64 v[154:155], 11, v[124:125]
	v_pk_add_f32 v[150:151], v[150:151], 1.0 op_sel_hi:[1,0]
	v_mul_f32_e32 v126, 0xbfb8aa3b, v126
	v_div_scale_f32 v153, s[30:31], v151, v151, v121
	v_rcp_f32_e32 v156, v153
	v_mul_f32_e32 v127, 0xbfb8aa3b, v127
	v_exp_f32_e32 v126, v126
	v_exp_f32_e32 v127, v127
	v_fma_f32 v125, -v153, v156, 1.0
	v_fmac_f32_e32 v156, v125, v156
	v_div_scale_f32 v125, vcc, v121, v151, v121
	v_mul_f32_e32 v157, v125, v156
	v_fma_f32 v158, -v153, v157, v125
	v_fmac_f32_e32 v157, v158, v156
	v_fma_f32 v125, -v153, v157, v125
	v_div_scale_f32 v153, s[30:31], v150, v150, v120
	v_rcp_f32_e32 v158, v153
	v_div_fmas_f32 v125, v125, v156, v157
	v_div_fixup_f32 v121, v125, v151, v121
	v_pk_add_f32 v[126:127], v[126:127], 1.0 op_sel_hi:[1,0]
	v_fma_f32 v125, -v153, v158, 1.0
	v_fmac_f32_e32 v158, v125, v158
	v_div_scale_f32 v125, vcc, v120, v150, v120
	v_mul_f32_e32 v151, v125, v158
	v_fma_f32 v156, -v153, v151, v125
	v_fmac_f32_e32 v151, v156, v158
	v_fma_f32 v125, -v153, v151, v125
	v_div_scale_f32 v153, s[30:31], v127, v127, v123
	v_rcp_f32_e32 v156, v153
	v_div_fmas_f32 v125, v125, v158, v151
	v_div_fixup_f32 v120, v125, v150, v120
	v_mul_f32_e32 v116, 0xbfb8aa3b, v116
	v_fma_f32 v125, -v153, v156, 1.0
	v_fmac_f32_e32 v156, v125, v156
	v_div_scale_f32 v125, vcc, v123, v127, v123
	v_mul_f32_e32 v150, v125, v156
	v_fma_f32 v151, -v153, v150, v125
	v_fmac_f32_e32 v150, v151, v156
	v_div_scale_f32 v151, s[30:31], v126, v126, v122
	v_fma_f32 v125, -v153, v150, v125
	v_rcp_f32_e32 v153, v151
	v_div_fmas_f32 v125, v125, v156, v150
	v_div_fixup_f32 v123, v125, v127, v123
	v_mul_f32_e32 v117, 0xbfb8aa3b, v117
	v_fma_f32 v125, -v151, v153, 1.0
	v_fmac_f32_e32 v153, v125, v153
	v_div_scale_f32 v125, vcc, v122, v126, v122
	v_mul_f32_e32 v127, v125, v153
	v_fma_f32 v150, -v151, v127, v125
	v_exp_f32_e32 v116, v116
	v_exp_f32_e32 v117, v117
	v_fmac_f32_e32 v127, v150, v153
	v_fma_f32 v125, -v151, v127, v125
	v_div_fmas_f32 v125, v125, v153, v127
	v_div_fixup_f32 v125, v125, v126, v122
	v_pk_add_f32 v[126:127], v[116:117], 1.0 op_sel_hi:[1,0]
	v_cvt_pk_bf16_f32 v123, v125, v123
	v_div_scale_f32 v125, s[30:31], v127, v127, v113
	v_lshl_or_b32 v152, s72, 7, v144
	v_rcp_f32_e32 v150, v125
	v_ashrrev_i32_e32 v153, 31, v152
	v_lshl_add_u64 v[154:155], s[46:47], 0, v[154:155]
	v_cvt_pk_bf16_f32 v122, v120, v121
	v_lshlrev_b64 v[120:121], 1, v[152:153]
	v_lshl_add_u64 v[116:117], v[154:155], 0, v[120:121]
	global_store_dwordx2 v[116:117], v[122:123], off
	v_fma_f32 v122, -v125, v150, 1.0
	v_fmac_f32_e32 v150, v122, v150
	v_div_scale_f32 v122, vcc, v113, v127, v113
	v_mul_f32_e32 v123, v122, v150
	v_fma_f32 v151, -v125, v123, v122
	v_fmac_f32_e32 v123, v151, v150
	v_fma_f32 v122, -v125, v123, v122
	v_div_scale_f32 v125, s[30:31], v126, v126, v112
	v_rcp_f32_e32 v151, v125
	v_div_fmas_f32 v122, v122, v150, v123
	v_mul_f32_e32 v118, 0xbfb8aa3b, v118
	v_mul_f32_e32 v119, 0xbfb8aa3b, v119
	v_div_fixup_f32 v113, v122, v127, v113
	v_fma_f32 v122, -v125, v151, 1.0
	v_exp_f32_e32 v118, v118
	v_exp_f32_e32 v119, v119
	v_fmac_f32_e32 v151, v122, v151
	v_div_scale_f32 v122, vcc, v112, v126, v112
	v_mul_f32_e32 v123, v122, v151
	v_fma_f32 v127, -v125, v123, v122
	v_fmac_f32_e32 v123, v127, v151
	v_pk_add_f32 v[118:119], v[118:119], 1.0 op_sel_hi:[1,0]
	v_fma_f32 v122, -v125, v123, v122
	v_div_scale_f32 v125, s[30:31], v119, v119, v115
	v_rcp_f32_e32 v127, v125
	v_div_fmas_f32 v122, v122, v151, v123
	v_div_fixup_f32 v112, v122, v126, v112
	v_mul_f32_e32 v108, 0xbfb8aa3b, v108
	v_fma_f32 v122, -v125, v127, 1.0
	v_fmac_f32_e32 v127, v122, v127
	v_div_scale_f32 v122, vcc, v115, v119, v115
	v_mul_f32_e32 v123, v122, v127
	v_fma_f32 v126, -v125, v123, v122
	v_fmac_f32_e32 v123, v126, v127
	v_fma_f32 v122, -v125, v123, v122
	v_div_scale_f32 v125, s[30:31], v118, v118, v114
	v_rcp_f32_e32 v126, v125
	v_div_fmas_f32 v122, v122, v127, v123
	v_div_fixup_f32 v115, v122, v119, v115
	v_mul_f32_e32 v109, 0xbfb8aa3b, v109
	v_fma_f32 v119, -v125, v126, 1.0
	v_fmac_f32_e32 v126, v119, v126
	v_div_scale_f32 v119, vcc, v114, v118, v114
	v_mul_f32_e32 v122, v119, v126
	v_fma_f32 v123, -v125, v122, v119
	v_exp_f32_e32 v108, v108
	v_exp_f32_e32 v109, v109
	v_fmac_f32_e32 v122, v123, v126
	v_fma_f32 v119, -v125, v122, v119
	v_div_fmas_f32 v119, v119, v126, v122
	v_div_fixup_f32 v114, v119, v118, v114
	v_pk_add_f32 v[108:109], v[108:109], 1.0 op_sel_hi:[1,0]
	v_cvt_pk_bf16_f32 v112, v112, v113
	v_cvt_pk_bf16_f32 v113, v114, v115
	v_div_scale_f32 v114, s[30:31], v109, v109, v105
	v_rcp_f32_e32 v115, v114
	v_mul_f32_e32 v110, 0xbfb8aa3b, v110
	v_mul_f32_e32 v111, 0xbfb8aa3b, v111
	v_exp_f32_e32 v110, v110
	v_fma_f32 v118, -v114, v115, 1.0
	v_fmac_f32_e32 v115, v118, v115
	v_div_scale_f32 v118, vcc, v105, v109, v105
	v_mul_f32_e32 v119, v118, v115
	v_fma_f32 v122, -v114, v119, v118
	v_fmac_f32_e32 v119, v122, v115
	v_fma_f32 v114, -v114, v119, v118
	v_div_scale_f32 v118, s[30:31], v108, v108, v104
	v_rcp_f32_e32 v122, v118
	v_div_fmas_f32 v114, v114, v115, v119
	v_exp_f32_e32 v111, v111
	v_div_fixup_f32 v105, v114, v109, v105
	v_fma_f32 v109, -v118, v122, 1.0
	v_fmac_f32_e32 v122, v109, v122
	v_div_scale_f32 v109, vcc, v104, v108, v104
	v_mul_f32_e32 v114, v109, v122
	v_fma_f32 v115, -v118, v114, v109
	v_pk_add_f32 v[110:111], v[110:111], 1.0 op_sel_hi:[1,0]
	v_fmac_f32_e32 v114, v115, v122
	v_div_scale_f32 v115, s[30:31], v111, v111, v107
	v_fma_f32 v109, -v118, v114, v109
	v_rcp_f32_e32 v118, v115
	v_div_fmas_f32 v109, v109, v122, v114
	v_div_fixup_f32 v104, v109, v108, v104
	v_mul_f32_e32 v100, 0xbfb8aa3b, v100
	v_fma_f32 v108, -v115, v118, 1.0
	v_fmac_f32_e32 v118, v108, v118
	v_div_scale_f32 v108, vcc, v107, v111, v107
	v_mul_f32_e32 v109, v108, v118
	v_fma_f32 v114, -v115, v109, v108
	v_fmac_f32_e32 v109, v114, v118
	v_div_scale_f32 v114, s[30:31], v110, v110, v106
	v_fma_f32 v108, -v115, v109, v108
	v_rcp_f32_e32 v115, v114
	v_div_fmas_f32 v108, v108, v118, v109
	v_div_fixup_f32 v107, v108, v111, v107
	v_mul_f32_e32 v101, 0xbfb8aa3b, v101
	v_fma_f32 v108, -v114, v115, 1.0
	v_fmac_f32_e32 v115, v108, v115
	v_div_scale_f32 v108, vcc, v106, v110, v106
	v_mul_f32_e32 v109, v108, v115
	v_exp_f32_e32 v100, v100
	v_exp_f32_e32 v101, v101
	v_fma_f32 v111, -v114, v109, v108
	v_fmac_f32_e32 v109, v111, v115
	v_fma_f32 v108, -v114, v109, v108
	v_div_fmas_f32 v108, v108, v115, v109
	v_pk_add_f32 v[100:101], v[100:101], 1.0 op_sel_hi:[1,0]
	global_store_dwordx2 v[116:117], v[112:113], off offset:128
	v_or_b32_e32 v112, 16, v124
	v_div_fixup_f32 v106, v108, v110, v106
	v_div_scale_f32 v108, s[30:31], v101, v101, v97
	v_ashrrev_i32_e32 v113, 31, v112
	v_rcp_f32_e32 v109, v108
	v_lshlrev_b64 v[112:113], 11, v[112:113]
	v_lshl_add_u64 v[112:113], s[46:47], 0, v[112:113]
	v_cvt_pk_bf16_f32 v104, v104, v105
	v_cvt_pk_bf16_f32 v105, v106, v107
	v_lshl_add_u64 v[106:107], v[112:113], 0, v[120:121]
	global_store_dwordx2 v[106:107], v[104:105], off
	v_fma_f32 v104, -v108, v109, 1.0
	v_fmac_f32_e32 v109, v104, v109
	v_div_scale_f32 v104, vcc, v97, v101, v97
	v_mul_f32_e32 v105, v104, v109
	v_fma_f32 v110, -v108, v105, v104
	v_fmac_f32_e32 v105, v110, v109
	v_fma_f32 v104, -v108, v105, v104
	v_div_scale_f32 v108, s[30:31], v100, v100, v96
	v_rcp_f32_e32 v110, v108
	v_mul_f32_e32 v102, 0xbfb8aa3b, v102
	v_mul_f32_e32 v103, 0xbfb8aa3b, v103
	v_div_fmas_f32 v104, v104, v109, v105
	v_exp_f32_e32 v102, v102
	v_exp_f32_e32 v103, v103
	v_div_fixup_f32 v97, v104, v101, v97
	v_fma_f32 v101, -v108, v110, 1.0
	v_fmac_f32_e32 v110, v101, v110
	v_div_scale_f32 v101, vcc, v96, v100, v96
	v_mul_f32_e32 v104, v101, v110
	v_fma_f32 v105, -v108, v104, v101
	v_pk_add_f32 v[102:103], v[102:103], 1.0 op_sel_hi:[1,0]
	v_fmac_f32_e32 v104, v105, v110
	v_div_scale_f32 v105, s[30:31], v103, v103, v99
	v_fma_f32 v101, -v108, v104, v101
	v_rcp_f32_e32 v108, v105
	v_div_fmas_f32 v101, v101, v110, v104
	v_div_fixup_f32 v96, v101, v100, v96
	v_mul_f32_e32 v92, 0xbfb8aa3b, v92
	v_fma_f32 v100, -v105, v108, 1.0
	v_fmac_f32_e32 v108, v100, v108
	v_div_scale_f32 v100, vcc, v99, v103, v99
	v_mul_f32_e32 v101, v100, v108
	v_fma_f32 v104, -v105, v101, v100
	v_fmac_f32_e32 v101, v104, v108
	v_div_scale_f32 v104, s[30:31], v102, v102, v98
	v_fma_f32 v100, -v105, v101, v100
	v_rcp_f32_e32 v105, v104
	v_div_fmas_f32 v100, v100, v108, v101
	v_div_fixup_f32 v99, v100, v103, v99
	v_mul_f32_e32 v93, 0xbfb8aa3b, v93
	v_fma_f32 v100, -v104, v105, 1.0
	v_fmac_f32_e32 v105, v100, v105
	v_div_scale_f32 v100, vcc, v98, v102, v98
	v_mul_f32_e32 v101, v100, v105
	v_fma_f32 v103, -v104, v101, v100
	v_exp_f32_e32 v92, v92
	v_exp_f32_e32 v93, v93
	v_fmac_f32_e32 v101, v103, v105
	v_fma_f32 v100, -v104, v101, v100
	v_div_fmas_f32 v100, v100, v105, v101
	v_div_fixup_f32 v98, v100, v102, v98
	v_pk_add_f32 v[92:93], v[92:93], 1.0 op_sel_hi:[1,0]
	v_cvt_pk_bf16_f32 v96, v96, v97
	v_cvt_pk_bf16_f32 v97, v98, v99
	v_div_scale_f32 v98, s[30:31], v93, v93, v89
	v_rcp_f32_e32 v99, v98
	v_mul_f32_e32 v94, 0xbfb8aa3b, v94
	v_mul_f32_e32 v95, 0xbfb8aa3b, v95
	v_exp_f32_e32 v94, v94
	v_fma_f32 v100, -v98, v99, 1.0
	v_fmac_f32_e32 v99, v100, v99
	v_div_scale_f32 v100, vcc, v89, v93, v89
	v_mul_f32_e32 v101, v100, v99
	v_fma_f32 v102, -v98, v101, v100
	v_fmac_f32_e32 v101, v102, v99
	v_fma_f32 v98, -v98, v101, v100
	v_div_scale_f32 v100, s[30:31], v92, v92, v88
	v_rcp_f32_e32 v102, v100
	v_div_fmas_f32 v98, v98, v99, v101
	v_exp_f32_e32 v95, v95
	v_div_fixup_f32 v89, v98, v93, v89
	v_fma_f32 v93, -v100, v102, 1.0
	v_fmac_f32_e32 v102, v93, v102
	v_div_scale_f32 v93, vcc, v88, v92, v88
	v_mul_f32_e32 v98, v93, v102
	v_fma_f32 v99, -v100, v98, v93
	v_pk_add_f32 v[94:95], v[94:95], 1.0 op_sel_hi:[1,0]
	v_fmac_f32_e32 v98, v99, v102
	v_div_scale_f32 v99, s[30:31], v95, v95, v91
	v_fma_f32 v93, -v100, v98, v93
	v_rcp_f32_e32 v100, v99
	v_div_fmas_f32 v93, v93, v102, v98
	v_div_fixup_f32 v88, v93, v92, v88
	v_mul_f32_e32 v84, 0xbfb8aa3b, v84
	v_fma_f32 v92, -v99, v100, 1.0
	v_fmac_f32_e32 v100, v92, v100
	v_div_scale_f32 v92, vcc, v91, v95, v91
	v_mul_f32_e32 v93, v92, v100
	v_fma_f32 v98, -v99, v93, v92
	v_fmac_f32_e32 v93, v98, v100
	v_div_scale_f32 v98, s[30:31], v94, v94, v90
	v_fma_f32 v92, -v99, v93, v92
	v_rcp_f32_e32 v99, v98
	v_div_fmas_f32 v92, v92, v100, v93
	v_div_fixup_f32 v91, v92, v95, v91
	v_mul_f32_e32 v85, 0xbfb8aa3b, v85
	v_fma_f32 v92, -v98, v99, 1.0
	v_fmac_f32_e32 v99, v92, v99
	v_div_scale_f32 v92, vcc, v90, v94, v90
	v_mul_f32_e32 v93, v92, v99
	v_exp_f32_e32 v84, v84
	v_exp_f32_e32 v85, v85
	v_fma_f32 v95, -v98, v93, v92
	v_fmac_f32_e32 v93, v95, v99
	v_fma_f32 v92, -v98, v93, v92
	v_div_fmas_f32 v92, v92, v99, v93
	v_pk_add_f32 v[84:85], v[84:85], 1.0 op_sel_hi:[1,0]
	global_store_dwordx2 v[106:107], v[96:97], off offset:128
	v_or_b32_e32 v96, 32, v124
	v_div_fixup_f32 v90, v92, v94, v90
	v_div_scale_f32 v92, s[30:31], v85, v85, v81
	v_ashrrev_i32_e32 v97, 31, v96
	v_rcp_f32_e32 v93, v92
	v_lshlrev_b64 v[96:97], 11, v[96:97]
	v_lshl_add_u64 v[96:97], s[46:47], 0, v[96:97]
	v_cvt_pk_bf16_f32 v88, v88, v89
	v_cvt_pk_bf16_f32 v89, v90, v91
	v_lshl_add_u64 v[90:91], v[96:97], 0, v[120:121]
	global_store_dwordx2 v[90:91], v[88:89], off
	v_fma_f32 v88, -v92, v93, 1.0
	v_fmac_f32_e32 v93, v88, v93
	v_div_scale_f32 v88, vcc, v81, v85, v81
	v_mul_f32_e32 v89, v88, v93
	v_fma_f32 v94, -v92, v89, v88
	v_fmac_f32_e32 v89, v94, v93
	v_fma_f32 v88, -v92, v89, v88
	v_div_scale_f32 v92, s[30:31], v84, v84, v80
	v_rcp_f32_e32 v94, v92
	v_mul_f32_e32 v86, 0xbfb8aa3b, v86
	v_mul_f32_e32 v87, 0xbfb8aa3b, v87
	v_div_fmas_f32 v88, v88, v93, v89
	v_exp_f32_e32 v86, v86
	v_exp_f32_e32 v87, v87
	v_div_fixup_f32 v81, v88, v85, v81
	v_fma_f32 v85, -v92, v94, 1.0
	v_fmac_f32_e32 v94, v85, v94
	v_div_scale_f32 v85, vcc, v80, v84, v80
	v_mul_f32_e32 v88, v85, v94
	v_fma_f32 v89, -v92, v88, v85
	v_pk_add_f32 v[86:87], v[86:87], 1.0 op_sel_hi:[1,0]
	v_fmac_f32_e32 v88, v89, v94
	v_div_scale_f32 v89, s[30:31], v87, v87, v83
	v_fma_f32 v85, -v92, v88, v85
	v_rcp_f32_e32 v92, v89
	v_div_fmas_f32 v85, v85, v94, v88
	v_div_fixup_f32 v80, v85, v84, v80
	v_mul_f32_e32 v76, 0xbfb8aa3b, v76
	v_fma_f32 v84, -v89, v92, 1.0
	v_fmac_f32_e32 v92, v84, v92
	v_div_scale_f32 v84, vcc, v83, v87, v83
	v_mul_f32_e32 v85, v84, v92
	v_fma_f32 v88, -v89, v85, v84
	v_fmac_f32_e32 v85, v88, v92
	v_div_scale_f32 v88, s[30:31], v86, v86, v82
	v_fma_f32 v84, -v89, v85, v84
	v_rcp_f32_e32 v89, v88
	v_div_fmas_f32 v84, v84, v92, v85
	v_div_fixup_f32 v83, v84, v87, v83
	v_mul_f32_e32 v77, 0xbfb8aa3b, v77
	v_fma_f32 v84, -v88, v89, 1.0
	v_fmac_f32_e32 v89, v84, v89
	v_div_scale_f32 v84, vcc, v82, v86, v82
	v_mul_f32_e32 v85, v84, v89
	v_fma_f32 v87, -v88, v85, v84
	v_exp_f32_e32 v76, v76
	v_exp_f32_e32 v77, v77
	v_fmac_f32_e32 v85, v87, v89
	v_fma_f32 v84, -v88, v85, v84
	v_div_fmas_f32 v84, v84, v89, v85
	v_div_fixup_f32 v82, v84, v86, v82
	v_pk_add_f32 v[76:77], v[76:77], 1.0 op_sel_hi:[1,0]
	v_cvt_pk_bf16_f32 v80, v80, v81
	v_cvt_pk_bf16_f32 v81, v82, v83
	v_div_scale_f32 v82, s[30:31], v77, v77, v73
	v_rcp_f32_e32 v83, v82
	v_mul_f32_e32 v78, 0xbfb8aa3b, v78
	v_mul_f32_e32 v79, 0xbfb8aa3b, v79
	v_exp_f32_e32 v78, v78
	v_fma_f32 v84, -v82, v83, 1.0
	v_fmac_f32_e32 v83, v84, v83
	v_div_scale_f32 v84, vcc, v73, v77, v73
	v_mul_f32_e32 v85, v84, v83
	v_fma_f32 v86, -v82, v85, v84
	v_fmac_f32_e32 v85, v86, v83
	v_fma_f32 v82, -v82, v85, v84
	v_div_scale_f32 v84, s[30:31], v76, v76, v72
	v_rcp_f32_e32 v86, v84
	v_div_fmas_f32 v82, v82, v83, v85
	v_exp_f32_e32 v79, v79
	v_div_fixup_f32 v73, v82, v77, v73
	v_fma_f32 v77, -v84, v86, 1.0
	v_fmac_f32_e32 v86, v77, v86
	v_div_scale_f32 v77, vcc, v72, v76, v72
	v_mul_f32_e32 v82, v77, v86
	v_fma_f32 v83, -v84, v82, v77
	v_pk_add_f32 v[78:79], v[78:79], 1.0 op_sel_hi:[1,0]
	v_fmac_f32_e32 v82, v83, v86
	v_div_scale_f32 v83, s[30:31], v79, v79, v75
	v_fma_f32 v77, -v84, v82, v77
	v_rcp_f32_e32 v84, v83
	v_div_fmas_f32 v77, v77, v86, v82
	v_div_fixup_f32 v72, v77, v76, v72
	v_mul_f32_e32 v68, 0xbfb8aa3b, v68
	v_fma_f32 v76, -v83, v84, 1.0
	v_fmac_f32_e32 v84, v76, v84
	v_div_scale_f32 v76, vcc, v75, v79, v75
	v_mul_f32_e32 v77, v76, v84
	v_fma_f32 v82, -v83, v77, v76
	v_fmac_f32_e32 v77, v82, v84
	v_div_scale_f32 v82, s[30:31], v78, v78, v74
	v_fma_f32 v76, -v83, v77, v76
	v_rcp_f32_e32 v83, v82
	v_div_fmas_f32 v76, v76, v84, v77
	v_div_fixup_f32 v75, v76, v79, v75
	v_mul_f32_e32 v69, 0xbfb8aa3b, v69
	v_fma_f32 v76, -v82, v83, 1.0
	v_fmac_f32_e32 v83, v76, v83
	v_div_scale_f32 v76, vcc, v74, v78, v74
	v_mul_f32_e32 v77, v76, v83
	v_exp_f32_e32 v68, v68
	v_exp_f32_e32 v69, v69
	v_fma_f32 v79, -v82, v77, v76
	v_fmac_f32_e32 v77, v79, v83
	v_fma_f32 v76, -v82, v77, v76
	v_div_fmas_f32 v76, v76, v83, v77
	v_pk_add_f32 v[68:69], v[68:69], 1.0 op_sel_hi:[1,0]
	global_store_dwordx2 v[90:91], v[80:81], off offset:128
	v_or_b32_e32 v80, 48, v124
	v_div_fixup_f32 v74, v76, v78, v74
	v_div_scale_f32 v76, s[30:31], v69, v69, v65
	v_ashrrev_i32_e32 v81, 31, v80
	v_rcp_f32_e32 v77, v76
	v_lshlrev_b64 v[80:81], 11, v[80:81]
	v_lshl_add_u64 v[80:81], s[46:47], 0, v[80:81]
	v_cvt_pk_bf16_f32 v72, v72, v73
	v_cvt_pk_bf16_f32 v73, v74, v75
	v_lshl_add_u64 v[74:75], v[80:81], 0, v[120:121]
	global_store_dwordx2 v[74:75], v[72:73], off
	v_fma_f32 v72, -v76, v77, 1.0
	v_fmac_f32_e32 v77, v72, v77
	v_div_scale_f32 v72, vcc, v65, v69, v65
	v_mul_f32_e32 v73, v72, v77
	v_fma_f32 v78, -v76, v73, v72
	v_fmac_f32_e32 v73, v78, v77
	v_fma_f32 v72, -v76, v73, v72
	v_div_scale_f32 v76, s[30:31], v68, v68, v64
	v_rcp_f32_e32 v78, v76
	v_mul_f32_e32 v70, 0xbfb8aa3b, v70
	v_mul_f32_e32 v71, 0xbfb8aa3b, v71
	v_div_fmas_f32 v72, v72, v77, v73
	v_exp_f32_e32 v70, v70
	v_exp_f32_e32 v71, v71
	v_div_fixup_f32 v65, v72, v69, v65
	v_fma_f32 v69, -v76, v78, 1.0
	v_fmac_f32_e32 v78, v69, v78
	v_div_scale_f32 v69, vcc, v64, v68, v64
	v_mul_f32_e32 v72, v69, v78
	v_fma_f32 v73, -v76, v72, v69
	v_pk_add_f32 v[70:71], v[70:71], 1.0 op_sel_hi:[1,0]
	v_fmac_f32_e32 v72, v73, v78
	v_div_scale_f32 v73, s[30:31], v71, v71, v67
	v_fma_f32 v69, -v76, v72, v69
	v_rcp_f32_e32 v76, v73
	v_div_fmas_f32 v69, v69, v78, v72
	v_div_fixup_f32 v64, v69, v68, v64
	v_mul_f32_e32 v60, 0xbfb8aa3b, v60
	v_fma_f32 v68, -v73, v76, 1.0
	v_fmac_f32_e32 v76, v68, v76
	v_div_scale_f32 v68, vcc, v67, v71, v67
	v_mul_f32_e32 v69, v68, v76
	v_fma_f32 v72, -v73, v69, v68
	v_fmac_f32_e32 v69, v72, v76
	v_div_scale_f32 v72, s[30:31], v70, v70, v66
	v_fma_f32 v68, -v73, v69, v68
	v_rcp_f32_e32 v73, v72
	v_div_fmas_f32 v68, v68, v76, v69
	v_div_fixup_f32 v67, v68, v71, v67
	v_mul_f32_e32 v61, 0xbfb8aa3b, v61
	v_fma_f32 v68, -v72, v73, 1.0
	v_fmac_f32_e32 v73, v68, v73
	v_div_scale_f32 v68, vcc, v66, v70, v66
	v_mul_f32_e32 v69, v68, v73
	v_exp_f32_e32 v60, v60
	v_exp_f32_e32 v61, v61
	v_fma_f32 v71, -v72, v69, v68
	v_fmac_f32_e32 v69, v71, v73
	v_fma_f32 v68, -v72, v69, v68
	v_div_fmas_f32 v68, v68, v73, v69
	v_pk_add_f32 v[60:61], v[60:61], 1.0 op_sel_hi:[1,0]
	v_div_fixup_f32 v66, v68, v70, v66
	v_div_scale_f32 v68, s[30:31], v61, v61, v57
	v_rcp_f32_e32 v69, v68
	v_cvt_pk_bf16_f32 v64, v64, v65
	v_cvt_pk_bf16_f32 v65, v66, v67
	global_store_dwordx2 v[74:75], v[64:65], off offset:128
	v_fma_f32 v64, -v68, v69, 1.0
	v_fmac_f32_e32 v69, v64, v69
	v_div_scale_f32 v64, vcc, v57, v61, v57
	v_mul_f32_e32 v65, v64, v69
	v_fma_f32 v66, -v68, v65, v64
	v_fmac_f32_e32 v65, v66, v69
	v_div_scale_f32 v66, s[30:31], v60, v60, v56
	v_rcp_f32_e32 v67, v66
	v_fma_f32 v64, -v68, v65, v64
	v_mul_f32_e32 v62, 0xbfb8aa3b, v62
	v_mul_f32_e32 v63, 0xbfb8aa3b, v63
	v_div_fmas_f32 v64, v64, v69, v65
	v_exp_f32_e32 v62, v62
	v_exp_f32_e32 v63, v63
	v_div_fixup_f32 v57, v64, v61, v57
	v_fma_f32 v61, -v66, v67, 1.0
	v_fmac_f32_e32 v67, v61, v67
	v_div_scale_f32 v61, vcc, v56, v60, v56
	v_mul_f32_e32 v64, v61, v67
	v_fma_f32 v65, -v66, v64, v61
	v_pk_add_f32 v[62:63], v[62:63], 1.0 op_sel_hi:[1,0]
	v_fmac_f32_e32 v64, v65, v67
	v_div_scale_f32 v65, s[30:31], v63, v63, v59
	v_fma_f32 v61, -v66, v64, v61
	v_rcp_f32_e32 v66, v65
	v_div_fmas_f32 v61, v61, v67, v64
	v_div_fixup_f32 v56, v61, v60, v56
	v_mul_f32_e32 v52, 0xbfb8aa3b, v52
	v_fma_f32 v60, -v65, v66, 1.0
	v_fmac_f32_e32 v66, v60, v66
	v_div_scale_f32 v60, vcc, v59, v63, v59
	v_mul_f32_e32 v61, v60, v66
	v_fma_f32 v64, -v65, v61, v60
	v_fmac_f32_e32 v61, v64, v66
	v_div_scale_f32 v64, s[30:31], v62, v62, v58
	v_fma_f32 v60, -v65, v61, v60
	v_rcp_f32_e32 v65, v64
	v_div_fmas_f32 v60, v60, v66, v61
	v_div_fixup_f32 v59, v60, v63, v59
	v_mul_f32_e32 v53, 0xbfb8aa3b, v53
	v_fma_f32 v60, -v64, v65, 1.0
	v_fmac_f32_e32 v65, v60, v65
	v_div_scale_f32 v60, vcc, v58, v62, v58
	v_mul_f32_e32 v61, v60, v65
	v_exp_f32_e32 v52, v52
	v_exp_f32_e32 v53, v53
	v_fma_f32 v63, -v64, v61, v60
	v_fmac_f32_e32 v61, v63, v65
	v_fma_f32 v60, -v64, v61, v60
	v_div_fmas_f32 v60, v60, v65, v61
	v_pk_add_f32 v[52:53], v[52:53], 1.0 op_sel_hi:[1,0]
	v_div_fixup_f32 v58, v60, v62, v58
	v_div_scale_f32 v62, s[30:31], v53, v53, v49
	v_rcp_f32_e32 v63, v62
	v_add_co_u32_e32 v60, vcc, s62, v116
	v_cvt_pk_bf16_f32 v56, v56, v57
	v_cvt_pk_bf16_f32 v57, v58, v59
	v_addc_co_u32_e32 v61, vcc, 0, v117, vcc
	global_store_dwordx2 v[60:61], v[56:57], off
	v_fma_f32 v56, -v62, v63, 1.0
	v_fmac_f32_e32 v63, v56, v63
	v_div_scale_f32 v56, vcc, v49, v53, v49
	v_mul_f32_e32 v57, v56, v63
	v_fma_f32 v60, -v62, v57, v56
	v_fmac_f32_e32 v57, v60, v63
	v_div_scale_f32 v60, s[30:31], v52, v52, v48
	v_rcp_f32_e32 v61, v60
	v_fma_f32 v56, -v62, v57, v56
	v_mul_f32_e32 v54, 0xbfb8aa3b, v54
	v_mul_f32_e32 v55, 0xbfb8aa3b, v55
	v_div_fmas_f32 v56, v56, v63, v57
	v_exp_f32_e32 v54, v54
	v_exp_f32_e32 v55, v55
	v_div_fixup_f32 v49, v56, v53, v49
	v_fma_f32 v53, -v60, v61, 1.0
	v_fmac_f32_e32 v61, v53, v61
	v_div_scale_f32 v53, vcc, v48, v52, v48
	v_mul_f32_e32 v56, v53, v61
	v_fma_f32 v57, -v60, v56, v53
	v_pk_add_f32 v[54:55], v[54:55], 1.0 op_sel_hi:[1,0]
	v_fmac_f32_e32 v56, v57, v61
	v_div_scale_f32 v57, s[30:31], v55, v55, v51
	v_fma_f32 v53, -v60, v56, v53
	v_rcp_f32_e32 v60, v57
	v_div_fmas_f32 v53, v53, v61, v56
	v_div_fixup_f32 v48, v53, v52, v48
	v_mul_f32_e32 v44, 0xbfb8aa3b, v44
	v_fma_f32 v52, -v57, v60, 1.0
	v_fmac_f32_e32 v60, v52, v60
	v_div_scale_f32 v52, vcc, v51, v55, v51
	v_mul_f32_e32 v53, v52, v60
	v_fma_f32 v56, -v57, v53, v52
	v_fmac_f32_e32 v53, v56, v60
	v_div_scale_f32 v56, s[30:31], v54, v54, v50
	v_fma_f32 v52, -v57, v53, v52
	v_rcp_f32_e32 v57, v56
	v_div_fmas_f32 v52, v52, v60, v53
	v_div_fixup_f32 v51, v52, v55, v51
	v_mul_f32_e32 v45, 0xbfb8aa3b, v45
	v_fma_f32 v52, -v56, v57, 1.0
	v_fmac_f32_e32 v57, v52, v57
	v_div_scale_f32 v52, vcc, v50, v54, v50
	v_mul_f32_e32 v53, v52, v57
	v_exp_f32_e32 v44, v44
	v_exp_f32_e32 v45, v45
	v_fma_f32 v55, -v56, v53, v52
	v_fmac_f32_e32 v53, v55, v57
	v_fma_f32 v52, -v56, v53, v52
	v_div_fmas_f32 v52, v52, v57, v53
	v_pk_add_f32 v[44:45], v[44:45], 1.0 op_sel_hi:[1,0]
	v_div_fixup_f32 v50, v52, v54, v50
	v_div_scale_f32 v52, s[30:31], v45, v45, v41
	v_rcp_f32_e32 v53, v52
	v_lshl_add_u64 v[58:59], v[116:117], 0, s[6:7]
	v_cvt_pk_bf16_f32 v48, v48, v49
	v_cvt_pk_bf16_f32 v49, v50, v51
	global_store_dwordx2 v[58:59], v[48:49], off offset:128
	v_fma_f32 v48, -v52, v53, 1.0
	v_fmac_f32_e32 v53, v48, v53
	v_div_scale_f32 v48, vcc, v41, v45, v41
	v_mul_f32_e32 v49, v48, v53
	v_fma_f32 v50, -v52, v49, v48
	v_fmac_f32_e32 v49, v50, v53
	v_div_scale_f32 v50, s[30:31], v44, v44, v40
	v_rcp_f32_e32 v51, v50
	v_fma_f32 v48, -v52, v49, v48
	v_mul_f32_e32 v46, 0xbfb8aa3b, v46
	v_mul_f32_e32 v47, 0xbfb8aa3b, v47
	v_div_fmas_f32 v48, v48, v53, v49
	v_exp_f32_e32 v46, v46
	v_exp_f32_e32 v47, v47
	v_div_fixup_f32 v41, v48, v45, v41
	v_fma_f32 v45, -v50, v51, 1.0
	v_fmac_f32_e32 v51, v45, v51
	v_div_scale_f32 v45, vcc, v40, v44, v40
	v_mul_f32_e32 v48, v45, v51
	v_fma_f32 v49, -v50, v48, v45
	v_pk_add_f32 v[46:47], v[46:47], 1.0 op_sel_hi:[1,0]
	v_fmac_f32_e32 v48, v49, v51
	v_div_scale_f32 v49, s[30:31], v47, v47, v43
	v_fma_f32 v45, -v50, v48, v45
	v_rcp_f32_e32 v50, v49
	v_div_fmas_f32 v45, v45, v51, v48
	v_div_fixup_f32 v40, v45, v44, v40
	v_mul_f32_e32 v36, 0xbfb8aa3b, v36
	v_fma_f32 v44, -v49, v50, 1.0
	v_fmac_f32_e32 v50, v44, v50
	v_div_scale_f32 v44, vcc, v43, v47, v43
	v_mul_f32_e32 v45, v44, v50
	v_fma_f32 v48, -v49, v45, v44
	v_fmac_f32_e32 v45, v48, v50
	v_div_scale_f32 v48, s[30:31], v46, v46, v42
	v_fma_f32 v44, -v49, v45, v44
	v_rcp_f32_e32 v49, v48
	v_div_fmas_f32 v44, v44, v50, v45
	v_div_fixup_f32 v43, v44, v47, v43
	v_mul_f32_e32 v37, 0xbfb8aa3b, v37
	v_fma_f32 v44, -v48, v49, 1.0
	v_fmac_f32_e32 v49, v44, v49
	v_div_scale_f32 v44, vcc, v42, v46, v42
	v_mul_f32_e32 v45, v44, v49
	v_exp_f32_e32 v36, v36
	v_exp_f32_e32 v37, v37
	v_fma_f32 v47, -v48, v45, v44
	v_fmac_f32_e32 v45, v47, v49
	v_fma_f32 v44, -v48, v45, v44
	v_div_fmas_f32 v44, v44, v49, v45
	v_pk_add_f32 v[36:37], v[36:37], 1.0 op_sel_hi:[1,0]
	v_div_fixup_f32 v42, v44, v46, v42
	v_div_scale_f32 v46, s[30:31], v37, v37, v33
	v_rcp_f32_e32 v47, v46
	v_add_co_u32_e32 v44, vcc, s63, v116
	v_cvt_pk_bf16_f32 v40, v40, v41
	v_cvt_pk_bf16_f32 v41, v42, v43
	v_addc_co_u32_e32 v45, vcc, 0, v117, vcc
	global_store_dwordx2 v[44:45], v[40:41], off
	v_fma_f32 v40, -v46, v47, 1.0
	v_fmac_f32_e32 v47, v40, v47
	v_div_scale_f32 v40, vcc, v33, v37, v33
	v_mul_f32_e32 v41, v40, v47
	v_fma_f32 v44, -v46, v41, v40
	v_fmac_f32_e32 v41, v44, v47
	v_div_scale_f32 v44, s[30:31], v36, v36, v32
	v_rcp_f32_e32 v45, v44
	v_fma_f32 v40, -v46, v41, v40
	v_mul_f32_e32 v38, 0xbfb8aa3b, v38
	v_mul_f32_e32 v39, 0xbfb8aa3b, v39
	v_div_fmas_f32 v40, v40, v47, v41
	v_exp_f32_e32 v38, v38
	v_exp_f32_e32 v39, v39
	v_div_fixup_f32 v33, v40, v37, v33
	v_fma_f32 v37, -v44, v45, 1.0
	v_fmac_f32_e32 v45, v37, v45
	v_div_scale_f32 v37, vcc, v32, v36, v32
	v_mul_f32_e32 v40, v37, v45
	v_fma_f32 v41, -v44, v40, v37
	v_pk_add_f32 v[38:39], v[38:39], 1.0 op_sel_hi:[1,0]
	v_fmac_f32_e32 v40, v41, v45
	v_div_scale_f32 v41, s[30:31], v39, v39, v35
	v_fma_f32 v37, -v44, v40, v37
	v_rcp_f32_e32 v44, v41
	v_div_fmas_f32 v37, v37, v45, v40
	v_div_fixup_f32 v32, v37, v36, v32
	v_mul_f32_e32 v28, 0xbfb8aa3b, v28
	v_fma_f32 v36, -v41, v44, 1.0
	v_fmac_f32_e32 v44, v36, v44
	v_div_scale_f32 v36, vcc, v35, v39, v35
	v_mul_f32_e32 v37, v36, v44
	v_fma_f32 v40, -v41, v37, v36
	v_fmac_f32_e32 v37, v40, v44
	v_div_scale_f32 v40, s[30:31], v38, v38, v34
	v_fma_f32 v36, -v41, v37, v36
	v_rcp_f32_e32 v41, v40
	v_div_fmas_f32 v36, v36, v44, v37
	v_div_fixup_f32 v35, v36, v39, v35
	v_mul_f32_e32 v29, 0xbfb8aa3b, v29
	v_fma_f32 v36, -v40, v41, 1.0
	v_fmac_f32_e32 v41, v36, v41
	v_div_scale_f32 v36, vcc, v34, v38, v34
	v_mul_f32_e32 v37, v36, v41
	v_exp_f32_e32 v28, v28
	v_exp_f32_e32 v29, v29
	v_fma_f32 v39, -v40, v37, v36
	v_fmac_f32_e32 v37, v39, v41
	v_fma_f32 v36, -v40, v37, v36
	v_div_fmas_f32 v36, v36, v41, v37
	v_pk_add_f32 v[28:29], v[28:29], 1.0 op_sel_hi:[1,0]
	v_div_fixup_f32 v34, v36, v38, v34
	v_div_scale_f32 v36, s[30:31], v29, v29, v25
	v_rcp_f32_e32 v37, v36
	v_lshl_add_u64 v[42:43], v[116:117], 0, s[10:11]
	v_cvt_pk_bf16_f32 v32, v32, v33
	v_cvt_pk_bf16_f32 v33, v34, v35
	global_store_dwordx2 v[42:43], v[32:33], off offset:128
	v_fma_f32 v32, -v36, v37, 1.0
	v_fmac_f32_e32 v37, v32, v37
	v_div_scale_f32 v32, vcc, v25, v29, v25
	v_mul_f32_e32 v33, v32, v37
	v_fma_f32 v34, -v36, v33, v32
	v_fmac_f32_e32 v33, v34, v37
	v_div_scale_f32 v34, s[30:31], v28, v28, v24
	v_rcp_f32_e32 v35, v34
	v_fma_f32 v32, -v36, v33, v32
	v_mul_f32_e32 v30, 0xbfb8aa3b, v30
	v_mul_f32_e32 v31, 0xbfb8aa3b, v31
	v_div_fmas_f32 v32, v32, v37, v33
	v_exp_f32_e32 v30, v30
	v_exp_f32_e32 v31, v31
	v_div_fixup_f32 v25, v32, v29, v25
	v_fma_f32 v29, -v34, v35, 1.0
	v_fmac_f32_e32 v35, v29, v35
	v_div_scale_f32 v29, vcc, v24, v28, v24
	v_mul_f32_e32 v32, v29, v35
	v_fma_f32 v33, -v34, v32, v29
	v_pk_add_f32 v[30:31], v[30:31], 1.0 op_sel_hi:[1,0]
	v_fmac_f32_e32 v32, v33, v35
	v_div_scale_f32 v33, s[30:31], v31, v31, v27
	v_fma_f32 v29, -v34, v32, v29
	v_rcp_f32_e32 v34, v33
	v_div_fmas_f32 v29, v29, v35, v32
	v_div_fixup_f32 v24, v29, v28, v24
	v_mul_f32_e32 v20, 0xbfb8aa3b, v20
	v_fma_f32 v28, -v33, v34, 1.0
	v_fmac_f32_e32 v34, v28, v34
	v_div_scale_f32 v28, vcc, v27, v31, v27
	v_mul_f32_e32 v29, v28, v34
	v_fma_f32 v32, -v33, v29, v28
	v_fmac_f32_e32 v29, v32, v34
	v_div_scale_f32 v32, s[30:31], v30, v30, v26
	v_fma_f32 v28, -v33, v29, v28
	v_rcp_f32_e32 v33, v32
	v_div_fmas_f32 v28, v28, v34, v29
	v_div_fixup_f32 v27, v28, v31, v27
	v_mul_f32_e32 v21, 0xbfb8aa3b, v21
	v_fma_f32 v28, -v32, v33, 1.0
	v_fmac_f32_e32 v33, v28, v33
	v_div_scale_f32 v28, vcc, v26, v30, v26
	v_mul_f32_e32 v29, v28, v33
	v_exp_f32_e32 v20, v20
	v_exp_f32_e32 v21, v21
	v_fma_f32 v31, -v32, v29, v28
	v_fmac_f32_e32 v29, v31, v33
	v_fma_f32 v28, -v32, v29, v28
	v_div_fmas_f32 v28, v28, v33, v29
	v_pk_add_f32 v[20:21], v[20:21], 1.0 op_sel_hi:[1,0]
	v_div_fixup_f32 v26, v28, v30, v26
	v_div_scale_f32 v30, s[30:31], v21, v21, v17
	v_rcp_f32_e32 v31, v30
	v_add_co_u32_e32 v28, vcc, s70, v116
	v_cvt_pk_bf16_f32 v24, v24, v25
	v_cvt_pk_bf16_f32 v25, v26, v27
	v_addc_co_u32_e32 v29, vcc, 0, v117, vcc
	global_store_dwordx2 v[28:29], v[24:25], off
	v_fma_f32 v24, -v30, v31, 1.0
	v_fmac_f32_e32 v31, v24, v31
	v_div_scale_f32 v24, vcc, v17, v21, v17
	v_mul_f32_e32 v25, v24, v31
	v_fma_f32 v28, -v30, v25, v24
	v_fmac_f32_e32 v25, v28, v31
	v_div_scale_f32 v28, s[30:31], v20, v20, v16
	v_rcp_f32_e32 v29, v28
	v_fma_f32 v24, -v30, v25, v24
	v_mul_f32_e32 v22, 0xbfb8aa3b, v22
	v_mul_f32_e32 v23, 0xbfb8aa3b, v23
	v_div_fmas_f32 v24, v24, v31, v25
	v_exp_f32_e32 v22, v22
	v_exp_f32_e32 v23, v23
	v_div_fixup_f32 v17, v24, v21, v17
	v_fma_f32 v21, -v28, v29, 1.0
	v_fmac_f32_e32 v29, v21, v29
	v_div_scale_f32 v21, vcc, v16, v20, v16
	v_mul_f32_e32 v24, v21, v29
	v_fma_f32 v25, -v28, v24, v21
	v_pk_add_f32 v[22:23], v[22:23], 1.0 op_sel_hi:[1,0]
	v_fmac_f32_e32 v24, v25, v29
	v_div_scale_f32 v25, s[30:31], v23, v23, v19
	v_fma_f32 v21, -v28, v24, v21
	v_rcp_f32_e32 v28, v25
	v_div_fmas_f32 v21, v21, v29, v24
	v_div_fixup_f32 v16, v21, v20, v16
	v_mul_f32_e32 v12, 0xbfb8aa3b, v12
	v_fma_f32 v20, -v25, v28, 1.0
	v_fmac_f32_e32 v28, v20, v28
	v_div_scale_f32 v20, vcc, v19, v23, v19
	v_mul_f32_e32 v21, v20, v28
	v_fma_f32 v24, -v25, v21, v20
	v_fmac_f32_e32 v21, v24, v28
	v_div_scale_f32 v24, s[30:31], v22, v22, v18
	v_fma_f32 v20, -v25, v21, v20
	v_rcp_f32_e32 v25, v24
	v_div_fmas_f32 v20, v20, v28, v21
	v_div_fixup_f32 v19, v20, v23, v19
	v_mul_f32_e32 v13, 0xbfb8aa3b, v13
	v_fma_f32 v20, -v24, v25, 1.0
	v_fmac_f32_e32 v25, v20, v25
	v_div_scale_f32 v20, vcc, v18, v22, v18
	v_mul_f32_e32 v21, v20, v25
	v_exp_f32_e32 v12, v12
	v_exp_f32_e32 v13, v13
	v_fma_f32 v23, -v24, v21, v20
	v_fmac_f32_e32 v21, v23, v25
	v_fma_f32 v20, -v24, v21, v20
	v_div_fmas_f32 v20, v20, v25, v21
	v_pk_add_f32 v[12:13], v[12:13], 1.0 op_sel_hi:[1,0]
	v_div_fixup_f32 v18, v20, v22, v18
	v_div_scale_f32 v20, s[30:31], v13, v13, v9
	v_rcp_f32_e32 v21, v20
	v_lshl_add_u64 v[26:27], v[116:117], 0, s[12:13]
	v_cvt_pk_bf16_f32 v16, v16, v17
	v_cvt_pk_bf16_f32 v17, v18, v19
	global_store_dwordx2 v[26:27], v[16:17], off offset:128
	v_fma_f32 v16, -v20, v21, 1.0
	v_fmac_f32_e32 v21, v16, v21
	v_div_scale_f32 v16, vcc, v9, v13, v9
	v_mul_f32_e32 v17, v16, v21
	v_fma_f32 v18, -v20, v17, v16
	v_fmac_f32_e32 v17, v18, v21
	v_div_scale_f32 v18, s[30:31], v12, v12, v8
	v_rcp_f32_e32 v19, v18
	v_fma_f32 v16, -v20, v17, v16
	v_mul_f32_e32 v14, 0xbfb8aa3b, v14
	v_mul_f32_e32 v15, 0xbfb8aa3b, v15
	v_div_fmas_f32 v16, v16, v21, v17
	v_exp_f32_e32 v14, v14
	v_exp_f32_e32 v15, v15
	v_div_fixup_f32 v9, v16, v13, v9
	v_fma_f32 v13, -v18, v19, 1.0
	v_fmac_f32_e32 v19, v13, v19
	v_div_scale_f32 v13, vcc, v8, v12, v8
	v_mul_f32_e32 v16, v13, v19
	v_fma_f32 v17, -v18, v16, v13
	v_pk_add_f32 v[14:15], v[14:15], 1.0 op_sel_hi:[1,0]
	v_fmac_f32_e32 v16, v17, v19
	v_div_scale_f32 v17, s[30:31], v15, v15, v11
	v_fma_f32 v13, -v18, v16, v13
	v_rcp_f32_e32 v18, v17
	v_div_fmas_f32 v13, v13, v19, v16
	v_div_fixup_f32 v8, v13, v12, v8
	v_mul_f32_e32 v4, 0xbfb8aa3b, v4
	v_fma_f32 v12, -v17, v18, 1.0
	v_fmac_f32_e32 v18, v12, v18
	v_div_scale_f32 v12, vcc, v11, v15, v11
	v_mul_f32_e32 v13, v12, v18
	v_fma_f32 v16, -v17, v13, v12
	v_fmac_f32_e32 v13, v16, v18
	v_div_scale_f32 v16, s[30:31], v14, v14, v10
	v_fma_f32 v12, -v17, v13, v12
	v_rcp_f32_e32 v17, v16
	v_div_fmas_f32 v12, v12, v18, v13
	v_div_fixup_f32 v11, v12, v15, v11
	v_mul_f32_e32 v5, 0xbfb8aa3b, v5
	v_fma_f32 v12, -v16, v17, 1.0
	v_fmac_f32_e32 v17, v12, v17
	v_div_scale_f32 v12, vcc, v10, v14, v10
	v_mul_f32_e32 v13, v12, v17
	v_exp_f32_e32 v4, v4
	v_exp_f32_e32 v5, v5
	v_fma_f32 v15, -v16, v13, v12
	v_fmac_f32_e32 v13, v15, v17
	v_fma_f32 v12, -v16, v13, v12
	v_div_fmas_f32 v12, v12, v17, v13
	v_pk_add_f32 v[4:5], v[4:5], 1.0 op_sel_hi:[1,0]
	v_div_fixup_f32 v10, v12, v14, v10
	v_div_scale_f32 v14, s[30:31], v5, v5, v1
	v_rcp_f32_e32 v15, v14
	v_add_co_u32_e32 v12, vcc, s71, v116
	v_cvt_pk_bf16_f32 v8, v8, v9
	v_cvt_pk_bf16_f32 v9, v10, v11
	v_addc_co_u32_e32 v13, vcc, 0, v117, vcc
	global_store_dwordx2 v[12:13], v[8:9], off
	v_fma_f32 v8, -v14, v15, 1.0
	v_fmac_f32_e32 v15, v8, v15
	v_div_scale_f32 v8, vcc, v1, v5, v1
	v_mul_f32_e32 v9, v8, v15
	v_fma_f32 v12, -v14, v9, v8
	v_fmac_f32_e32 v9, v12, v15
	v_div_scale_f32 v12, s[30:31], v4, v4, v0
	v_rcp_f32_e32 v13, v12
	v_fma_f32 v8, -v14, v9, v8
	v_mul_f32_e32 v6, 0xbfb8aa3b, v6
	v_mul_f32_e32 v7, 0xbfb8aa3b, v7
	v_div_fmas_f32 v8, v8, v15, v9
	v_exp_f32_e32 v6, v6
	v_exp_f32_e32 v7, v7
	v_div_fixup_f32 v1, v8, v5, v1
	v_fma_f32 v5, -v12, v13, 1.0
	v_fmac_f32_e32 v13, v5, v13
	v_div_scale_f32 v5, vcc, v0, v4, v0
	v_mul_f32_e32 v8, v5, v13
	v_fma_f32 v9, -v12, v8, v5
	v_pk_add_f32 v[6:7], v[6:7], 1.0 op_sel_hi:[1,0]
	v_fmac_f32_e32 v8, v9, v13
	v_div_scale_f32 v9, s[30:31], v7, v7, v3
	v_fma_f32 v5, -v12, v8, v5
	v_rcp_f32_e32 v12, v9
	v_div_fmas_f32 v5, v5, v13, v8
	v_div_fixup_f32 v0, v5, v4, v0
	v_lshl_add_u64 v[10:11], v[116:117], 0, s[14:15]
	v_fma_f32 v4, -v9, v12, 1.0
	v_fmac_f32_e32 v12, v4, v12
	v_div_scale_f32 v4, vcc, v3, v7, v3
	v_mul_f32_e32 v5, v4, v12
	v_fma_f32 v8, -v9, v5, v4
	v_fmac_f32_e32 v5, v8, v12
	v_div_scale_f32 v8, s[30:31], v6, v6, v2
	v_fma_f32 v4, -v9, v5, v4
	v_rcp_f32_e32 v9, v8
	v_div_fmas_f32 v4, v4, v12, v5
	v_div_fixup_f32 v3, v4, v7, v3
	v_cvt_pk_bf16_f32 v0, v0, v1
	v_fma_f32 v4, -v8, v9, 1.0
	v_fmac_f32_e32 v9, v4, v9
	v_div_scale_f32 v4, vcc, v2, v6, v2
	v_mul_f32_e32 v5, v4, v9
	v_fma_f32 v7, -v8, v5, v4
	v_fmac_f32_e32 v5, v7, v9
	v_fma_f32 v4, -v8, v5, v4
	v_div_fmas_f32 v4, v4, v9, v5
	v_div_fixup_f32 v2, v4, v6, v2
	v_cvt_pk_bf16_f32 v1, v2, v3
	s_and_b64 vcc, exec, s[4:5]
	s_mov_b32 s72, s16
	s_mov_b32 s28, s18
	s_mov_b64 s[34:35], s[26:27]
	s_mov_b64 s[30:31], s[20:21]
	global_store_dwordx2 v[10:11], v[0:1], off offset:128
	s_cbranch_vccz .LBB0_1134
	s_waitcnt vmcnt(0)
	s_cmpk_gt_u32 s40, 0xff
	s_cbranch_scc1 .LBB0_1145
	s_barrier

.LBB0_1291:
	ds_read_b128 v[154:157], v151
	ds_read_b128 v[158:161], v151 offset:1024
	ds_read_b128 v[162:165], v151 offset:2048
	ds_read_b128 v[166:169], v151 offset:3072
	s_add_u32 s36, s34, 0xfffc0080
	s_addc_u32 s37, s35, -1
	s_cmp_eq_u32 s79, 12
	s_cselect_b32 s39, s21, s37
	s_cselect_b32 s38, s75, s36
	s_cselect_b32 s37, s19, s78
	s_cselect_b32 s36, s76, s77
	v_lshl_add_u64 v[202:203], s[34:35], 0, v[138:139]
	s_add_i32 m0, s31, 0xc000
	ds_read_b128 v[170:173], v152
	ds_read_b128 v[174:177], v152 offset:1024
	ds_read_b128 v[178:181], v152 offset:2048
	ds_read_b128 v[182:185], v152 offset:3072
	ds_read_b128 v[186:189], v152 offset:4096
	ds_read_b128 v[190:193], v152 offset:5120
	ds_read_b128 v[194:197], v152 offset:6144
	ds_read_b128 v[198:201], v152 offset:7168
	global_load_lds_dwordx4 v[202:203], off
	v_lshl_add_u64 v[202:203], s[34:35], 0, v[140:141]
	s_add_i32 m0, s31, 0xe000
	s_nop 0
	global_load_lds_dwordx4 v[202:203], off
	s_waitcnt lgkmcnt(8)
	s_barrier
	s_waitcnt lgkmcnt(0)
	s_waitcnt lgkmcnt(0)
	v_mfma_f32_16x16x32_bf16 v[124:127], v[154:157], v[170:173], v[124:127]
	v_mfma_f32_16x16x32_bf16 v[120:123], v[162:165], v[170:173], v[120:123]
	v_mfma_f32_16x16x32_bf16 v[108:111], v[154:157], v[178:181], v[108:111]
	v_mfma_f32_16x16x32_bf16 v[104:107], v[162:165], v[178:181], v[104:107]
	v_mfma_f32_16x16x32_bf16 v[92:95], v[154:157], v[186:189], v[92:95]
	v_mfma_f32_16x16x32_bf16 v[88:91], v[162:165], v[186:189], v[88:91]
	v_mfma_f32_16x16x32_bf16 v[76:79], v[154:157], v[194:197], v[76:79]
	v_mfma_f32_16x16x32_bf16 v[72:75], v[162:165], v[194:197], v[72:75]
	v_mfma_f32_16x16x32_bf16 v[124:127], v[158:161], v[174:177], v[124:127]
	v_mfma_f32_16x16x32_bf16 v[120:123], v[166:169], v[174:177], v[120:123]
	v_mfma_f32_16x16x32_bf16 v[108:111], v[158:161], v[182:185], v[108:111]
	v_mfma_f32_16x16x32_bf16 v[104:107], v[166:169], v[182:185], v[104:107]
	v_mfma_f32_16x16x32_bf16 v[92:95], v[158:161], v[190:193], v[92:95]
	v_mfma_f32_16x16x32_bf16 v[88:91], v[166:169], v[190:193], v[88:91]
	v_mfma_f32_16x16x32_bf16 v[76:79], v[158:161], v[198:201], v[76:79]
	v_mfma_f32_16x16x32_bf16 v[72:75], v[166:169], v[198:201], v[72:75]
	s_barrier
	s_add_i32 s80, s62, s52
	v_lshl_add_u64 v[218:219], s[36:37], 0, v[132:133]
	s_mov_b32 m0, s80
	ds_read_b128 v[202:205], v153
	ds_read_b128 v[206:209], v153 offset:1024
	ds_read_b128 v[210:213], v153 offset:2048
	ds_read_b128 v[214:217], v153 offset:3072
	global_load_lds_dwordx4 v[218:219], off
	v_lshl_add_u64 v[220:221], s[36:37], 0, v[136:137]
	s_add_i32 m0, s80, 0x2000
	s_nop 0
	global_load_lds_dwordx4 v[220:221], off
	s_barrier
	s_waitcnt lgkmcnt(0)
	s_waitcnt lgkmcnt(0)
	v_mfma_f32_16x16x32_bf16 v[116:119], v[202:205], v[170:173], v[116:119]
	v_mfma_f32_16x16x32_bf16 v[112:115], v[210:213], v[170:173], v[112:115]
	v_mfma_f32_16x16x32_bf16 v[100:103], v[202:205], v[178:181], v[100:103]
	v_mfma_f32_16x16x32_bf16 v[96:99], v[210:213], v[178:181], v[96:99]
	v_mfma_f32_16x16x32_bf16 v[84:87], v[202:205], v[186:189], v[84:87]
	v_mfma_f32_16x16x32_bf16 v[80:83], v[210:213], v[186:189], v[80:83]
	v_mfma_f32_16x16x32_bf16 v[68:71], v[202:205], v[194:197], v[68:71]
	v_mfma_f32_16x16x32_bf16 v[64:67], v[210:213], v[194:197], v[64:67]
	v_mfma_f32_16x16x32_bf16 v[116:119], v[206:209], v[174:177], v[116:119]
	v_mfma_f32_16x16x32_bf16 v[112:115], v[214:217], v[174:177], v[112:115]
	v_mfma_f32_16x16x32_bf16 v[100:103], v[206:209], v[182:185], v[100:103]
	v_mfma_f32_16x16x32_bf16 v[96:99], v[214:217], v[182:185], v[96:99]
	v_mfma_f32_16x16x32_bf16 v[84:87], v[206:209], v[190:193], v[84:87]
	v_mfma_f32_16x16x32_bf16 v[80:83], v[214:217], v[190:193], v[80:83]
	v_mfma_f32_16x16x32_bf16 v[68:71], v[206:209], v[198:201], v[68:71]
	v_mfma_f32_16x16x32_bf16 v[64:67], v[214:217], v[198:201], v[64:67]
	s_mov_b32 m0, s31
	v_lshl_add_u64 v[222:223], s[38:39], 0, v[130:131]
	s_barrier
	ds_read_b128 v[170:173], v152 offset:16384
	ds_read_b128 v[174:177], v152 offset:17408
	ds_read_b128 v[178:181], v152 offset:18432
	ds_read_b128 v[182:185], v152 offset:19456
	ds_read_b128 v[186:189], v152 offset:20480
	ds_read_b128 v[190:193], v152 offset:21504
	ds_read_b128 v[194:197], v152 offset:22528
	ds_read_b128 v[198:201], v152 offset:23552
	global_load_lds_dwordx4 v[222:223], off
	v_lshl_add_u64 v[224:225], s[38:39], 0, v[134:135]
	s_mov_b32 m0, s53
	s_nop 0
	global_load_lds_dwordx4 v[224:225], off
	s_barrier
	s_waitcnt lgkmcnt(0)
	s_waitcnt lgkmcnt(0)
	v_mfma_f32_16x16x32_bf16 v[60:63], v[154:157], v[170:173], v[60:63]
	v_mfma_f32_16x16x32_bf16 v[56:59], v[162:165], v[170:173], v[56:59]
	v_mfma_f32_16x16x32_bf16 v[44:47], v[154:157], v[178:181], v[44:47]
	v_mfma_f32_16x16x32_bf16 v[40:43], v[162:165], v[178:181], v[40:43]
	v_mfma_f32_16x16x32_bf16 v[28:31], v[154:157], v[186:189], v[28:31]
	v_mfma_f32_16x16x32_bf16 v[24:27], v[162:165], v[186:189], v[24:27]
	v_mfma_f32_16x16x32_bf16 v[12:15], v[154:157], v[194:197], v[12:15]
	v_mfma_f32_16x16x32_bf16 v[8:11], v[162:165], v[194:197], v[8:11]
	v_mfma_f32_16x16x32_bf16 v[60:63], v[158:161], v[174:177], v[60:63]
	v_mfma_f32_16x16x32_bf16 v[56:59], v[166:169], v[174:177], v[56:59]
	v_mfma_f32_16x16x32_bf16 v[44:47], v[158:161], v[182:185], v[44:47]
	v_mfma_f32_16x16x32_bf16 v[40:43], v[166:169], v[182:185], v[40:43]
	v_mfma_f32_16x16x32_bf16 v[28:31], v[158:161], v[190:193], v[28:31]
	v_mfma_f32_16x16x32_bf16 v[24:27], v[166:169], v[190:193], v[24:27]
	v_mfma_f32_16x16x32_bf16 v[12:15], v[158:161], v[198:201], v[12:15]
	v_mfma_f32_16x16x32_bf16 v[8:11], v[166:169], v[198:201], v[8:11]
	s_barrier
	s_add_u32 s80, s36, 0x40000
	s_addc_u32 s81, s37, 0
	s_add_i32 s82, s63, s52
	v_lshl_add_u64 v[154:155], s[80:81], 0, v[132:133]
	s_mov_b32 m0, s82
	s_nop 0
	global_load_lds_dwordx4 v[154:155], off
	v_lshl_add_u64 v[154:155], s[80:81], 0, v[136:137]
	s_add_i32 m0, s82, 0x2000
	s_nop 0
	global_load_lds_dwordx4 v[154:155], off
	s_waitcnt vmcnt(6)
	s_barrier
	v_mfma_f32_16x16x32_bf16 v[52:55], v[202:205], v[170:173], v[52:55]
	v_mfma_f32_16x16x32_bf16 v[48:51], v[210:213], v[170:173], v[48:51]
	v_mfma_f32_16x16x32_bf16 v[36:39], v[202:205], v[178:181], v[36:39]
	v_mfma_f32_16x16x32_bf16 v[32:35], v[210:213], v[178:181], v[32:35]
	v_mfma_f32_16x16x32_bf16 v[20:23], v[202:205], v[186:189], v[20:23]
	v_mfma_f32_16x16x32_bf16 v[16:19], v[210:213], v[186:189], v[16:19]
	v_mfma_f32_16x16x32_bf16 v[4:7], v[202:205], v[194:197], v[4:7]
	v_mfma_f32_16x16x32_bf16 v[0:3], v[210:213], v[194:197], v[0:3]
	v_mfma_f32_16x16x32_bf16 v[52:55], v[206:209], v[174:177], v[52:55]
	v_mfma_f32_16x16x32_bf16 v[48:51], v[214:217], v[174:177], v[48:51]
	v_mfma_f32_16x16x32_bf16 v[36:39], v[206:209], v[182:185], v[36:39]
	v_mfma_f32_16x16x32_bf16 v[32:35], v[214:217], v[182:185], v[32:35]
	v_mfma_f32_16x16x32_bf16 v[20:23], v[206:209], v[190:193], v[20:23]
	v_mfma_f32_16x16x32_bf16 v[16:19], v[214:217], v[190:193], v[16:19]
	v_mfma_f32_16x16x32_bf16 v[4:7], v[206:209], v[198:201], v[4:7]
	v_mfma_f32_16x16x32_bf16 v[0:3], v[214:217], v[198:201], v[0:3]
	s_add_i32 s80, 0, 0x18000
	v_add_u32_e32 v166, s80, v149
	s_barrier
	ds_read_b128 v[154:157], v166
	ds_read_b128 v[158:161], v166 offset:1024
	ds_read_b128 v[162:165], v166 offset:2048
	ds_read_b128 v[166:169], v166 offset:3072
	s_add_u32 s38, s38, 0x40000
	s_addc_u32 s39, s39, 0
	s_mov_b32 m0, s54
	v_lshl_add_u64 v[202:203], s[38:39], 0, v[130:131]
	ds_read_b128 v[170:173], v152 offset:32768
	ds_read_b128 v[174:177], v152 offset:33792
	ds_read_b128 v[178:181], v152 offset:34816
	ds_read_b128 v[182:185], v152 offset:35840
	ds_read_b128 v[186:189], v152 offset:36864
	ds_read_b128 v[190:193], v152 offset:37888
	ds_read_b128 v[194:197], v152 offset:38912
	ds_read_b128 v[198:201], v152 offset:39936
	global_load_lds_dwordx4 v[202:203], off
	v_lshl_add_u64 v[202:203], s[38:39], 0, v[134:135]
	s_mov_b32 m0, s55
	s_nop 0
	global_load_lds_dwordx4 v[202:203], off
	s_waitcnt lgkmcnt(8)
	s_barrier
	s_waitcnt lgkmcnt(0)
	s_waitcnt lgkmcnt(0)
	v_mfma_f32_16x16x32_bf16 v[124:127], v[154:157], v[170:173], v[124:127]
	v_mfma_f32_16x16x32_bf16 v[120:123], v[162:165], v[170:173], v[120:123]
	v_mfma_f32_16x16x32_bf16 v[108:111], v[154:157], v[178:181], v[108:111]
	v_mfma_f32_16x16x32_bf16 v[104:107], v[162:165], v[178:181], v[104:107]
	v_mfma_f32_16x16x32_bf16 v[92:95], v[154:157], v[186:189], v[92:95]
	v_mfma_f32_16x16x32_bf16 v[88:91], v[162:165], v[186:189], v[88:91]
	v_mfma_f32_16x16x32_bf16 v[76:79], v[154:157], v[194:197], v[76:79]
	v_mfma_f32_16x16x32_bf16 v[72:75], v[162:165], v[194:197], v[72:75]
	v_mfma_f32_16x16x32_bf16 v[124:127], v[158:161], v[174:177], v[124:127]
	v_mfma_f32_16x16x32_bf16 v[120:123], v[166:169], v[174:177], v[120:123]
	v_mfma_f32_16x16x32_bf16 v[108:111], v[158:161], v[182:185], v[108:111]
	v_mfma_f32_16x16x32_bf16 v[104:107], v[166:169], v[182:185], v[104:107]
	v_mfma_f32_16x16x32_bf16 v[92:95], v[158:161], v[190:193], v[92:95]
	v_mfma_f32_16x16x32_bf16 v[88:91], v[166:169], v[190:193], v[88:91]
	v_mfma_f32_16x16x32_bf16 v[76:79], v[158:161], v[198:201], v[76:79]
	v_mfma_f32_16x16x32_bf16 v[72:75], v[166:169], v[198:201], v[72:75]
	s_barrier
	s_add_i32 s38, 0, 0x1c000
	s_add_i32 s39, s80, s52
	v_add_u32_e32 v214, s38, v149
	v_lshl_add_u64 v[218:219], v[218:219], 0, s[8:9]
	s_mov_b32 m0, s39
	ds_read_b128 v[202:205], v214
	ds_read_b128 v[206:209], v214 offset:1024
	ds_read_b128 v[210:213], v214 offset:2048
	ds_read_b128 v[214:217], v214 offset:3072
	global_load_lds_dwordx4 v[218:219], off
	v_lshl_add_u64 v[218:219], v[220:221], 0, s[8:9]
	s_add_i32 m0, s39, 0x2000
	s_nop 0
	global_load_lds_dwordx4 v[218:219], off
	s_barrier
	s_waitcnt lgkmcnt(0)
	s_waitcnt lgkmcnt(0)
	v_mfma_f32_16x16x32_bf16 v[116:119], v[202:205], v[170:173], v[116:119]
	v_mfma_f32_16x16x32_bf16 v[112:115], v[210:213], v[170:173], v[112:115]
	v_mfma_f32_16x16x32_bf16 v[100:103], v[202:205], v[178:181], v[100:103]
	v_mfma_f32_16x16x32_bf16 v[96:99], v[210:213], v[178:181], v[96:99]
	v_mfma_f32_16x16x32_bf16 v[84:87], v[202:205], v[186:189], v[84:87]
	v_mfma_f32_16x16x32_bf16 v[80:83], v[210:213], v[186:189], v[80:83]
	v_mfma_f32_16x16x32_bf16 v[68:71], v[202:205], v[194:197], v[68:71]
	v_mfma_f32_16x16x32_bf16 v[64:67], v[210:213], v[194:197], v[64:67]
	v_mfma_f32_16x16x32_bf16 v[116:119], v[206:209], v[174:177], v[116:119]
	v_mfma_f32_16x16x32_bf16 v[112:115], v[214:217], v[174:177], v[112:115]
	v_mfma_f32_16x16x32_bf16 v[100:103], v[206:209], v[182:185], v[100:103]
	v_mfma_f32_16x16x32_bf16 v[96:99], v[214:217], v[182:185], v[96:99]
	v_mfma_f32_16x16x32_bf16 v[84:87], v[206:209], v[190:193], v[84:87]
	v_mfma_f32_16x16x32_bf16 v[80:83], v[214:217], v[190:193], v[80:83]
	v_mfma_f32_16x16x32_bf16 v[68:71], v[206:209], v[198:201], v[68:71]
	v_mfma_f32_16x16x32_bf16 v[64:67], v[214:217], v[198:201], v[64:67]
	s_mov_b32 m0, s57
	v_lshl_add_u64 v[218:219], v[222:223], 0, s[8:9]
	s_barrier
	ds_read_b128 v[170:173], v152 offset:49152
	ds_read_b128 v[174:177], v152 offset:50176
	ds_read_b128 v[178:181], v152 offset:51200
	ds_read_b128 v[182:185], v152 offset:52224
	ds_read_b128 v[186:189], v152 offset:53248
	ds_read_b128 v[190:193], v152 offset:54272
	ds_read_b128 v[194:197], v152 offset:55296
	ds_read_b128 v[198:201], v152 offset:56320
	global_load_lds_dwordx4 v[218:219], off
	v_lshl_add_u64 v[218:219], v[224:225], 0, s[8:9]
	s_mov_b32 m0, s60
	s_nop 0
	global_load_lds_dwordx4 v[218:219], off
	s_barrier
	s_waitcnt lgkmcnt(0)
	s_waitcnt lgkmcnt(0)
	v_mfma_f32_16x16x32_bf16 v[60:63], v[154:157], v[170:173], v[60:63]
	v_mfma_f32_16x16x32_bf16 v[56:59], v[162:165], v[170:173], v[56:59]
	v_mfma_f32_16x16x32_bf16 v[44:47], v[154:157], v[178:181], v[44:47]
	v_mfma_f32_16x16x32_bf16 v[40:43], v[162:165], v[178:181], v[40:43]
	v_mfma_f32_16x16x32_bf16 v[28:31], v[154:157], v[186:189], v[28:31]
	v_mfma_f32_16x16x32_bf16 v[24:27], v[162:165], v[186:189], v[24:27]
	v_mfma_f32_16x16x32_bf16 v[12:15], v[154:157], v[194:197], v[12:15]
	v_mfma_f32_16x16x32_bf16 v[8:11], v[162:165], v[194:197], v[8:11]
	v_mfma_f32_16x16x32_bf16 v[60:63], v[158:161], v[174:177], v[60:63]
	v_mfma_f32_16x16x32_bf16 v[56:59], v[166:169], v[174:177], v[56:59]
	v_mfma_f32_16x16x32_bf16 v[44:47], v[158:161], v[182:185], v[44:47]
	v_mfma_f32_16x16x32_bf16 v[40:43], v[166:169], v[182:185], v[40:43]
	v_mfma_f32_16x16x32_bf16 v[28:31], v[158:161], v[190:193], v[28:31]
	v_mfma_f32_16x16x32_bf16 v[24:27], v[166:169], v[190:193], v[24:27]
	v_mfma_f32_16x16x32_bf16 v[12:15], v[158:161], v[198:201], v[12:15]
	v_mfma_f32_16x16x32_bf16 v[8:11], v[166:169], v[198:201], v[8:11]
	s_barrier
	s_add_u32 s36, s36, 0x40080
	s_addc_u32 s37, s37, 0
	s_add_i32 s38, s38, s52
	v_lshl_add_u64 v[154:155], s[36:37], 0, v[132:133]
	s_mov_b32 m0, s38
	s_nop 0
	global_load_lds_dwordx4 v[154:155], off
	v_lshl_add_u64 v[154:155], s[36:37], 0, v[136:137]
	s_add_i32 m0, s38, 0x2000
	s_nop 0
	global_load_lds_dwordx4 v[154:155], off
	s_waitcnt vmcnt(6)
	s_barrier
	v_mfma_f32_16x16x32_bf16 v[52:55], v[202:205], v[170:173], v[52:55]
	v_mfma_f32_16x16x32_bf16 v[48:51], v[210:213], v[170:173], v[48:51]
	v_mfma_f32_16x16x32_bf16 v[36:39], v[202:205], v[178:181], v[36:39]
	v_mfma_f32_16x16x32_bf16 v[32:35], v[210:213], v[178:181], v[32:35]
	v_mfma_f32_16x16x32_bf16 v[20:23], v[202:205], v[186:189], v[20:23]
	v_mfma_f32_16x16x32_bf16 v[16:19], v[210:213], v[186:189], v[16:19]
	v_mfma_f32_16x16x32_bf16 v[4:7], v[202:205], v[194:197], v[4:7]
	v_mfma_f32_16x16x32_bf16 v[0:3], v[210:213], v[194:197], v[0:3]
	v_mfma_f32_16x16x32_bf16 v[52:55], v[206:209], v[174:177], v[52:55]
	v_mfma_f32_16x16x32_bf16 v[48:51], v[214:217], v[174:177], v[48:51]
	v_mfma_f32_16x16x32_bf16 v[36:39], v[206:209], v[182:185], v[36:39]
	v_mfma_f32_16x16x32_bf16 v[32:35], v[214:217], v[182:185], v[32:35]
	v_mfma_f32_16x16x32_bf16 v[20:23], v[206:209], v[190:193], v[20:23]
	v_mfma_f32_16x16x32_bf16 v[16:19], v[214:217], v[190:193], v[16:19]
	v_mfma_f32_16x16x32_bf16 v[4:7], v[206:209], v[198:201], v[4:7]
	v_mfma_f32_16x16x32_bf16 v[0:3], v[214:217], v[198:201], v[0:3]
	s_add_i32 s79, s79, 2
	s_add_u32 s34, s34, 0x100
	s_addc_u32 s35, s35, 0
	s_add_u32 s77, s77, 0x100
	s_addc_u32 s78, s78, 0
	s_cmp_gt_u32 s79, 13
	s_barrier
	s_cbranch_scc0 .LBB0_1291
	v_lshl_add_u32 v154, s30, 8, v148
	v_max_f32_e32 v126, v126, v126
	v_max_f32_e32 v127, v127, v127
	v_lshl_or_b32 v156, s74, 8, v150
	v_ashrrev_i32_e32 v155, 31, v154
	v_max_f32_e32 v124, v124, v124
	v_max_f32_e32 v120, v120, v120
	v_max_f32_e32 v125, v125, v125
	v_max_f32_e32 v121, v121, v121
	v_max_f32_e32 v126, 0, v126
	v_max_f32_e32 v122, v122, v122
	v_max_f32_e32 v127, 0, v127
	v_max_f32_e32 v123, v123, v123
	v_lshlrev_b64 v[158:159], 13, v[154:155]
	v_max_f32_e32 v124, 0, v124
	v_max_f32_e32 v120, 0, v120
	v_max_f32_e32 v125, 0, v125
	v_max_f32_e32 v121, 0, v121
	v_max_f32_e32 v122, 0, v122
	v_max_f32_e32 v123, 0, v123
	v_pk_mul_f32 v[126:127], v[126:127], v[126:127]
	v_ashrrev_i32_e32 v157, 31, v156
	v_lshl_add_u64 v[158:159], s[46:47], 0, v[158:159]
	v_pk_mul_f32 v[124:125], v[124:125], v[124:125]
	v_pk_mul_f32 v[120:121], v[120:121], v[120:121]
	v_pk_mul_f32 v[160:161], v[122:123], v[122:123]
	v_cvt_pk_bf16_f32 v123, v126, v127
	v_lshlrev_b64 v[126:127], 1, v[156:157]
	v_max_f32_e32 v112, v112, v112
	v_max_f32_e32 v113, v113, v113
	v_cvt_pk_bf16_f32 v122, v124, v125
	v_cvt_pk_bf16_f32 v124, v120, v121
	v_cvt_pk_bf16_f32 v125, v160, v161
	v_lshl_add_u64 v[120:121], v[158:159], 0, v[126:127]
	v_max_f32_e32 v112, 0, v112
	v_max_f32_e32 v113, 0, v113
	global_store_dwordx4 v[120:121], v[122:125], off
	v_max_f32_e32 v116, v116, v116
	v_max_f32_e32 v117, v117, v117
	v_pk_mul_f32 v[122:123], v[112:113], v[112:113]
	v_max_f32_e32 v113, v114, v114
	v_max_f32_e32 v112, v118, v118
	v_max_f32_e32 v114, 0, v113
	v_max_f32_e32 v113, v119, v119
	v_max_f32_e32 v115, v115, v115
	v_max_f32_e32 v116, 0, v116
	v_max_f32_e32 v117, 0, v117
	v_max_f32_e32 v112, 0, v112
	v_max_f32_e32 v113, 0, v113
	v_max_f32_e32 v115, 0, v115
	v_pk_mul_f32 v[116:117], v[116:117], v[116:117]
	v_pk_mul_f32 v[118:119], v[112:113], v[112:113]
	v_pk_mul_f32 v[124:125], v[114:115], v[114:115]
	v_max_f32_e32 v104, v104, v104
	v_max_f32_e32 v105, v105, v105
	v_cvt_pk_bf16_f32 v112, v116, v117
	v_cvt_pk_bf16_f32 v113, v118, v119
	v_cvt_pk_bf16_f32 v114, v122, v123
	v_cvt_pk_bf16_f32 v115, v124, v125
	v_max_f32_e32 v104, 0, v104
	v_max_f32_e32 v105, 0, v105
	global_store_dwordx4 v[120:121], v[112:115], off offset:256
	v_max_f32_e32 v108, v108, v108
	v_max_f32_e32 v109, v109, v109
	v_or_b32_e32 v112, 16, v154
	v_pk_mul_f32 v[114:115], v[104:105], v[104:105]
	v_max_f32_e32 v105, v106, v106
	v_ashrrev_i32_e32 v113, 31, v112
	v_max_f32_e32 v104, v110, v110
	v_max_f32_e32 v106, 0, v105
	v_max_f32_e32 v105, v111, v111
	v_max_f32_e32 v107, v107, v107
	v_lshlrev_b64 v[112:113], 13, v[112:113]
	v_max_f32_e32 v108, 0, v108
	v_max_f32_e32 v109, 0, v109
	v_max_f32_e32 v104, 0, v104
	v_max_f32_e32 v105, 0, v105
	v_max_f32_e32 v107, 0, v107
	v_lshl_add_u64 v[112:113], s[46:47], 0, v[112:113]
	v_pk_mul_f32 v[108:109], v[108:109], v[108:109]
	v_pk_mul_f32 v[110:111], v[104:105], v[104:105]
	v_pk_mul_f32 v[116:117], v[106:107], v[106:107]
	v_max_f32_e32 v96, v96, v96
	v_max_f32_e32 v97, v97, v97
	v_cvt_pk_bf16_f32 v104, v108, v109
	v_cvt_pk_bf16_f32 v105, v110, v111
	v_cvt_pk_bf16_f32 v106, v114, v115
	v_cvt_pk_bf16_f32 v107, v116, v117
	v_lshl_add_u64 v[108:109], v[112:113], 0, v[126:127]
	v_max_f32_e32 v96, 0, v96
	v_max_f32_e32 v97, 0, v97
	global_store_dwordx4 v[108:109], v[104:107], off
	v_max_f32_e32 v100, v100, v100
	v_max_f32_e32 v101, v101, v101
	v_pk_mul_f32 v[104:105], v[96:97], v[96:97]
	v_max_f32_e32 v97, v98, v98
	v_max_f32_e32 v96, v102, v102
	v_max_f32_e32 v98, 0, v97
	v_max_f32_e32 v97, v103, v103
	v_max_f32_e32 v99, v99, v99
	v_max_f32_e32 v100, 0, v100
	v_max_f32_e32 v101, 0, v101
	v_max_f32_e32 v96, 0, v96
	v_max_f32_e32 v97, 0, v97
	v_max_f32_e32 v99, 0, v99
	v_pk_mul_f32 v[100:101], v[100:101], v[100:101]
	v_pk_mul_f32 v[102:103], v[96:97], v[96:97]
	v_pk_mul_f32 v[106:107], v[98:99], v[98:99]
	v_max_f32_e32 v88, v88, v88
	v_max_f32_e32 v89, v89, v89
	v_cvt_pk_bf16_f32 v96, v100, v101
	v_cvt_pk_bf16_f32 v97, v102, v103
	v_cvt_pk_bf16_f32 v98, v104, v105
	v_cvt_pk_bf16_f32 v99, v106, v107
	v_max_f32_e32 v88, 0, v88
	v_max_f32_e32 v89, 0, v89
	global_store_dwordx4 v[108:109], v[96:99], off offset:256
	v_max_f32_e32 v92, v92, v92
	v_max_f32_e32 v93, v93, v93
	v_or_b32_e32 v96, 32, v154
	v_pk_mul_f32 v[98:99], v[88:89], v[88:89]
	v_max_f32_e32 v89, v90, v90
	v_ashrrev_i32_e32 v97, 31, v96
	v_max_f32_e32 v88, v94, v94
	v_max_f32_e32 v90, 0, v89
	v_max_f32_e32 v89, v95, v95
	v_max_f32_e32 v91, v91, v91
	v_lshlrev_b64 v[96:97], 13, v[96:97]
	v_max_f32_e32 v92, 0, v92
	v_max_f32_e32 v93, 0, v93
	v_max_f32_e32 v88, 0, v88
	v_max_f32_e32 v89, 0, v89
	v_max_f32_e32 v91, 0, v91
	v_lshl_add_u64 v[96:97], s[46:47], 0, v[96:97]
	v_pk_mul_f32 v[92:93], v[92:93], v[92:93]
	v_pk_mul_f32 v[94:95], v[88:89], v[88:89]
	v_pk_mul_f32 v[100:101], v[90:91], v[90:91]
	v_max_f32_e32 v80, v80, v80
	v_max_f32_e32 v81, v81, v81
	v_cvt_pk_bf16_f32 v88, v92, v93
	v_cvt_pk_bf16_f32 v89, v94, v95
	v_cvt_pk_bf16_f32 v90, v98, v99
	v_cvt_pk_bf16_f32 v91, v100, v101
	v_lshl_add_u64 v[92:93], v[96:97], 0, v[126:127]
	v_max_f32_e32 v80, 0, v80
	v_max_f32_e32 v81, 0, v81
	global_store_dwordx4 v[92:93], v[88:91], off
	v_max_f32_e32 v84, v84, v84
	v_max_f32_e32 v85, v85, v85
	v_pk_mul_f32 v[88:89], v[80:81], v[80:81]
	v_max_f32_e32 v81, v82, v82
	v_max_f32_e32 v80, v86, v86
	v_max_f32_e32 v82, 0, v81
	v_max_f32_e32 v81, v87, v87
	v_max_f32_e32 v83, v83, v83
	v_max_f32_e32 v84, 0, v84
	v_max_f32_e32 v85, 0, v85
	v_max_f32_e32 v80, 0, v80
	v_max_f32_e32 v81, 0, v81
	v_max_f32_e32 v83, 0, v83
	v_pk_mul_f32 v[84:85], v[84:85], v[84:85]
	v_pk_mul_f32 v[86:87], v[80:81], v[80:81]
	v_pk_mul_f32 v[90:91], v[82:83], v[82:83]
	v_max_f32_e32 v72, v72, v72
	v_max_f32_e32 v73, v73, v73
	v_cvt_pk_bf16_f32 v80, v84, v85
	v_cvt_pk_bf16_f32 v81, v86, v87
	v_cvt_pk_bf16_f32 v82, v88, v89
	v_cvt_pk_bf16_f32 v83, v90, v91
	v_max_f32_e32 v72, 0, v72
	v_max_f32_e32 v73, 0, v73
	global_store_dwordx4 v[92:93], v[80:83], off offset:256
	v_max_f32_e32 v76, v76, v76
	v_max_f32_e32 v77, v77, v77
	v_or_b32_e32 v80, 48, v154
	v_pk_mul_f32 v[82:83], v[72:73], v[72:73]
	v_max_f32_e32 v73, v74, v74
	v_ashrrev_i32_e32 v81, 31, v80
	v_max_f32_e32 v72, v78, v78
	v_max_f32_e32 v74, 0, v73
	v_max_f32_e32 v73, v79, v79
	v_max_f32_e32 v75, v75, v75
	v_lshlrev_b64 v[80:81], 13, v[80:81]
	v_max_f32_e32 v76, 0, v76
	v_max_f32_e32 v77, 0, v77
	v_max_f32_e32 v72, 0, v72
	v_max_f32_e32 v73, 0, v73
	v_max_f32_e32 v75, 0, v75
	v_lshl_add_u64 v[80:81], s[46:47], 0, v[80:81]
	v_pk_mul_f32 v[76:77], v[76:77], v[76:77]
	v_pk_mul_f32 v[78:79], v[72:73], v[72:73]
	v_pk_mul_f32 v[84:85], v[74:75], v[74:75]
	v_max_f32_e32 v64, v64, v64
	v_max_f32_e32 v65, v65, v65
	v_cvt_pk_bf16_f32 v72, v76, v77
	v_cvt_pk_bf16_f32 v73, v78, v79
	v_cvt_pk_bf16_f32 v74, v82, v83
	v_cvt_pk_bf16_f32 v75, v84, v85
	v_lshl_add_u64 v[76:77], v[80:81], 0, v[126:127]
	v_max_f32_e32 v64, 0, v64
	v_max_f32_e32 v65, 0, v65
	global_store_dwordx4 v[76:77], v[72:75], off
	v_max_f32_e32 v68, v68, v68
	v_max_f32_e32 v69, v69, v69
	v_pk_mul_f32 v[72:73], v[64:65], v[64:65]
	v_max_f32_e32 v65, v66, v66
	v_max_f32_e32 v64, v70, v70
	v_max_f32_e32 v66, 0, v65
	v_max_f32_e32 v65, v71, v71
	v_max_f32_e32 v67, v67, v67
	v_max_f32_e32 v68, 0, v68
	v_max_f32_e32 v69, 0, v69
	v_max_f32_e32 v64, 0, v64
	v_max_f32_e32 v65, 0, v65
	v_max_f32_e32 v67, 0, v67
	v_pk_mul_f32 v[68:69], v[68:69], v[68:69]
	v_pk_mul_f32 v[70:71], v[64:65], v[64:65]
	v_pk_mul_f32 v[74:75], v[66:67], v[66:67]
	v_max_f32_e32 v56, v56, v56
	v_max_f32_e32 v57, v57, v57
	v_cvt_pk_bf16_f32 v64, v68, v69
	v_cvt_pk_bf16_f32 v65, v70, v71
	v_cvt_pk_bf16_f32 v66, v72, v73
	v_cvt_pk_bf16_f32 v67, v74, v75
	v_max_f32_e32 v56, 0, v56
	v_max_f32_e32 v57, 0, v57
	global_store_dwordx4 v[76:77], v[64:67], off offset:256
	v_max_f32_e32 v60, v60, v60
	v_max_f32_e32 v61, v61, v61
	v_pk_mul_f32 v[64:65], v[56:57], v[56:57]
	v_max_f32_e32 v57, v58, v58
	v_max_f32_e32 v56, v62, v62
	v_max_f32_e32 v58, 0, v57
	v_max_f32_e32 v57, v63, v63
	v_max_f32_e32 v56, 0, v56
	v_max_f32_e32 v57, 0, v57
	v_max_f32_e32 v59, v59, v59
	v_max_f32_e32 v60, 0, v60
	v_max_f32_e32 v61, 0, v61
	v_max_f32_e32 v59, 0, v59
	v_pk_mul_f32 v[62:63], v[56:57], v[56:57]
	v_pk_mul_f32 v[60:61], v[60:61], v[60:61]
	v_pk_mul_f32 v[66:67], v[58:59], v[58:59]
	v_cvt_pk_bf16_f32 v57, v62, v63
	v_add_co_u32_e32 v62, vcc, s70, v120
	v_max_f32_e32 v48, v48, v48
	v_max_f32_e32 v49, v49, v49
	v_cvt_pk_bf16_f32 v56, v60, v61
	v_cvt_pk_bf16_f32 v58, v64, v65
	v_cvt_pk_bf16_f32 v59, v66, v67
	v_addc_co_u32_e32 v63, vcc, 0, v121, vcc
	v_max_f32_e32 v48, 0, v48
	v_max_f32_e32 v49, 0, v49
	global_store_dwordx4 v[62:63], v[56:59], off
	v_max_f32_e32 v52, v52, v52
	v_max_f32_e32 v53, v53, v53
	v_pk_mul_f32 v[56:57], v[48:49], v[48:49]
	v_max_f32_e32 v49, v50, v50
	v_max_f32_e32 v48, v54, v54
	v_max_f32_e32 v50, 0, v49
	v_max_f32_e32 v49, v55, v55
	v_max_f32_e32 v51, v51, v51
	v_max_f32_e32 v52, 0, v52
	v_max_f32_e32 v53, 0, v53
	v_max_f32_e32 v48, 0, v48
	v_max_f32_e32 v49, 0, v49
	v_max_f32_e32 v51, 0, v51
	v_pk_mul_f32 v[52:53], v[52:53], v[52:53]
	v_pk_mul_f32 v[54:55], v[48:49], v[48:49]
	v_pk_mul_f32 v[58:59], v[50:51], v[50:51]
	v_max_f32_e32 v40, v40, v40
	v_max_f32_e32 v41, v41, v41
	v_lshl_add_u64 v[60:61], v[120:121], 0, s[10:11]
	v_cvt_pk_bf16_f32 v48, v52, v53
	v_cvt_pk_bf16_f32 v49, v54, v55
	v_cvt_pk_bf16_f32 v50, v56, v57
	v_cvt_pk_bf16_f32 v51, v58, v59
	v_max_f32_e32 v40, 0, v40
	v_max_f32_e32 v41, 0, v41
	global_store_dwordx4 v[60:61], v[48:51], off offset:256
	v_max_f32_e32 v44, v44, v44
	v_max_f32_e32 v45, v45, v45
	v_pk_mul_f32 v[48:49], v[40:41], v[40:41]
	v_max_f32_e32 v41, v42, v42
	v_max_f32_e32 v40, v46, v46
	v_max_f32_e32 v42, 0, v41
	v_max_f32_e32 v41, v47, v47
	v_max_f32_e32 v40, 0, v40
	v_max_f32_e32 v41, 0, v41
	v_max_f32_e32 v43, v43, v43
	v_max_f32_e32 v44, 0, v44
	v_max_f32_e32 v45, 0, v45
	v_max_f32_e32 v43, 0, v43
	v_pk_mul_f32 v[46:47], v[40:41], v[40:41]
	v_pk_mul_f32 v[44:45], v[44:45], v[44:45]
	v_pk_mul_f32 v[50:51], v[42:43], v[42:43]
	v_cvt_pk_bf16_f32 v41, v46, v47
	v_add_co_u32_e32 v46, vcc, s71, v120
	v_max_f32_e32 v32, v32, v32
	v_max_f32_e32 v33, v33, v33
	v_cvt_pk_bf16_f32 v40, v44, v45
	v_cvt_pk_bf16_f32 v42, v48, v49
	v_cvt_pk_bf16_f32 v43, v50, v51
	v_addc_co_u32_e32 v47, vcc, 0, v121, vcc
	v_max_f32_e32 v32, 0, v32
	v_max_f32_e32 v33, 0, v33
	global_store_dwordx4 v[46:47], v[40:43], off
	v_max_f32_e32 v36, v36, v36
	v_max_f32_e32 v37, v37, v37
	v_pk_mul_f32 v[40:41], v[32:33], v[32:33]
	v_max_f32_e32 v33, v34, v34
	v_max_f32_e32 v32, v38, v38
	v_max_f32_e32 v34, 0, v33
	v_max_f32_e32 v33, v39, v39
	v_max_f32_e32 v35, v35, v35
	v_max_f32_e32 v36, 0, v36
	v_max_f32_e32 v37, 0, v37
	v_max_f32_e32 v32, 0, v32
	v_max_f32_e32 v33, 0, v33
	v_max_f32_e32 v35, 0, v35
	v_pk_mul_f32 v[36:37], v[36:37], v[36:37]
	v_pk_mul_f32 v[38:39], v[32:33], v[32:33]
	v_pk_mul_f32 v[42:43], v[34:35], v[34:35]
	v_max_f32_e32 v24, v24, v24
	v_max_f32_e32 v25, v25, v25
	v_lshl_add_u64 v[44:45], v[120:121], 0, s[12:13]
	v_cvt_pk_bf16_f32 v32, v36, v37
	v_cvt_pk_bf16_f32 v33, v38, v39
	v_cvt_pk_bf16_f32 v34, v40, v41
	v_cvt_pk_bf16_f32 v35, v42, v43
	v_max_f32_e32 v24, 0, v24
	v_max_f32_e32 v25, 0, v25
	global_store_dwordx4 v[44:45], v[32:35], off offset:256
	v_max_f32_e32 v28, v28, v28
	v_max_f32_e32 v29, v29, v29
	v_pk_mul_f32 v[32:33], v[24:25], v[24:25]
	v_max_f32_e32 v25, v26, v26
	v_max_f32_e32 v24, v30, v30
	v_max_f32_e32 v26, 0, v25
	v_max_f32_e32 v25, v31, v31
	v_max_f32_e32 v24, 0, v24
	v_max_f32_e32 v25, 0, v25
	v_max_f32_e32 v27, v27, v27
	v_max_f32_e32 v28, 0, v28
	v_max_f32_e32 v29, 0, v29
	v_max_f32_e32 v27, 0, v27
	v_pk_mul_f32 v[30:31], v[24:25], v[24:25]
	v_pk_mul_f32 v[28:29], v[28:29], v[28:29]
	v_pk_mul_f32 v[34:35], v[26:27], v[26:27]
	v_cvt_pk_bf16_f32 v25, v30, v31
	v_add_co_u32_e32 v30, vcc, s72, v120
	v_max_f32_e32 v16, v16, v16
	v_max_f32_e32 v17, v17, v17
	v_cvt_pk_bf16_f32 v24, v28, v29
	v_cvt_pk_bf16_f32 v26, v32, v33
	v_cvt_pk_bf16_f32 v27, v34, v35
	v_addc_co_u32_e32 v31, vcc, 0, v121, vcc
	v_max_f32_e32 v16, 0, v16
	v_max_f32_e32 v17, 0, v17
	global_store_dwordx4 v[30:31], v[24:27], off
	v_max_f32_e32 v20, v20, v20
	v_max_f32_e32 v21, v21, v21
	v_pk_mul_f32 v[24:25], v[16:17], v[16:17]
	v_max_f32_e32 v17, v18, v18
	v_max_f32_e32 v16, v22, v22
	v_max_f32_e32 v18, 0, v17
	v_max_f32_e32 v17, v23, v23
	v_max_f32_e32 v19, v19, v19
	v_max_f32_e32 v20, 0, v20
	v_max_f32_e32 v21, 0, v21
	v_max_f32_e32 v16, 0, v16
	v_max_f32_e32 v17, 0, v17
	v_max_f32_e32 v19, 0, v19
	v_pk_mul_f32 v[20:21], v[20:21], v[20:21]
	v_pk_mul_f32 v[22:23], v[16:17], v[16:17]
	v_pk_mul_f32 v[26:27], v[18:19], v[18:19]
	v_max_f32_e32 v8, v8, v8
	v_max_f32_e32 v9, v9, v9
	v_lshl_add_u64 v[28:29], v[120:121], 0, s[14:15]
	v_cvt_pk_bf16_f32 v16, v20, v21
	v_cvt_pk_bf16_f32 v17, v22, v23
	v_cvt_pk_bf16_f32 v18, v24, v25
	v_cvt_pk_bf16_f32 v19, v26, v27
	v_max_f32_e32 v8, 0, v8
	v_max_f32_e32 v9, 0, v9
	global_store_dwordx4 v[28:29], v[16:19], off offset:256
	v_max_f32_e32 v12, v12, v12
	v_max_f32_e32 v13, v13, v13
	v_pk_mul_f32 v[16:17], v[8:9], v[8:9]
	v_max_f32_e32 v9, v10, v10
	v_max_f32_e32 v8, v14, v14
	v_max_f32_e32 v10, 0, v9
	v_max_f32_e32 v9, v15, v15
	v_max_f32_e32 v8, 0, v8
	v_max_f32_e32 v9, 0, v9
	v_max_f32_e32 v11, v11, v11
	v_max_f32_e32 v12, 0, v12
	v_max_f32_e32 v13, 0, v13
	v_max_f32_e32 v11, 0, v11
	v_pk_mul_f32 v[14:15], v[8:9], v[8:9]
	v_pk_mul_f32 v[12:13], v[12:13], v[12:13]
	v_pk_mul_f32 v[18:19], v[10:11], v[10:11]
	v_cvt_pk_bf16_f32 v9, v14, v15
	v_add_co_u32_e32 v14, vcc, s73, v120
	v_max_f32_e32 v0, v0, v0
	v_max_f32_e32 v1, v1, v1
	v_cvt_pk_bf16_f32 v8, v12, v13
	v_cvt_pk_bf16_f32 v10, v16, v17
	v_cvt_pk_bf16_f32 v11, v18, v19
	v_addc_co_u32_e32 v15, vcc, 0, v121, vcc
	v_max_f32_e32 v0, 0, v0
	v_max_f32_e32 v1, 0, v1
	global_store_dwordx4 v[14:15], v[8:11], off
	v_max_f32_e32 v4, v4, v4
	v_max_f32_e32 v5, v5, v5
	v_pk_mul_f32 v[8:9], v[0:1], v[0:1]
	v_max_f32_e32 v1, v2, v2
	v_max_f32_e32 v0, v6, v6
	v_max_f32_e32 v2, 0, v1
	v_max_f32_e32 v1, v7, v7
	v_max_f32_e32 v3, v3, v3
	v_max_f32_e32 v4, 0, v4
	v_max_f32_e32 v5, 0, v5
	v_max_f32_e32 v0, 0, v0
	v_max_f32_e32 v1, 0, v1
	v_max_f32_e32 v3, 0, v3
	v_pk_mul_f32 v[4:5], v[4:5], v[4:5]
	v_pk_mul_f32 v[6:7], v[0:1], v[0:1]
	v_pk_mul_f32 v[10:11], v[2:3], v[2:3]
	v_lshl_add_u64 v[12:13], v[120:121], 0, s[16:17]
	v_cvt_pk_bf16_f32 v0, v4, v5
	v_cvt_pk_bf16_f32 v1, v6, v7
	v_cvt_pk_bf16_f32 v2, v8, v9
	v_cvt_pk_bf16_f32 v3, v10, v11
	s_and_b64 vcc, exec, s[4:5]
	s_mov_b32 s74, s18
	s_mov_b32 s30, s20
	s_mov_b64 s[36:37], s[28:29]
	s_mov_b64 s[34:35], s[26:27]
	global_store_dwordx4 v[12:13], v[0:3], off offset:256
	s_cbranch_vccz .LBB0_1284
	s_waitcnt vmcnt(0)
	s_cmpk_gt_u32 s40, 0xff
	s_cbranch_scc1 .LBB0_1295
	s_barrier

.LBB0_1310:
	ds_read_b128 v[154:157], v151
	ds_read_b128 v[158:161], v151 offset:1024
	ds_read_b128 v[162:165], v151 offset:2048
	ds_read_b128 v[166:169], v151 offset:3072
	s_add_u32 s38, s36, 0xfffc0080
	s_addc_u32 s39, s37, -1
	s_cmp_eq_u32 s77, 12
	s_cselect_b32 s41, s27, s39
	s_cselect_b32 s40, s73, s38
	s_cselect_b32 s39, s21, s76
	s_cselect_b32 s38, s74, s75
	v_lshl_add_u64 v[202:203], s[36:37], 0, v[138:139]
	s_add_i32 m0, s35, 0xc000
	ds_read_b128 v[170:173], v152
	ds_read_b128 v[174:177], v152 offset:1024
	ds_read_b128 v[178:181], v152 offset:2048
	ds_read_b128 v[182:185], v152 offset:3072
	ds_read_b128 v[186:189], v152 offset:4096
	ds_read_b128 v[190:193], v152 offset:5120
	ds_read_b128 v[194:197], v152 offset:6144
	ds_read_b128 v[198:201], v152 offset:7168
	global_load_lds_dwordx4 v[202:203], off
	v_lshl_add_u64 v[202:203], s[36:37], 0, v[140:141]
	s_add_i32 m0, s35, 0xe000
	s_nop 0
	global_load_lds_dwordx4 v[202:203], off
	s_waitcnt lgkmcnt(8)
	s_barrier
	s_waitcnt lgkmcnt(0)
	s_waitcnt lgkmcnt(0)
	v_mfma_f32_16x16x32_bf16 v[124:127], v[154:157], v[170:173], v[124:127]
	v_mfma_f32_16x16x32_bf16 v[120:123], v[162:165], v[170:173], v[120:123]
	v_mfma_f32_16x16x32_bf16 v[108:111], v[154:157], v[178:181], v[108:111]
	v_mfma_f32_16x16x32_bf16 v[104:107], v[162:165], v[178:181], v[104:107]
	v_mfma_f32_16x16x32_bf16 v[92:95], v[154:157], v[186:189], v[92:95]
	v_mfma_f32_16x16x32_bf16 v[88:91], v[162:165], v[186:189], v[88:91]
	v_mfma_f32_16x16x32_bf16 v[76:79], v[154:157], v[194:197], v[76:79]
	v_mfma_f32_16x16x32_bf16 v[72:75], v[162:165], v[194:197], v[72:75]
	v_mfma_f32_16x16x32_bf16 v[124:127], v[158:161], v[174:177], v[124:127]
	v_mfma_f32_16x16x32_bf16 v[120:123], v[166:169], v[174:177], v[120:123]
	v_mfma_f32_16x16x32_bf16 v[108:111], v[158:161], v[182:185], v[108:111]
	v_mfma_f32_16x16x32_bf16 v[104:107], v[166:169], v[182:185], v[104:107]
	v_mfma_f32_16x16x32_bf16 v[92:95], v[158:161], v[190:193], v[92:95]
	v_mfma_f32_16x16x32_bf16 v[88:91], v[166:169], v[190:193], v[88:91]
	v_mfma_f32_16x16x32_bf16 v[76:79], v[158:161], v[198:201], v[76:79]
	v_mfma_f32_16x16x32_bf16 v[72:75], v[166:169], v[198:201], v[72:75]
	s_barrier
	s_add_i32 s78, s62, s52
	v_lshl_add_u64 v[218:219], s[38:39], 0, v[132:133]
	s_mov_b32 m0, s78
	ds_read_b128 v[202:205], v153
	ds_read_b128 v[206:209], v153 offset:1024
	ds_read_b128 v[210:213], v153 offset:2048
	ds_read_b128 v[214:217], v153 offset:3072
	global_load_lds_dwordx4 v[218:219], off
	v_lshl_add_u64 v[220:221], s[38:39], 0, v[136:137]
	s_add_i32 m0, s78, 0x2000
	s_nop 0
	global_load_lds_dwordx4 v[220:221], off
	s_barrier
	s_waitcnt lgkmcnt(0)
	s_waitcnt lgkmcnt(0)
	v_mfma_f32_16x16x32_bf16 v[116:119], v[202:205], v[170:173], v[116:119]
	v_mfma_f32_16x16x32_bf16 v[112:115], v[210:213], v[170:173], v[112:115]
	v_mfma_f32_16x16x32_bf16 v[100:103], v[202:205], v[178:181], v[100:103]
	v_mfma_f32_16x16x32_bf16 v[96:99], v[210:213], v[178:181], v[96:99]
	v_mfma_f32_16x16x32_bf16 v[84:87], v[202:205], v[186:189], v[84:87]
	v_mfma_f32_16x16x32_bf16 v[80:83], v[210:213], v[186:189], v[80:83]
	v_mfma_f32_16x16x32_bf16 v[68:71], v[202:205], v[194:197], v[68:71]
	v_mfma_f32_16x16x32_bf16 v[64:67], v[210:213], v[194:197], v[64:67]
	v_mfma_f32_16x16x32_bf16 v[116:119], v[206:209], v[174:177], v[116:119]
	v_mfma_f32_16x16x32_bf16 v[112:115], v[214:217], v[174:177], v[112:115]
	v_mfma_f32_16x16x32_bf16 v[100:103], v[206:209], v[182:185], v[100:103]
	v_mfma_f32_16x16x32_bf16 v[96:99], v[214:217], v[182:185], v[96:99]
	v_mfma_f32_16x16x32_bf16 v[84:87], v[206:209], v[190:193], v[84:87]
	v_mfma_f32_16x16x32_bf16 v[80:83], v[214:217], v[190:193], v[80:83]
	v_mfma_f32_16x16x32_bf16 v[68:71], v[206:209], v[198:201], v[68:71]
	v_mfma_f32_16x16x32_bf16 v[64:67], v[214:217], v[198:201], v[64:67]
	s_mov_b32 m0, s35
	v_lshl_add_u64 v[222:223], s[40:41], 0, v[130:131]
	s_barrier
	ds_read_b128 v[170:173], v152 offset:16384
	ds_read_b128 v[174:177], v152 offset:17408
	ds_read_b128 v[178:181], v152 offset:18432
	ds_read_b128 v[182:185], v152 offset:19456
	ds_read_b128 v[186:189], v152 offset:20480
	ds_read_b128 v[190:193], v152 offset:21504
	ds_read_b128 v[194:197], v152 offset:22528
	ds_read_b128 v[198:201], v152 offset:23552
	global_load_lds_dwordx4 v[222:223], off
	v_lshl_add_u64 v[224:225], s[40:41], 0, v[134:135]
	s_mov_b32 m0, s53
	s_nop 0
	global_load_lds_dwordx4 v[224:225], off
	s_barrier
	s_waitcnt lgkmcnt(0)
	s_waitcnt lgkmcnt(0)
	v_mfma_f32_16x16x32_bf16 v[60:63], v[154:157], v[170:173], v[60:63]
	v_mfma_f32_16x16x32_bf16 v[56:59], v[162:165], v[170:173], v[56:59]
	v_mfma_f32_16x16x32_bf16 v[44:47], v[154:157], v[178:181], v[44:47]
	v_mfma_f32_16x16x32_bf16 v[40:43], v[162:165], v[178:181], v[40:43]
	v_mfma_f32_16x16x32_bf16 v[28:31], v[154:157], v[186:189], v[28:31]
	v_mfma_f32_16x16x32_bf16 v[24:27], v[162:165], v[186:189], v[24:27]
	v_mfma_f32_16x16x32_bf16 v[12:15], v[154:157], v[194:197], v[12:15]
	v_mfma_f32_16x16x32_bf16 v[8:11], v[162:165], v[194:197], v[8:11]
	v_mfma_f32_16x16x32_bf16 v[60:63], v[158:161], v[174:177], v[60:63]
	v_mfma_f32_16x16x32_bf16 v[56:59], v[166:169], v[174:177], v[56:59]
	v_mfma_f32_16x16x32_bf16 v[44:47], v[158:161], v[182:185], v[44:47]
	v_mfma_f32_16x16x32_bf16 v[40:43], v[166:169], v[182:185], v[40:43]
	v_mfma_f32_16x16x32_bf16 v[28:31], v[158:161], v[190:193], v[28:31]
	v_mfma_f32_16x16x32_bf16 v[24:27], v[166:169], v[190:193], v[24:27]
	v_mfma_f32_16x16x32_bf16 v[12:15], v[158:161], v[198:201], v[12:15]
	v_mfma_f32_16x16x32_bf16 v[8:11], v[166:169], v[198:201], v[8:11]
	s_barrier
	s_add_u32 s78, s38, 0x40000
	s_addc_u32 s79, s39, 0
	s_add_i32 s80, s63, s52
	v_lshl_add_u64 v[154:155], s[78:79], 0, v[132:133]
	s_mov_b32 m0, s80
	s_nop 0
	global_load_lds_dwordx4 v[154:155], off
	v_lshl_add_u64 v[154:155], s[78:79], 0, v[136:137]
	s_add_i32 m0, s80, 0x2000
	s_nop 0
	global_load_lds_dwordx4 v[154:155], off
	s_waitcnt vmcnt(6)
	s_barrier
	v_mfma_f32_16x16x32_bf16 v[52:55], v[202:205], v[170:173], v[52:55]
	v_mfma_f32_16x16x32_bf16 v[48:51], v[210:213], v[170:173], v[48:51]
	v_mfma_f32_16x16x32_bf16 v[36:39], v[202:205], v[178:181], v[36:39]
	v_mfma_f32_16x16x32_bf16 v[32:35], v[210:213], v[178:181], v[32:35]
	v_mfma_f32_16x16x32_bf16 v[20:23], v[202:205], v[186:189], v[20:23]
	v_mfma_f32_16x16x32_bf16 v[16:19], v[210:213], v[186:189], v[16:19]
	v_mfma_f32_16x16x32_bf16 v[4:7], v[202:205], v[194:197], v[4:7]
	v_mfma_f32_16x16x32_bf16 v[0:3], v[210:213], v[194:197], v[0:3]
	v_mfma_f32_16x16x32_bf16 v[52:55], v[206:209], v[174:177], v[52:55]
	v_mfma_f32_16x16x32_bf16 v[48:51], v[214:217], v[174:177], v[48:51]
	v_mfma_f32_16x16x32_bf16 v[36:39], v[206:209], v[182:185], v[36:39]
	v_mfma_f32_16x16x32_bf16 v[32:35], v[214:217], v[182:185], v[32:35]
	v_mfma_f32_16x16x32_bf16 v[20:23], v[206:209], v[190:193], v[20:23]
	v_mfma_f32_16x16x32_bf16 v[16:19], v[214:217], v[190:193], v[16:19]
	v_mfma_f32_16x16x32_bf16 v[4:7], v[206:209], v[198:201], v[4:7]
	v_mfma_f32_16x16x32_bf16 v[0:3], v[214:217], v[198:201], v[0:3]
	s_add_i32 s78, 0, 0x18000
	v_add_u32_e32 v166, s78, v149
	s_barrier
	ds_read_b128 v[154:157], v166
	ds_read_b128 v[158:161], v166 offset:1024
	ds_read_b128 v[162:165], v166 offset:2048
	ds_read_b128 v[166:169], v166 offset:3072
	s_add_u32 s40, s40, 0x40000
	s_addc_u32 s41, s41, 0
	s_mov_b32 m0, s54
	v_lshl_add_u64 v[202:203], s[40:41], 0, v[130:131]
	ds_read_b128 v[170:173], v152 offset:32768
	ds_read_b128 v[174:177], v152 offset:33792
	ds_read_b128 v[178:181], v152 offset:34816
	ds_read_b128 v[182:185], v152 offset:35840
	ds_read_b128 v[186:189], v152 offset:36864
	ds_read_b128 v[190:193], v152 offset:37888
	ds_read_b128 v[194:197], v152 offset:38912
	ds_read_b128 v[198:201], v152 offset:39936
	global_load_lds_dwordx4 v[202:203], off
	v_lshl_add_u64 v[202:203], s[40:41], 0, v[134:135]
	s_mov_b32 m0, s55
	s_nop 0
	global_load_lds_dwordx4 v[202:203], off
	s_waitcnt lgkmcnt(8)
	s_barrier
	s_waitcnt lgkmcnt(0)
	s_waitcnt lgkmcnt(0)
	v_mfma_f32_16x16x32_bf16 v[124:127], v[154:157], v[170:173], v[124:127]
	v_mfma_f32_16x16x32_bf16 v[120:123], v[162:165], v[170:173], v[120:123]
	v_mfma_f32_16x16x32_bf16 v[108:111], v[154:157], v[178:181], v[108:111]
	v_mfma_f32_16x16x32_bf16 v[104:107], v[162:165], v[178:181], v[104:107]
	v_mfma_f32_16x16x32_bf16 v[92:95], v[154:157], v[186:189], v[92:95]
	v_mfma_f32_16x16x32_bf16 v[88:91], v[162:165], v[186:189], v[88:91]
	v_mfma_f32_16x16x32_bf16 v[76:79], v[154:157], v[194:197], v[76:79]
	v_mfma_f32_16x16x32_bf16 v[72:75], v[162:165], v[194:197], v[72:75]
	v_mfma_f32_16x16x32_bf16 v[124:127], v[158:161], v[174:177], v[124:127]
	v_mfma_f32_16x16x32_bf16 v[120:123], v[166:169], v[174:177], v[120:123]
	v_mfma_f32_16x16x32_bf16 v[108:111], v[158:161], v[182:185], v[108:111]
	v_mfma_f32_16x16x32_bf16 v[104:107], v[166:169], v[182:185], v[104:107]
	v_mfma_f32_16x16x32_bf16 v[92:95], v[158:161], v[190:193], v[92:95]
	v_mfma_f32_16x16x32_bf16 v[88:91], v[166:169], v[190:193], v[88:91]
	v_mfma_f32_16x16x32_bf16 v[76:79], v[158:161], v[198:201], v[76:79]
	v_mfma_f32_16x16x32_bf16 v[72:75], v[166:169], v[198:201], v[72:75]
	s_barrier
	s_add_i32 s40, 0, 0x1c000
	s_add_i32 s41, s78, s52
	v_add_u32_e32 v214, s40, v149
	v_lshl_add_u64 v[218:219], v[218:219], 0, s[10:11]
	s_mov_b32 m0, s41
	ds_read_b128 v[202:205], v214
	ds_read_b128 v[206:209], v214 offset:1024
	ds_read_b128 v[210:213], v214 offset:2048
	ds_read_b128 v[214:217], v214 offset:3072
	global_load_lds_dwordx4 v[218:219], off
	v_lshl_add_u64 v[218:219], v[220:221], 0, s[10:11]
	s_add_i32 m0, s41, 0x2000
	s_nop 0
	global_load_lds_dwordx4 v[218:219], off
	s_barrier
	s_waitcnt lgkmcnt(0)
	s_waitcnt lgkmcnt(0)
	v_mfma_f32_16x16x32_bf16 v[116:119], v[202:205], v[170:173], v[116:119]
	v_mfma_f32_16x16x32_bf16 v[112:115], v[210:213], v[170:173], v[112:115]
	v_mfma_f32_16x16x32_bf16 v[100:103], v[202:205], v[178:181], v[100:103]
	v_mfma_f32_16x16x32_bf16 v[96:99], v[210:213], v[178:181], v[96:99]
	v_mfma_f32_16x16x32_bf16 v[84:87], v[202:205], v[186:189], v[84:87]
	v_mfma_f32_16x16x32_bf16 v[80:83], v[210:213], v[186:189], v[80:83]
	v_mfma_f32_16x16x32_bf16 v[68:71], v[202:205], v[194:197], v[68:71]
	v_mfma_f32_16x16x32_bf16 v[64:67], v[210:213], v[194:197], v[64:67]
	v_mfma_f32_16x16x32_bf16 v[116:119], v[206:209], v[174:177], v[116:119]
	v_mfma_f32_16x16x32_bf16 v[112:115], v[214:217], v[174:177], v[112:115]
	v_mfma_f32_16x16x32_bf16 v[100:103], v[206:209], v[182:185], v[100:103]
	v_mfma_f32_16x16x32_bf16 v[96:99], v[214:217], v[182:185], v[96:99]
	v_mfma_f32_16x16x32_bf16 v[84:87], v[206:209], v[190:193], v[84:87]
	v_mfma_f32_16x16x32_bf16 v[80:83], v[214:217], v[190:193], v[80:83]
	v_mfma_f32_16x16x32_bf16 v[68:71], v[206:209], v[198:201], v[68:71]
	v_mfma_f32_16x16x32_bf16 v[64:67], v[214:217], v[198:201], v[64:67]
	s_mov_b32 m0, s57
	v_lshl_add_u64 v[218:219], v[222:223], 0, s[10:11]
	s_barrier
	ds_read_b128 v[170:173], v152 offset:49152
	ds_read_b128 v[174:177], v152 offset:50176
	ds_read_b128 v[178:181], v152 offset:51200
	ds_read_b128 v[182:185], v152 offset:52224
	ds_read_b128 v[186:189], v152 offset:53248
	ds_read_b128 v[190:193], v152 offset:54272
	ds_read_b128 v[194:197], v152 offset:55296
	ds_read_b128 v[198:201], v152 offset:56320
	global_load_lds_dwordx4 v[218:219], off
	v_lshl_add_u64 v[218:219], v[224:225], 0, s[10:11]
	s_mov_b32 m0, s60
	s_nop 0
	global_load_lds_dwordx4 v[218:219], off
	s_barrier
	s_waitcnt lgkmcnt(0)
	s_waitcnt lgkmcnt(0)
	v_mfma_f32_16x16x32_bf16 v[60:63], v[154:157], v[170:173], v[60:63]
	v_mfma_f32_16x16x32_bf16 v[56:59], v[162:165], v[170:173], v[56:59]
	v_mfma_f32_16x16x32_bf16 v[44:47], v[154:157], v[178:181], v[44:47]
	v_mfma_f32_16x16x32_bf16 v[40:43], v[162:165], v[178:181], v[40:43]
	v_mfma_f32_16x16x32_bf16 v[28:31], v[154:157], v[186:189], v[28:31]
	v_mfma_f32_16x16x32_bf16 v[24:27], v[162:165], v[186:189], v[24:27]
	v_mfma_f32_16x16x32_bf16 v[12:15], v[154:157], v[194:197], v[12:15]
	v_mfma_f32_16x16x32_bf16 v[8:11], v[162:165], v[194:197], v[8:11]
	v_mfma_f32_16x16x32_bf16 v[60:63], v[158:161], v[174:177], v[60:63]
	v_mfma_f32_16x16x32_bf16 v[56:59], v[166:169], v[174:177], v[56:59]
	v_mfma_f32_16x16x32_bf16 v[44:47], v[158:161], v[182:185], v[44:47]
	v_mfma_f32_16x16x32_bf16 v[40:43], v[166:169], v[182:185], v[40:43]
	v_mfma_f32_16x16x32_bf16 v[28:31], v[158:161], v[190:193], v[28:31]
	v_mfma_f32_16x16x32_bf16 v[24:27], v[166:169], v[190:193], v[24:27]
	v_mfma_f32_16x16x32_bf16 v[12:15], v[158:161], v[198:201], v[12:15]
	v_mfma_f32_16x16x32_bf16 v[8:11], v[166:169], v[198:201], v[8:11]
	s_barrier
	s_add_u32 s38, s38, 0x40080
	s_addc_u32 s39, s39, 0
	s_add_i32 s40, s40, s52
	v_lshl_add_u64 v[154:155], s[38:39], 0, v[132:133]
	s_mov_b32 m0, s40
	s_nop 0
	global_load_lds_dwordx4 v[154:155], off
	v_lshl_add_u64 v[154:155], s[38:39], 0, v[136:137]
	s_add_i32 m0, s40, 0x2000
	s_nop 0
	global_load_lds_dwordx4 v[154:155], off
	s_waitcnt vmcnt(6)
	s_barrier
	v_mfma_f32_16x16x32_bf16 v[52:55], v[202:205], v[170:173], v[52:55]
	v_mfma_f32_16x16x32_bf16 v[48:51], v[210:213], v[170:173], v[48:51]
	v_mfma_f32_16x16x32_bf16 v[36:39], v[202:205], v[178:181], v[36:39]
	v_mfma_f32_16x16x32_bf16 v[32:35], v[210:213], v[178:181], v[32:35]
	v_mfma_f32_16x16x32_bf16 v[20:23], v[202:205], v[186:189], v[20:23]
	v_mfma_f32_16x16x32_bf16 v[16:19], v[210:213], v[186:189], v[16:19]
	v_mfma_f32_16x16x32_bf16 v[4:7], v[202:205], v[194:197], v[4:7]
	v_mfma_f32_16x16x32_bf16 v[0:3], v[210:213], v[194:197], v[0:3]
	v_mfma_f32_16x16x32_bf16 v[52:55], v[206:209], v[174:177], v[52:55]
	v_mfma_f32_16x16x32_bf16 v[48:51], v[214:217], v[174:177], v[48:51]
	v_mfma_f32_16x16x32_bf16 v[36:39], v[206:209], v[182:185], v[36:39]
	v_mfma_f32_16x16x32_bf16 v[32:35], v[214:217], v[182:185], v[32:35]
	v_mfma_f32_16x16x32_bf16 v[20:23], v[206:209], v[190:193], v[20:23]
	v_mfma_f32_16x16x32_bf16 v[16:19], v[214:217], v[190:193], v[16:19]
	v_mfma_f32_16x16x32_bf16 v[4:7], v[206:209], v[198:201], v[4:7]
	v_mfma_f32_16x16x32_bf16 v[0:3], v[214:217], v[198:201], v[0:3]
	s_add_i32 s77, s77, 2
	s_add_u32 s36, s36, 0x100
	s_addc_u32 s37, s37, 0
	s_add_u32 s75, s75, 0x100
	s_addc_u32 s76, s76, 0
	s_cmp_gt_u32 s77, 13
	s_barrier
	s_cbranch_scc0 .LBB0_1310
	v_lshl_add_u32 v154, s34, 8, v148
	v_max_f32_e32 v126, v126, v126
	v_max_f32_e32 v127, v127, v127
	v_lshl_or_b32 v156, s72, 8, v150
	v_ashrrev_i32_e32 v155, 31, v154
	v_max_f32_e32 v124, v124, v124
	v_max_f32_e32 v120, v120, v120
	v_max_f32_e32 v125, v125, v125
	v_max_f32_e32 v121, v121, v121
	v_max_f32_e32 v126, 0, v126
	v_max_f32_e32 v122, v122, v122
	v_max_f32_e32 v127, 0, v127
	v_max_f32_e32 v123, v123, v123
	v_lshlrev_b64 v[158:159], 13, v[154:155]
	v_max_f32_e32 v124, 0, v124
	v_max_f32_e32 v120, 0, v120
	v_max_f32_e32 v125, 0, v125
	v_max_f32_e32 v121, 0, v121
	v_max_f32_e32 v122, 0, v122
	v_max_f32_e32 v123, 0, v123
	v_pk_mul_f32 v[126:127], v[126:127], v[126:127]
	v_ashrrev_i32_e32 v157, 31, v156
	v_lshl_add_u64 v[158:159], s[46:47], 0, v[158:159]
	v_pk_mul_f32 v[124:125], v[124:125], v[124:125]
	v_pk_mul_f32 v[120:121], v[120:121], v[120:121]
	v_pk_mul_f32 v[160:161], v[122:123], v[122:123]
	v_cvt_pk_bf16_f32 v123, v126, v127
	v_lshlrev_b64 v[126:127], 1, v[156:157]
	v_max_f32_e32 v112, v112, v112
	v_max_f32_e32 v113, v113, v113
	v_cvt_pk_bf16_f32 v122, v124, v125
	v_cvt_pk_bf16_f32 v124, v120, v121
	v_cvt_pk_bf16_f32 v125, v160, v161
	v_lshl_add_u64 v[120:121], v[158:159], 0, v[126:127]
	v_max_f32_e32 v112, 0, v112
	v_max_f32_e32 v113, 0, v113
	global_store_dwordx4 v[120:121], v[122:125], off
	v_max_f32_e32 v116, v116, v116
	v_max_f32_e32 v117, v117, v117
	v_pk_mul_f32 v[122:123], v[112:113], v[112:113]
	v_max_f32_e32 v113, v114, v114
	v_max_f32_e32 v112, v118, v118
	v_max_f32_e32 v114, 0, v113
	v_max_f32_e32 v113, v119, v119
	v_max_f32_e32 v115, v115, v115
	v_max_f32_e32 v116, 0, v116
	v_max_f32_e32 v117, 0, v117
	v_max_f32_e32 v112, 0, v112
	v_max_f32_e32 v113, 0, v113
	v_max_f32_e32 v115, 0, v115
	v_pk_mul_f32 v[116:117], v[116:117], v[116:117]
	v_pk_mul_f32 v[118:119], v[112:113], v[112:113]
	v_pk_mul_f32 v[124:125], v[114:115], v[114:115]
	v_max_f32_e32 v104, v104, v104
	v_max_f32_e32 v105, v105, v105
	v_cvt_pk_bf16_f32 v112, v116, v117
	v_cvt_pk_bf16_f32 v113, v118, v119
	v_cvt_pk_bf16_f32 v114, v122, v123
	v_cvt_pk_bf16_f32 v115, v124, v125
	v_max_f32_e32 v104, 0, v104
	v_max_f32_e32 v105, 0, v105
	global_store_dwordx4 v[120:121], v[112:115], off offset:256
	v_max_f32_e32 v108, v108, v108
	v_max_f32_e32 v109, v109, v109
	v_or_b32_e32 v112, 16, v154
	v_pk_mul_f32 v[114:115], v[104:105], v[104:105]
	v_max_f32_e32 v105, v106, v106
	v_ashrrev_i32_e32 v113, 31, v112
	v_max_f32_e32 v104, v110, v110
	v_max_f32_e32 v106, 0, v105
	v_max_f32_e32 v105, v111, v111
	v_max_f32_e32 v107, v107, v107
	v_lshlrev_b64 v[112:113], 13, v[112:113]
	v_max_f32_e32 v108, 0, v108
	v_max_f32_e32 v109, 0, v109
	v_max_f32_e32 v104, 0, v104
	v_max_f32_e32 v105, 0, v105
	v_max_f32_e32 v107, 0, v107
	v_lshl_add_u64 v[112:113], s[46:47], 0, v[112:113]
	v_pk_mul_f32 v[108:109], v[108:109], v[108:109]
	v_pk_mul_f32 v[110:111], v[104:105], v[104:105]
	v_pk_mul_f32 v[116:117], v[106:107], v[106:107]
	v_max_f32_e32 v96, v96, v96
	v_max_f32_e32 v97, v97, v97
	v_cvt_pk_bf16_f32 v104, v108, v109
	v_cvt_pk_bf16_f32 v105, v110, v111
	v_cvt_pk_bf16_f32 v106, v114, v115
	v_cvt_pk_bf16_f32 v107, v116, v117
	v_lshl_add_u64 v[108:109], v[112:113], 0, v[126:127]
	v_max_f32_e32 v96, 0, v96
	v_max_f32_e32 v97, 0, v97
	global_store_dwordx4 v[108:109], v[104:107], off
	v_max_f32_e32 v100, v100, v100
	v_max_f32_e32 v101, v101, v101
	v_pk_mul_f32 v[104:105], v[96:97], v[96:97]
	v_max_f32_e32 v97, v98, v98
	v_max_f32_e32 v96, v102, v102
	v_max_f32_e32 v98, 0, v97
	v_max_f32_e32 v97, v103, v103
	v_max_f32_e32 v99, v99, v99
	v_max_f32_e32 v100, 0, v100
	v_max_f32_e32 v101, 0, v101
	v_max_f32_e32 v96, 0, v96
	v_max_f32_e32 v97, 0, v97
	v_max_f32_e32 v99, 0, v99
	v_pk_mul_f32 v[100:101], v[100:101], v[100:101]
	v_pk_mul_f32 v[102:103], v[96:97], v[96:97]
	v_pk_mul_f32 v[106:107], v[98:99], v[98:99]
	v_max_f32_e32 v88, v88, v88
	v_max_f32_e32 v89, v89, v89
	v_cvt_pk_bf16_f32 v96, v100, v101
	v_cvt_pk_bf16_f32 v97, v102, v103
	v_cvt_pk_bf16_f32 v98, v104, v105
	v_cvt_pk_bf16_f32 v99, v106, v107
	v_max_f32_e32 v88, 0, v88
	v_max_f32_e32 v89, 0, v89
	global_store_dwordx4 v[108:109], v[96:99], off offset:256
	v_max_f32_e32 v92, v92, v92
	v_max_f32_e32 v93, v93, v93
	v_or_b32_e32 v96, 32, v154
	v_pk_mul_f32 v[98:99], v[88:89], v[88:89]
	v_max_f32_e32 v89, v90, v90
	v_ashrrev_i32_e32 v97, 31, v96
	v_max_f32_e32 v88, v94, v94
	v_max_f32_e32 v90, 0, v89
	v_max_f32_e32 v89, v95, v95
	v_max_f32_e32 v91, v91, v91
	v_lshlrev_b64 v[96:97], 13, v[96:97]
	v_max_f32_e32 v92, 0, v92
	v_max_f32_e32 v93, 0, v93
	v_max_f32_e32 v88, 0, v88
	v_max_f32_e32 v89, 0, v89
	v_max_f32_e32 v91, 0, v91
	v_lshl_add_u64 v[96:97], s[46:47], 0, v[96:97]
	v_pk_mul_f32 v[92:93], v[92:93], v[92:93]
	v_pk_mul_f32 v[94:95], v[88:89], v[88:89]
	v_pk_mul_f32 v[100:101], v[90:91], v[90:91]
	v_max_f32_e32 v80, v80, v80
	v_max_f32_e32 v81, v81, v81
	v_cvt_pk_bf16_f32 v88, v92, v93
	v_cvt_pk_bf16_f32 v89, v94, v95
	v_cvt_pk_bf16_f32 v90, v98, v99
	v_cvt_pk_bf16_f32 v91, v100, v101
	v_lshl_add_u64 v[92:93], v[96:97], 0, v[126:127]
	v_max_f32_e32 v80, 0, v80
	v_max_f32_e32 v81, 0, v81
	global_store_dwordx4 v[92:93], v[88:91], off
	v_max_f32_e32 v84, v84, v84
	v_max_f32_e32 v85, v85, v85
	v_pk_mul_f32 v[88:89], v[80:81], v[80:81]
	v_max_f32_e32 v81, v82, v82
	v_max_f32_e32 v80, v86, v86
	v_max_f32_e32 v82, 0, v81
	v_max_f32_e32 v81, v87, v87
	v_max_f32_e32 v83, v83, v83
	v_max_f32_e32 v84, 0, v84
	v_max_f32_e32 v85, 0, v85
	v_max_f32_e32 v80, 0, v80
	v_max_f32_e32 v81, 0, v81
	v_max_f32_e32 v83, 0, v83
	v_pk_mul_f32 v[84:85], v[84:85], v[84:85]
	v_pk_mul_f32 v[86:87], v[80:81], v[80:81]
	v_pk_mul_f32 v[90:91], v[82:83], v[82:83]
	v_max_f32_e32 v72, v72, v72
	v_max_f32_e32 v73, v73, v73
	v_cvt_pk_bf16_f32 v80, v84, v85
	v_cvt_pk_bf16_f32 v81, v86, v87
	v_cvt_pk_bf16_f32 v82, v88, v89
	v_cvt_pk_bf16_f32 v83, v90, v91
	v_max_f32_e32 v72, 0, v72
	v_max_f32_e32 v73, 0, v73
	global_store_dwordx4 v[92:93], v[80:83], off offset:256
	v_max_f32_e32 v76, v76, v76
	v_max_f32_e32 v77, v77, v77
	v_or_b32_e32 v80, 48, v154
	v_pk_mul_f32 v[82:83], v[72:73], v[72:73]
	v_max_f32_e32 v73, v74, v74
	v_ashrrev_i32_e32 v81, 31, v80
	v_max_f32_e32 v72, v78, v78
	v_max_f32_e32 v74, 0, v73
	v_max_f32_e32 v73, v79, v79
	v_max_f32_e32 v75, v75, v75
	v_lshlrev_b64 v[80:81], 13, v[80:81]
	v_max_f32_e32 v76, 0, v76
	v_max_f32_e32 v77, 0, v77
	v_max_f32_e32 v72, 0, v72
	v_max_f32_e32 v73, 0, v73
	v_max_f32_e32 v75, 0, v75
	v_lshl_add_u64 v[80:81], s[46:47], 0, v[80:81]
	v_pk_mul_f32 v[76:77], v[76:77], v[76:77]
	v_pk_mul_f32 v[78:79], v[72:73], v[72:73]
	v_pk_mul_f32 v[84:85], v[74:75], v[74:75]
	v_max_f32_e32 v64, v64, v64
	v_max_f32_e32 v65, v65, v65
	v_cvt_pk_bf16_f32 v72, v76, v77
	v_cvt_pk_bf16_f32 v73, v78, v79
	v_cvt_pk_bf16_f32 v74, v82, v83
	v_cvt_pk_bf16_f32 v75, v84, v85
	v_lshl_add_u64 v[76:77], v[80:81], 0, v[126:127]
	v_max_f32_e32 v64, 0, v64
	v_max_f32_e32 v65, 0, v65
	global_store_dwordx4 v[76:77], v[72:75], off
	v_max_f32_e32 v68, v68, v68
	v_max_f32_e32 v69, v69, v69
	v_pk_mul_f32 v[72:73], v[64:65], v[64:65]
	v_max_f32_e32 v65, v66, v66
	v_max_f32_e32 v64, v70, v70
	v_max_f32_e32 v66, 0, v65
	v_max_f32_e32 v65, v71, v71
	v_max_f32_e32 v67, v67, v67
	v_max_f32_e32 v68, 0, v68
	v_max_f32_e32 v69, 0, v69
	v_max_f32_e32 v64, 0, v64
	v_max_f32_e32 v65, 0, v65
	v_max_f32_e32 v67, 0, v67
	v_pk_mul_f32 v[68:69], v[68:69], v[68:69]
	v_pk_mul_f32 v[70:71], v[64:65], v[64:65]
	v_pk_mul_f32 v[74:75], v[66:67], v[66:67]
	v_max_f32_e32 v56, v56, v56
	v_max_f32_e32 v57, v57, v57
	v_cvt_pk_bf16_f32 v64, v68, v69
	v_cvt_pk_bf16_f32 v65, v70, v71
	v_cvt_pk_bf16_f32 v66, v72, v73
	v_cvt_pk_bf16_f32 v67, v74, v75
	v_max_f32_e32 v56, 0, v56
	v_max_f32_e32 v57, 0, v57
	global_store_dwordx4 v[76:77], v[64:67], off offset:256
	v_max_f32_e32 v60, v60, v60
	v_max_f32_e32 v61, v61, v61
	v_pk_mul_f32 v[64:65], v[56:57], v[56:57]
	v_max_f32_e32 v57, v58, v58
	v_max_f32_e32 v56, v62, v62
	v_max_f32_e32 v58, 0, v57
	v_max_f32_e32 v57, v63, v63
	v_max_f32_e32 v56, 0, v56
	v_max_f32_e32 v57, 0, v57
	v_max_f32_e32 v59, v59, v59
	v_max_f32_e32 v60, 0, v60
	v_max_f32_e32 v61, 0, v61
	v_max_f32_e32 v59, 0, v59
	v_pk_mul_f32 v[62:63], v[56:57], v[56:57]
	v_pk_mul_f32 v[60:61], v[60:61], v[60:61]
	v_pk_mul_f32 v[66:67], v[58:59], v[58:59]
	v_cvt_pk_bf16_f32 v57, v62, v63
	v_add_co_u32_e32 v62, vcc, s64, v120
	v_max_f32_e32 v48, v48, v48
	v_max_f32_e32 v49, v49, v49
	v_cvt_pk_bf16_f32 v56, v60, v61
	v_cvt_pk_bf16_f32 v58, v64, v65
	v_cvt_pk_bf16_f32 v59, v66, v67
	v_addc_co_u32_e32 v63, vcc, 0, v121, vcc
	v_max_f32_e32 v48, 0, v48
	v_max_f32_e32 v49, 0, v49
	global_store_dwordx4 v[62:63], v[56:59], off
	v_max_f32_e32 v52, v52, v52
	v_max_f32_e32 v53, v53, v53
	v_pk_mul_f32 v[56:57], v[48:49], v[48:49]
	v_max_f32_e32 v49, v50, v50
	v_max_f32_e32 v48, v54, v54
	v_max_f32_e32 v50, 0, v49
	v_max_f32_e32 v49, v55, v55
	v_max_f32_e32 v51, v51, v51
	v_max_f32_e32 v52, 0, v52
	v_max_f32_e32 v53, 0, v53
	v_max_f32_e32 v48, 0, v48
	v_max_f32_e32 v49, 0, v49
	v_max_f32_e32 v51, 0, v51
	v_pk_mul_f32 v[52:53], v[52:53], v[52:53]
	v_pk_mul_f32 v[54:55], v[48:49], v[48:49]
	v_pk_mul_f32 v[58:59], v[50:51], v[50:51]
	v_max_f32_e32 v40, v40, v40
	v_max_f32_e32 v41, v41, v41
	v_lshl_add_u64 v[60:61], v[120:121], 0, s[12:13]
	v_cvt_pk_bf16_f32 v48, v52, v53
	v_cvt_pk_bf16_f32 v49, v54, v55
	v_cvt_pk_bf16_f32 v50, v56, v57
	v_cvt_pk_bf16_f32 v51, v58, v59
	v_max_f32_e32 v40, 0, v40
	v_max_f32_e32 v41, 0, v41
	global_store_dwordx4 v[60:61], v[48:51], off offset:256
	v_max_f32_e32 v44, v44, v44
	v_max_f32_e32 v45, v45, v45
	v_pk_mul_f32 v[48:49], v[40:41], v[40:41]
	v_max_f32_e32 v41, v42, v42
	v_max_f32_e32 v40, v46, v46
	v_max_f32_e32 v42, 0, v41
	v_max_f32_e32 v41, v47, v47
	v_max_f32_e32 v40, 0, v40
	v_max_f32_e32 v41, 0, v41
	v_max_f32_e32 v43, v43, v43
	v_max_f32_e32 v44, 0, v44
	v_max_f32_e32 v45, 0, v45
	v_max_f32_e32 v43, 0, v43
	v_pk_mul_f32 v[46:47], v[40:41], v[40:41]
	v_pk_mul_f32 v[44:45], v[44:45], v[44:45]
	v_pk_mul_f32 v[50:51], v[42:43], v[42:43]
	v_cvt_pk_bf16_f32 v41, v46, v47
	v_add_co_u32_e32 v46, vcc, s65, v120
	v_max_f32_e32 v32, v32, v32
	v_max_f32_e32 v33, v33, v33
	v_cvt_pk_bf16_f32 v40, v44, v45
	v_cvt_pk_bf16_f32 v42, v48, v49
	v_cvt_pk_bf16_f32 v43, v50, v51
	v_addc_co_u32_e32 v47, vcc, 0, v121, vcc
	v_max_f32_e32 v32, 0, v32
	v_max_f32_e32 v33, 0, v33
	global_store_dwordx4 v[46:47], v[40:43], off
	v_max_f32_e32 v36, v36, v36
	v_max_f32_e32 v37, v37, v37
	v_pk_mul_f32 v[40:41], v[32:33], v[32:33]
	v_max_f32_e32 v33, v34, v34
	v_max_f32_e32 v32, v38, v38
	v_max_f32_e32 v34, 0, v33
	v_max_f32_e32 v33, v39, v39
	v_max_f32_e32 v35, v35, v35
	v_max_f32_e32 v36, 0, v36
	v_max_f32_e32 v37, 0, v37
	v_max_f32_e32 v32, 0, v32
	v_max_f32_e32 v33, 0, v33
	v_max_f32_e32 v35, 0, v35
	v_pk_mul_f32 v[36:37], v[36:37], v[36:37]
	v_pk_mul_f32 v[38:39], v[32:33], v[32:33]
	v_pk_mul_f32 v[42:43], v[34:35], v[34:35]
	v_max_f32_e32 v24, v24, v24
	v_max_f32_e32 v25, v25, v25
	v_lshl_add_u64 v[44:45], v[120:121], 0, s[14:15]
	v_cvt_pk_bf16_f32 v32, v36, v37
	v_cvt_pk_bf16_f32 v33, v38, v39
	v_cvt_pk_bf16_f32 v34, v40, v41
	v_cvt_pk_bf16_f32 v35, v42, v43
	v_max_f32_e32 v24, 0, v24
	v_max_f32_e32 v25, 0, v25
	global_store_dwordx4 v[44:45], v[32:35], off offset:256
	v_max_f32_e32 v28, v28, v28
	v_max_f32_e32 v29, v29, v29
	v_pk_mul_f32 v[32:33], v[24:25], v[24:25]
	v_max_f32_e32 v25, v26, v26
	v_max_f32_e32 v24, v30, v30
	v_max_f32_e32 v26, 0, v25
	v_max_f32_e32 v25, v31, v31
	v_max_f32_e32 v24, 0, v24
	v_max_f32_e32 v25, 0, v25
	v_max_f32_e32 v27, v27, v27
	v_max_f32_e32 v28, 0, v28
	v_max_f32_e32 v29, 0, v29
	v_max_f32_e32 v27, 0, v27
	v_pk_mul_f32 v[30:31], v[24:25], v[24:25]
	v_pk_mul_f32 v[28:29], v[28:29], v[28:29]
	v_pk_mul_f32 v[34:35], v[26:27], v[26:27]
	v_cvt_pk_bf16_f32 v25, v30, v31
	v_add_co_u32_e32 v30, vcc, s70, v120
	v_max_f32_e32 v16, v16, v16
	v_max_f32_e32 v17, v17, v17
	v_cvt_pk_bf16_f32 v24, v28, v29
	v_cvt_pk_bf16_f32 v26, v32, v33
	v_cvt_pk_bf16_f32 v27, v34, v35
	v_addc_co_u32_e32 v31, vcc, 0, v121, vcc
	v_max_f32_e32 v16, 0, v16
	v_max_f32_e32 v17, 0, v17
	global_store_dwordx4 v[30:31], v[24:27], off
	v_max_f32_e32 v20, v20, v20
	v_max_f32_e32 v21, v21, v21
	v_pk_mul_f32 v[24:25], v[16:17], v[16:17]
	v_max_f32_e32 v17, v18, v18
	v_max_f32_e32 v16, v22, v22
	v_max_f32_e32 v18, 0, v17
	v_max_f32_e32 v17, v23, v23
	v_max_f32_e32 v19, v19, v19
	v_max_f32_e32 v20, 0, v20
	v_max_f32_e32 v21, 0, v21
	v_max_f32_e32 v16, 0, v16
	v_max_f32_e32 v17, 0, v17
	v_max_f32_e32 v19, 0, v19
	v_pk_mul_f32 v[20:21], v[20:21], v[20:21]
	v_pk_mul_f32 v[22:23], v[16:17], v[16:17]
	v_pk_mul_f32 v[26:27], v[18:19], v[18:19]
	v_max_f32_e32 v8, v8, v8
	v_max_f32_e32 v9, v9, v9
	v_lshl_add_u64 v[28:29], v[120:121], 0, s[16:17]
	v_cvt_pk_bf16_f32 v16, v20, v21
	v_cvt_pk_bf16_f32 v17, v22, v23
	v_cvt_pk_bf16_f32 v18, v24, v25
	v_cvt_pk_bf16_f32 v19, v26, v27
	v_max_f32_e32 v8, 0, v8
	v_max_f32_e32 v9, 0, v9
	global_store_dwordx4 v[28:29], v[16:19], off offset:256
	v_max_f32_e32 v12, v12, v12
	v_max_f32_e32 v13, v13, v13
	v_pk_mul_f32 v[16:17], v[8:9], v[8:9]
	v_max_f32_e32 v9, v10, v10
	v_max_f32_e32 v8, v14, v14
	v_max_f32_e32 v10, 0, v9
	v_max_f32_e32 v9, v15, v15
	v_max_f32_e32 v8, 0, v8
	v_max_f32_e32 v9, 0, v9
	v_max_f32_e32 v11, v11, v11
	v_max_f32_e32 v12, 0, v12
	v_max_f32_e32 v13, 0, v13
	v_max_f32_e32 v11, 0, v11
	v_pk_mul_f32 v[14:15], v[8:9], v[8:9]
	v_pk_mul_f32 v[12:13], v[12:13], v[12:13]
	v_pk_mul_f32 v[18:19], v[10:11], v[10:11]
	v_cvt_pk_bf16_f32 v9, v14, v15
	v_add_co_u32_e32 v14, vcc, s71, v120
	v_max_f32_e32 v0, v0, v0
	v_max_f32_e32 v1, v1, v1
	v_cvt_pk_bf16_f32 v8, v12, v13
	v_cvt_pk_bf16_f32 v10, v16, v17
	v_cvt_pk_bf16_f32 v11, v18, v19
	v_addc_co_u32_e32 v15, vcc, 0, v121, vcc
	v_max_f32_e32 v0, 0, v0
	v_max_f32_e32 v1, 0, v1
	global_store_dwordx4 v[14:15], v[8:11], off
	v_max_f32_e32 v4, v4, v4
	v_max_f32_e32 v5, v5, v5
	v_pk_mul_f32 v[8:9], v[0:1], v[0:1]
	v_max_f32_e32 v1, v2, v2
	v_max_f32_e32 v0, v6, v6
	v_max_f32_e32 v2, 0, v1
	v_max_f32_e32 v1, v7, v7
	v_max_f32_e32 v3, v3, v3
	v_max_f32_e32 v4, 0, v4
	v_max_f32_e32 v5, 0, v5
	v_max_f32_e32 v0, 0, v0
	v_max_f32_e32 v1, 0, v1
	v_max_f32_e32 v3, 0, v3
	v_pk_mul_f32 v[4:5], v[4:5], v[4:5]
	v_pk_mul_f32 v[6:7], v[0:1], v[0:1]
	v_pk_mul_f32 v[10:11], v[2:3], v[2:3]
	v_lshl_add_u64 v[12:13], v[120:121], 0, s[18:19]
	v_cvt_pk_bf16_f32 v0, v4, v5
	v_cvt_pk_bf16_f32 v1, v6, v7
	v_cvt_pk_bf16_f32 v2, v8, v9
	v_cvt_pk_bf16_f32 v3, v10, v11
	s_and_b64 vcc, exec, s[4:5]
	s_mov_b32 s72, s20
	s_mov_b32 s34, s26
	s_mov_b64 s[38:39], s[30:31]
	s_mov_b64 s[36:37], s[28:29]
	global_store_dwordx4 v[12:13], v[0:3], off offset:256
	s_cbranch_vccz .LBB0_1303
	s_waitcnt vmcnt(0)
	s_cmpk_gt_u32 s42, 0xff
	s_cbranch_scc1 .LBB0_1314
	s_barrier

.LBB0_1384:
	ds_read_b128 v[156:159], v153
	ds_read_b128 v[160:163], v153 offset:1024
	ds_read_b128 v[164:167], v153 offset:2048
	ds_read_b128 v[168:171], v153 offset:3072
	s_add_u32 s36, s34, 0xfff00080
	s_addc_u32 s37, s35, -1
	s_cmp_eq_u32 s77, 60
	s_cselect_b32 s39, s27, s37
	s_cselect_b32 s38, s73, s36
	s_cselect_b32 s37, s21, s76
	s_cselect_b32 s36, s74, s75
	v_lshl_add_u64 v[204:205], s[34:35], 0, v[138:139]
	s_add_i32 m0, s19, 0xc000
	ds_read_b128 v[172:175], v154
	ds_read_b128 v[176:179], v154 offset:1024
	ds_read_b128 v[180:183], v154 offset:2048
	ds_read_b128 v[184:187], v154 offset:3072
	ds_read_b128 v[188:191], v154 offset:4096
	ds_read_b128 v[192:195], v154 offset:5120
	ds_read_b128 v[196:199], v154 offset:6144
	ds_read_b128 v[200:203], v154 offset:7168
	global_load_lds_dwordx4 v[204:205], off
	v_lshl_add_u64 v[204:205], s[34:35], 0, v[140:141]
	s_add_i32 m0, s19, 0xe000
	s_nop 0
	global_load_lds_dwordx4 v[204:205], off
	s_waitcnt lgkmcnt(8)
	s_barrier
	s_waitcnt lgkmcnt(0)
	s_waitcnt lgkmcnt(0)
	v_mfma_f32_16x16x32_bf16 v[124:127], v[156:159], v[172:175], v[124:127]
	v_mfma_f32_16x16x32_bf16 v[120:123], v[164:167], v[172:175], v[120:123]
	v_mfma_f32_16x16x32_bf16 v[116:119], v[156:159], v[180:183], v[116:119]
	v_mfma_f32_16x16x32_bf16 v[112:115], v[164:167], v[180:183], v[112:115]
	v_mfma_f32_16x16x32_bf16 v[100:103], v[156:159], v[188:191], v[100:103]
	v_mfma_f32_16x16x32_bf16 v[96:99], v[164:167], v[188:191], v[96:99]
	v_mfma_f32_16x16x32_bf16 v[84:87], v[156:159], v[196:199], v[84:87]
	v_mfma_f32_16x16x32_bf16 v[80:83], v[164:167], v[196:199], v[80:83]
	v_mfma_f32_16x16x32_bf16 v[124:127], v[160:163], v[176:179], v[124:127]
	v_mfma_f32_16x16x32_bf16 v[120:123], v[168:171], v[176:179], v[120:123]
	v_mfma_f32_16x16x32_bf16 v[116:119], v[160:163], v[184:187], v[116:119]
	v_mfma_f32_16x16x32_bf16 v[112:115], v[168:171], v[184:187], v[112:115]
	v_mfma_f32_16x16x32_bf16 v[100:103], v[160:163], v[192:195], v[100:103]
	v_mfma_f32_16x16x32_bf16 v[96:99], v[168:171], v[192:195], v[96:99]
	v_mfma_f32_16x16x32_bf16 v[84:87], v[160:163], v[200:203], v[84:87]
	v_mfma_f32_16x16x32_bf16 v[80:83], v[168:171], v[200:203], v[80:83]
	s_barrier
	s_add_i32 s78, s62, s43
	v_lshl_add_u64 v[220:221], s[36:37], 0, v[134:135]
	s_mov_b32 m0, s78
	ds_read_b128 v[204:207], v155
	ds_read_b128 v[208:211], v155 offset:1024
	ds_read_b128 v[212:215], v155 offset:2048
	ds_read_b128 v[216:219], v155 offset:3072
	global_load_lds_dwordx4 v[220:221], off
	v_lshl_add_u64 v[222:223], s[36:37], 0, v[130:131]
	s_add_i32 m0, s78, 0x2000
	s_nop 0
	global_load_lds_dwordx4 v[222:223], off
	s_barrier
	s_waitcnt lgkmcnt(0)
	s_waitcnt lgkmcnt(0)
	v_mfma_f32_16x16x32_bf16 v[108:111], v[204:207], v[172:175], v[108:111]
	v_mfma_f32_16x16x32_bf16 v[104:107], v[212:215], v[172:175], v[104:107]
	v_mfma_f32_16x16x32_bf16 v[92:95], v[204:207], v[180:183], v[92:95]
	v_mfma_f32_16x16x32_bf16 v[88:91], v[212:215], v[180:183], v[88:91]
	v_mfma_f32_16x16x32_bf16 v[76:79], v[204:207], v[188:191], v[76:79]
	v_mfma_f32_16x16x32_bf16 v[72:75], v[212:215], v[188:191], v[72:75]
	v_mfma_f32_16x16x32_bf16 v[68:71], v[204:207], v[196:199], v[68:71]
	v_mfma_f32_16x16x32_bf16 v[64:67], v[212:215], v[196:199], v[64:67]
	v_mfma_f32_16x16x32_bf16 v[108:111], v[208:211], v[176:179], v[108:111]
	v_mfma_f32_16x16x32_bf16 v[104:107], v[216:219], v[176:179], v[104:107]
	v_mfma_f32_16x16x32_bf16 v[92:95], v[208:211], v[184:187], v[92:95]
	v_mfma_f32_16x16x32_bf16 v[88:91], v[216:219], v[184:187], v[88:91]
	v_mfma_f32_16x16x32_bf16 v[76:79], v[208:211], v[192:195], v[76:79]
	v_mfma_f32_16x16x32_bf16 v[72:75], v[216:219], v[192:195], v[72:75]
	v_mfma_f32_16x16x32_bf16 v[68:71], v[208:211], v[200:203], v[68:71]
	v_mfma_f32_16x16x32_bf16 v[64:67], v[216:219], v[200:203], v[64:67]
	s_mov_b32 m0, s19
	v_lshl_add_u64 v[224:225], s[38:39], 0, v[136:137]
	s_barrier
	ds_read_b128 v[172:175], v154 offset:16384
	ds_read_b128 v[176:179], v154 offset:17408
	ds_read_b128 v[180:183], v154 offset:18432
	ds_read_b128 v[184:187], v154 offset:19456
	ds_read_b128 v[188:191], v154 offset:20480
	ds_read_b128 v[192:195], v154 offset:21504
	ds_read_b128 v[196:199], v154 offset:22528
	ds_read_b128 v[200:203], v154 offset:23552
	global_load_lds_dwordx4 v[224:225], off
	v_lshl_add_u64 v[226:227], s[38:39], 0, v[132:133]
	s_mov_b32 m0, s53
	s_nop 0
	global_load_lds_dwordx4 v[226:227], off
	s_barrier
	s_waitcnt lgkmcnt(0)
	s_waitcnt lgkmcnt(0)
	v_mfma_f32_16x16x32_bf16 v[60:63], v[156:159], v[172:175], v[60:63]
	v_mfma_f32_16x16x32_bf16 v[56:59], v[164:167], v[172:175], v[56:59]
	v_mfma_f32_16x16x32_bf16 v[52:55], v[156:159], v[180:183], v[52:55]
	v_mfma_f32_16x16x32_bf16 v[48:51], v[164:167], v[180:183], v[48:51]
	v_mfma_f32_16x16x32_bf16 v[36:39], v[156:159], v[188:191], v[36:39]
	v_mfma_f32_16x16x32_bf16 v[32:35], v[164:167], v[188:191], v[32:35]
	v_mfma_f32_16x16x32_bf16 v[20:23], v[156:159], v[196:199], v[20:23]
	v_mfma_f32_16x16x32_bf16 v[16:19], v[164:167], v[196:199], v[16:19]
	v_mfma_f32_16x16x32_bf16 v[60:63], v[160:163], v[176:179], v[60:63]
	v_mfma_f32_16x16x32_bf16 v[56:59], v[168:171], v[176:179], v[56:59]
	v_mfma_f32_16x16x32_bf16 v[52:55], v[160:163], v[184:187], v[52:55]
	v_mfma_f32_16x16x32_bf16 v[48:51], v[168:171], v[184:187], v[48:51]
	v_mfma_f32_16x16x32_bf16 v[36:39], v[160:163], v[192:195], v[36:39]
	v_mfma_f32_16x16x32_bf16 v[32:35], v[168:171], v[192:195], v[32:35]
	v_mfma_f32_16x16x32_bf16 v[20:23], v[160:163], v[200:203], v[20:23]
	v_mfma_f32_16x16x32_bf16 v[16:19], v[168:171], v[200:203], v[16:19]
	s_barrier
	s_add_u32 s78, s36, 0x100000
	s_addc_u32 s79, s37, 0
	s_add_i32 s80, s63, s43
	v_lshl_add_u64 v[156:157], s[78:79], 0, v[134:135]
	s_mov_b32 m0, s80
	s_nop 0
	global_load_lds_dwordx4 v[156:157], off
	v_lshl_add_u64 v[156:157], s[78:79], 0, v[130:131]
	s_add_i32 m0, s80, 0x2000
	s_nop 0
	global_load_lds_dwordx4 v[156:157], off
	s_waitcnt vmcnt(6)
	s_barrier
	v_mfma_f32_16x16x32_bf16 v[44:47], v[204:207], v[172:175], v[44:47]
	v_mfma_f32_16x16x32_bf16 v[40:43], v[212:215], v[172:175], v[40:43]
	v_mfma_f32_16x16x32_bf16 v[28:31], v[204:207], v[180:183], v[28:31]
	v_mfma_f32_16x16x32_bf16 v[24:27], v[212:215], v[180:183], v[24:27]
	v_mfma_f32_16x16x32_bf16 v[12:15], v[204:207], v[188:191], v[12:15]
	v_mfma_f32_16x16x32_bf16 v[8:11], v[212:215], v[188:191], v[8:11]
	v_mfma_f32_16x16x32_bf16 v[4:7], v[204:207], v[196:199], v[4:7]
	v_mfma_f32_16x16x32_bf16 v[0:3], v[212:215], v[196:199], v[0:3]
	v_mfma_f32_16x16x32_bf16 v[44:47], v[208:211], v[176:179], v[44:47]
	v_mfma_f32_16x16x32_bf16 v[40:43], v[216:219], v[176:179], v[40:43]
	v_mfma_f32_16x16x32_bf16 v[28:31], v[208:211], v[184:187], v[28:31]
	v_mfma_f32_16x16x32_bf16 v[24:27], v[216:219], v[184:187], v[24:27]
	v_mfma_f32_16x16x32_bf16 v[12:15], v[208:211], v[192:195], v[12:15]
	v_mfma_f32_16x16x32_bf16 v[8:11], v[216:219], v[192:195], v[8:11]
	v_mfma_f32_16x16x32_bf16 v[4:7], v[208:211], v[200:203], v[4:7]
	v_mfma_f32_16x16x32_bf16 v[0:3], v[216:219], v[200:203], v[0:3]
	s_add_i32 s78, 0, 0x18000
	v_add_u32_e32 v168, s78, v151
	s_barrier
	ds_read_b128 v[156:159], v168
	ds_read_b128 v[160:163], v168 offset:1024
	ds_read_b128 v[164:167], v168 offset:2048
	ds_read_b128 v[168:171], v168 offset:3072
	s_add_u32 s38, s38, 0x100000
	s_addc_u32 s39, s39, 0
	s_mov_b32 m0, s54
	v_lshl_add_u64 v[204:205], s[38:39], 0, v[136:137]
	ds_read_b128 v[172:175], v154 offset:32768
	ds_read_b128 v[176:179], v154 offset:33792
	ds_read_b128 v[180:183], v154 offset:34816
	ds_read_b128 v[184:187], v154 offset:35840
	ds_read_b128 v[188:191], v154 offset:36864
	ds_read_b128 v[192:195], v154 offset:37888
	ds_read_b128 v[196:199], v154 offset:38912
	ds_read_b128 v[200:203], v154 offset:39936
	global_load_lds_dwordx4 v[204:205], off
	v_lshl_add_u64 v[204:205], s[38:39], 0, v[132:133]
	s_mov_b32 m0, s55
	s_nop 0
	global_load_lds_dwordx4 v[204:205], off
	s_waitcnt lgkmcnt(8)
	s_barrier
	s_waitcnt lgkmcnt(0)
	s_waitcnt lgkmcnt(0)
	v_mfma_f32_16x16x32_bf16 v[124:127], v[156:159], v[172:175], v[124:127]
	v_mfma_f32_16x16x32_bf16 v[120:123], v[164:167], v[172:175], v[120:123]
	v_mfma_f32_16x16x32_bf16 v[116:119], v[156:159], v[180:183], v[116:119]
	v_mfma_f32_16x16x32_bf16 v[112:115], v[164:167], v[180:183], v[112:115]
	v_mfma_f32_16x16x32_bf16 v[100:103], v[156:159], v[188:191], v[100:103]
	v_mfma_f32_16x16x32_bf16 v[96:99], v[164:167], v[188:191], v[96:99]
	v_mfma_f32_16x16x32_bf16 v[84:87], v[156:159], v[196:199], v[84:87]
	v_mfma_f32_16x16x32_bf16 v[80:83], v[164:167], v[196:199], v[80:83]
	v_mfma_f32_16x16x32_bf16 v[124:127], v[160:163], v[176:179], v[124:127]
	v_mfma_f32_16x16x32_bf16 v[120:123], v[168:171], v[176:179], v[120:123]
	v_mfma_f32_16x16x32_bf16 v[116:119], v[160:163], v[184:187], v[116:119]
	v_mfma_f32_16x16x32_bf16 v[112:115], v[168:171], v[184:187], v[112:115]
	v_mfma_f32_16x16x32_bf16 v[100:103], v[160:163], v[192:195], v[100:103]
	v_mfma_f32_16x16x32_bf16 v[96:99], v[168:171], v[192:195], v[96:99]
	v_mfma_f32_16x16x32_bf16 v[84:87], v[160:163], v[200:203], v[84:87]
	v_mfma_f32_16x16x32_bf16 v[80:83], v[168:171], v[200:203], v[80:83]
	s_barrier
	s_add_i32 s38, 0, 0x1c000
	s_add_i32 s39, s78, s43
	v_add_u32_e32 v216, s38, v151
	v_lshl_add_u64 v[220:221], v[220:221], 0, s[8:9]
	s_mov_b32 m0, s39
	ds_read_b128 v[204:207], v216
	ds_read_b128 v[208:211], v216 offset:1024
	ds_read_b128 v[212:215], v216 offset:2048
	ds_read_b128 v[216:219], v216 offset:3072
	global_load_lds_dwordx4 v[220:221], off
	v_lshl_add_u64 v[220:221], v[222:223], 0, s[8:9]
	s_add_i32 m0, s39, 0x2000
	s_nop 0
	global_load_lds_dwordx4 v[220:221], off
	s_barrier
	s_waitcnt lgkmcnt(0)
	s_waitcnt lgkmcnt(0)
	v_mfma_f32_16x16x32_bf16 v[108:111], v[204:207], v[172:175], v[108:111]
	v_mfma_f32_16x16x32_bf16 v[104:107], v[212:215], v[172:175], v[104:107]
	v_mfma_f32_16x16x32_bf16 v[92:95], v[204:207], v[180:183], v[92:95]
	v_mfma_f32_16x16x32_bf16 v[88:91], v[212:215], v[180:183], v[88:91]
	v_mfma_f32_16x16x32_bf16 v[76:79], v[204:207], v[188:191], v[76:79]
	v_mfma_f32_16x16x32_bf16 v[72:75], v[212:215], v[188:191], v[72:75]
	v_mfma_f32_16x16x32_bf16 v[68:71], v[204:207], v[196:199], v[68:71]
	v_mfma_f32_16x16x32_bf16 v[64:67], v[212:215], v[196:199], v[64:67]
	v_mfma_f32_16x16x32_bf16 v[108:111], v[208:211], v[176:179], v[108:111]
	v_mfma_f32_16x16x32_bf16 v[104:107], v[216:219], v[176:179], v[104:107]
	v_mfma_f32_16x16x32_bf16 v[92:95], v[208:211], v[184:187], v[92:95]
	v_mfma_f32_16x16x32_bf16 v[88:91], v[216:219], v[184:187], v[88:91]
	v_mfma_f32_16x16x32_bf16 v[76:79], v[208:211], v[192:195], v[76:79]
	v_mfma_f32_16x16x32_bf16 v[72:75], v[216:219], v[192:195], v[72:75]
	v_mfma_f32_16x16x32_bf16 v[68:71], v[208:211], v[200:203], v[68:71]
	v_mfma_f32_16x16x32_bf16 v[64:67], v[216:219], v[200:203], v[64:67]
	s_mov_b32 m0, s57
	v_lshl_add_u64 v[220:221], v[224:225], 0, s[8:9]
	s_barrier
	ds_read_b128 v[172:175], v154 offset:49152
	ds_read_b128 v[176:179], v154 offset:50176
	ds_read_b128 v[180:183], v154 offset:51200
	ds_read_b128 v[184:187], v154 offset:52224
	ds_read_b128 v[188:191], v154 offset:53248
	ds_read_b128 v[192:195], v154 offset:54272
	ds_read_b128 v[196:199], v154 offset:55296
	ds_read_b128 v[200:203], v154 offset:56320
	global_load_lds_dwordx4 v[220:221], off
	v_lshl_add_u64 v[220:221], v[226:227], 0, s[8:9]
	s_mov_b32 m0, s60
	s_nop 0
	global_load_lds_dwordx4 v[220:221], off
	s_barrier
	s_waitcnt lgkmcnt(0)
	s_waitcnt lgkmcnt(0)
	v_mfma_f32_16x16x32_bf16 v[60:63], v[156:159], v[172:175], v[60:63]
	v_mfma_f32_16x16x32_bf16 v[56:59], v[164:167], v[172:175], v[56:59]
	v_mfma_f32_16x16x32_bf16 v[52:55], v[156:159], v[180:183], v[52:55]
	v_mfma_f32_16x16x32_bf16 v[48:51], v[164:167], v[180:183], v[48:51]
	v_mfma_f32_16x16x32_bf16 v[36:39], v[156:159], v[188:191], v[36:39]
	v_mfma_f32_16x16x32_bf16 v[32:35], v[164:167], v[188:191], v[32:35]
	v_mfma_f32_16x16x32_bf16 v[20:23], v[156:159], v[196:199], v[20:23]
	v_mfma_f32_16x16x32_bf16 v[16:19], v[164:167], v[196:199], v[16:19]
	v_mfma_f32_16x16x32_bf16 v[60:63], v[160:163], v[176:179], v[60:63]
	v_mfma_f32_16x16x32_bf16 v[56:59], v[168:171], v[176:179], v[56:59]
	v_mfma_f32_16x16x32_bf16 v[52:55], v[160:163], v[184:187], v[52:55]
	v_mfma_f32_16x16x32_bf16 v[48:51], v[168:171], v[184:187], v[48:51]
	v_mfma_f32_16x16x32_bf16 v[36:39], v[160:163], v[192:195], v[36:39]
	v_mfma_f32_16x16x32_bf16 v[32:35], v[168:171], v[192:195], v[32:35]
	v_mfma_f32_16x16x32_bf16 v[20:23], v[160:163], v[200:203], v[20:23]
	v_mfma_f32_16x16x32_bf16 v[16:19], v[168:171], v[200:203], v[16:19]
	s_barrier
	s_add_u32 s36, s36, 0x100080
	s_addc_u32 s37, s37, 0
	s_add_i32 s38, s38, s43
	v_lshl_add_u64 v[156:157], s[36:37], 0, v[134:135]
	s_mov_b32 m0, s38
	s_nop 0
	global_load_lds_dwordx4 v[156:157], off
	v_lshl_add_u64 v[156:157], s[36:37], 0, v[130:131]
	s_add_i32 m0, s38, 0x2000
	s_nop 0
	global_load_lds_dwordx4 v[156:157], off
	s_waitcnt vmcnt(6)
	s_barrier
	v_mfma_f32_16x16x32_bf16 v[44:47], v[204:207], v[172:175], v[44:47]
	v_mfma_f32_16x16x32_bf16 v[40:43], v[212:215], v[172:175], v[40:43]
	v_mfma_f32_16x16x32_bf16 v[28:31], v[204:207], v[180:183], v[28:31]
	v_mfma_f32_16x16x32_bf16 v[24:27], v[212:215], v[180:183], v[24:27]
	v_mfma_f32_16x16x32_bf16 v[12:15], v[204:207], v[188:191], v[12:15]
	v_mfma_f32_16x16x32_bf16 v[8:11], v[212:215], v[188:191], v[8:11]
	v_mfma_f32_16x16x32_bf16 v[4:7], v[204:207], v[196:199], v[4:7]
	v_mfma_f32_16x16x32_bf16 v[0:3], v[212:215], v[196:199], v[0:3]
	v_mfma_f32_16x16x32_bf16 v[44:47], v[208:211], v[176:179], v[44:47]
	v_mfma_f32_16x16x32_bf16 v[40:43], v[216:219], v[176:179], v[40:43]
	v_mfma_f32_16x16x32_bf16 v[28:31], v[208:211], v[184:187], v[28:31]
	v_mfma_f32_16x16x32_bf16 v[24:27], v[216:219], v[184:187], v[24:27]
	v_mfma_f32_16x16x32_bf16 v[12:15], v[208:211], v[192:195], v[12:15]
	v_mfma_f32_16x16x32_bf16 v[8:11], v[216:219], v[192:195], v[8:11]
	v_mfma_f32_16x16x32_bf16 v[4:7], v[208:211], v[200:203], v[4:7]
	v_mfma_f32_16x16x32_bf16 v[0:3], v[216:219], v[200:203], v[0:3]
	s_add_i32 s77, s77, 2
	s_add_u32 s34, s34, 0x100
	s_addc_u32 s35, s35, 0
	s_add_u32 s75, s75, 0x100
	s_addc_u32 s76, s76, 0
	s_cmp_gt_u32 s77, 61
	s_barrier
	s_cbranch_scc0 .LBB0_1384
	v_lshl_add_u32 v156, s18, 8, v150
	v_lshl_or_b32 v158, s72, 8, v152
	v_ashrrev_i32_e32 v157, 31, v156
	v_lshlrev_b64 v[160:161], 11, v[156:157]
	v_ashrrev_i32_e32 v159, 31, v158
	v_lshl_add_u64 v[160:161], s[44:45], 0, v[160:161]
	v_cvt_pk_bf16_f32 v124, v124, v125
	v_cvt_pk_bf16_f32 v125, v126, v127
	v_cvt_pk_bf16_f32 v126, v120, v121
	v_lshlrev_b64 v[120:121], 1, v[158:159]
	v_cvt_pk_bf16_f32 v127, v122, v123
	v_lshl_add_u64 v[122:123], v[160:161], 0, v[120:121]
	v_cvt_pk_bf16_f32 v108, v108, v109
	v_cvt_pk_bf16_f32 v109, v110, v111
	v_cvt_pk_bf16_f32 v110, v104, v105
	v_or_b32_e32 v104, 16, v156
	v_cvt_pk_bf16_f32 v60, v60, v61
	v_cvt_pk_bf16_f32 v61, v62, v63
	v_cvt_pk_bf16_f32 v63, v58, v59
	v_add_co_u32_e32 v58, vcc, s64, v122
	v_ashrrev_i32_e32 v105, 31, v104
	v_cvt_pk_bf16_f32 v62, v56, v57
	v_lshl_add_u64 v[56:57], v[122:123], 0, s[10:11]
	v_addc_co_u32_e32 v59, vcc, 0, v123, vcc
	v_cvt_pk_bf16_f32 v44, v44, v45
	v_cvt_pk_bf16_f32 v45, v46, v47
	v_cvt_pk_bf16_f32 v46, v40, v41
	v_cvt_pk_bf16_f32 v47, v42, v43
	v_cvt_pk_bf16_f32 v111, v106, v107
	v_lshlrev_b64 v[104:105], 11, v[104:105]
	v_cvt_pk_bf16_f32 v92, v92, v93
	v_cvt_pk_bf16_f32 v93, v94, v95
	v_cvt_pk_bf16_f32 v94, v88, v89
	v_or_b32_e32 v88, 32, v156
	global_store_dwordx4 v[56:57], v[44:47], off offset:256
	global_store_dwordx4 v[122:123], v[108:111], off offset:256
	v_ashrrev_i32_e32 v89, 31, v88
	v_add_co_u32_e32 v46, vcc, s65, v122
	v_lshl_add_u64 v[108:109], s[44:45], 0, v[104:105]
	v_lshl_add_u64 v[44:45], v[122:123], 0, s[12:13]
	v_addc_co_u32_e32 v47, vcc, 0, v123, vcc
	v_cvt_pk_bf16_f32 v28, v28, v29
	v_cvt_pk_bf16_f32 v29, v30, v31
	v_cvt_pk_bf16_f32 v30, v24, v25
	v_cvt_pk_bf16_f32 v31, v26, v27
	v_lshl_add_u64 v[108:109], v[108:109], 0, v[120:121]
	v_cvt_pk_bf16_f32 v95, v90, v91
	v_lshlrev_b64 v[88:89], 11, v[88:89]
	v_cvt_pk_bf16_f32 v76, v76, v77
	v_cvt_pk_bf16_f32 v77, v78, v79
	v_cvt_pk_bf16_f32 v78, v72, v73
	v_or_b32_e32 v72, 48, v156
	global_store_dwordx4 v[44:45], v[28:31], off offset:256
	global_store_dwordx4 v[108:109], v[92:95], off offset:256
	v_ashrrev_i32_e32 v73, 31, v72
	v_add_co_u32_e32 v30, vcc, s70, v122
	v_lshl_add_u64 v[92:93], s[44:45], 0, v[88:89]
	v_lshl_add_u64 v[28:29], v[122:123], 0, s[14:15]
	v_addc_co_u32_e32 v31, vcc, 0, v123, vcc
	v_cvt_pk_bf16_f32 v12, v12, v13
	v_cvt_pk_bf16_f32 v13, v14, v15
	v_cvt_pk_bf16_f32 v14, v8, v9
	v_cvt_pk_bf16_f32 v15, v10, v11
	v_lshl_add_u64 v[92:93], v[92:93], 0, v[120:121]
	v_cvt_pk_bf16_f32 v79, v74, v75
	v_lshlrev_b64 v[72:73], 11, v[72:73]
	global_store_dwordx4 v[28:29], v[12:15], off offset:256
	global_store_dwordx4 v[92:93], v[76:79], off offset:256
	v_cvt_pk_bf16_f32 v104, v116, v117
	v_add_co_u32_e32 v14, vcc, s71, v122
	v_lshl_add_u64 v[76:77], s[44:45], 0, v[72:73]
	s_nop 0
	v_addc_co_u32_e32 v15, vcc, 0, v123, vcc
	v_cvt_pk_bf16_f32 v105, v118, v119
	v_cvt_pk_bf16_f32 v106, v112, v113
	v_cvt_pk_bf16_f32 v107, v114, v115
	v_cvt_pk_bf16_f32 v88, v100, v101
	v_cvt_pk_bf16_f32 v89, v102, v103
	v_cvt_pk_bf16_f32 v90, v96, v97
	v_cvt_pk_bf16_f32 v91, v98, v99
	v_cvt_pk_bf16_f32 v72, v84, v85
	v_cvt_pk_bf16_f32 v73, v86, v87
	v_cvt_pk_bf16_f32 v74, v80, v81
	v_cvt_pk_bf16_f32 v75, v82, v83
	v_lshl_add_u64 v[76:77], v[76:77], 0, v[120:121]
	v_cvt_pk_bf16_f32 v68, v68, v69
	v_cvt_pk_bf16_f32 v69, v70, v71
	v_cvt_pk_bf16_f32 v70, v64, v65
	v_cvt_pk_bf16_f32 v71, v66, v67
	v_cvt_pk_bf16_f32 v40, v52, v53
	v_cvt_pk_bf16_f32 v41, v54, v55
	v_cvt_pk_bf16_f32 v42, v48, v49
	v_cvt_pk_bf16_f32 v43, v50, v51
	v_cvt_pk_bf16_f32 v24, v36, v37
	v_cvt_pk_bf16_f32 v25, v38, v39
	v_cvt_pk_bf16_f32 v26, v32, v33
	v_cvt_pk_bf16_f32 v27, v34, v35
	v_cvt_pk_bf16_f32 v8, v20, v21
	v_cvt_pk_bf16_f32 v9, v22, v23
	v_cvt_pk_bf16_f32 v10, v16, v17
	v_cvt_pk_bf16_f32 v11, v18, v19
	v_lshl_add_u64 v[12:13], v[122:123], 0, s[16:17]
	v_cvt_pk_bf16_f32 v4, v4, v5
	v_cvt_pk_bf16_f32 v5, v6, v7
	v_cvt_pk_bf16_f32 v6, v0, v1
	v_cvt_pk_bf16_f32 v7, v2, v3
	s_and_b64 vcc, exec, s[4:5]
	s_mov_b32 s72, s20
	s_mov_b32 s18, s26
	s_mov_b64 s[36:37], s[30:31]
	s_mov_b64 s[34:35], s[28:29]
	global_store_dwordx4 v[122:123], v[124:127], off
	global_store_dwordx4 v[108:109], v[104:107], off
	global_store_dwordx4 v[92:93], v[88:91], off
	global_store_dwordx4 v[76:77], v[72:75], off
	global_store_dwordx4 v[76:77], v[68:71], off offset:256
	global_store_dwordx4 v[58:59], v[60:63], off
	global_store_dwordx4 v[46:47], v[40:43], off
	global_store_dwordx4 v[30:31], v[24:27], off
	global_store_dwordx4 v[14:15], v[8:11], off
	global_store_dwordx4 v[12:13], v[4:7], off offset:256
	s_cbranch_vccz .LBB0_1381
	s_waitcnt vmcnt(0)
	s_cmpk_gt_u32 s40, 0xff
	s_cbranch_scc1 .LBB0_1388
	s_barrier

	.amdhsa_kernel _Z11mega_kernel6Params
		.amdhsa_group_segment_fixed_size 0
		.amdhsa_private_segment_fixed_size 0
		.amdhsa_kernarg_size 584
		.amdhsa_user_sgpr_count 2
		.amdhsa_user_sgpr_dispatch_ptr 0
		.amdhsa_user_sgpr_queue_ptr 0
		.amdhsa_user_sgpr_kernarg_segment_ptr 1
		.amdhsa_user_sgpr_dispatch_id 0
		.amdhsa_user_sgpr_kernarg_preload_length 0
		.amdhsa_user_sgpr_kernarg_preload_offset 0
		.amdhsa_user_sgpr_private_segment_size 0
		.amdhsa_uses_dynamic_stack 0
		.amdhsa_enable_private_segment 0
		.amdhsa_system_sgpr_workgroup_id_x 1
		.amdhsa_system_sgpr_workgroup_id_y 0
		.amdhsa_system_sgpr_workgroup_id_z 0
		.amdhsa_system_sgpr_workgroup_info 0
		.amdhsa_system_vgpr_workitem_id 2
		.amdhsa_next_free_vgpr 256
		.amdhsa_next_free_sgpr 96
		.amdhsa_accum_offset 256
		.amdhsa_reserve_vcc 1
		.amdhsa_float_round_mode_32 0
		.amdhsa_float_round_mode_16_64 0
		.amdhsa_float_denorm_mode_32 3
		.amdhsa_float_denorm_mode_16_64 3
		.amdhsa_dx10_clamp 1
		.amdhsa_ieee_mode 1
		.amdhsa_fp16_overflow 0
		.amdhsa_tg_split 0
		.amdhsa_exception_fp_ieee_invalid_op 0
		.amdhsa_exception_fp_denorm_src 0
		.amdhsa_exception_fp_ieee_div_zero 0
		.amdhsa_exception_fp_ieee_overflow 0
		.amdhsa_exception_fp_ieee_underflow 0
		.amdhsa_exception_fp_ieee_inexact 0
		.amdhsa_exception_int_div_zero 0
	.end_amdhsa_kernel

amdhsa.kernels:
  - .agpr_count:     0
    .args:
      - .offset:         0
        .size:           328
        .value_kind:     by_value
      - .offset:         328
        .size:           4
        .value_kind:     hidden_block_count_x
      - .offset:         332
        .size:           4
        .value_kind:     hidden_block_count_y
      - .offset:         336
        .size:           4
        .value_kind:     hidden_block_count_z
      - .offset:         340
        .size:           2
        .value_kind:     hidden_group_size_x
      - .offset:         342
        .size:           2
        .value_kind:     hidden_group_size_y
      - .offset:         344
        .size:           2
        .value_kind:     hidden_group_size_z
      - .offset:         346
        .size:           2
        .value_kind:     hidden_remainder_x
      - .offset:         348
        .size:           2
        .value_kind:     hidden_remainder_y
      - .offset:         350
        .size:           2
        .value_kind:     hidden_remainder_z
      - .offset:         368
        .size:           8
        .value_kind:     hidden_global_offset_x
      - .offset:         376
        .size:           8
        .value_kind:     hidden_global_offset_y
      - .offset:         384
        .size:           8
        .value_kind:     hidden_global_offset_z
      - .offset:         392
        .size:           2
        .value_kind:     hidden_grid_dims
      - .offset:         416
        .size:           8
        .value_kind:     hidden_multigrid_sync_arg
      - .offset:         448
        .size:           4
        .value_kind:     hidden_dynamic_lds_size
    .group_segment_fixed_size: 0
    .kernarg_segment_align: 8
    .kernarg_segment_size: 584
    .language:       OpenCL C
    .language_version:
      - 2
      - 0
    .max_flat_workgroup_size: 512
    .name:           _Z11mega_kernel6Params
    .private_segment_fixed_size: 0
    .sgpr_count:     102
    .sgpr_spill_count: 16
    .symbol:         _Z11mega_kernel6Params.kd
    .uniform_work_group_size: 1
    .uses_dynamic_stack: false
    .vgpr_count:     256
    .vgpr_spill_count: 0
    .wavefront_size: 64
